# plus: f32 v_rsq_f32 for the rsqrt chains (RMSNorm rstd), row-scale epilogues preload ss before the K-loop and no longer drain vmcnt at their top, subln_g 4-load ladders batched, layer-0 attention tail
# speedup vs baseline: 1.0042x; 1.0042x over previous
.LBB0_478:
	global_load_dword v2, v[42:43], off
	s_waitcnt vmcnt(0)
	v_fmamk_f32 v2, v2, 0x3a800000, v208
	v_mul_f32_e32 v28, 0x4f800000, v2
	s_nop 1
	s_nop 0
	s_nop 1
	s_nop 1
	s_nop 1
	s_mov_b64 s[0:1], -1
	v_rsq_f32_e32 v2, v2
	s_nop 0
	v_mul_f32_e32 v28, 0x3e38aa3b, v2
	v_cndmask_b32_e64 v2, v2, v28, s[6:7]
	s_and_b64 vcc, exec, s[8:9]
	v_pk_mul_f32 v[26:27], v[26:27], v[2:3] op_sel_hi:[1,0]
	v_pk_mul_f32 v[24:25], v[24:25], v[2:3] op_sel_hi:[1,0]
	s_nop 0
	v_cvt_pk_bf16_f32 v28, v24, v25
	v_cvt_pk_bf16_f32 v29, v26, v27
	s_cbranch_vccnz .LBB0_485
	s_mov_b64 s[12:13], -1
	s_mov_b64 s[0:1], 0
	s_cmp_lt_i32 s17, 2
	s_mov_b64 s[10:11], 0
	s_cbranch_scc0 .LBB0_1014
	s_and_b64 vcc, exec, s[12:13]
	s_cbranch_vccnz .LBB0_1017

.LBB0_487:
	global_load_dword v2, v[42:43], off
	s_waitcnt vmcnt(0)
	v_fmamk_f32 v2, v2, 0x3a800000, v208
	v_mul_f32_e32 v24, 0x4f800000, v2
	s_nop 1
	s_nop 0
	s_nop 1
	s_nop 1
	s_nop 1
	s_mov_b64 s[0:1], -1
	v_rsq_f32_e32 v2, v2
	s_nop 0
	v_mul_f32_e32 v24, 0x3e38aa3b, v2
	v_cndmask_b32_e64 v2, v2, v24, s[6:7]
	s_and_b64 vcc, exec, s[8:9]
	v_pk_mul_f32 v[22:23], v[22:23], v[2:3] op_sel_hi:[1,0]
	v_pk_mul_f32 v[20:21], v[20:21], v[2:3] op_sel_hi:[1,0]
	s_nop 0
	v_cvt_pk_bf16_f32 v24, v20, v21
	v_cvt_pk_bf16_f32 v25, v22, v23
	s_cbranch_vccnz .LBB0_494
	s_mov_b64 s[12:13], -1
	s_mov_b64 s[0:1], 0
	s_cmp_lt_i32 s17, 2
	s_mov_b64 s[10:11], 0
	s_cbranch_scc0 .LBB0_1021
	s_and_b64 vcc, exec, s[12:13]
	s_cbranch_vccnz .LBB0_1024

.LBB0_540:
	s_ashr_i32 s75, s74, 31
	s_lshl_b64 s[0:1], s[74:75], 19
	s_add_u32 s0, s81, s0
	s_addc_u32 s1, s82, s1
	s_and_b64 s[12:13], s[8:9], exec
	s_cselect_b32 s11, s1, s5
	s_cselect_b32 s12, s0, s4
	s_ashr_i32 s41, s40, 31
	s_lshl_b64 s[14:15], s[40:41], 19
	s_add_u32 s96, s62, s14
	s_addc_u32 s97, s63, s15
	s_and_b64 s[8:9], s[8:9], exec
	s_cselect_b32 s13, s97, s7
	s_cselect_b32 s14, s96, s6
	s_add_u32 s4, s4, 0x40080
	s_addc_u32 s5, s5, 0
	s_add_u32 s15, s6, 0x100
	v_mov_b32_e32 v4, 0
	s_addc_u32 s16, s7, 0
	s_mov_b32 s17, -2
	v_mov_b32_e32 v5, v4
	v_mov_b32_e32 v6, v4
	v_mov_b32_e32 v7, v4
	v_mov_b32_e32 v8, v4
	v_mov_b32_e32 v9, v4
	v_mov_b32_e32 v10, v4
	v_mov_b32_e32 v11, v4
	v_mov_b32_e32 v20, v4
	v_mov_b32_e32 v21, v4
	v_mov_b32_e32 v22, v4
	v_mov_b32_e32 v23, v4
	v_mov_b32_e32 v24, v4
	v_mov_b32_e32 v25, v4
	v_mov_b32_e32 v26, v4
	v_mov_b32_e32 v27, v4
	v_mov_b32_e32 v36, v4
	v_mov_b32_e32 v37, v4
	v_mov_b32_e32 v38, v4
	v_mov_b32_e32 v39, v4
	v_mov_b32_e32 v40, v4
	v_mov_b32_e32 v41, v4
	v_mov_b32_e32 v42, v4
	v_mov_b32_e32 v43, v4
	v_mov_b32_e32 v52, v4
	v_mov_b32_e32 v53, v4
	v_mov_b32_e32 v54, v4
	v_mov_b32_e32 v55, v4
	v_mov_b32_e32 v56, v4
	v_mov_b32_e32 v57, v4
	v_mov_b32_e32 v58, v4
	v_mov_b32_e32 v59, v4
	v_mov_b32_e32 v12, v4
	v_mov_b32_e32 v13, v4
	v_mov_b32_e32 v14, v4
	v_mov_b32_e32 v15, v4
	v_mov_b32_e32 v16, v4
	v_mov_b32_e32 v17, v4
	v_mov_b32_e32 v18, v4
	v_mov_b32_e32 v19, v4
	v_mov_b32_e32 v28, v4
	v_mov_b32_e32 v29, v4
	v_mov_b32_e32 v30, v4
	v_mov_b32_e32 v31, v4
	v_mov_b32_e32 v32, v4
	v_mov_b32_e32 v33, v4
	v_mov_b32_e32 v34, v4
	v_mov_b32_e32 v35, v4
	v_mov_b32_e32 v44, v4
	v_mov_b32_e32 v45, v4
	v_mov_b32_e32 v46, v4
	v_mov_b32_e32 v47, v4
	v_mov_b32_e32 v48, v4
	v_mov_b32_e32 v49, v4
	v_mov_b32_e32 v50, v4
	v_mov_b32_e32 v51, v4
	v_mov_b32_e32 v60, v4
	v_mov_b32_e32 v61, v4
	v_mov_b32_e32 v62, v4
	v_mov_b32_e32 v63, v4
	v_mov_b32_e32 v64, v4
	v_mov_b32_e32 v65, v4
	v_mov_b32_e32 v66, v4
	v_mov_b32_e32 v67, v4
	v_mov_b32_e32 v68, v4
	v_mov_b32_e32 v69, v4
	v_mov_b32_e32 v70, v4
	v_mov_b32_e32 v71, v4
	v_mov_b32_e32 v72, v4
	v_mov_b32_e32 v73, v4
	v_mov_b32_e32 v74, v4
	v_mov_b32_e32 v75, v4
	v_mov_b32_e32 v84, v4
	v_mov_b32_e32 v85, v4
	v_mov_b32_e32 v86, v4
	v_mov_b32_e32 v87, v4
	v_mov_b32_e32 v88, v4
	v_mov_b32_e32 v89, v4
	v_mov_b32_e32 v90, v4
	v_mov_b32_e32 v91, v4
	v_mov_b32_e32 v100, v4
	v_mov_b32_e32 v101, v4
	v_mov_b32_e32 v102, v4
	v_mov_b32_e32 v103, v4
	v_mov_b32_e32 v104, v4
	v_mov_b32_e32 v105, v4
	v_mov_b32_e32 v106, v4
	v_mov_b32_e32 v107, v4
	v_mov_b32_e32 v116, v4
	v_mov_b32_e32 v117, v4
	v_mov_b32_e32 v118, v4
	v_mov_b32_e32 v119, v4
	v_mov_b32_e32 v120, v4
	v_mov_b32_e32 v121, v4
	v_mov_b32_e32 v122, v4
	v_mov_b32_e32 v123, v4
	v_mov_b32_e32 v76, v4
	v_mov_b32_e32 v77, v4
	v_mov_b32_e32 v78, v4
	v_mov_b32_e32 v79, v4
	v_mov_b32_e32 v80, v4
	v_mov_b32_e32 v81, v4
	v_mov_b32_e32 v82, v4
	v_mov_b32_e32 v83, v4
	v_mov_b32_e32 v92, v4
	v_mov_b32_e32 v93, v4
	v_mov_b32_e32 v94, v4
	v_mov_b32_e32 v95, v4
	v_mov_b32_e32 v96, v4
	v_mov_b32_e32 v97, v4
	v_mov_b32_e32 v98, v4
	v_mov_b32_e32 v99, v4
	v_mov_b32_e32 v108, v4
	v_mov_b32_e32 v109, v4
	v_mov_b32_e32 v110, v4
	v_mov_b32_e32 v111, v4
	v_mov_b32_e32 v112, v4
	v_mov_b32_e32 v113, v4
	v_mov_b32_e32 v114, v4
	v_mov_b32_e32 v115, v4
	v_mov_b32_e32 v124, v4
	v_mov_b32_e32 v125, v4
	v_mov_b32_e32 v126, v4
	v_mov_b32_e32 v127, v4
	v_mov_b32_e32 v128, v4
	v_mov_b32_e32 v129, v4
	v_mov_b32_e32 v130, v4
	v_mov_b32_e32 v131, v4
	s_lshl_b32 s8, s10, 8
	v_mov_b32_e32 v217, v1
	s_add_i32 s8, s8, s70
	v_add_u32_e32 v228, s8, v217
	v_ashrrev_i32_e32 v229, 31, v228
	v_lshl_add_u64 v[230:231], v[228:229], 2, s[50:51]
	global_load_dword v232, v[230:231], off
	global_load_dword v233, v[230:231], off offset:64
	global_load_dword v234, v[230:231], off offset:128
	global_load_dword v235, v[230:231], off offset:192
	global_load_dword v236, v[230:231], off offset:512
	global_load_dword v237, v[230:231], off offset:576
	global_load_dword v238, v[230:231], off offset:640
	global_load_dword v239, v[230:231], off offset:704

.LBB0_544:
	s_ashr_i32 s75, s20, 1
	s_and_b32 s8, s20, 1
	s_cmpk_gt_i32 s10, 0xff
	s_cselect_b64 s[4:5], -1, 0
	s_cmpk_lt_i32 s10, 0x100
	s_cselect_b64 s[52:53], -1, 0
	s_cmp_lt_u32 s20, 2
	s_cselect_b64 s[6:7], -1, 0
	s_cmp_gt_u32 s20, 1
	s_cselect_b64 s[14:15], -1, 0
	s_lshl_b32 s41, s8, 8
	s_lshl_b32 s43, s8, 6
	s_lshl_b32 s8, s10, 8
	v_mov_b32_e32 v2, v166
	v_mov_b32_e32 v169, v1
	s_add_i32 s8, s8, s70
	s_nop 0
	v_add_u32_e32 v150, s8, v169
	v_ashrrev_i32_e32 v151, 31, v150
	v_lshl_add_u64 v[152:153], v[150:151], 2, s[50:51]
	v_lshl_add_u32 v148, v2, 3, s71
	v_mov_b32_e32 v2, v232
	v_mov_b32_e32 v171, v233
	v_mov_b32_e32 v176, v234
	v_mov_b32_e32 v177, v235
	v_mov_b32_e32 v178, v236
	v_mov_b32_e32 v179, v237
	v_mov_b32_e32 v180, v238
	v_mov_b32_e32 v181, v239
	v_and_b32_e32 v170, 63, v169
	v_lshlrev_b64 v[158:159], 13, v[150:151]
	v_lshlrev_b64 v[154:155], 11, v[150:151]
	v_cmp_lt_u32_e64 s[10:11], 48, v170
	s_waitcnt vmcnt(8)
	v_fmamk_f32 v2, v2, 0x3a800000, v208
	s_nop 0
	s_nop 0
	s_nop 0
	s_nop 1
	s_nop 1
	s_movk_i32 s8, 0x1ff0
	v_rsq_f32_e32 v2, v2
	s_nop 0
	v_mul_f32_e32 v132, 0x3e38aa3b, v2
	v_cndmask_b32_e64 v164, v2, v132, s[6:7]
	v_add_u32_e32 v132, 0xffff0000, v150
	v_ashrrev_i32_e32 v133, 31, v132
	v_lshlrev_b64 v[156:157], 11, v[132:133]
	v_and_b32_e32 v2, 0x1fff, v150
	v_ashrrev_i32_e32 v133, 13, v150
	v_cmp_lt_u32_e64 s[12:13], s8, v2
	v_mul_i32_i24_e32 v133, 15, v133
	s_movk_i32 s8, 0xe00f
	v_add3_u32 v134, v2, v133, s8
	v_ashrrev_i32_e32 v132, 6, v132
	v_subrev_u32_e32 v2, 49, v170
	v_mad_u64_u32 v[132:133], s[8:9], v132, 15, v[2:3]
	v_ashrrev_i32_e32 v135, 31, v134
	v_ashrrev_i32_e32 v133, 31, v132
	v_lshlrev_b64 v[162:163], 11, v[134:135]
	v_lshlrev_b64 v[160:161], 11, v[132:133]
	v_pk_mul_f32 v[130:131], v[130:131], v[164:165] op_sel_hi:[1,0]
	v_pk_mul_f32 v[128:129], v[128:129], v[164:165] op_sel_hi:[1,0]
	v_pk_mul_f32 v[134:135], v[126:127], v[164:165] op_sel_hi:[1,0]
	v_pk_mul_f32 v[132:133], v[124:125], v[164:165] op_sel_hi:[1,0]
	s_mov_b64 s[8:9], -1
	s_and_b64 vcc, exec, s[14:15]
	v_cvt_pk_bf16_f32 v124, v128, v129
	v_cvt_pk_bf16_f32 v125, v130, v131
	v_cvt_pk_bf16_f32 v126, v132, v133
	v_cvt_pk_bf16_f32 v127, v134, v135
	s_cbranch_vccz .LBB0_551
	s_mov_b64 s[18:19], -1
	s_mov_b64 s[8:9], 0
	s_cmp_lt_i32 s75, 2
	s_mov_b64 s[16:17], 0
	s_cbranch_scc0 .LBB0_691
	s_and_b64 vcc, exec, s[18:19]
	s_cbranch_vccnz .LBB0_694

.LBB0_616:
	s_nop 1
	v_mov_b32_e32 v70, v178
	s_nop 0
	v_add_u32_e32 v68, 0x80, v150
	v_ashrrev_i32_e32 v69, 31, v68
	s_movk_i32 s21, 0xe00f
	s_mov_b64 s[86:87], -1
	v_fmamk_f32 v70, v70, 0x3a800000, v208
	s_nop 0
	s_nop 0
	s_nop 0
	s_nop 1
	s_nop 1
	s_movk_i32 s18, 0x1ff0
	v_lshlrev_b64 v[74:75], 13, v[68:69]
	v_lshlrev_b64 v[72:73], 11, v[68:69]
	v_and_b32_e32 v69, 0x1fff, v68
	v_ashrrev_i32_e32 v68, 13, v68
	v_rsq_f32_e32 v70, v70
	s_nop 0
	v_mul_i32_i24_e32 v68, 15, v68
	v_mul_f32_e32 v71, 0x3e38aa3b, v70
	v_add3_u32 v68, v69, v68, s21
	v_cndmask_b32_e64 v78, v70, v71, s[6:7]
	v_add_u32_e32 v70, 0xffff0080, v150
	v_cmp_lt_u32_e64 s[18:19], s18, v69
	v_ashrrev_i32_e32 v69, 31, v68
	v_lshlrev_b64 v[80:81], 11, v[68:69]
	v_ashrrev_i32_e32 v68, 6, v70
	v_mad_u64_u32 v[68:69], s[22:23], v68, 15, v[2:3]
	v_ashrrev_i32_e32 v71, 31, v70
	v_ashrrev_i32_e32 v69, 31, v68
	v_lshlrev_b64 v[76:77], 11, v[70:71]
	v_lshlrev_b64 v[82:83], 11, v[68:69]
	v_pk_mul_f32 v[66:67], v[66:67], v[78:79] op_sel_hi:[1,0]
	v_pk_mul_f32 v[64:65], v[64:65], v[78:79] op_sel_hi:[1,0]
	v_pk_mul_f32 v[70:71], v[62:63], v[78:79] op_sel_hi:[1,0]
	v_pk_mul_f32 v[68:69], v[60:61], v[78:79] op_sel_hi:[1,0]
	s_and_b64 vcc, exec, s[8:9]
	v_cvt_pk_bf16_f32 v60, v64, v65
	v_cvt_pk_bf16_f32 v61, v66, v67
	v_cvt_pk_bf16_f32 v62, v68, v69
	v_cvt_pk_bf16_f32 v63, v70, v71
	s_cbranch_vccnz .LBB0_623
	s_mov_b64 vcc, -1
	s_mov_b64 s[86:87], 0
	s_cmp_lt_i32 s75, 2
	s_mov_b64 s[88:89], 0
	s_cbranch_scc0 .LBB0_795
	s_and_b64 vcc, exec, vcc
	s_cbranch_vccnz .LBB0_798

.LBB0_634:
	s_nop 1
	v_mov_b32_e32 v2, v179
	s_nop 0
	v_add_u32_e32 v52, 0x90, v150
	v_ashrrev_i32_e32 v53, 31, v52
	s_movk_i32 s18, 0xe00f
	v_fmamk_f32 v2, v2, 0x3a800000, v208
	s_nop 0
	s_nop 0
	s_nop 0
	s_nop 1
	s_nop 1
	s_movk_i32 s10, 0x1ff0
	v_rsq_f32_e32 v2, v2
	s_nop 0
	v_mul_f32_e32 v54, 0x3e38aa3b, v2
	v_cndmask_b32_e64 v62, v2, v54, s[6:7]
	v_lshlrev_b64 v[58:59], 13, v[52:53]
	v_lshlrev_b64 v[56:57], 11, v[52:53]
	v_and_b32_e32 v2, 0x1fff, v52
	v_ashrrev_i32_e32 v52, 13, v52
	v_mul_i32_i24_e32 v52, 15, v52
	v_add_u32_e32 v54, 0xffff0090, v150
	v_add3_u32 v52, v2, v52, s18
	v_cmp_lt_u32_e64 s[10:11], s10, v2
	v_ashrrev_i32_e32 v53, 31, v52
	v_ashrrev_i32_e32 v2, 6, v54
	v_lshlrev_b64 v[64:65], 11, v[52:53]
	v_mad_u64_u32 v[52:53], s[18:19], v2, 15, v[122:123]
	v_ashrrev_i32_e32 v55, 31, v54
	v_ashrrev_i32_e32 v53, 31, v52
	v_lshlrev_b64 v[60:61], 11, v[54:55]
	v_lshlrev_b64 v[66:67], 11, v[52:53]
	v_pk_mul_f32 v[50:51], v[50:51], v[62:63] op_sel_hi:[1,0]
	v_pk_mul_f32 v[48:49], v[48:49], v[62:63] op_sel_hi:[1,0]
	v_pk_mul_f32 v[54:55], v[46:47], v[62:63] op_sel_hi:[1,0]
	v_pk_mul_f32 v[52:53], v[44:45], v[62:63] op_sel_hi:[1,0]
	s_mov_b64 s[18:19], -1
	s_and_b64 vcc, exec, s[8:9]
	v_cvt_pk_bf16_f32 v44, v48, v49
	v_cvt_pk_bf16_f32 v45, v50, v51
	v_cvt_pk_bf16_f32 v46, v52, v53
	v_cvt_pk_bf16_f32 v47, v54, v55
	s_cbranch_vccnz .LBB0_641
	s_mov_b64 s[88:89], -1
	s_mov_b64 s[18:19], 0
	s_cmp_lt_i32 s75, 2
	s_mov_b64 s[86:87], 0
	s_cbranch_scc0 .LBB0_821
	s_and_b64 vcc, exec, s[88:89]
	s_cbranch_vccnz .LBB0_824

.LBB0_652:
	s_nop 1
	v_mov_b32_e32 v2, v180
	s_nop 0
	v_add_u32_e32 v36, 0xa0, v150
	v_ashrrev_i32_e32 v37, 31, v36
	s_movk_i32 s12, 0xe00f
	v_fmamk_f32 v2, v2, 0x3a800000, v208
	s_nop 0
	s_nop 0
	s_nop 0
	s_nop 1
	s_nop 1
	s_movk_i32 s10, 0x1ff0
	v_rsq_f32_e32 v2, v2
	s_nop 0
	v_mul_f32_e32 v38, 0x3e38aa3b, v2
	v_cndmask_b32_e64 v46, v2, v38, s[6:7]
	v_lshlrev_b64 v[42:43], 13, v[36:37]
	v_lshlrev_b64 v[40:41], 11, v[36:37]
	v_and_b32_e32 v2, 0x1fff, v36
	v_ashrrev_i32_e32 v36, 13, v36
	v_mul_i32_i24_e32 v36, 15, v36
	v_add_u32_e32 v38, 0xffff00a0, v150
	v_add3_u32 v36, v2, v36, s12
	v_cmp_lt_u32_e64 s[10:11], s10, v2
	v_ashrrev_i32_e32 v37, 31, v36
	v_ashrrev_i32_e32 v2, 6, v38
	v_lshlrev_b64 v[48:49], 11, v[36:37]
	v_mad_u64_u32 v[36:37], s[12:13], v2, 15, v[104:105]
	v_ashrrev_i32_e32 v39, 31, v38
	v_ashrrev_i32_e32 v37, 31, v36
	v_lshlrev_b64 v[44:45], 11, v[38:39]
	v_lshlrev_b64 v[50:51], 11, v[36:37]
	v_pk_mul_f32 v[34:35], v[34:35], v[46:47] op_sel_hi:[1,0]
	v_pk_mul_f32 v[32:33], v[32:33], v[46:47] op_sel_hi:[1,0]
	v_pk_mul_f32 v[38:39], v[30:31], v[46:47] op_sel_hi:[1,0]
	v_pk_mul_f32 v[36:37], v[28:29], v[46:47] op_sel_hi:[1,0]
	s_mov_b64 s[12:13], -1
	s_and_b64 vcc, exec, s[8:9]
	v_cvt_pk_bf16_f32 v28, v32, v33
	v_cvt_pk_bf16_f32 v29, v34, v35
	v_cvt_pk_bf16_f32 v30, v36, v37
	v_cvt_pk_bf16_f32 v31, v38, v39
	s_cbranch_vccnz .LBB0_659
	s_mov_b64 s[86:87], -1
	s_mov_b64 s[12:13], 0
	s_cmp_lt_i32 s75, 2
	s_mov_b64 s[18:19], 0
	s_cbranch_scc0 .LBB0_847
	s_and_b64 vcc, exec, s[86:87]
	s_cbranch_vccnz .LBB0_850

.LBB0_670:
	s_nop 1
	v_mov_b32_e32 v2, v181
	s_nop 0
	v_add_u32_e32 v20, 0xb0, v150
	v_ashrrev_i32_e32 v21, 31, v20
	v_fmamk_f32 v2, v2, 0x3a800000, v208
	s_nop 0
	s_nop 0
	s_nop 0
	s_nop 1
	s_nop 1
	s_movk_i32 s10, 0xe00f
	v_rsq_f32_e32 v2, v2
	s_nop 0
	v_mul_f32_e32 v22, 0x3e38aa3b, v2
	v_cndmask_b32_e64 v30, v2, v22, s[6:7]
	v_lshlrev_b64 v[26:27], 13, v[20:21]
	v_lshlrev_b64 v[24:25], 11, v[20:21]
	v_and_b32_e32 v2, 0x1fff, v20
	v_ashrrev_i32_e32 v20, 13, v20
	v_mul_i32_i24_e32 v20, 15, v20
	v_add_u32_e32 v22, 0xffff00b0, v150
	s_movk_i32 s6, 0x1ff0
	v_add3_u32 v20, v2, v20, s10
	v_cmp_lt_u32_e64 s[6:7], s6, v2
	v_ashrrev_i32_e32 v21, 31, v20
	v_ashrrev_i32_e32 v2, 6, v22
	v_lshlrev_b64 v[32:33], 11, v[20:21]
	v_mad_u64_u32 v[20:21], s[10:11], v2, 15, v[88:89]
	v_ashrrev_i32_e32 v23, 31, v22
	v_ashrrev_i32_e32 v21, 31, v20
	v_lshlrev_b64 v[28:29], 11, v[22:23]
	v_lshlrev_b64 v[34:35], 11, v[20:21]
	v_pk_mul_f32 v[18:19], v[18:19], v[30:31] op_sel_hi:[1,0]
	v_pk_mul_f32 v[16:17], v[16:17], v[30:31] op_sel_hi:[1,0]
	v_pk_mul_f32 v[22:23], v[14:15], v[30:31] op_sel_hi:[1,0]
	v_pk_mul_f32 v[20:21], v[12:13], v[30:31] op_sel_hi:[1,0]
	s_mov_b64 s[10:11], -1
	s_and_b64 vcc, exec, s[8:9]
	v_cvt_pk_bf16_f32 v12, v16, v17
	v_cvt_pk_bf16_f32 v13, v18, v19
	v_cvt_pk_bf16_f32 v14, v20, v21
	v_cvt_pk_bf16_f32 v15, v22, v23
	s_cbranch_vccnz .LBB0_677
	s_mov_b64 s[14:15], -1
	s_mov_b64 s[10:11], 0
	s_cmp_lt_i32 s75, 2
	s_mov_b64 s[12:13], 0
	s_cbranch_scc0 .LBB0_873
	s_and_b64 vcc, exec, s[14:15]
	s_cbranch_vccnz .LBB0_876

.LBB0_926:
	global_load_dword v2, v[42:43], off
	s_waitcnt vmcnt(0)
	v_fmamk_f32 v2, v2, 0x3a800000, v208
	v_mul_f32_e32 v28, 0x4f800000, v2
	s_nop 1
	s_nop 0
	s_nop 1
	s_nop 1
	s_nop 1
	s_mov_b64 s[0:1], -1
	v_rsq_f32_e32 v2, v2
	s_nop 0
	v_mul_f32_e32 v28, 0x3e38aa3b, v2
	v_cndmask_b32_e64 v2, v2, v28, s[6:7]
	s_and_b64 vcc, exec, s[8:9]
	v_pk_mul_f32 v[26:27], v[26:27], v[2:3] op_sel_hi:[1,0]
	v_pk_mul_f32 v[24:25], v[24:25], v[2:3] op_sel_hi:[1,0]
	s_nop 0
	v_cvt_pk_bf16_f32 v28, v24, v25
	v_cvt_pk_bf16_f32 v29, v26, v27
	s_cbranch_vccnz .LBB0_933
	s_mov_b64 s[12:13], -1
	s_mov_b64 s[0:1], 0
	s_cmp_lt_i32 s16, 2
	s_mov_b64 s[10:11], 0
	s_cbranch_scc0 .LBB0_1070
	s_and_b64 vcc, exec, s[12:13]
	s_cbranch_vccnz .LBB0_1073

.LBB0_935:
	global_load_dword v2, v[42:43], off
	s_waitcnt vmcnt(0)
	v_fmamk_f32 v2, v2, 0x3a800000, v208
	v_mul_f32_e32 v24, 0x4f800000, v2
	s_nop 1
	s_nop 0
	s_nop 1
	s_nop 1
	s_nop 1
	s_mov_b64 s[0:1], -1
	v_rsq_f32_e32 v2, v2
	s_nop 0
	v_mul_f32_e32 v24, 0x3e38aa3b, v2
	v_cndmask_b32_e64 v2, v2, v24, s[6:7]
	s_and_b64 vcc, exec, s[8:9]
	v_pk_mul_f32 v[22:23], v[22:23], v[2:3] op_sel_hi:[1,0]
	v_pk_mul_f32 v[20:21], v[20:21], v[2:3] op_sel_hi:[1,0]
	s_nop 0
	v_cvt_pk_bf16_f32 v24, v20, v21
	v_cvt_pk_bf16_f32 v25, v22, v23
	s_cbranch_vccnz .LBB0_942
	s_mov_b64 s[12:13], -1
	s_mov_b64 s[0:1], 0
	s_cmp_lt_i32 s16, 2
	s_mov_b64 s[10:11], 0
	s_cbranch_scc0 .LBB0_1077
	s_and_b64 vcc, exec, s[12:13]
	s_cbranch_vccnz .LBB0_1080

.LBB0_944:
	global_load_dword v2, v[42:43], off
	s_waitcnt vmcnt(0)
	v_fmamk_f32 v2, v2, 0x3a800000, v208
	v_mul_f32_e32 v20, 0x4f800000, v2
	s_nop 1
	s_nop 0
	s_nop 1
	s_nop 1
	s_nop 1
	s_mov_b64 s[0:1], -1
	v_rsq_f32_e32 v2, v2
	s_nop 0
	v_mul_f32_e32 v20, 0x3e38aa3b, v2
	v_cndmask_b32_e64 v2, v2, v20, s[6:7]
	s_and_b64 vcc, exec, s[8:9]
	v_pk_mul_f32 v[18:19], v[18:19], v[2:3] op_sel_hi:[1,0]
	v_pk_mul_f32 v[16:17], v[16:17], v[2:3] op_sel_hi:[1,0]
	s_nop 0
	v_cvt_pk_bf16_f32 v20, v16, v17
	v_cvt_pk_bf16_f32 v21, v18, v19
	s_cbranch_vccnz .LBB0_951
	s_mov_b64 s[12:13], -1
	s_mov_b64 s[0:1], 0
	s_cmp_lt_i32 s16, 2
	s_mov_b64 s[10:11], 0
	s_cbranch_scc0 .LBB0_1084
	s_and_b64 vcc, exec, s[12:13]
	s_cbranch_vccnz .LBB0_1087

.LBB0_988:
	v_readlane_b32 s8, v255, 26
	v_readlane_b32 s10, v255, 28
	v_readlane_b32 s11, v255, 29
	s_add_u32 s6, s10, 0x2ce000
	s_addc_u32 s7, s11, 0
	s_bitcmp0_b32 s48, 2
	s_mov_b32 s0, 0x30878000
	s_cselect_b32 s0, s0, 0x31878000
	s_mov_b32 s1, 0x4400000
	v_readlane_b32 s9, v255, 27
	s_cselect_b32 s1, s1, 0x4c00000
	s_add_u32 s0, s8, s0
	v_readlane_b32 s8, v255, 37
	s_addc_u32 s3, s9, 0
	s_lshl_b32 s2, s8, 18
	s_and_b32 s5, s2, 0x200000
	s_lshl_b32 s2, s5, 2
	s_add_u32 s2, s0, s2
	s_addc_u32 s3, s3, 0
	s_add_u32 s0, s10, s1
	s_addc_u32 s1, s11, 0
	s_lshl_b32 s5, s5, 1
	s_add_u32 s0, s0, s5
	s_addc_u32 s1, s1, 0
	s_lshl_b32 s4, s4, 8
	s_add_i32 s14, s14, s4
	s_nop 0
	v_add_u32_e32 v134, s14, v1
	v_ashrrev_i32_e32 v135, 31, v134
	v_lshl_add_u64 v[136:137], v[134:135], 2, s[6:7]
	global_load_dword v1, v[136:137], off
	v_lshlrev_b32_e32 v132, 3, v2
	v_ashrrev_i32_e32 v133, 31, v132
	v_lshl_add_u64 v[132:133], v[132:133], 0, s[46:47]
	s_waitcnt vmcnt(0)
	v_fmamk_f32 v1, v1, 0x3a800000, v208
	v_cmp_gt_f32_e32 vcc, s90, v1
	v_mul_f32_e32 v2, 0x4f800000, v1
	s_nop 0
	v_cndmask_b32_e32 v1, v1, v2, vcc
	v_sqrt_f32_e32 v2, v1
	s_nop 0
	v_add_u32_e32 v136, -1, v2
	v_fma_f32 v137, -v136, v2, v1
	v_cmp_ge_f32_e64 s[4:5], 0, v137
	v_add_u32_e32 v137, 1, v2
	s_nop 0
	v_cndmask_b32_e64 v136, v2, v136, s[4:5]
	v_fma_f32 v2, -v137, v2, v1
	v_cmp_lt_f32_e64 s[4:5], 0, v2
	s_nop 1
	v_cndmask_b32_e64 v2, v136, v137, s[4:5]
	v_mul_f32_e32 v136, 0x37800000, v2
	v_cndmask_b32_e32 v2, v2, v136, vcc
	v_cmp_class_f32_e32 vcc, v1, v209
	s_nop 1
	v_cndmask_b32_e32 v1, v2, v1, vcc
	v_div_scale_f32 v2, s[4:5], v1, v1, 1.0
	v_rcp_f32_e32 v136, v2
	s_lshl_b32 s4, s8, 8
	s_and_b32 s46, s4, 0x300
	v_fma_f32 v137, -v2, v136, 1.0
	v_fmac_f32_e32 v136, v137, v136
	v_div_scale_f32 v137, vcc, 1.0, v1, 1.0
	v_mul_f32_e32 v138, v137, v136
	v_fma_f32 v139, -v2, v138, v137
	v_fmac_f32_e32 v138, v139, v136
	v_fma_f32 v2, -v2, v138, v137
	v_div_fmas_f32 v2, v2, v136, v138
	v_lshlrev_b64 v[136:137], 10, v[134:135]
	v_lshl_add_u64 v[136:137], v[136:137], 0, v[132:133]
	v_div_fixup_f32 v2, v2, v1, 1.0
	v_lshl_add_u64 v[136:137], v[136:137], 0, s[46:47]
	v_pk_mul_f32 v[130:131], v[130:131], v[2:3] op_sel_hi:[1,0]
	v_pk_mul_f32 v[128:129], v[128:129], v[2:3] op_sel_hi:[1,0]
	v_pk_mul_f32 v[124:125], v[124:125], v[2:3] op_sel_hi:[1,0]
	v_lshl_add_u64 v[138:139], v[136:137], 2, s[2:3]
	v_pk_mul_f32 v[126:127], v[126:127], v[2:3] op_sel_hi:[1,0]
	global_store_dwordx4 v[138:139], v[128:131], off
	global_store_dwordx4 v[138:139], v[124:127], off offset:16
	v_pk_mul_f32 v[122:123], v[122:123], v[2:3] op_sel_hi:[1,0]
	v_cvt_pk_bf16_f32 v128, v128, v129
	v_cvt_pk_bf16_f32 v129, v130, v131
	v_cvt_pk_bf16_f32 v130, v124, v125
	v_pk_mul_f32 v[120:121], v[120:121], v[2:3] op_sel_hi:[1,0]
	v_lshl_add_u64 v[124:125], v[136:137], 1, s[0:1]
	v_pk_mul_f32 v[116:117], v[116:117], v[2:3] op_sel_hi:[1,0]
	v_cvt_pk_bf16_f32 v131, v126, v127
	global_store_dwordx4 v[124:125], v[128:131], off
	v_pk_mul_f32 v[118:119], v[118:119], v[2:3] op_sel_hi:[1,0]
	global_store_dwordx4 v[138:139], v[120:123], off offset:512
	global_store_dwordx4 v[138:139], v[116:119], off offset:528
	s_nop 0
	v_cvt_pk_bf16_f32 v120, v120, v121
	v_cvt_pk_bf16_f32 v121, v122, v123
	v_cvt_pk_bf16_f32 v122, v116, v117
	v_cvt_pk_bf16_f32 v123, v118, v119
	s_nop 0
	v_add_u32_e32 v116, 16, v134
	v_ashrrev_i32_e32 v117, 31, v116
	global_store_dwordx4 v[124:125], v[120:123], off offset:256
	v_lshl_add_u64 v[118:119], v[116:117], 2, s[6:7]
	global_load_dword v1, v[118:119], off
	v_lshlrev_b64 v[116:117], 10, v[116:117]
	v_lshl_add_u64 v[116:117], v[116:117], 0, v[132:133]
	v_lshl_add_u64 v[116:117], v[116:117], 0, s[46:47]
	s_waitcnt vmcnt(0)
	v_fmamk_f32 v1, v1, 0x3a800000, v208
	v_cmp_gt_f32_e32 vcc, s90, v1
	v_mul_f32_e32 v2, 0x4f800000, v1
	s_nop 0
	v_cndmask_b32_e32 v1, v1, v2, vcc
	v_sqrt_f32_e32 v2, v1
	s_nop 0
	v_add_u32_e32 v118, -1, v2
	v_fma_f32 v119, -v118, v2, v1
	v_cmp_ge_f32_e64 s[4:5], 0, v119
	v_add_u32_e32 v119, 1, v2
	s_nop 0
	v_cndmask_b32_e64 v118, v2, v118, s[4:5]
	v_fma_f32 v2, -v119, v2, v1
	v_cmp_lt_f32_e64 s[4:5], 0, v2
	s_nop 1
	v_cndmask_b32_e64 v2, v118, v119, s[4:5]
	v_mul_f32_e32 v118, 0x37800000, v2
	v_cndmask_b32_e32 v2, v2, v118, vcc
	v_cmp_class_f32_e32 vcc, v1, v209
	s_nop 1
	v_cndmask_b32_e32 v1, v2, v1, vcc
	v_div_scale_f32 v2, s[4:5], v1, v1, 1.0
	v_rcp_f32_e32 v118, v2
	s_nop 0
	v_fma_f32 v119, -v2, v118, 1.0
	v_fmac_f32_e32 v118, v119, v118
	v_div_scale_f32 v119, vcc, 1.0, v1, 1.0
	v_mul_f32_e32 v120, v119, v118
	v_fma_f32 v121, -v2, v120, v119
	v_fmac_f32_e32 v120, v121, v118
	v_fma_f32 v2, -v2, v120, v119
	v_div_fmas_f32 v2, v2, v118, v120
	v_div_fixup_f32 v2, v2, v1, 1.0
	v_pk_mul_f32 v[114:115], v[114:115], v[2:3] op_sel_hi:[1,0]
	v_pk_mul_f32 v[112:113], v[112:113], v[2:3] op_sel_hi:[1,0]
	v_pk_mul_f32 v[108:109], v[108:109], v[2:3] op_sel_hi:[1,0]
	v_lshl_add_u64 v[118:119], v[116:117], 2, s[2:3]
	v_pk_mul_f32 v[110:111], v[110:111], v[2:3] op_sel_hi:[1,0]
	global_store_dwordx4 v[118:119], v[112:115], off
	global_store_dwordx4 v[118:119], v[108:111], off offset:16
	v_pk_mul_f32 v[106:107], v[106:107], v[2:3] op_sel_hi:[1,0]
	v_cvt_pk_bf16_f32 v112, v112, v113
	v_cvt_pk_bf16_f32 v113, v114, v115
	v_cvt_pk_bf16_f32 v114, v108, v109
	v_pk_mul_f32 v[104:105], v[104:105], v[2:3] op_sel_hi:[1,0]
	v_lshl_add_u64 v[108:109], v[116:117], 1, s[0:1]
	v_pk_mul_f32 v[100:101], v[100:101], v[2:3] op_sel_hi:[1,0]
	v_cvt_pk_bf16_f32 v115, v110, v111
	global_store_dwordx4 v[108:109], v[112:115], off
	v_pk_mul_f32 v[102:103], v[102:103], v[2:3] op_sel_hi:[1,0]
	global_store_dwordx4 v[118:119], v[104:107], off offset:512
	global_store_dwordx4 v[118:119], v[100:103], off offset:528
	s_nop 0
	v_cvt_pk_bf16_f32 v104, v104, v105
	v_cvt_pk_bf16_f32 v105, v106, v107
	v_cvt_pk_bf16_f32 v106, v100, v101
	v_cvt_pk_bf16_f32 v107, v102, v103
	s_nop 0
	v_add_u32_e32 v100, 32, v134
	v_ashrrev_i32_e32 v101, 31, v100
	global_store_dwordx4 v[108:109], v[104:107], off offset:256
	v_lshl_add_u64 v[102:103], v[100:101], 2, s[6:7]
	global_load_dword v1, v[102:103], off
	v_lshlrev_b64 v[100:101], 10, v[100:101]
	v_lshl_add_u64 v[100:101], v[100:101], 0, v[132:133]
	v_lshl_add_u64 v[100:101], v[100:101], 0, s[46:47]
	s_waitcnt vmcnt(0)
	v_fmamk_f32 v1, v1, 0x3a800000, v208
	v_cmp_gt_f32_e32 vcc, s90, v1
	v_mul_f32_e32 v2, 0x4f800000, v1
	s_nop 0
	v_cndmask_b32_e32 v1, v1, v2, vcc
	v_sqrt_f32_e32 v2, v1
	s_nop 0
	v_add_u32_e32 v102, -1, v2
	v_fma_f32 v103, -v102, v2, v1
	v_cmp_ge_f32_e64 s[4:5], 0, v103
	v_add_u32_e32 v103, 1, v2
	s_nop 0
	v_cndmask_b32_e64 v102, v2, v102, s[4:5]
	v_fma_f32 v2, -v103, v2, v1
	v_cmp_lt_f32_e64 s[4:5], 0, v2
	s_nop 1
	v_cndmask_b32_e64 v2, v102, v103, s[4:5]
	v_mul_f32_e32 v102, 0x37800000, v2
	v_cndmask_b32_e32 v2, v2, v102, vcc
	v_cmp_class_f32_e32 vcc, v1, v209
	s_nop 1
	v_cndmask_b32_e32 v1, v2, v1, vcc
	v_div_scale_f32 v2, s[4:5], v1, v1, 1.0
	v_rcp_f32_e32 v102, v2
	s_nop 0
	v_fma_f32 v103, -v2, v102, 1.0
	v_fmac_f32_e32 v102, v103, v102
	v_div_scale_f32 v103, vcc, 1.0, v1, 1.0
	v_mul_f32_e32 v104, v103, v102
	v_fma_f32 v105, -v2, v104, v103
	v_fmac_f32_e32 v104, v105, v102
	v_fma_f32 v2, -v2, v104, v103
	v_div_fmas_f32 v2, v2, v102, v104
	v_div_fixup_f32 v2, v2, v1, 1.0
	v_pk_mul_f32 v[98:99], v[98:99], v[2:3] op_sel_hi:[1,0]
	v_pk_mul_f32 v[96:97], v[96:97], v[2:3] op_sel_hi:[1,0]
	v_pk_mul_f32 v[92:93], v[92:93], v[2:3] op_sel_hi:[1,0]
	v_lshl_add_u64 v[102:103], v[100:101], 2, s[2:3]
	v_pk_mul_f32 v[94:95], v[94:95], v[2:3] op_sel_hi:[1,0]
	global_store_dwordx4 v[102:103], v[96:99], off
	global_store_dwordx4 v[102:103], v[92:95], off offset:16
	v_pk_mul_f32 v[90:91], v[90:91], v[2:3] op_sel_hi:[1,0]
	v_cvt_pk_bf16_f32 v96, v96, v97
	v_cvt_pk_bf16_f32 v97, v98, v99
	v_cvt_pk_bf16_f32 v98, v92, v93
	v_pk_mul_f32 v[88:89], v[88:89], v[2:3] op_sel_hi:[1,0]
	v_lshl_add_u64 v[92:93], v[100:101], 1, s[0:1]
	v_pk_mul_f32 v[84:85], v[84:85], v[2:3] op_sel_hi:[1,0]
	v_cvt_pk_bf16_f32 v99, v94, v95
	global_store_dwordx4 v[92:93], v[96:99], off
	v_pk_mul_f32 v[86:87], v[86:87], v[2:3] op_sel_hi:[1,0]
	global_store_dwordx4 v[102:103], v[88:91], off offset:512
	global_store_dwordx4 v[102:103], v[84:87], off offset:528
	s_nop 0
	v_cvt_pk_bf16_f32 v88, v88, v89
	v_cvt_pk_bf16_f32 v89, v90, v91
	v_cvt_pk_bf16_f32 v90, v84, v85
	v_cvt_pk_bf16_f32 v91, v86, v87
	s_nop 0
	v_add_u32_e32 v84, 48, v134
	v_ashrrev_i32_e32 v85, 31, v84
	global_store_dwordx4 v[92:93], v[88:91], off offset:256
	v_lshl_add_u64 v[86:87], v[84:85], 2, s[6:7]
	global_load_dword v1, v[86:87], off
	v_lshlrev_b64 v[84:85], 10, v[84:85]
	v_lshl_add_u64 v[84:85], v[84:85], 0, v[132:133]
	v_lshl_add_u64 v[84:85], v[84:85], 0, s[46:47]
	s_waitcnt vmcnt(0)
	v_fmamk_f32 v1, v1, 0x3a800000, v208
	v_cmp_gt_f32_e32 vcc, s90, v1
	v_mul_f32_e32 v2, 0x4f800000, v1
	s_nop 0
	v_cndmask_b32_e32 v1, v1, v2, vcc
	v_sqrt_f32_e32 v2, v1
	s_nop 0
	v_add_u32_e32 v86, -1, v2
	v_fma_f32 v87, -v86, v2, v1
	v_cmp_ge_f32_e64 s[4:5], 0, v87
	v_add_u32_e32 v87, 1, v2
	s_nop 0
	v_cndmask_b32_e64 v86, v2, v86, s[4:5]
	v_fma_f32 v2, -v87, v2, v1
	v_cmp_lt_f32_e64 s[4:5], 0, v2
	s_nop 1
	v_cndmask_b32_e64 v2, v86, v87, s[4:5]
	v_mul_f32_e32 v86, 0x37800000, v2
	v_cndmask_b32_e32 v2, v2, v86, vcc
	v_cmp_class_f32_e32 vcc, v1, v209
	s_nop 1
	v_cndmask_b32_e32 v1, v2, v1, vcc
	v_div_scale_f32 v2, s[4:5], v1, v1, 1.0
	v_rcp_f32_e32 v86, v2
	s_nop 0
	v_fma_f32 v87, -v2, v86, 1.0
	v_fmac_f32_e32 v86, v87, v86
	v_div_scale_f32 v87, vcc, 1.0, v1, 1.0
	v_mul_f32_e32 v88, v87, v86
	v_fma_f32 v89, -v2, v88, v87
	v_fmac_f32_e32 v88, v89, v86
	v_fma_f32 v2, -v2, v88, v87
	v_div_fmas_f32 v2, v2, v86, v88
	v_div_fixup_f32 v2, v2, v1, 1.0
	v_pk_mul_f32 v[82:83], v[82:83], v[2:3] op_sel_hi:[1,0]
	v_pk_mul_f32 v[80:81], v[80:81], v[2:3] op_sel_hi:[1,0]
	v_pk_mul_f32 v[76:77], v[76:77], v[2:3] op_sel_hi:[1,0]
	v_lshl_add_u64 v[86:87], v[84:85], 2, s[2:3]
	v_pk_mul_f32 v[78:79], v[78:79], v[2:3] op_sel_hi:[1,0]
	global_store_dwordx4 v[86:87], v[80:83], off
	global_store_dwordx4 v[86:87], v[76:79], off offset:16
	v_pk_mul_f32 v[74:75], v[74:75], v[2:3] op_sel_hi:[1,0]
	v_cvt_pk_bf16_f32 v80, v80, v81
	v_cvt_pk_bf16_f32 v81, v82, v83
	v_cvt_pk_bf16_f32 v82, v76, v77
	v_pk_mul_f32 v[72:73], v[72:73], v[2:3] op_sel_hi:[1,0]
	v_lshl_add_u64 v[76:77], v[84:85], 1, s[0:1]
	v_pk_mul_f32 v[68:69], v[68:69], v[2:3] op_sel_hi:[1,0]
	v_cvt_pk_bf16_f32 v83, v78, v79
	global_store_dwordx4 v[76:77], v[80:83], off
	v_pk_mul_f32 v[70:71], v[70:71], v[2:3] op_sel_hi:[1,0]
	global_store_dwordx4 v[86:87], v[72:75], off offset:512
	global_store_dwordx4 v[86:87], v[68:71], off offset:528
	s_nop 0
	v_cvt_pk_bf16_f32 v72, v72, v73
	v_cvt_pk_bf16_f32 v73, v74, v75
	v_cvt_pk_bf16_f32 v74, v68, v69
	v_cvt_pk_bf16_f32 v75, v70, v71
	s_nop 0
	v_add_u32_e32 v68, 0x80, v134
	v_ashrrev_i32_e32 v69, 31, v68
	global_store_dwordx4 v[76:77], v[72:75], off offset:256
	v_lshl_add_u64 v[70:71], v[68:69], 2, s[6:7]
	global_load_dword v1, v[70:71], off
	v_lshlrev_b64 v[68:69], 10, v[68:69]
	v_lshl_add_u64 v[68:69], v[68:69], 0, v[132:133]
	v_lshl_add_u64 v[68:69], v[68:69], 0, s[46:47]
	s_waitcnt vmcnt(0)
	v_fmamk_f32 v1, v1, 0x3a800000, v208
	v_cmp_gt_f32_e32 vcc, s90, v1
	v_mul_f32_e32 v2, 0x4f800000, v1
	s_nop 0
	v_cndmask_b32_e32 v1, v1, v2, vcc
	v_sqrt_f32_e32 v2, v1
	s_nop 0
	v_add_u32_e32 v70, -1, v2
	v_fma_f32 v71, -v70, v2, v1
	v_cmp_ge_f32_e64 s[4:5], 0, v71
	v_add_u32_e32 v71, 1, v2
	s_nop 0
	v_cndmask_b32_e64 v70, v2, v70, s[4:5]
	v_fma_f32 v2, -v71, v2, v1
	v_cmp_lt_f32_e64 s[4:5], 0, v2
	s_nop 1
	v_cndmask_b32_e64 v2, v70, v71, s[4:5]
	v_mul_f32_e32 v70, 0x37800000, v2
	v_cndmask_b32_e32 v2, v2, v70, vcc
	v_cmp_class_f32_e32 vcc, v1, v209
	s_nop 1
	v_cndmask_b32_e32 v1, v2, v1, vcc
	v_div_scale_f32 v2, s[4:5], v1, v1, 1.0
	v_rcp_f32_e32 v70, v2
	s_nop 0
	v_fma_f32 v71, -v2, v70, 1.0
	v_fmac_f32_e32 v70, v71, v70
	v_div_scale_f32 v71, vcc, 1.0, v1, 1.0
	v_mul_f32_e32 v72, v71, v70
	v_fma_f32 v73, -v2, v72, v71
	v_fmac_f32_e32 v72, v73, v70
	v_fma_f32 v2, -v2, v72, v71
	v_div_fmas_f32 v2, v2, v70, v72
	v_div_fixup_f32 v2, v2, v1, 1.0
	v_pk_mul_f32 v[66:67], v[66:67], v[2:3] op_sel_hi:[1,0]
	v_pk_mul_f32 v[64:65], v[64:65], v[2:3] op_sel_hi:[1,0]
	v_pk_mul_f32 v[60:61], v[60:61], v[2:3] op_sel_hi:[1,0]
	v_lshl_add_u64 v[70:71], v[68:69], 2, s[2:3]
	v_pk_mul_f32 v[62:63], v[62:63], v[2:3] op_sel_hi:[1,0]
	global_store_dwordx4 v[70:71], v[64:67], off
	global_store_dwordx4 v[70:71], v[60:63], off offset:16
	v_pk_mul_f32 v[58:59], v[58:59], v[2:3] op_sel_hi:[1,0]
	v_cvt_pk_bf16_f32 v64, v64, v65
	v_cvt_pk_bf16_f32 v65, v66, v67
	v_cvt_pk_bf16_f32 v66, v60, v61
	v_pk_mul_f32 v[56:57], v[56:57], v[2:3] op_sel_hi:[1,0]
	v_lshl_add_u64 v[60:61], v[68:69], 1, s[0:1]
	v_pk_mul_f32 v[52:53], v[52:53], v[2:3] op_sel_hi:[1,0]
	v_cvt_pk_bf16_f32 v67, v62, v63
	global_store_dwordx4 v[60:61], v[64:67], off
	v_pk_mul_f32 v[54:55], v[54:55], v[2:3] op_sel_hi:[1,0]
	global_store_dwordx4 v[70:71], v[56:59], off offset:512
	global_store_dwordx4 v[70:71], v[52:55], off offset:528
	s_nop 0
	v_cvt_pk_bf16_f32 v56, v56, v57
	v_cvt_pk_bf16_f32 v57, v58, v59
	v_cvt_pk_bf16_f32 v58, v52, v53
	v_cvt_pk_bf16_f32 v59, v54, v55
	s_nop 0
	v_add_u32_e32 v52, 0x90, v134
	v_ashrrev_i32_e32 v53, 31, v52
	global_store_dwordx4 v[60:61], v[56:59], off offset:256
	v_lshl_add_u64 v[54:55], v[52:53], 2, s[6:7]
	global_load_dword v1, v[54:55], off
	v_lshlrev_b64 v[52:53], 10, v[52:53]
	v_lshl_add_u64 v[52:53], v[52:53], 0, v[132:133]
	v_lshl_add_u64 v[52:53], v[52:53], 0, s[46:47]
	s_waitcnt vmcnt(0)
	v_fmamk_f32 v1, v1, 0x3a800000, v208
	s_nop 0
	s_nop 0
	s_nop 0
	s_nop 1
	s_nop 1
	s_nop 0
	v_rsq_f32_e32 v2, v1
	s_nop 0
	v_pk_mul_f32 v[50:51], v[50:51], v[2:3] op_sel_hi:[1,0]
	v_pk_mul_f32 v[48:49], v[48:49], v[2:3] op_sel_hi:[1,0]
	v_pk_mul_f32 v[44:45], v[44:45], v[2:3] op_sel_hi:[1,0]
	v_lshl_add_u64 v[54:55], v[52:53], 2, s[2:3]
	v_pk_mul_f32 v[46:47], v[46:47], v[2:3] op_sel_hi:[1,0]
	global_store_dwordx4 v[54:55], v[48:51], off
	global_store_dwordx4 v[54:55], v[44:47], off offset:16
	v_pk_mul_f32 v[42:43], v[42:43], v[2:3] op_sel_hi:[1,0]
	v_cvt_pk_bf16_f32 v48, v48, v49
	v_cvt_pk_bf16_f32 v49, v50, v51
	v_cvt_pk_bf16_f32 v50, v44, v45
	v_pk_mul_f32 v[40:41], v[40:41], v[2:3] op_sel_hi:[1,0]
	v_lshl_add_u64 v[44:45], v[52:53], 1, s[0:1]
	v_pk_mul_f32 v[36:37], v[36:37], v[2:3] op_sel_hi:[1,0]
	v_cvt_pk_bf16_f32 v51, v46, v47
	global_store_dwordx4 v[44:45], v[48:51], off
	v_pk_mul_f32 v[38:39], v[38:39], v[2:3] op_sel_hi:[1,0]
	global_store_dwordx4 v[54:55], v[40:43], off offset:512
	global_store_dwordx4 v[54:55], v[36:39], off offset:528
	s_nop 0
	v_cvt_pk_bf16_f32 v40, v40, v41
	v_cvt_pk_bf16_f32 v41, v42, v43
	v_cvt_pk_bf16_f32 v42, v36, v37
	v_cvt_pk_bf16_f32 v43, v38, v39
	s_nop 0
	v_add_u32_e32 v36, 0xa0, v134
	v_ashrrev_i32_e32 v37, 31, v36
	global_store_dwordx4 v[44:45], v[40:43], off offset:256
	v_lshl_add_u64 v[38:39], v[36:37], 2, s[6:7]
	global_load_dword v1, v[38:39], off
	v_lshlrev_b64 v[36:37], 10, v[36:37]
	v_lshl_add_u64 v[36:37], v[36:37], 0, v[132:133]
	v_lshl_add_u64 v[36:37], v[36:37], 0, s[46:47]
	s_waitcnt vmcnt(0)
	v_fmamk_f32 v1, v1, 0x3a800000, v208
	s_nop 0
	s_nop 0
	s_nop 0
	s_nop 1
	s_nop 1
	s_nop 0
	v_rsq_f32_e32 v2, v1
	s_nop 0
	v_pk_mul_f32 v[34:35], v[34:35], v[2:3] op_sel_hi:[1,0]
	v_pk_mul_f32 v[32:33], v[32:33], v[2:3] op_sel_hi:[1,0]
	v_pk_mul_f32 v[28:29], v[28:29], v[2:3] op_sel_hi:[1,0]
	v_lshl_add_u64 v[38:39], v[36:37], 2, s[2:3]
	v_pk_mul_f32 v[30:31], v[30:31], v[2:3] op_sel_hi:[1,0]
	global_store_dwordx4 v[38:39], v[32:35], off
	global_store_dwordx4 v[38:39], v[28:31], off offset:16
	v_pk_mul_f32 v[26:27], v[26:27], v[2:3] op_sel_hi:[1,0]
	v_cvt_pk_bf16_f32 v32, v32, v33
	v_cvt_pk_bf16_f32 v33, v34, v35
	v_cvt_pk_bf16_f32 v34, v28, v29
	v_pk_mul_f32 v[24:25], v[24:25], v[2:3] op_sel_hi:[1,0]
	v_lshl_add_u64 v[28:29], v[36:37], 1, s[0:1]
	v_pk_mul_f32 v[20:21], v[20:21], v[2:3] op_sel_hi:[1,0]
	v_cvt_pk_bf16_f32 v35, v30, v31
	global_store_dwordx4 v[28:29], v[32:35], off
	v_pk_mul_f32 v[22:23], v[22:23], v[2:3] op_sel_hi:[1,0]
	global_store_dwordx4 v[38:39], v[24:27], off offset:512
	global_store_dwordx4 v[38:39], v[20:23], off offset:528
	s_nop 0
	v_cvt_pk_bf16_f32 v24, v24, v25
	v_cvt_pk_bf16_f32 v25, v26, v27
	v_cvt_pk_bf16_f32 v26, v20, v21
	v_cvt_pk_bf16_f32 v27, v22, v23
	s_nop 0
	v_add_u32_e32 v20, 0xb0, v134
	v_ashrrev_i32_e32 v21, 31, v20
	global_store_dwordx4 v[28:29], v[24:27], off offset:256
	v_lshl_add_u64 v[22:23], v[20:21], 2, s[6:7]
	global_load_dword v1, v[22:23], off
	v_lshlrev_b64 v[20:21], 10, v[20:21]
	v_lshl_add_u64 v[20:21], v[20:21], 0, v[132:133]
	v_lshl_add_u64 v[20:21], v[20:21], 0, s[46:47]
	s_waitcnt vmcnt(0)
	v_fmamk_f32 v1, v1, 0x3a800000, v208
	s_nop 0
	s_nop 0
	s_nop 0
	s_nop 1
	s_nop 1
	s_nop 0
	v_rsq_f32_e32 v2, v1
	s_nop 0
	v_pk_mul_f32 v[18:19], v[18:19], v[2:3] op_sel_hi:[1,0]
	v_pk_mul_f32 v[16:17], v[16:17], v[2:3] op_sel_hi:[1,0]
	v_pk_mul_f32 v[12:13], v[12:13], v[2:3] op_sel_hi:[1,0]
	v_lshl_add_u64 v[22:23], v[20:21], 2, s[2:3]
	v_pk_mul_f32 v[14:15], v[14:15], v[2:3] op_sel_hi:[1,0]
	global_store_dwordx4 v[22:23], v[16:19], off
	global_store_dwordx4 v[22:23], v[12:15], off offset:16
	v_pk_mul_f32 v[10:11], v[10:11], v[2:3] op_sel_hi:[1,0]
	v_cvt_pk_bf16_f32 v16, v16, v17
	v_cvt_pk_bf16_f32 v17, v18, v19
	v_cvt_pk_bf16_f32 v18, v12, v13
	v_pk_mul_f32 v[8:9], v[8:9], v[2:3] op_sel_hi:[1,0]
	v_lshl_add_u64 v[12:13], v[20:21], 1, s[0:1]
	v_cvt_pk_bf16_f32 v19, v14, v15
	global_store_dwordx4 v[12:13], v[16:19], off
	v_pk_mul_f32 v[6:7], v[6:7], v[2:3] op_sel_hi:[1,0]
	v_pk_mul_f32 v[4:5], v[4:5], v[2:3] op_sel_hi:[1,0]
	global_store_dwordx4 v[22:23], v[8:11], off offset:512
	global_store_dwordx4 v[22:23], v[4:7], off offset:528
	s_nop 0
	v_cvt_pk_bf16_f32 v8, v8, v9
	v_cvt_pk_bf16_f32 v9, v10, v11
	v_cvt_pk_bf16_f32 v10, v4, v5
	v_cvt_pk_bf16_f32 v11, v6, v7
	global_store_dwordx4 v[12:13], v[8:11], off offset:256
	s_waitcnt vmcnt(0)
	s_barrier

.LBB0_1174:
	s_or_b64 exec, exec, s[4:5]
	s_waitcnt lgkmcnt(0)
	v_lshlrev_b32_e32 v2, 2, v158
	global_load_dword v249, v2, s[0:1]
	global_load_dword v250, v2, s[0:1] offset:128
	global_load_dword v251, v2, s[0:1] offset:256
	global_load_dword v253, v2, s[0:1] offset:384
	v_add_u32_e32 v10, s19, v148
	s_lshl_b64 s[4:5], s[10:11], 13
	s_add_u32 s4, s86, s4
	s_addc_u32 s5, s87, s5
	s_add_u32 s6, s4, s46
	s_addc_u32 s7, s5, 0
	s_waitcnt vmcnt(0)
	v_mul_f32_e32 v7, v164, v249
	v_mul_f32_e32 v9, v164, v250
	v_mul_f32_e32 v6, v164, v251
	v_mul_f32_e32 v8, v164, v253
	v_lshl_or_b32 v2, v159, 14, v158
	ds_read_b32 v11, v10
	ds_read2st64_b32 v[4:5], v1 offset1:16
	s_waitcnt lgkmcnt(0)
	v_fma_f32 v12, v84, v11, -v4
	v_fma_f32 v13, v100, v11, -v5
	ds_read2st64_b32 v[4:5], v1 offset0:32 offset1:48
	v_mul_f32_e32 v14, v13, v13
	v_fmac_f32_e32 v14, v12, v12
	s_waitcnt lgkmcnt(0)
	v_fma_f32 v15, v116, v11, -v4
	v_fmac_f32_e32 v14, v15, v15
	v_fma_f32 v11, v132, v11, -v5
	v_fmac_f32_e32 v14, v11, v11
	ds_swizzle_b32 v4, v14 offset:swizzle(SWAP,1)
	s_waitcnt lgkmcnt(0)
	v_add_f32_e32 v4, v14, v4
	ds_swizzle_b32 v5, v4 offset:swizzle(SWAP,2)
	s_waitcnt lgkmcnt(0)
	v_add_f32_e32 v4, v4, v5
	ds_swizzle_b32 v5, v4 offset:swizzle(SWAP,4)
	s_waitcnt lgkmcnt(0)
	v_add_f32_e32 v4, v4, v5
	ds_swizzle_b32 v5, v4 offset:swizzle(SWAP,8)
	s_waitcnt lgkmcnt(0)
	v_add_f32_e32 v4, v4, v5
	ds_swizzle_b32 v5, v4 offset:swizzle(SWAP,16)
	s_waitcnt lgkmcnt(0)
	v_add_f32_e32 v4, v4, v5
	v_fmamk_f32 v4, v4, 0x3c000000, v254
	s_nop 0
	s_nop 0
	s_nop 0
	s_nop 1
	s_nop 1
	s_nop 0
	v_rsq_f32_e32 v14, v4
	s_nop 0
	v_mul_f32_e32 v4, v12, v14
	v_mul_f32_e32 v5, v13, v14
	v_mul_f32_e32 v4, v7, v4
	v_mul_f32_e32 v5, v9, v5
	v_cvt_pk_bf16_f32 v12, v4, v5
	v_lshl_add_u64 v[4:5], v[2:3], 1, s[6:7]
	global_store_short v[4:5], v12, off
	v_add_u32_e32 v4, 32, v2
	v_mov_b32_e32 v5, v3
	v_lshl_add_u64 v[4:5], v[4:5], 1, s[6:7]
	global_store_short_d16_hi v[4:5], v12, off
	v_mul_f32_e32 v4, v15, v14
	v_mul_f32_e32 v5, v11, v14
	v_mul_f32_e32 v4, v6, v4
	v_mul_f32_e32 v5, v8, v5
	v_cvt_pk_bf16_f32 v11, v4, v5
	v_add_u32_e32 v4, 64, v2
	v_mov_b32_e32 v5, v3
	v_lshl_add_u64 v[4:5], v[4:5], 1, s[6:7]
	global_store_short v[4:5], v11, off
	v_add_u32_e32 v4, 0x60, v2
	v_mov_b32_e32 v5, v3
	v_lshl_add_u64 v[4:5], v[4:5], 1, s[6:7]
	global_store_short_d16_hi v[4:5], v11, off
	ds_read_b32 v11, v10 offset:4
	ds_read2st64_b32 v[4:5], v1 offset0:1 offset1:17
	s_waitcnt lgkmcnt(0)
	v_fma_f32 v12, v85, v11, -v4
	v_fma_f32 v13, v101, v11, -v5
	ds_read2st64_b32 v[4:5], v1 offset0:33 offset1:49
	v_mul_f32_e32 v14, v13, v13
	v_fmac_f32_e32 v14, v12, v12
	s_waitcnt lgkmcnt(0)
	v_fma_f32 v15, v117, v11, -v4
	v_fmac_f32_e32 v14, v15, v15
	v_fma_f32 v11, v133, v11, -v5
	v_fmac_f32_e32 v14, v11, v11
	ds_swizzle_b32 v4, v14 offset:swizzle(SWAP,1)
	s_waitcnt lgkmcnt(0)
	v_add_f32_e32 v4, v14, v4
	ds_swizzle_b32 v5, v4 offset:swizzle(SWAP,2)
	s_waitcnt lgkmcnt(0)
	v_add_f32_e32 v4, v4, v5
	ds_swizzle_b32 v5, v4 offset:swizzle(SWAP,4)
	s_waitcnt lgkmcnt(0)
	v_add_f32_e32 v4, v4, v5
	ds_swizzle_b32 v5, v4 offset:swizzle(SWAP,8)
	s_waitcnt lgkmcnt(0)
	v_add_f32_e32 v4, v4, v5
	ds_swizzle_b32 v5, v4 offset:swizzle(SWAP,16)
	s_waitcnt lgkmcnt(0)
	v_add_f32_e32 v4, v4, v5
	v_fmamk_f32 v4, v4, 0x3c000000, v254
	s_nop 0
	s_nop 0
	s_nop 0
	s_nop 1
	s_nop 1
	s_nop 0
	v_rsq_f32_e32 v14, v4
	s_nop 0
	v_mul_f32_e32 v5, v12, v14
	v_mul_f32_e32 v12, v13, v14
	v_mul_f32_e32 v5, v7, v5
	v_mul_f32_e32 v12, v9, v12
	v_add_u32_e32 v4, 0x1000, v2
	v_cvt_pk_bf16_f32 v12, v5, v12
	v_mov_b32_e32 v5, v3
	v_lshl_add_u64 v[4:5], v[4:5], 1, s[6:7]
	global_store_short v[4:5], v12, off
	v_add_u32_e32 v4, 0x1020, v2
	v_mov_b32_e32 v5, v3
	v_lshl_add_u64 v[4:5], v[4:5], 1, s[6:7]
	global_store_short_d16_hi v[4:5], v12, off
	v_mul_f32_e32 v4, v15, v14
	v_mul_f32_e32 v5, v11, v14
	v_mul_f32_e32 v4, v6, v4
	v_mul_f32_e32 v5, v8, v5
	v_cvt_pk_bf16_f32 v11, v4, v5
	v_add_u32_e32 v4, 0x1040, v2
	v_mov_b32_e32 v5, v3
	v_lshl_add_u64 v[4:5], v[4:5], 1, s[6:7]
	global_store_short v[4:5], v11, off
	v_add_u32_e32 v4, 0x1060, v2
	v_mov_b32_e32 v5, v3
	v_lshl_add_u64 v[4:5], v[4:5], 1, s[6:7]
	global_store_short_d16_hi v[4:5], v11, off
	ds_read_b32 v11, v10 offset:8
	ds_read2st64_b32 v[4:5], v1 offset0:2 offset1:18
	s_waitcnt lgkmcnt(0)
	v_fma_f32 v12, v86, v11, -v4
	v_fma_f32 v13, v102, v11, -v5
	ds_read2st64_b32 v[4:5], v1 offset0:34 offset1:50
	v_mul_f32_e32 v14, v13, v13
	v_fmac_f32_e32 v14, v12, v12
	s_waitcnt lgkmcnt(0)
	v_fma_f32 v15, v118, v11, -v4
	v_fmac_f32_e32 v14, v15, v15
	v_fma_f32 v11, v134, v11, -v5
	v_fmac_f32_e32 v14, v11, v11
	ds_swizzle_b32 v4, v14 offset:swizzle(SWAP,1)
	s_waitcnt lgkmcnt(0)
	v_add_f32_e32 v4, v14, v4
	ds_swizzle_b32 v5, v4 offset:swizzle(SWAP,2)
	s_waitcnt lgkmcnt(0)
	v_add_f32_e32 v4, v4, v5
	ds_swizzle_b32 v5, v4 offset:swizzle(SWAP,4)
	s_waitcnt lgkmcnt(0)
	v_add_f32_e32 v4, v4, v5
	ds_swizzle_b32 v5, v4 offset:swizzle(SWAP,8)
	s_waitcnt lgkmcnt(0)
	v_add_f32_e32 v4, v4, v5
	ds_swizzle_b32 v5, v4 offset:swizzle(SWAP,16)
	s_waitcnt lgkmcnt(0)
	v_add_f32_e32 v4, v4, v5
	v_fmamk_f32 v4, v4, 0x3c000000, v254
	s_nop 0
	s_nop 0
	s_nop 0
	s_nop 1
	s_nop 1
	s_nop 0
	v_rsq_f32_e32 v14, v4
	s_nop 0
	v_mul_f32_e32 v5, v12, v14
	v_mul_f32_e32 v12, v13, v14
	v_mul_f32_e32 v5, v7, v5
	v_mul_f32_e32 v12, v9, v12
	v_add_u32_e32 v4, 0x2000, v2
	v_cvt_pk_bf16_f32 v12, v5, v12
	v_mov_b32_e32 v5, v3
	v_lshl_add_u64 v[4:5], v[4:5], 1, s[6:7]
	global_store_short v[4:5], v12, off
	v_add_u32_e32 v4, 0x2020, v2
	v_mov_b32_e32 v5, v3
	v_lshl_add_u64 v[4:5], v[4:5], 1, s[6:7]
	global_store_short_d16_hi v[4:5], v12, off
	v_mul_f32_e32 v4, v15, v14
	v_mul_f32_e32 v5, v11, v14
	v_mul_f32_e32 v4, v6, v4
	v_mul_f32_e32 v5, v8, v5
	v_cvt_pk_bf16_f32 v11, v4, v5
	v_add_u32_e32 v4, 0x2040, v2
	v_mov_b32_e32 v5, v3
	v_lshl_add_u64 v[4:5], v[4:5], 1, s[6:7]
	global_store_short v[4:5], v11, off
	v_add_u32_e32 v4, 0x2060, v2
	v_mov_b32_e32 v5, v3
	v_lshl_add_u64 v[4:5], v[4:5], 1, s[6:7]
	global_store_short_d16_hi v[4:5], v11, off
	ds_read_b32 v11, v10 offset:12
	ds_read2st64_b32 v[4:5], v1 offset0:3 offset1:19
	s_waitcnt lgkmcnt(0)
	v_fma_f32 v12, v87, v11, -v4
	v_fma_f32 v13, v103, v11, -v5
	ds_read2st64_b32 v[4:5], v1 offset0:35 offset1:51
	v_mul_f32_e32 v14, v13, v13
	v_fmac_f32_e32 v14, v12, v12
	s_waitcnt lgkmcnt(0)
	v_fma_f32 v15, v119, v11, -v4
	v_fmac_f32_e32 v14, v15, v15
	v_fma_f32 v11, v135, v11, -v5
	v_fmac_f32_e32 v14, v11, v11
	ds_swizzle_b32 v4, v14 offset:swizzle(SWAP,1)
	s_waitcnt lgkmcnt(0)
	v_add_f32_e32 v4, v14, v4
	ds_swizzle_b32 v5, v4 offset:swizzle(SWAP,2)
	s_waitcnt lgkmcnt(0)
	v_add_f32_e32 v4, v4, v5
	ds_swizzle_b32 v5, v4 offset:swizzle(SWAP,4)
	s_waitcnt lgkmcnt(0)
	v_add_f32_e32 v4, v4, v5
	ds_swizzle_b32 v5, v4 offset:swizzle(SWAP,8)
	s_waitcnt lgkmcnt(0)
	v_add_f32_e32 v4, v4, v5
	ds_swizzle_b32 v5, v4 offset:swizzle(SWAP,16)
	s_waitcnt lgkmcnt(0)
	v_add_f32_e32 v4, v4, v5
	v_fmamk_f32 v4, v4, 0x3c000000, v254
	s_nop 0
	s_nop 0
	s_nop 0
	s_nop 1
	s_nop 1
	s_nop 0
	v_rsq_f32_e32 v14, v4
	s_nop 0
	v_mul_f32_e32 v5, v12, v14
	v_mul_f32_e32 v12, v13, v14
	v_mul_f32_e32 v5, v7, v5
	v_mul_f32_e32 v12, v9, v12
	v_add_u32_e32 v4, 0x3000, v2
	v_cvt_pk_bf16_f32 v12, v5, v12
	v_mov_b32_e32 v5, v3
	v_lshl_add_u64 v[4:5], v[4:5], 1, s[6:7]
	global_store_short v[4:5], v12, off
	v_add_u32_e32 v4, 0x3020, v2
	v_mov_b32_e32 v5, v3
	v_lshl_add_u64 v[4:5], v[4:5], 1, s[6:7]
	global_store_short_d16_hi v[4:5], v12, off
	v_mul_f32_e32 v4, v15, v14
	v_mul_f32_e32 v5, v11, v14
	v_mul_f32_e32 v4, v6, v4
	v_mul_f32_e32 v5, v8, v5
	v_cvt_pk_bf16_f32 v11, v4, v5
	v_add_u32_e32 v4, 0x3040, v2
	v_mov_b32_e32 v5, v3
	v_lshl_add_u64 v[4:5], v[4:5], 1, s[6:7]
	global_store_short v[4:5], v11, off
	v_add_u32_e32 v4, 0x3060, v2
	v_mov_b32_e32 v5, v3
	v_lshl_add_u64 v[4:5], v[4:5], 1, s[6:7]
	global_store_short_d16_hi v[4:5], v11, off
	ds_read_b32 v11, v10 offset:32
	ds_read2st64_b32 v[4:5], v1 offset0:4 offset1:20
	s_waitcnt lgkmcnt(0)
	v_fma_f32 v12, v88, v11, -v4
	v_fma_f32 v13, v104, v11, -v5
	ds_read2st64_b32 v[4:5], v1 offset0:36 offset1:52
	v_mul_f32_e32 v14, v13, v13
	v_fmac_f32_e32 v14, v12, v12
	s_waitcnt lgkmcnt(0)
	v_fma_f32 v15, v120, v11, -v4
	v_fmac_f32_e32 v14, v15, v15
	v_fma_f32 v11, v136, v11, -v5
	v_fmac_f32_e32 v14, v11, v11
	ds_swizzle_b32 v4, v14 offset:swizzle(SWAP,1)
	s_waitcnt lgkmcnt(0)
	v_add_f32_e32 v4, v14, v4
	ds_swizzle_b32 v5, v4 offset:swizzle(SWAP,2)
	s_waitcnt lgkmcnt(0)
	v_add_f32_e32 v4, v4, v5
	ds_swizzle_b32 v5, v4 offset:swizzle(SWAP,4)
	s_waitcnt lgkmcnt(0)
	v_add_f32_e32 v4, v4, v5
	ds_swizzle_b32 v5, v4 offset:swizzle(SWAP,8)
	s_waitcnt lgkmcnt(0)
	v_add_f32_e32 v4, v4, v5
	ds_swizzle_b32 v5, v4 offset:swizzle(SWAP,16)
	s_waitcnt lgkmcnt(0)
	v_add_f32_e32 v4, v4, v5
	v_fmamk_f32 v4, v4, 0x3c000000, v254
	s_nop 0
	s_nop 0
	s_nop 0
	s_nop 1
	s_nop 1
	s_nop 0
	v_rsq_f32_e32 v14, v4
	s_nop 0
	v_mul_f32_e32 v5, v12, v14
	v_mul_f32_e32 v12, v13, v14
	v_mul_f32_e32 v5, v7, v5
	v_mul_f32_e32 v12, v9, v12
	v_add_u32_e32 v4, 0x8000, v2
	v_cvt_pk_bf16_f32 v12, v5, v12
	v_mov_b32_e32 v5, v3
	v_lshl_add_u64 v[4:5], v[4:5], 1, s[6:7]
	global_store_short v[4:5], v12, off
	v_add_u32_e32 v4, 0x8020, v2
	v_mov_b32_e32 v5, v3
	v_lshl_add_u64 v[4:5], v[4:5], 1, s[6:7]
	global_store_short_d16_hi v[4:5], v12, off
	v_mul_f32_e32 v4, v15, v14
	v_mul_f32_e32 v5, v11, v14
	v_mul_f32_e32 v4, v6, v4
	v_mul_f32_e32 v5, v8, v5
	v_cvt_pk_bf16_f32 v11, v4, v5
	v_add_u32_e32 v4, 0x8040, v2
	v_mov_b32_e32 v5, v3
	v_lshl_add_u64 v[4:5], v[4:5], 1, s[6:7]
	global_store_short v[4:5], v11, off
	v_add_u32_e32 v4, 0x8060, v2
	v_mov_b32_e32 v5, v3
	v_lshl_add_u64 v[4:5], v[4:5], 1, s[6:7]
	global_store_short_d16_hi v[4:5], v11, off
	ds_read_b32 v11, v10 offset:36
	ds_read2st64_b32 v[4:5], v1 offset0:5 offset1:21
	s_waitcnt lgkmcnt(0)
	v_fma_f32 v12, v89, v11, -v4
	v_fma_f32 v13, v105, v11, -v5
	ds_read2st64_b32 v[4:5], v1 offset0:37 offset1:53
	v_mul_f32_e32 v14, v13, v13
	v_fmac_f32_e32 v14, v12, v12
	s_waitcnt lgkmcnt(0)
	v_fma_f32 v15, v121, v11, -v4
	v_fmac_f32_e32 v14, v15, v15
	v_fma_f32 v11, v137, v11, -v5
	v_fmac_f32_e32 v14, v11, v11
	ds_swizzle_b32 v4, v14 offset:swizzle(SWAP,1)
	s_waitcnt lgkmcnt(0)
	v_add_f32_e32 v4, v14, v4
	ds_swizzle_b32 v5, v4 offset:swizzle(SWAP,2)
	s_waitcnt lgkmcnt(0)
	v_add_f32_e32 v4, v4, v5
	ds_swizzle_b32 v5, v4 offset:swizzle(SWAP,4)
	s_waitcnt lgkmcnt(0)
	v_add_f32_e32 v4, v4, v5
	ds_swizzle_b32 v5, v4 offset:swizzle(SWAP,8)
	s_waitcnt lgkmcnt(0)
	v_add_f32_e32 v4, v4, v5
	ds_swizzle_b32 v5, v4 offset:swizzle(SWAP,16)
	s_waitcnt lgkmcnt(0)
	v_add_f32_e32 v4, v4, v5
	v_fmamk_f32 v4, v4, 0x3c000000, v254
	s_nop 0
	s_nop 0
	s_nop 0
	s_nop 1
	s_nop 1
	s_nop 0
	v_rsq_f32_e32 v14, v4
	s_nop 0
	v_mul_f32_e32 v5, v12, v14
	v_mul_f32_e32 v12, v13, v14
	v_mul_f32_e32 v5, v7, v5
	v_mul_f32_e32 v12, v9, v12
	v_add_u32_e32 v4, 0x9000, v2
	v_cvt_pk_bf16_f32 v12, v5, v12
	v_mov_b32_e32 v5, v3
	v_lshl_add_u64 v[4:5], v[4:5], 1, s[6:7]
	global_store_short v[4:5], v12, off
	v_add_u32_e32 v4, 0x9020, v2
	v_mov_b32_e32 v5, v3
	v_lshl_add_u64 v[4:5], v[4:5], 1, s[6:7]
	global_store_short_d16_hi v[4:5], v12, off
	v_mul_f32_e32 v4, v15, v14
	v_mul_f32_e32 v5, v11, v14
	v_mul_f32_e32 v4, v6, v4
	v_mul_f32_e32 v5, v8, v5
	v_cvt_pk_bf16_f32 v11, v4, v5
	v_add_u32_e32 v4, 0x9040, v2
	v_mov_b32_e32 v5, v3
	v_lshl_add_u64 v[4:5], v[4:5], 1, s[6:7]
	global_store_short v[4:5], v11, off
	v_add_u32_e32 v4, 0x9060, v2
	v_mov_b32_e32 v5, v3
	v_lshl_add_u64 v[4:5], v[4:5], 1, s[6:7]
	global_store_short_d16_hi v[4:5], v11, off
	ds_read_b32 v11, v10 offset:40
	ds_read2st64_b32 v[4:5], v1 offset0:6 offset1:22
	s_waitcnt lgkmcnt(0)
	v_fma_f32 v12, v90, v11, -v4
	v_fma_f32 v13, v106, v11, -v5
	ds_read2st64_b32 v[4:5], v1 offset0:38 offset1:54
	v_mul_f32_e32 v14, v13, v13
	v_fmac_f32_e32 v14, v12, v12
	s_waitcnt lgkmcnt(0)
	v_fma_f32 v15, v122, v11, -v4
	v_fmac_f32_e32 v14, v15, v15
	v_fma_f32 v11, v138, v11, -v5
	v_fmac_f32_e32 v14, v11, v11
	ds_swizzle_b32 v4, v14 offset:swizzle(SWAP,1)
	s_waitcnt lgkmcnt(0)
	v_add_f32_e32 v4, v14, v4
	ds_swizzle_b32 v5, v4 offset:swizzle(SWAP,2)
	s_waitcnt lgkmcnt(0)
	v_add_f32_e32 v4, v4, v5
	ds_swizzle_b32 v5, v4 offset:swizzle(SWAP,4)
	s_waitcnt lgkmcnt(0)
	v_add_f32_e32 v4, v4, v5
	ds_swizzle_b32 v5, v4 offset:swizzle(SWAP,8)
	s_waitcnt lgkmcnt(0)
	v_add_f32_e32 v4, v4, v5
	ds_swizzle_b32 v5, v4 offset:swizzle(SWAP,16)
	s_waitcnt lgkmcnt(0)
	v_add_f32_e32 v4, v4, v5
	v_fmamk_f32 v4, v4, 0x3c000000, v254
	s_nop 0
	s_nop 0
	s_nop 0
	s_nop 1
	s_nop 1
	s_nop 0
	v_rsq_f32_e32 v14, v4
	s_nop 0
	v_mul_f32_e32 v5, v12, v14
	v_mul_f32_e32 v12, v13, v14
	v_mul_f32_e32 v5, v7, v5
	v_mul_f32_e32 v12, v9, v12
	v_add_u32_e32 v4, 0xa000, v2
	v_cvt_pk_bf16_f32 v12, v5, v12
	v_mov_b32_e32 v5, v3
	v_lshl_add_u64 v[4:5], v[4:5], 1, s[6:7]
	global_store_short v[4:5], v12, off
	v_add_u32_e32 v4, 0xa020, v2
	v_mov_b32_e32 v5, v3
	v_lshl_add_u64 v[4:5], v[4:5], 1, s[6:7]
	global_store_short_d16_hi v[4:5], v12, off
	v_mul_f32_e32 v4, v15, v14
	v_mul_f32_e32 v5, v11, v14
	v_mul_f32_e32 v4, v6, v4
	v_mul_f32_e32 v5, v8, v5
	v_cvt_pk_bf16_f32 v11, v4, v5
	v_add_u32_e32 v4, 0xa040, v2
	v_mov_b32_e32 v5, v3
	v_lshl_add_u64 v[4:5], v[4:5], 1, s[6:7]
	global_store_short v[4:5], v11, off
	v_add_u32_e32 v4, 0xa060, v2
	v_mov_b32_e32 v5, v3
	v_lshl_add_u64 v[4:5], v[4:5], 1, s[6:7]
	global_store_short_d16_hi v[4:5], v11, off
	ds_read_b32 v11, v10 offset:44
	ds_read2st64_b32 v[4:5], v1 offset0:7 offset1:23
	s_waitcnt lgkmcnt(0)
	v_fma_f32 v12, v91, v11, -v4
	v_fma_f32 v13, v107, v11, -v5
	ds_read2st64_b32 v[4:5], v1 offset0:39 offset1:55
	v_mul_f32_e32 v14, v13, v13
	v_fmac_f32_e32 v14, v12, v12
	s_waitcnt lgkmcnt(0)
	v_fma_f32 v15, v123, v11, -v4
	v_fmac_f32_e32 v14, v15, v15
	v_fma_f32 v11, v139, v11, -v5
	v_fmac_f32_e32 v14, v11, v11
	ds_swizzle_b32 v4, v14 offset:swizzle(SWAP,1)
	s_waitcnt lgkmcnt(0)
	v_add_f32_e32 v4, v14, v4
	ds_swizzle_b32 v5, v4 offset:swizzle(SWAP,2)
	s_waitcnt lgkmcnt(0)
	v_add_f32_e32 v4, v4, v5
	ds_swizzle_b32 v5, v4 offset:swizzle(SWAP,4)
	s_waitcnt lgkmcnt(0)
	v_add_f32_e32 v4, v4, v5
	ds_swizzle_b32 v5, v4 offset:swizzle(SWAP,8)
	s_waitcnt lgkmcnt(0)
	v_add_f32_e32 v4, v4, v5
	ds_swizzle_b32 v5, v4 offset:swizzle(SWAP,16)
	s_waitcnt lgkmcnt(0)
	v_add_f32_e32 v4, v4, v5
	v_fmamk_f32 v4, v4, 0x3c000000, v254
	s_nop 0
	s_nop 0
	s_nop 0
	s_nop 1
	s_nop 1
	s_nop 0
	v_rsq_f32_e32 v14, v4
	s_nop 0
	v_mul_f32_e32 v5, v12, v14
	v_mul_f32_e32 v12, v13, v14
	v_mul_f32_e32 v5, v7, v5
	v_mul_f32_e32 v12, v9, v12
	v_add_u32_e32 v4, 0xb000, v2
	v_cvt_pk_bf16_f32 v12, v5, v12
	v_mov_b32_e32 v5, v3
	v_lshl_add_u64 v[4:5], v[4:5], 1, s[6:7]
	global_store_short v[4:5], v12, off
	v_add_u32_e32 v4, 0xb020, v2
	v_mov_b32_e32 v5, v3
	v_lshl_add_u64 v[4:5], v[4:5], 1, s[6:7]
	global_store_short_d16_hi v[4:5], v12, off
	v_mul_f32_e32 v4, v15, v14
	v_mul_f32_e32 v5, v11, v14
	v_mul_f32_e32 v4, v6, v4
	v_mul_f32_e32 v5, v8, v5
	v_cvt_pk_bf16_f32 v11, v4, v5
	v_add_u32_e32 v4, 0xb040, v2
	v_mov_b32_e32 v5, v3
	v_lshl_add_u64 v[4:5], v[4:5], 1, s[6:7]
	global_store_short v[4:5], v11, off
	v_add_u32_e32 v4, 0xb060, v2
	v_mov_b32_e32 v5, v3
	v_lshl_add_u64 v[4:5], v[4:5], 1, s[6:7]
	global_store_short_d16_hi v[4:5], v11, off
	ds_read_b32 v11, v10 offset:64
	ds_read2st64_b32 v[4:5], v1 offset0:8 offset1:24
	s_waitcnt lgkmcnt(0)
	v_fma_f32 v12, v92, v11, -v4
	v_fma_f32 v13, v108, v11, -v5
	ds_read2st64_b32 v[4:5], v1 offset0:40 offset1:56
	v_mul_f32_e32 v14, v13, v13
	v_fmac_f32_e32 v14, v12, v12
	s_waitcnt lgkmcnt(0)
	v_fma_f32 v15, v124, v11, -v4
	v_fmac_f32_e32 v14, v15, v15
	v_fma_f32 v11, v140, v11, -v5
	v_fmac_f32_e32 v14, v11, v11
	ds_swizzle_b32 v4, v14 offset:swizzle(SWAP,1)
	s_waitcnt lgkmcnt(0)
	v_add_f32_e32 v4, v14, v4
	ds_swizzle_b32 v5, v4 offset:swizzle(SWAP,2)
	s_waitcnt lgkmcnt(0)
	v_add_f32_e32 v4, v4, v5
	ds_swizzle_b32 v5, v4 offset:swizzle(SWAP,4)
	s_waitcnt lgkmcnt(0)
	v_add_f32_e32 v4, v4, v5
	ds_swizzle_b32 v5, v4 offset:swizzle(SWAP,8)
	s_waitcnt lgkmcnt(0)
	v_add_f32_e32 v4, v4, v5
	ds_swizzle_b32 v5, v4 offset:swizzle(SWAP,16)
	s_waitcnt lgkmcnt(0)
	v_add_f32_e32 v4, v4, v5
	v_fmamk_f32 v4, v4, 0x3c000000, v254
	s_nop 0
	s_nop 0
	s_nop 0
	s_nop 1
	s_nop 1
	s_nop 0
	v_rsq_f32_e32 v14, v4
	s_nop 0
	v_mul_f32_e32 v5, v12, v14
	v_mul_f32_e32 v12, v13, v14
	v_mul_f32_e32 v5, v7, v5
	v_mul_f32_e32 v12, v9, v12
	v_add_u32_e32 v4, 0x10000, v2
	v_cvt_pk_bf16_f32 v12, v5, v12
	v_mov_b32_e32 v5, v3
	v_lshl_add_u64 v[4:5], v[4:5], 1, s[6:7]
	global_store_short v[4:5], v12, off
	v_add_u32_e32 v4, 0x10020, v2
	v_mov_b32_e32 v5, v3
	v_lshl_add_u64 v[4:5], v[4:5], 1, s[6:7]
	global_store_short_d16_hi v[4:5], v12, off
	v_mul_f32_e32 v4, v15, v14
	v_mul_f32_e32 v5, v11, v14
	v_mul_f32_e32 v4, v6, v4
	v_mul_f32_e32 v5, v8, v5
	v_cvt_pk_bf16_f32 v11, v4, v5
	v_add_u32_e32 v4, 0x10040, v2
	v_mov_b32_e32 v5, v3
	v_lshl_add_u64 v[4:5], v[4:5], 1, s[6:7]
	global_store_short v[4:5], v11, off
	v_add_u32_e32 v4, 0x10060, v2
	v_mov_b32_e32 v5, v3
	v_lshl_add_u64 v[4:5], v[4:5], 1, s[6:7]
	global_store_short_d16_hi v[4:5], v11, off
	ds_read_b32 v11, v10 offset:68
	ds_read2st64_b32 v[4:5], v1 offset0:9 offset1:25
	s_waitcnt lgkmcnt(0)
	v_fma_f32 v12, v93, v11, -v4
	v_fma_f32 v13, v109, v11, -v5
	ds_read2st64_b32 v[4:5], v1 offset0:41 offset1:57
	v_mul_f32_e32 v14, v13, v13
	v_fmac_f32_e32 v14, v12, v12
	s_waitcnt lgkmcnt(0)
	v_fma_f32 v15, v125, v11, -v4
	v_fmac_f32_e32 v14, v15, v15
	v_fma_f32 v11, v141, v11, -v5
	v_fmac_f32_e32 v14, v11, v11
	ds_swizzle_b32 v4, v14 offset:swizzle(SWAP,1)
	s_waitcnt lgkmcnt(0)
	v_add_f32_e32 v4, v14, v4
	ds_swizzle_b32 v5, v4 offset:swizzle(SWAP,2)
	s_waitcnt lgkmcnt(0)
	v_add_f32_e32 v4, v4, v5
	ds_swizzle_b32 v5, v4 offset:swizzle(SWAP,4)
	s_waitcnt lgkmcnt(0)
	v_add_f32_e32 v4, v4, v5
	ds_swizzle_b32 v5, v4 offset:swizzle(SWAP,8)
	s_waitcnt lgkmcnt(0)
	v_add_f32_e32 v4, v4, v5
	ds_swizzle_b32 v5, v4 offset:swizzle(SWAP,16)
	s_waitcnt lgkmcnt(0)
	v_add_f32_e32 v4, v4, v5
	v_fmamk_f32 v4, v4, 0x3c000000, v254
	s_nop 0
	s_nop 0
	s_nop 0
	s_nop 1
	s_nop 1
	s_nop 0
	v_rsq_f32_e32 v14, v4
	s_nop 0
	v_mul_f32_e32 v5, v12, v14
	v_mul_f32_e32 v12, v13, v14
	v_mul_f32_e32 v5, v7, v5
	v_mul_f32_e32 v12, v9, v12
	v_add_u32_e32 v4, 0x11000, v2
	v_cvt_pk_bf16_f32 v12, v5, v12
	v_mov_b32_e32 v5, v3
	v_lshl_add_u64 v[4:5], v[4:5], 1, s[6:7]
	global_store_short v[4:5], v12, off
	v_add_u32_e32 v4, 0x11020, v2
	v_mov_b32_e32 v5, v3
	v_lshl_add_u64 v[4:5], v[4:5], 1, s[6:7]
	global_store_short_d16_hi v[4:5], v12, off
	v_mul_f32_e32 v4, v15, v14
	v_mul_f32_e32 v5, v11, v14
	v_mul_f32_e32 v4, v6, v4
	v_mul_f32_e32 v5, v8, v5
	v_cvt_pk_bf16_f32 v11, v4, v5
	v_add_u32_e32 v4, 0x11040, v2
	v_mov_b32_e32 v5, v3
	v_lshl_add_u64 v[4:5], v[4:5], 1, s[6:7]
	global_store_short v[4:5], v11, off
	v_add_u32_e32 v4, 0x11060, v2
	v_mov_b32_e32 v5, v3
	v_lshl_add_u64 v[4:5], v[4:5], 1, s[6:7]
	global_store_short_d16_hi v[4:5], v11, off
	ds_read_b32 v11, v10 offset:72
	ds_read2st64_b32 v[4:5], v1 offset0:10 offset1:26
	s_waitcnt lgkmcnt(0)
	v_fma_f32 v12, v94, v11, -v4
	v_fma_f32 v13, v110, v11, -v5
	ds_read2st64_b32 v[4:5], v1 offset0:42 offset1:58
	v_mul_f32_e32 v14, v13, v13
	v_fmac_f32_e32 v14, v12, v12
	s_waitcnt lgkmcnt(0)
	v_fma_f32 v15, v126, v11, -v4
	v_fmac_f32_e32 v14, v15, v15
	v_fma_f32 v11, v142, v11, -v5
	v_fmac_f32_e32 v14, v11, v11
	ds_swizzle_b32 v4, v14 offset:swizzle(SWAP,1)
	s_waitcnt lgkmcnt(0)
	v_add_f32_e32 v4, v14, v4
	ds_swizzle_b32 v5, v4 offset:swizzle(SWAP,2)
	s_waitcnt lgkmcnt(0)
	v_add_f32_e32 v4, v4, v5
	ds_swizzle_b32 v5, v4 offset:swizzle(SWAP,4)
	s_waitcnt lgkmcnt(0)
	v_add_f32_e32 v4, v4, v5
	ds_swizzle_b32 v5, v4 offset:swizzle(SWAP,8)
	s_waitcnt lgkmcnt(0)
	v_add_f32_e32 v4, v4, v5
	ds_swizzle_b32 v5, v4 offset:swizzle(SWAP,16)
	s_waitcnt lgkmcnt(0)
	v_add_f32_e32 v4, v4, v5
	v_fmamk_f32 v4, v4, 0x3c000000, v254
	s_nop 0
	s_nop 0
	s_nop 0
	s_nop 1
	s_nop 1
	s_nop 0
	v_rsq_f32_e32 v14, v4
	s_nop 0
	v_mul_f32_e32 v5, v12, v14
	v_mul_f32_e32 v12, v13, v14
	v_mul_f32_e32 v5, v7, v5
	v_mul_f32_e32 v12, v9, v12
	v_add_u32_e32 v4, 0x12000, v2
	v_cvt_pk_bf16_f32 v12, v5, v12
	v_mov_b32_e32 v5, v3
	v_lshl_add_u64 v[4:5], v[4:5], 1, s[6:7]
	global_store_short v[4:5], v12, off
	v_add_u32_e32 v4, 0x12020, v2
	v_mov_b32_e32 v5, v3
	v_lshl_add_u64 v[4:5], v[4:5], 1, s[6:7]
	global_store_short_d16_hi v[4:5], v12, off
	v_mul_f32_e32 v4, v15, v14
	v_mul_f32_e32 v5, v11, v14
	v_mul_f32_e32 v4, v6, v4
	v_mul_f32_e32 v5, v8, v5
	v_cvt_pk_bf16_f32 v11, v4, v5
	v_add_u32_e32 v4, 0x12040, v2
	v_mov_b32_e32 v5, v3
	v_lshl_add_u64 v[4:5], v[4:5], 1, s[6:7]
	global_store_short v[4:5], v11, off
	v_add_u32_e32 v4, 0x12060, v2
	v_mov_b32_e32 v5, v3
	v_lshl_add_u64 v[4:5], v[4:5], 1, s[6:7]
	global_store_short_d16_hi v[4:5], v11, off
	ds_read_b32 v11, v10 offset:76
	ds_read2st64_b32 v[4:5], v1 offset0:11 offset1:27
	s_waitcnt lgkmcnt(0)
	v_fma_f32 v12, v95, v11, -v4
	v_fma_f32 v13, v111, v11, -v5
	ds_read2st64_b32 v[4:5], v1 offset0:43 offset1:59
	v_mul_f32_e32 v14, v13, v13
	v_fmac_f32_e32 v14, v12, v12
	s_waitcnt lgkmcnt(0)
	v_fma_f32 v15, v127, v11, -v4
	v_fmac_f32_e32 v14, v15, v15
	v_fma_f32 v11, v143, v11, -v5
	v_fmac_f32_e32 v14, v11, v11
	ds_swizzle_b32 v4, v14 offset:swizzle(SWAP,1)
	s_waitcnt lgkmcnt(0)
	v_add_f32_e32 v4, v14, v4
	ds_swizzle_b32 v5, v4 offset:swizzle(SWAP,2)
	s_waitcnt lgkmcnt(0)
	v_add_f32_e32 v4, v4, v5
	ds_swizzle_b32 v5, v4 offset:swizzle(SWAP,4)
	s_waitcnt lgkmcnt(0)
	v_add_f32_e32 v4, v4, v5
	ds_swizzle_b32 v5, v4 offset:swizzle(SWAP,8)
	s_waitcnt lgkmcnt(0)
	v_add_f32_e32 v4, v4, v5
	ds_swizzle_b32 v5, v4 offset:swizzle(SWAP,16)
	s_waitcnt lgkmcnt(0)
	v_add_f32_e32 v4, v4, v5
	v_fmamk_f32 v4, v4, 0x3c000000, v254
	s_nop 0
	s_nop 0
	s_nop 0
	s_nop 1
	s_nop 1
	s_nop 0
	v_rsq_f32_e32 v14, v4
	s_nop 0
	v_mul_f32_e32 v5, v12, v14
	v_mul_f32_e32 v12, v13, v14
	v_mul_f32_e32 v5, v7, v5
	v_mul_f32_e32 v12, v9, v12
	v_add_u32_e32 v4, 0x13000, v2
	v_cvt_pk_bf16_f32 v12, v5, v12
	v_mov_b32_e32 v5, v3
	v_lshl_add_u64 v[4:5], v[4:5], 1, s[6:7]
	global_store_short v[4:5], v12, off
	v_add_u32_e32 v4, 0x13020, v2
	v_mov_b32_e32 v5, v3
	v_lshl_add_u64 v[4:5], v[4:5], 1, s[6:7]
	global_store_short_d16_hi v[4:5], v12, off
	v_mul_f32_e32 v4, v15, v14
	v_mul_f32_e32 v5, v11, v14
	v_mul_f32_e32 v4, v6, v4
	v_mul_f32_e32 v5, v8, v5
	v_cvt_pk_bf16_f32 v11, v4, v5
	v_add_u32_e32 v4, 0x13040, v2
	v_mov_b32_e32 v5, v3
	v_lshl_add_u64 v[4:5], v[4:5], 1, s[6:7]
	global_store_short v[4:5], v11, off
	v_add_u32_e32 v4, 0x13060, v2
	v_mov_b32_e32 v5, v3
	v_lshl_add_u64 v[4:5], v[4:5], 1, s[6:7]
	global_store_short_d16_hi v[4:5], v11, off
	ds_read_b32 v11, v10 offset:96
	ds_read2st64_b32 v[4:5], v1 offset0:12 offset1:28
	s_waitcnt lgkmcnt(0)
	v_fma_f32 v12, v96, v11, -v4
	v_fma_f32 v13, v112, v11, -v5
	ds_read2st64_b32 v[4:5], v1 offset0:44 offset1:60
	v_mul_f32_e32 v14, v13, v13
	v_fmac_f32_e32 v14, v12, v12
	s_waitcnt lgkmcnt(0)
	v_fma_f32 v15, v128, v11, -v4
	v_fmac_f32_e32 v14, v15, v15
	v_fma_f32 v11, v144, v11, -v5
	v_fmac_f32_e32 v14, v11, v11
	ds_swizzle_b32 v4, v14 offset:swizzle(SWAP,1)
	s_waitcnt lgkmcnt(0)
	v_add_f32_e32 v4, v14, v4
	ds_swizzle_b32 v5, v4 offset:swizzle(SWAP,2)
	s_waitcnt lgkmcnt(0)
	v_add_f32_e32 v4, v4, v5
	ds_swizzle_b32 v5, v4 offset:swizzle(SWAP,4)
	s_waitcnt lgkmcnt(0)
	v_add_f32_e32 v4, v4, v5
	ds_swizzle_b32 v5, v4 offset:swizzle(SWAP,8)
	s_waitcnt lgkmcnt(0)
	v_add_f32_e32 v4, v4, v5
	ds_swizzle_b32 v5, v4 offset:swizzle(SWAP,16)
	s_waitcnt lgkmcnt(0)
	v_add_f32_e32 v4, v4, v5
	v_fmamk_f32 v4, v4, 0x3c000000, v254
	s_nop 0
	s_nop 0
	s_nop 0
	s_nop 1
	s_nop 1
	s_nop 0
	v_rsq_f32_e32 v14, v4
	s_nop 0
	v_mul_f32_e32 v5, v12, v14
	v_mul_f32_e32 v12, v13, v14
	v_mul_f32_e32 v5, v7, v5
	v_mul_f32_e32 v12, v9, v12
	v_add_u32_e32 v4, 0x18000, v2
	v_cvt_pk_bf16_f32 v12, v5, v12
	v_mov_b32_e32 v5, v3
	v_lshl_add_u64 v[4:5], v[4:5], 1, s[6:7]
	global_store_short v[4:5], v12, off
	v_add_u32_e32 v4, 0x18020, v2
	v_mov_b32_e32 v5, v3
	v_lshl_add_u64 v[4:5], v[4:5], 1, s[6:7]
	global_store_short_d16_hi v[4:5], v12, off
	v_mul_f32_e32 v4, v15, v14
	v_mul_f32_e32 v5, v11, v14
	v_mul_f32_e32 v4, v6, v4
	v_mul_f32_e32 v5, v8, v5
	v_cvt_pk_bf16_f32 v11, v4, v5
	v_add_u32_e32 v4, 0x18040, v2
	v_mov_b32_e32 v5, v3
	v_lshl_add_u64 v[4:5], v[4:5], 1, s[6:7]
	global_store_short v[4:5], v11, off
	v_add_u32_e32 v4, 0x18060, v2
	v_mov_b32_e32 v5, v3
	v_lshl_add_u64 v[4:5], v[4:5], 1, s[6:7]
	global_store_short_d16_hi v[4:5], v11, off
	ds_read_b32 v11, v10 offset:100
	ds_read2st64_b32 v[4:5], v1 offset0:13 offset1:29
	s_waitcnt lgkmcnt(0)
	v_fma_f32 v12, v97, v11, -v4
	v_fma_f32 v13, v113, v11, -v5
	ds_read2st64_b32 v[4:5], v1 offset0:45 offset1:61
	v_mul_f32_e32 v14, v13, v13
	v_fmac_f32_e32 v14, v12, v12
	s_waitcnt lgkmcnt(0)
	v_fma_f32 v15, v129, v11, -v4
	v_fmac_f32_e32 v14, v15, v15
	v_fma_f32 v11, v145, v11, -v5
	v_fmac_f32_e32 v14, v11, v11
	ds_swizzle_b32 v4, v14 offset:swizzle(SWAP,1)
	s_waitcnt lgkmcnt(0)
	v_add_f32_e32 v4, v14, v4
	ds_swizzle_b32 v5, v4 offset:swizzle(SWAP,2)
	s_waitcnt lgkmcnt(0)
	v_add_f32_e32 v4, v4, v5
	ds_swizzle_b32 v5, v4 offset:swizzle(SWAP,4)
	s_waitcnt lgkmcnt(0)
	v_add_f32_e32 v4, v4, v5
	ds_swizzle_b32 v5, v4 offset:swizzle(SWAP,8)
	s_waitcnt lgkmcnt(0)
	v_add_f32_e32 v4, v4, v5
	ds_swizzle_b32 v5, v4 offset:swizzle(SWAP,16)
	s_waitcnt lgkmcnt(0)
	v_add_f32_e32 v4, v4, v5
	v_fmamk_f32 v4, v4, 0x3c000000, v254
	s_nop 0
	s_nop 0
	s_nop 0
	s_nop 1
	s_nop 1
	s_nop 0
	v_rsq_f32_e32 v14, v4
	s_nop 0
	v_mul_f32_e32 v5, v12, v14
	v_mul_f32_e32 v12, v13, v14
	v_mul_f32_e32 v5, v7, v5
	v_mul_f32_e32 v12, v9, v12
	v_add_u32_e32 v4, 0x19000, v2
	v_cvt_pk_bf16_f32 v12, v5, v12
	v_mov_b32_e32 v5, v3
	v_lshl_add_u64 v[4:5], v[4:5], 1, s[6:7]
	global_store_short v[4:5], v12, off
	v_add_u32_e32 v4, 0x19020, v2
	v_mov_b32_e32 v5, v3
	v_lshl_add_u64 v[4:5], v[4:5], 1, s[6:7]
	global_store_short_d16_hi v[4:5], v12, off
	v_mul_f32_e32 v4, v15, v14
	v_mul_f32_e32 v5, v11, v14
	v_mul_f32_e32 v4, v6, v4
	v_mul_f32_e32 v5, v8, v5
	v_cvt_pk_bf16_f32 v11, v4, v5
	v_add_u32_e32 v4, 0x19040, v2
	v_mov_b32_e32 v5, v3
	v_lshl_add_u64 v[4:5], v[4:5], 1, s[6:7]
	global_store_short v[4:5], v11, off
	v_add_u32_e32 v4, 0x19060, v2
	v_mov_b32_e32 v5, v3
	v_lshl_add_u64 v[4:5], v[4:5], 1, s[6:7]
	global_store_short_d16_hi v[4:5], v11, off
	ds_read_b32 v11, v10 offset:104
	ds_read2st64_b32 v[4:5], v1 offset0:14 offset1:30
	s_waitcnt lgkmcnt(0)
	v_fma_f32 v12, v98, v11, -v4
	v_fma_f32 v13, v114, v11, -v5
	ds_read2st64_b32 v[4:5], v1 offset0:46 offset1:62
	v_mul_f32_e32 v14, v13, v13
	v_fmac_f32_e32 v14, v12, v12
	s_waitcnt lgkmcnt(0)
	v_fma_f32 v15, v130, v11, -v4
	v_fmac_f32_e32 v14, v15, v15
	v_fma_f32 v11, v146, v11, -v5
	v_fmac_f32_e32 v14, v11, v11
	ds_swizzle_b32 v4, v14 offset:swizzle(SWAP,1)
	s_waitcnt lgkmcnt(0)
	v_add_f32_e32 v4, v14, v4
	ds_swizzle_b32 v5, v4 offset:swizzle(SWAP,2)
	s_waitcnt lgkmcnt(0)
	v_add_f32_e32 v4, v4, v5
	ds_swizzle_b32 v5, v4 offset:swizzle(SWAP,4)
	s_waitcnt lgkmcnt(0)
	v_add_f32_e32 v4, v4, v5
	ds_swizzle_b32 v5, v4 offset:swizzle(SWAP,8)
	s_waitcnt lgkmcnt(0)
	v_add_f32_e32 v4, v4, v5
	ds_swizzle_b32 v5, v4 offset:swizzle(SWAP,16)
	s_waitcnt lgkmcnt(0)
	v_add_f32_e32 v4, v4, v5
	v_fmamk_f32 v4, v4, 0x3c000000, v254
	s_nop 0
	s_nop 0
	s_nop 0
	s_nop 1
	s_nop 1
	s_nop 0
	v_rsq_f32_e32 v14, v4
	s_nop 0
	v_mul_f32_e32 v5, v12, v14
	v_mul_f32_e32 v12, v13, v14
	v_mul_f32_e32 v5, v7, v5
	v_mul_f32_e32 v12, v9, v12
	v_add_u32_e32 v4, 0x1a000, v2
	v_cvt_pk_bf16_f32 v12, v5, v12
	v_mov_b32_e32 v5, v3
	v_lshl_add_u64 v[4:5], v[4:5], 1, s[6:7]
	global_store_short v[4:5], v12, off
	v_add_u32_e32 v4, 0x1a020, v2
	v_mov_b32_e32 v5, v3
	v_lshl_add_u64 v[4:5], v[4:5], 1, s[6:7]
	global_store_short_d16_hi v[4:5], v12, off
	v_mul_f32_e32 v4, v15, v14
	v_mul_f32_e32 v5, v11, v14
	v_mul_f32_e32 v4, v6, v4
	v_mul_f32_e32 v5, v8, v5
	v_cvt_pk_bf16_f32 v11, v4, v5
	v_add_u32_e32 v4, 0x1a040, v2
	v_mov_b32_e32 v5, v3
	v_lshl_add_u64 v[4:5], v[4:5], 1, s[6:7]
	global_store_short v[4:5], v11, off
	v_add_u32_e32 v4, 0x1a060, v2
	v_mov_b32_e32 v5, v3
	v_lshl_add_u64 v[4:5], v[4:5], 1, s[6:7]
	global_store_short_d16_hi v[4:5], v11, off
	ds_read_b32 v10, v10 offset:108
	ds_read2st64_b32 v[4:5], v1 offset0:15 offset1:31
	s_waitcnt lgkmcnt(0)
	v_fma_f32 v11, v99, v10, -v4
	v_fma_f32 v12, v115, v10, -v5
	ds_read2st64_b32 v[4:5], v1 offset0:47 offset1:63
	v_mul_f32_e32 v13, v12, v12
	v_fmac_f32_e32 v13, v11, v11
	s_waitcnt lgkmcnt(0)
	v_fma_f32 v1, v131, v10, -v4
	v_fmac_f32_e32 v13, v1, v1
	v_fma_f32 v10, v147, v10, -v5
	v_fmac_f32_e32 v13, v10, v10
	ds_swizzle_b32 v4, v13 offset:swizzle(SWAP,1)
	s_waitcnt lgkmcnt(0)
	v_add_f32_e32 v4, v13, v4
	ds_swizzle_b32 v5, v4 offset:swizzle(SWAP,2)
	s_waitcnt lgkmcnt(0)
	v_add_f32_e32 v4, v4, v5
	ds_swizzle_b32 v5, v4 offset:swizzle(SWAP,4)
	s_waitcnt lgkmcnt(0)
	v_add_f32_e32 v4, v4, v5
	ds_swizzle_b32 v5, v4 offset:swizzle(SWAP,8)
	s_waitcnt lgkmcnt(0)
	v_add_f32_e32 v4, v4, v5
	ds_swizzle_b32 v5, v4 offset:swizzle(SWAP,16)
	s_waitcnt lgkmcnt(0)
	v_add_f32_e32 v4, v4, v5
	v_fmamk_f32 v4, v4, 0x3c000000, v254
	s_nop 0
	s_nop 0
	s_nop 0
	s_nop 1
	s_nop 1
	s_nop 0
	v_rsq_f32_e32 v13, v4
	s_nop 0
	v_mul_f32_e32 v5, v11, v13
	v_mul_f32_e32 v5, v7, v5
	v_mul_f32_e32 v7, v12, v13
	v_mul_f32_e32 v7, v9, v7
	v_add_u32_e32 v4, 0x1b000, v2
	v_cvt_pk_bf16_f32 v7, v5, v7
	v_mov_b32_e32 v5, v3
	v_lshl_add_u64 v[4:5], v[4:5], 1, s[6:7]
	global_store_short v[4:5], v7, off
	v_add_u32_e32 v4, 0x1b020, v2
	v_mov_b32_e32 v5, v3
	v_lshl_add_u64 v[4:5], v[4:5], 1, s[6:7]
	global_store_short_d16_hi v[4:5], v7, off
	v_mul_f32_e32 v1, v1, v13
	v_mul_f32_e32 v4, v10, v13
	v_mul_f32_e32 v1, v6, v1
	v_mul_f32_e32 v4, v8, v4
	v_cvt_pk_bf16_f32 v1, v1, v4
	v_add_u32_e32 v4, 0x1b040, v2
	v_mov_b32_e32 v5, v3
	v_lshl_add_u64 v[4:5], v[4:5], 1, s[6:7]
	v_add_u32_e32 v2, 0x1b060, v2
	global_store_short v[4:5], v1, off
	v_lshl_add_u64 v[4:5], v[2:3], 1, s[6:7]
	global_store_short_d16_hi v[4:5], v1, off

.LBB0_1239:
	s_or_b64 exec, exec, s[4:5]
	s_waitcnt lgkmcnt(0)
	v_lshlrev_b32_e32 v2, 2, v158
	global_load_dword v249, v2, s[0:1]
	global_load_dword v250, v2, s[0:1] offset:128
	global_load_dword v251, v2, s[0:1] offset:256
	global_load_dword v253, v2, s[0:1] offset:384
	v_add_u32_e32 v10, s43, v148
	s_lshl_b64 s[4:5], s[24:25], 13
	s_add_u32 s4, s86, s4
	s_addc_u32 s5, s87, s5
	s_lshl_b32 s6, s8, 1
	s_add_u32 s6, s4, s6
	s_addc_u32 s7, s5, 0
	s_waitcnt vmcnt(0)
	v_mul_f32_e32 v7, v164, v249
	v_mul_f32_e32 v9, v164, v250
	v_mul_f32_e32 v6, v164, v251
	v_mul_f32_e32 v8, v164, v253
	v_lshl_or_b32 v2, v159, 14, v158
	ds_read_b32 v11, v10
	ds_read2st64_b32 v[4:5], v1 offset1:16
	s_waitcnt lgkmcnt(0)
	v_fma_f32 v12, v68, v11, -v4
	v_fma_f32 v13, v84, v11, -v5
	ds_read2st64_b32 v[4:5], v1 offset0:32 offset1:48
	v_mul_f32_e32 v14, v13, v13
	v_fmac_f32_e32 v14, v12, v12
	s_waitcnt lgkmcnt(0)
	v_fma_f32 v15, v100, v11, -v4
	v_fmac_f32_e32 v14, v15, v15
	v_fma_f32 v11, v116, v11, -v5
	v_fmac_f32_e32 v14, v11, v11
	ds_swizzle_b32 v4, v14 offset:swizzle(SWAP,1)
	s_waitcnt lgkmcnt(0)
	v_add_f32_e32 v4, v14, v4
	ds_swizzle_b32 v5, v4 offset:swizzle(SWAP,2)
	s_waitcnt lgkmcnt(0)
	v_add_f32_e32 v4, v4, v5
	ds_swizzle_b32 v5, v4 offset:swizzle(SWAP,4)
	s_waitcnt lgkmcnt(0)
	v_add_f32_e32 v4, v4, v5
	ds_swizzle_b32 v5, v4 offset:swizzle(SWAP,8)
	s_waitcnt lgkmcnt(0)
	v_add_f32_e32 v4, v4, v5
	ds_swizzle_b32 v5, v4 offset:swizzle(SWAP,16)
	s_waitcnt lgkmcnt(0)
	v_add_f32_e32 v4, v4, v5
	v_fmamk_f32 v4, v4, 0x3c000000, v254
	s_nop 0
	s_nop 0
	s_nop 0
	s_nop 1
	s_nop 1
	s_nop 0
	v_rsq_f32_e32 v14, v4
	s_nop 0
	v_mul_f32_e32 v4, v12, v14
	v_mul_f32_e32 v5, v13, v14
	v_mul_f32_e32 v4, v7, v4
	v_mul_f32_e32 v5, v9, v5
	v_cvt_pk_bf16_f32 v12, v4, v5
	v_lshl_add_u64 v[4:5], v[2:3], 1, s[6:7]
	global_store_short v[4:5], v12, off
	v_add_u32_e32 v4, 32, v2
	v_mov_b32_e32 v5, v3
	v_lshl_add_u64 v[4:5], v[4:5], 1, s[6:7]
	global_store_short_d16_hi v[4:5], v12, off
	v_mul_f32_e32 v4, v15, v14
	v_mul_f32_e32 v5, v11, v14
	v_mul_f32_e32 v4, v6, v4
	v_mul_f32_e32 v5, v8, v5
	v_cvt_pk_bf16_f32 v11, v4, v5
	v_add_u32_e32 v4, 64, v2
	v_mov_b32_e32 v5, v3
	v_lshl_add_u64 v[4:5], v[4:5], 1, s[6:7]
	global_store_short v[4:5], v11, off
	v_add_u32_e32 v4, 0x60, v2
	v_mov_b32_e32 v5, v3
	v_lshl_add_u64 v[4:5], v[4:5], 1, s[6:7]
	global_store_short_d16_hi v[4:5], v11, off
	ds_read_b32 v11, v10 offset:4
	ds_read2st64_b32 v[4:5], v1 offset0:1 offset1:17
	s_waitcnt lgkmcnt(0)
	v_fma_f32 v12, v69, v11, -v4
	v_fma_f32 v13, v85, v11, -v5
	ds_read2st64_b32 v[4:5], v1 offset0:33 offset1:49
	v_mul_f32_e32 v14, v13, v13
	v_fmac_f32_e32 v14, v12, v12
	s_waitcnt lgkmcnt(0)
	v_fma_f32 v15, v101, v11, -v4
	v_fmac_f32_e32 v14, v15, v15
	v_fma_f32 v11, v117, v11, -v5
	v_fmac_f32_e32 v14, v11, v11
	ds_swizzle_b32 v4, v14 offset:swizzle(SWAP,1)
	s_waitcnt lgkmcnt(0)
	v_add_f32_e32 v4, v14, v4
	ds_swizzle_b32 v5, v4 offset:swizzle(SWAP,2)
	s_waitcnt lgkmcnt(0)
	v_add_f32_e32 v4, v4, v5
	ds_swizzle_b32 v5, v4 offset:swizzle(SWAP,4)
	s_waitcnt lgkmcnt(0)
	v_add_f32_e32 v4, v4, v5
	ds_swizzle_b32 v5, v4 offset:swizzle(SWAP,8)
	s_waitcnt lgkmcnt(0)
	v_add_f32_e32 v4, v4, v5
	ds_swizzle_b32 v5, v4 offset:swizzle(SWAP,16)
	s_waitcnt lgkmcnt(0)
	v_add_f32_e32 v4, v4, v5
	v_fmamk_f32 v4, v4, 0x3c000000, v254
	s_nop 0
	s_nop 0
	s_nop 0
	s_nop 1
	s_nop 1
	s_nop 0
	v_rsq_f32_e32 v14, v4
	s_nop 0
	v_mul_f32_e32 v5, v12, v14
	v_mul_f32_e32 v12, v13, v14
	v_mul_f32_e32 v5, v7, v5
	v_mul_f32_e32 v12, v9, v12
	v_add_u32_e32 v4, 0x1000, v2
	v_cvt_pk_bf16_f32 v12, v5, v12
	v_mov_b32_e32 v5, v3
	v_lshl_add_u64 v[4:5], v[4:5], 1, s[6:7]
	global_store_short v[4:5], v12, off
	v_add_u32_e32 v4, 0x1020, v2
	v_mov_b32_e32 v5, v3
	v_lshl_add_u64 v[4:5], v[4:5], 1, s[6:7]
	global_store_short_d16_hi v[4:5], v12, off
	v_mul_f32_e32 v4, v15, v14
	v_mul_f32_e32 v5, v11, v14
	v_mul_f32_e32 v4, v6, v4
	v_mul_f32_e32 v5, v8, v5
	v_cvt_pk_bf16_f32 v11, v4, v5
	v_add_u32_e32 v4, 0x1040, v2
	v_mov_b32_e32 v5, v3
	v_lshl_add_u64 v[4:5], v[4:5], 1, s[6:7]
	global_store_short v[4:5], v11, off
	v_add_u32_e32 v4, 0x1060, v2
	v_mov_b32_e32 v5, v3
	v_lshl_add_u64 v[4:5], v[4:5], 1, s[6:7]
	global_store_short_d16_hi v[4:5], v11, off
	ds_read_b32 v11, v10 offset:8
	ds_read2st64_b32 v[4:5], v1 offset0:2 offset1:18
	s_waitcnt lgkmcnt(0)
	v_fma_f32 v12, v70, v11, -v4
	v_fma_f32 v13, v86, v11, -v5
	ds_read2st64_b32 v[4:5], v1 offset0:34 offset1:50
	v_mul_f32_e32 v14, v13, v13
	v_fmac_f32_e32 v14, v12, v12
	s_waitcnt lgkmcnt(0)
	v_fma_f32 v15, v102, v11, -v4
	v_fmac_f32_e32 v14, v15, v15
	v_fma_f32 v11, v118, v11, -v5
	v_fmac_f32_e32 v14, v11, v11
	ds_swizzle_b32 v4, v14 offset:swizzle(SWAP,1)
	s_waitcnt lgkmcnt(0)
	v_add_f32_e32 v4, v14, v4
	ds_swizzle_b32 v5, v4 offset:swizzle(SWAP,2)
	s_waitcnt lgkmcnt(0)
	v_add_f32_e32 v4, v4, v5
	ds_swizzle_b32 v5, v4 offset:swizzle(SWAP,4)
	s_waitcnt lgkmcnt(0)
	v_add_f32_e32 v4, v4, v5
	ds_swizzle_b32 v5, v4 offset:swizzle(SWAP,8)
	s_waitcnt lgkmcnt(0)
	v_add_f32_e32 v4, v4, v5
	ds_swizzle_b32 v5, v4 offset:swizzle(SWAP,16)
	s_waitcnt lgkmcnt(0)
	v_add_f32_e32 v4, v4, v5
	v_fmamk_f32 v4, v4, 0x3c000000, v254
	s_nop 0
	s_nop 0
	s_nop 0
	s_nop 1
	s_nop 1
	s_nop 0
	v_rsq_f32_e32 v14, v4
	s_nop 0
	v_mul_f32_e32 v5, v12, v14
	v_mul_f32_e32 v12, v13, v14
	v_mul_f32_e32 v5, v7, v5
	v_mul_f32_e32 v12, v9, v12
	v_add_u32_e32 v4, 0x2000, v2
	v_cvt_pk_bf16_f32 v12, v5, v12
	v_mov_b32_e32 v5, v3
	v_lshl_add_u64 v[4:5], v[4:5], 1, s[6:7]
	global_store_short v[4:5], v12, off
	v_add_u32_e32 v4, 0x2020, v2
	v_mov_b32_e32 v5, v3
	v_lshl_add_u64 v[4:5], v[4:5], 1, s[6:7]
	global_store_short_d16_hi v[4:5], v12, off
	v_mul_f32_e32 v4, v15, v14
	v_mul_f32_e32 v5, v11, v14
	v_mul_f32_e32 v4, v6, v4
	v_mul_f32_e32 v5, v8, v5
	v_cvt_pk_bf16_f32 v11, v4, v5
	v_add_u32_e32 v4, 0x2040, v2
	v_mov_b32_e32 v5, v3
	v_lshl_add_u64 v[4:5], v[4:5], 1, s[6:7]
	global_store_short v[4:5], v11, off
	v_add_u32_e32 v4, 0x2060, v2
	v_mov_b32_e32 v5, v3
	v_lshl_add_u64 v[4:5], v[4:5], 1, s[6:7]
	global_store_short_d16_hi v[4:5], v11, off
	ds_read_b32 v11, v10 offset:12
	ds_read2st64_b32 v[4:5], v1 offset0:3 offset1:19
	s_waitcnt lgkmcnt(0)
	v_fma_f32 v12, v71, v11, -v4
	v_fma_f32 v13, v87, v11, -v5
	ds_read2st64_b32 v[4:5], v1 offset0:35 offset1:51
	v_mul_f32_e32 v14, v13, v13
	v_fmac_f32_e32 v14, v12, v12
	s_waitcnt lgkmcnt(0)
	v_fma_f32 v15, v103, v11, -v4
	v_fmac_f32_e32 v14, v15, v15
	v_fma_f32 v11, v119, v11, -v5
	v_fmac_f32_e32 v14, v11, v11
	ds_swizzle_b32 v4, v14 offset:swizzle(SWAP,1)
	s_waitcnt lgkmcnt(0)
	v_add_f32_e32 v4, v14, v4
	ds_swizzle_b32 v5, v4 offset:swizzle(SWAP,2)
	s_waitcnt lgkmcnt(0)
	v_add_f32_e32 v4, v4, v5
	ds_swizzle_b32 v5, v4 offset:swizzle(SWAP,4)
	s_waitcnt lgkmcnt(0)
	v_add_f32_e32 v4, v4, v5
	ds_swizzle_b32 v5, v4 offset:swizzle(SWAP,8)
	s_waitcnt lgkmcnt(0)
	v_add_f32_e32 v4, v4, v5
	ds_swizzle_b32 v5, v4 offset:swizzle(SWAP,16)
	s_waitcnt lgkmcnt(0)
	v_add_f32_e32 v4, v4, v5
	v_fmamk_f32 v4, v4, 0x3c000000, v254
	s_nop 0
	s_nop 0
	s_nop 0
	s_nop 1
	s_nop 1
	s_nop 0
	v_rsq_f32_e32 v14, v4
	s_nop 0
	v_mul_f32_e32 v5, v12, v14
	v_mul_f32_e32 v12, v13, v14
	v_mul_f32_e32 v5, v7, v5
	v_mul_f32_e32 v12, v9, v12
	v_add_u32_e32 v4, 0x3000, v2
	v_cvt_pk_bf16_f32 v12, v5, v12
	v_mov_b32_e32 v5, v3
	v_lshl_add_u64 v[4:5], v[4:5], 1, s[6:7]
	global_store_short v[4:5], v12, off
	v_add_u32_e32 v4, 0x3020, v2
	v_mov_b32_e32 v5, v3
	v_lshl_add_u64 v[4:5], v[4:5], 1, s[6:7]
	global_store_short_d16_hi v[4:5], v12, off
	v_mul_f32_e32 v4, v15, v14
	v_mul_f32_e32 v5, v11, v14
	v_mul_f32_e32 v4, v6, v4
	v_mul_f32_e32 v5, v8, v5
	v_cvt_pk_bf16_f32 v11, v4, v5
	v_add_u32_e32 v4, 0x3040, v2
	v_mov_b32_e32 v5, v3
	v_lshl_add_u64 v[4:5], v[4:5], 1, s[6:7]
	global_store_short v[4:5], v11, off
	v_add_u32_e32 v4, 0x3060, v2
	v_mov_b32_e32 v5, v3
	v_lshl_add_u64 v[4:5], v[4:5], 1, s[6:7]
	global_store_short_d16_hi v[4:5], v11, off
	ds_read_b32 v11, v10 offset:32
	ds_read2st64_b32 v[4:5], v1 offset0:4 offset1:20
	s_waitcnt lgkmcnt(0)
	v_fma_f32 v12, v72, v11, -v4
	v_fma_f32 v13, v88, v11, -v5
	ds_read2st64_b32 v[4:5], v1 offset0:36 offset1:52
	v_mul_f32_e32 v14, v13, v13
	v_fmac_f32_e32 v14, v12, v12
	s_waitcnt lgkmcnt(0)
	v_fma_f32 v15, v104, v11, -v4
	v_fmac_f32_e32 v14, v15, v15
	v_fma_f32 v11, v120, v11, -v5
	v_fmac_f32_e32 v14, v11, v11
	ds_swizzle_b32 v4, v14 offset:swizzle(SWAP,1)
	s_waitcnt lgkmcnt(0)
	v_add_f32_e32 v4, v14, v4
	ds_swizzle_b32 v5, v4 offset:swizzle(SWAP,2)
	s_waitcnt lgkmcnt(0)
	v_add_f32_e32 v4, v4, v5
	ds_swizzle_b32 v5, v4 offset:swizzle(SWAP,4)
	s_waitcnt lgkmcnt(0)
	v_add_f32_e32 v4, v4, v5
	ds_swizzle_b32 v5, v4 offset:swizzle(SWAP,8)
	s_waitcnt lgkmcnt(0)
	v_add_f32_e32 v4, v4, v5
	ds_swizzle_b32 v5, v4 offset:swizzle(SWAP,16)
	s_waitcnt lgkmcnt(0)
	v_add_f32_e32 v4, v4, v5
	v_fmamk_f32 v4, v4, 0x3c000000, v254
	s_nop 0
	s_nop 0
	s_nop 0
	s_nop 1
	s_nop 1
	s_nop 0
	v_rsq_f32_e32 v14, v4
	s_nop 0
	v_mul_f32_e32 v5, v12, v14
	v_mul_f32_e32 v12, v13, v14
	v_mul_f32_e32 v5, v7, v5
	v_mul_f32_e32 v12, v9, v12
	v_add_u32_e32 v4, 0x8000, v2
	v_cvt_pk_bf16_f32 v12, v5, v12
	v_mov_b32_e32 v5, v3
	v_lshl_add_u64 v[4:5], v[4:5], 1, s[6:7]
	global_store_short v[4:5], v12, off
	v_add_u32_e32 v4, 0x8020, v2
	v_mov_b32_e32 v5, v3
	v_lshl_add_u64 v[4:5], v[4:5], 1, s[6:7]
	global_store_short_d16_hi v[4:5], v12, off
	v_mul_f32_e32 v4, v15, v14
	v_mul_f32_e32 v5, v11, v14
	v_mul_f32_e32 v4, v6, v4
	v_mul_f32_e32 v5, v8, v5
	v_cvt_pk_bf16_f32 v11, v4, v5
	v_add_u32_e32 v4, 0x8040, v2
	v_mov_b32_e32 v5, v3
	v_lshl_add_u64 v[4:5], v[4:5], 1, s[6:7]
	global_store_short v[4:5], v11, off
	v_add_u32_e32 v4, 0x8060, v2
	v_mov_b32_e32 v5, v3
	v_lshl_add_u64 v[4:5], v[4:5], 1, s[6:7]
	global_store_short_d16_hi v[4:5], v11, off
	ds_read_b32 v11, v10 offset:36
	ds_read2st64_b32 v[4:5], v1 offset0:5 offset1:21
	s_waitcnt lgkmcnt(0)
	v_fma_f32 v12, v73, v11, -v4
	v_fma_f32 v13, v89, v11, -v5
	ds_read2st64_b32 v[4:5], v1 offset0:37 offset1:53
	v_mul_f32_e32 v14, v13, v13
	v_fmac_f32_e32 v14, v12, v12
	s_waitcnt lgkmcnt(0)
	v_fma_f32 v15, v105, v11, -v4
	v_fmac_f32_e32 v14, v15, v15
	v_fma_f32 v11, v121, v11, -v5
	v_fmac_f32_e32 v14, v11, v11
	ds_swizzle_b32 v4, v14 offset:swizzle(SWAP,1)
	s_waitcnt lgkmcnt(0)
	v_add_f32_e32 v4, v14, v4
	ds_swizzle_b32 v5, v4 offset:swizzle(SWAP,2)
	s_waitcnt lgkmcnt(0)
	v_add_f32_e32 v4, v4, v5
	ds_swizzle_b32 v5, v4 offset:swizzle(SWAP,4)
	s_waitcnt lgkmcnt(0)
	v_add_f32_e32 v4, v4, v5
	ds_swizzle_b32 v5, v4 offset:swizzle(SWAP,8)
	s_waitcnt lgkmcnt(0)
	v_add_f32_e32 v4, v4, v5
	ds_swizzle_b32 v5, v4 offset:swizzle(SWAP,16)
	s_waitcnt lgkmcnt(0)
	v_add_f32_e32 v4, v4, v5
	v_fmamk_f32 v4, v4, 0x3c000000, v254
	s_nop 0
	s_nop 0
	s_nop 0
	s_nop 1
	s_nop 1
	s_nop 0
	v_rsq_f32_e32 v14, v4
	s_nop 0
	v_mul_f32_e32 v5, v12, v14
	v_mul_f32_e32 v12, v13, v14
	v_mul_f32_e32 v5, v7, v5
	v_mul_f32_e32 v12, v9, v12
	v_add_u32_e32 v4, 0x9000, v2
	v_cvt_pk_bf16_f32 v12, v5, v12
	v_mov_b32_e32 v5, v3
	v_lshl_add_u64 v[4:5], v[4:5], 1, s[6:7]
	global_store_short v[4:5], v12, off
	v_add_u32_e32 v4, 0x9020, v2
	v_mov_b32_e32 v5, v3
	v_lshl_add_u64 v[4:5], v[4:5], 1, s[6:7]
	global_store_short_d16_hi v[4:5], v12, off
	v_mul_f32_e32 v4, v15, v14
	v_mul_f32_e32 v5, v11, v14
	v_mul_f32_e32 v4, v6, v4
	v_mul_f32_e32 v5, v8, v5
	v_cvt_pk_bf16_f32 v11, v4, v5
	v_add_u32_e32 v4, 0x9040, v2
	v_mov_b32_e32 v5, v3
	v_lshl_add_u64 v[4:5], v[4:5], 1, s[6:7]
	global_store_short v[4:5], v11, off
	v_add_u32_e32 v4, 0x9060, v2
	v_mov_b32_e32 v5, v3
	v_lshl_add_u64 v[4:5], v[4:5], 1, s[6:7]
	global_store_short_d16_hi v[4:5], v11, off
	ds_read_b32 v11, v10 offset:40
	ds_read2st64_b32 v[4:5], v1 offset0:6 offset1:22
	s_waitcnt lgkmcnt(0)
	v_fma_f32 v12, v74, v11, -v4
	v_fma_f32 v13, v90, v11, -v5
	ds_read2st64_b32 v[4:5], v1 offset0:38 offset1:54
	v_mul_f32_e32 v14, v13, v13
	v_fmac_f32_e32 v14, v12, v12
	s_waitcnt lgkmcnt(0)
	v_fma_f32 v15, v106, v11, -v4
	v_fmac_f32_e32 v14, v15, v15
	v_fma_f32 v11, v122, v11, -v5
	v_fmac_f32_e32 v14, v11, v11
	ds_swizzle_b32 v4, v14 offset:swizzle(SWAP,1)
	s_waitcnt lgkmcnt(0)
	v_add_f32_e32 v4, v14, v4
	ds_swizzle_b32 v5, v4 offset:swizzle(SWAP,2)
	s_waitcnt lgkmcnt(0)
	v_add_f32_e32 v4, v4, v5
	ds_swizzle_b32 v5, v4 offset:swizzle(SWAP,4)
	s_waitcnt lgkmcnt(0)
	v_add_f32_e32 v4, v4, v5
	ds_swizzle_b32 v5, v4 offset:swizzle(SWAP,8)
	s_waitcnt lgkmcnt(0)
	v_add_f32_e32 v4, v4, v5
	ds_swizzle_b32 v5, v4 offset:swizzle(SWAP,16)
	s_waitcnt lgkmcnt(0)
	v_add_f32_e32 v4, v4, v5
	v_fmamk_f32 v4, v4, 0x3c000000, v254
	s_nop 0
	s_nop 0
	s_nop 0
	s_nop 1
	s_nop 1
	s_nop 0
	v_rsq_f32_e32 v14, v4
	s_nop 0
	v_mul_f32_e32 v5, v12, v14
	v_mul_f32_e32 v12, v13, v14
	v_mul_f32_e32 v5, v7, v5
	v_mul_f32_e32 v12, v9, v12
	v_add_u32_e32 v4, 0xa000, v2
	v_cvt_pk_bf16_f32 v12, v5, v12
	v_mov_b32_e32 v5, v3
	v_lshl_add_u64 v[4:5], v[4:5], 1, s[6:7]
	global_store_short v[4:5], v12, off
	v_add_u32_e32 v4, 0xa020, v2
	v_mov_b32_e32 v5, v3
	v_lshl_add_u64 v[4:5], v[4:5], 1, s[6:7]
	global_store_short_d16_hi v[4:5], v12, off
	v_mul_f32_e32 v4, v15, v14
	v_mul_f32_e32 v5, v11, v14
	v_mul_f32_e32 v4, v6, v4
	v_mul_f32_e32 v5, v8, v5
	v_cvt_pk_bf16_f32 v11, v4, v5
	v_add_u32_e32 v4, 0xa040, v2
	v_mov_b32_e32 v5, v3
	v_lshl_add_u64 v[4:5], v[4:5], 1, s[6:7]
	global_store_short v[4:5], v11, off
	v_add_u32_e32 v4, 0xa060, v2
	v_mov_b32_e32 v5, v3
	v_lshl_add_u64 v[4:5], v[4:5], 1, s[6:7]
	global_store_short_d16_hi v[4:5], v11, off
	ds_read_b32 v11, v10 offset:44
	ds_read2st64_b32 v[4:5], v1 offset0:7 offset1:23
	s_waitcnt lgkmcnt(0)
	v_fma_f32 v12, v75, v11, -v4
	v_fma_f32 v13, v91, v11, -v5
	ds_read2st64_b32 v[4:5], v1 offset0:39 offset1:55
	v_mul_f32_e32 v14, v13, v13
	v_fmac_f32_e32 v14, v12, v12
	s_waitcnt lgkmcnt(0)
	v_fma_f32 v15, v107, v11, -v4
	v_fmac_f32_e32 v14, v15, v15
	v_fma_f32 v11, v123, v11, -v5
	v_fmac_f32_e32 v14, v11, v11
	ds_swizzle_b32 v4, v14 offset:swizzle(SWAP,1)
	s_waitcnt lgkmcnt(0)
	v_add_f32_e32 v4, v14, v4
	ds_swizzle_b32 v5, v4 offset:swizzle(SWAP,2)
	s_waitcnt lgkmcnt(0)
	v_add_f32_e32 v4, v4, v5
	ds_swizzle_b32 v5, v4 offset:swizzle(SWAP,4)
	s_waitcnt lgkmcnt(0)
	v_add_f32_e32 v4, v4, v5
	ds_swizzle_b32 v5, v4 offset:swizzle(SWAP,8)
	s_waitcnt lgkmcnt(0)
	v_add_f32_e32 v4, v4, v5
	ds_swizzle_b32 v5, v4 offset:swizzle(SWAP,16)
	s_waitcnt lgkmcnt(0)
	v_add_f32_e32 v4, v4, v5
	v_fmamk_f32 v4, v4, 0x3c000000, v254
	s_nop 0
	s_nop 0
	s_nop 0
	s_nop 1
	s_nop 1
	s_nop 0
	v_rsq_f32_e32 v14, v4
	s_nop 0
	v_mul_f32_e32 v5, v12, v14
	v_mul_f32_e32 v12, v13, v14
	v_mul_f32_e32 v5, v7, v5
	v_mul_f32_e32 v12, v9, v12
	v_add_u32_e32 v4, 0xb000, v2
	v_cvt_pk_bf16_f32 v12, v5, v12
	v_mov_b32_e32 v5, v3
	v_lshl_add_u64 v[4:5], v[4:5], 1, s[6:7]
	global_store_short v[4:5], v12, off
	v_add_u32_e32 v4, 0xb020, v2
	v_mov_b32_e32 v5, v3
	v_lshl_add_u64 v[4:5], v[4:5], 1, s[6:7]
	global_store_short_d16_hi v[4:5], v12, off
	v_mul_f32_e32 v4, v15, v14
	v_mul_f32_e32 v5, v11, v14
	v_mul_f32_e32 v4, v6, v4
	v_mul_f32_e32 v5, v8, v5
	v_cvt_pk_bf16_f32 v11, v4, v5
	v_add_u32_e32 v4, 0xb040, v2
	v_mov_b32_e32 v5, v3
	v_lshl_add_u64 v[4:5], v[4:5], 1, s[6:7]
	global_store_short v[4:5], v11, off
	v_add_u32_e32 v4, 0xb060, v2
	v_mov_b32_e32 v5, v3
	v_lshl_add_u64 v[4:5], v[4:5], 1, s[6:7]
	global_store_short_d16_hi v[4:5], v11, off
	ds_read_b32 v11, v10 offset:64
	ds_read2st64_b32 v[4:5], v1 offset0:8 offset1:24
	s_waitcnt lgkmcnt(0)
	v_fma_f32 v12, v76, v11, -v4
	v_fma_f32 v13, v92, v11, -v5
	ds_read2st64_b32 v[4:5], v1 offset0:40 offset1:56
	v_mul_f32_e32 v14, v13, v13
	v_fmac_f32_e32 v14, v12, v12
	s_waitcnt lgkmcnt(0)
	v_fma_f32 v15, v108, v11, -v4
	v_fmac_f32_e32 v14, v15, v15
	v_fma_f32 v11, v124, v11, -v5
	v_fmac_f32_e32 v14, v11, v11
	ds_swizzle_b32 v4, v14 offset:swizzle(SWAP,1)
	s_waitcnt lgkmcnt(0)
	v_add_f32_e32 v4, v14, v4
	ds_swizzle_b32 v5, v4 offset:swizzle(SWAP,2)
	s_waitcnt lgkmcnt(0)
	v_add_f32_e32 v4, v4, v5
	ds_swizzle_b32 v5, v4 offset:swizzle(SWAP,4)
	s_waitcnt lgkmcnt(0)
	v_add_f32_e32 v4, v4, v5
	ds_swizzle_b32 v5, v4 offset:swizzle(SWAP,8)
	s_waitcnt lgkmcnt(0)
	v_add_f32_e32 v4, v4, v5
	ds_swizzle_b32 v5, v4 offset:swizzle(SWAP,16)
	s_waitcnt lgkmcnt(0)
	v_add_f32_e32 v4, v4, v5
	v_fmamk_f32 v4, v4, 0x3c000000, v254
	s_nop 0
	s_nop 0
	s_nop 0
	s_nop 1
	s_nop 1
	s_nop 0
	v_rsq_f32_e32 v14, v4
	s_nop 0
	v_mul_f32_e32 v5, v12, v14
	v_mul_f32_e32 v12, v13, v14
	v_mul_f32_e32 v5, v7, v5
	v_mul_f32_e32 v12, v9, v12
	v_add_u32_e32 v4, 0x10000, v2
	v_cvt_pk_bf16_f32 v12, v5, v12
	v_mov_b32_e32 v5, v3
	v_lshl_add_u64 v[4:5], v[4:5], 1, s[6:7]
	global_store_short v[4:5], v12, off
	v_add_u32_e32 v4, 0x10020, v2
	v_mov_b32_e32 v5, v3
	v_lshl_add_u64 v[4:5], v[4:5], 1, s[6:7]
	global_store_short_d16_hi v[4:5], v12, off
	v_mul_f32_e32 v4, v15, v14
	v_mul_f32_e32 v5, v11, v14
	v_mul_f32_e32 v4, v6, v4
	v_mul_f32_e32 v5, v8, v5
	v_cvt_pk_bf16_f32 v11, v4, v5
	v_add_u32_e32 v4, 0x10040, v2
	v_mov_b32_e32 v5, v3
	v_lshl_add_u64 v[4:5], v[4:5], 1, s[6:7]
	global_store_short v[4:5], v11, off
	v_add_u32_e32 v4, 0x10060, v2
	v_mov_b32_e32 v5, v3
	v_lshl_add_u64 v[4:5], v[4:5], 1, s[6:7]
	global_store_short_d16_hi v[4:5], v11, off
	ds_read_b32 v11, v10 offset:68
	ds_read2st64_b32 v[4:5], v1 offset0:9 offset1:25
	s_waitcnt lgkmcnt(0)
	v_fma_f32 v12, v77, v11, -v4
	v_fma_f32 v13, v93, v11, -v5
	ds_read2st64_b32 v[4:5], v1 offset0:41 offset1:57
	v_mul_f32_e32 v14, v13, v13
	v_fmac_f32_e32 v14, v12, v12
	s_waitcnt lgkmcnt(0)
	v_fma_f32 v15, v109, v11, -v4
	v_fmac_f32_e32 v14, v15, v15
	v_fma_f32 v11, v125, v11, -v5
	v_fmac_f32_e32 v14, v11, v11
	ds_swizzle_b32 v4, v14 offset:swizzle(SWAP,1)
	s_waitcnt lgkmcnt(0)
	v_add_f32_e32 v4, v14, v4
	ds_swizzle_b32 v5, v4 offset:swizzle(SWAP,2)
	s_waitcnt lgkmcnt(0)
	v_add_f32_e32 v4, v4, v5
	ds_swizzle_b32 v5, v4 offset:swizzle(SWAP,4)
	s_waitcnt lgkmcnt(0)
	v_add_f32_e32 v4, v4, v5
	ds_swizzle_b32 v5, v4 offset:swizzle(SWAP,8)
	s_waitcnt lgkmcnt(0)
	v_add_f32_e32 v4, v4, v5
	ds_swizzle_b32 v5, v4 offset:swizzle(SWAP,16)
	s_waitcnt lgkmcnt(0)
	v_add_f32_e32 v4, v4, v5
	v_fmamk_f32 v4, v4, 0x3c000000, v254
	s_nop 0
	s_nop 0
	s_nop 0
	s_nop 1
	s_nop 1
	s_nop 0
	v_rsq_f32_e32 v14, v4
	s_nop 0
	v_mul_f32_e32 v5, v12, v14
	v_mul_f32_e32 v12, v13, v14
	v_mul_f32_e32 v5, v7, v5
	v_mul_f32_e32 v12, v9, v12
	v_add_u32_e32 v4, 0x11000, v2
	v_cvt_pk_bf16_f32 v12, v5, v12
	v_mov_b32_e32 v5, v3
	v_lshl_add_u64 v[4:5], v[4:5], 1, s[6:7]
	global_store_short v[4:5], v12, off
	v_add_u32_e32 v4, 0x11020, v2
	v_mov_b32_e32 v5, v3
	v_lshl_add_u64 v[4:5], v[4:5], 1, s[6:7]
	global_store_short_d16_hi v[4:5], v12, off
	v_mul_f32_e32 v4, v15, v14
	v_mul_f32_e32 v5, v11, v14
	v_mul_f32_e32 v4, v6, v4
	v_mul_f32_e32 v5, v8, v5
	v_cvt_pk_bf16_f32 v11, v4, v5
	v_add_u32_e32 v4, 0x11040, v2
	v_mov_b32_e32 v5, v3
	v_lshl_add_u64 v[4:5], v[4:5], 1, s[6:7]
	global_store_short v[4:5], v11, off
	v_add_u32_e32 v4, 0x11060, v2
	v_mov_b32_e32 v5, v3
	v_lshl_add_u64 v[4:5], v[4:5], 1, s[6:7]
	global_store_short_d16_hi v[4:5], v11, off
	ds_read_b32 v11, v10 offset:72
	ds_read2st64_b32 v[4:5], v1 offset0:10 offset1:26
	s_waitcnt lgkmcnt(0)
	v_fma_f32 v12, v78, v11, -v4
	v_fma_f32 v13, v94, v11, -v5
	ds_read2st64_b32 v[4:5], v1 offset0:42 offset1:58
	v_mul_f32_e32 v14, v13, v13
	v_fmac_f32_e32 v14, v12, v12
	s_waitcnt lgkmcnt(0)
	v_fma_f32 v15, v110, v11, -v4
	v_fmac_f32_e32 v14, v15, v15
	v_fma_f32 v11, v126, v11, -v5
	v_fmac_f32_e32 v14, v11, v11
	ds_swizzle_b32 v4, v14 offset:swizzle(SWAP,1)
	s_waitcnt lgkmcnt(0)
	v_add_f32_e32 v4, v14, v4
	ds_swizzle_b32 v5, v4 offset:swizzle(SWAP,2)
	s_waitcnt lgkmcnt(0)
	v_add_f32_e32 v4, v4, v5
	ds_swizzle_b32 v5, v4 offset:swizzle(SWAP,4)
	s_waitcnt lgkmcnt(0)
	v_add_f32_e32 v4, v4, v5
	ds_swizzle_b32 v5, v4 offset:swizzle(SWAP,8)
	s_waitcnt lgkmcnt(0)
	v_add_f32_e32 v4, v4, v5
	ds_swizzle_b32 v5, v4 offset:swizzle(SWAP,16)
	s_waitcnt lgkmcnt(0)
	v_add_f32_e32 v4, v4, v5
	v_fmamk_f32 v4, v4, 0x3c000000, v254
	s_nop 0
	s_nop 0
	s_nop 0
	s_nop 1
	s_nop 1
	s_nop 0
	v_rsq_f32_e32 v14, v4
	s_nop 0
	v_mul_f32_e32 v5, v12, v14
	v_mul_f32_e32 v12, v13, v14
	v_mul_f32_e32 v5, v7, v5
	v_mul_f32_e32 v12, v9, v12
	v_add_u32_e32 v4, 0x12000, v2
	v_cvt_pk_bf16_f32 v12, v5, v12
	v_mov_b32_e32 v5, v3
	v_lshl_add_u64 v[4:5], v[4:5], 1, s[6:7]
	global_store_short v[4:5], v12, off
	v_add_u32_e32 v4, 0x12020, v2
	v_mov_b32_e32 v5, v3
	v_lshl_add_u64 v[4:5], v[4:5], 1, s[6:7]
	global_store_short_d16_hi v[4:5], v12, off
	v_mul_f32_e32 v4, v15, v14
	v_mul_f32_e32 v5, v11, v14
	v_mul_f32_e32 v4, v6, v4
	v_mul_f32_e32 v5, v8, v5
	v_cvt_pk_bf16_f32 v11, v4, v5
	v_add_u32_e32 v4, 0x12040, v2
	v_mov_b32_e32 v5, v3
	v_lshl_add_u64 v[4:5], v[4:5], 1, s[6:7]
	global_store_short v[4:5], v11, off
	v_add_u32_e32 v4, 0x12060, v2
	v_mov_b32_e32 v5, v3
	v_lshl_add_u64 v[4:5], v[4:5], 1, s[6:7]
	global_store_short_d16_hi v[4:5], v11, off
	ds_read_b32 v11, v10 offset:76
	ds_read2st64_b32 v[4:5], v1 offset0:11 offset1:27
	s_waitcnt lgkmcnt(0)
	v_fma_f32 v12, v79, v11, -v4
	v_fma_f32 v13, v95, v11, -v5
	ds_read2st64_b32 v[4:5], v1 offset0:43 offset1:59
	v_mul_f32_e32 v14, v13, v13
	v_fmac_f32_e32 v14, v12, v12
	s_waitcnt lgkmcnt(0)
	v_fma_f32 v15, v111, v11, -v4
	v_fmac_f32_e32 v14, v15, v15
	v_fma_f32 v11, v127, v11, -v5
	v_fmac_f32_e32 v14, v11, v11
	ds_swizzle_b32 v4, v14 offset:swizzle(SWAP,1)
	s_waitcnt lgkmcnt(0)
	v_add_f32_e32 v4, v14, v4
	ds_swizzle_b32 v5, v4 offset:swizzle(SWAP,2)
	s_waitcnt lgkmcnt(0)
	v_add_f32_e32 v4, v4, v5
	ds_swizzle_b32 v5, v4 offset:swizzle(SWAP,4)
	s_waitcnt lgkmcnt(0)
	v_add_f32_e32 v4, v4, v5
	ds_swizzle_b32 v5, v4 offset:swizzle(SWAP,8)
	s_waitcnt lgkmcnt(0)
	v_add_f32_e32 v4, v4, v5
	ds_swizzle_b32 v5, v4 offset:swizzle(SWAP,16)
	s_waitcnt lgkmcnt(0)
	v_add_f32_e32 v4, v4, v5
	v_fmamk_f32 v4, v4, 0x3c000000, v254
	s_nop 0
	s_nop 0
	s_nop 0
	s_nop 1
	s_nop 1
	s_nop 0
	v_rsq_f32_e32 v14, v4
	s_nop 0
	v_mul_f32_e32 v5, v12, v14
	v_mul_f32_e32 v12, v13, v14
	v_mul_f32_e32 v5, v7, v5
	v_mul_f32_e32 v12, v9, v12
	v_add_u32_e32 v4, 0x13000, v2
	v_cvt_pk_bf16_f32 v12, v5, v12
	v_mov_b32_e32 v5, v3
	v_lshl_add_u64 v[4:5], v[4:5], 1, s[6:7]
	global_store_short v[4:5], v12, off
	v_add_u32_e32 v4, 0x13020, v2
	v_mov_b32_e32 v5, v3
	v_lshl_add_u64 v[4:5], v[4:5], 1, s[6:7]
	global_store_short_d16_hi v[4:5], v12, off
	v_mul_f32_e32 v4, v15, v14
	v_mul_f32_e32 v5, v11, v14
	v_mul_f32_e32 v4, v6, v4
	v_mul_f32_e32 v5, v8, v5
	v_cvt_pk_bf16_f32 v11, v4, v5
	v_add_u32_e32 v4, 0x13040, v2
	v_mov_b32_e32 v5, v3
	v_lshl_add_u64 v[4:5], v[4:5], 1, s[6:7]
	global_store_short v[4:5], v11, off
	v_add_u32_e32 v4, 0x13060, v2
	v_mov_b32_e32 v5, v3
	v_lshl_add_u64 v[4:5], v[4:5], 1, s[6:7]
	global_store_short_d16_hi v[4:5], v11, off
	ds_read_b32 v11, v10 offset:96
	ds_read2st64_b32 v[4:5], v1 offset0:12 offset1:28
	s_waitcnt lgkmcnt(0)
	v_fma_f32 v12, v80, v11, -v4
	v_fma_f32 v13, v96, v11, -v5
	ds_read2st64_b32 v[4:5], v1 offset0:44 offset1:60
	v_mul_f32_e32 v14, v13, v13
	v_fmac_f32_e32 v14, v12, v12
	s_waitcnt lgkmcnt(0)
	v_fma_f32 v15, v112, v11, -v4
	v_fmac_f32_e32 v14, v15, v15
	v_fma_f32 v11, v128, v11, -v5
	v_fmac_f32_e32 v14, v11, v11
	ds_swizzle_b32 v4, v14 offset:swizzle(SWAP,1)
	s_waitcnt lgkmcnt(0)
	v_add_f32_e32 v4, v14, v4
	ds_swizzle_b32 v5, v4 offset:swizzle(SWAP,2)
	s_waitcnt lgkmcnt(0)
	v_add_f32_e32 v4, v4, v5
	ds_swizzle_b32 v5, v4 offset:swizzle(SWAP,4)
	s_waitcnt lgkmcnt(0)
	v_add_f32_e32 v4, v4, v5
	ds_swizzle_b32 v5, v4 offset:swizzle(SWAP,8)
	s_waitcnt lgkmcnt(0)
	v_add_f32_e32 v4, v4, v5
	ds_swizzle_b32 v5, v4 offset:swizzle(SWAP,16)
	s_waitcnt lgkmcnt(0)
	v_add_f32_e32 v4, v4, v5
	v_fmamk_f32 v4, v4, 0x3c000000, v254
	s_nop 0
	s_nop 0
	s_nop 0
	s_nop 1
	s_nop 1
	s_nop 0
	v_rsq_f32_e32 v14, v4
	s_nop 0
	v_mul_f32_e32 v5, v12, v14
	v_mul_f32_e32 v12, v13, v14
	v_mul_f32_e32 v5, v7, v5
	v_mul_f32_e32 v12, v9, v12
	v_add_u32_e32 v4, 0x18000, v2
	v_cvt_pk_bf16_f32 v12, v5, v12
	v_mov_b32_e32 v5, v3
	v_lshl_add_u64 v[4:5], v[4:5], 1, s[6:7]
	global_store_short v[4:5], v12, off
	v_add_u32_e32 v4, 0x18020, v2
	v_mov_b32_e32 v5, v3
	v_lshl_add_u64 v[4:5], v[4:5], 1, s[6:7]
	global_store_short_d16_hi v[4:5], v12, off
	v_mul_f32_e32 v4, v15, v14
	v_mul_f32_e32 v5, v11, v14
	v_mul_f32_e32 v4, v6, v4
	v_mul_f32_e32 v5, v8, v5
	v_cvt_pk_bf16_f32 v11, v4, v5
	v_add_u32_e32 v4, 0x18040, v2
	v_mov_b32_e32 v5, v3
	v_lshl_add_u64 v[4:5], v[4:5], 1, s[6:7]
	global_store_short v[4:5], v11, off
	v_add_u32_e32 v4, 0x18060, v2
	v_mov_b32_e32 v5, v3
	v_lshl_add_u64 v[4:5], v[4:5], 1, s[6:7]
	global_store_short_d16_hi v[4:5], v11, off
	ds_read_b32 v11, v10 offset:100
	ds_read2st64_b32 v[4:5], v1 offset0:13 offset1:29
	s_waitcnt lgkmcnt(0)
	v_fma_f32 v12, v81, v11, -v4
	v_fma_f32 v13, v97, v11, -v5
	ds_read2st64_b32 v[4:5], v1 offset0:45 offset1:61
	v_mul_f32_e32 v14, v13, v13
	v_fmac_f32_e32 v14, v12, v12
	s_waitcnt lgkmcnt(0)
	v_fma_f32 v15, v113, v11, -v4
	v_fmac_f32_e32 v14, v15, v15
	v_fma_f32 v11, v129, v11, -v5
	v_fmac_f32_e32 v14, v11, v11
	ds_swizzle_b32 v4, v14 offset:swizzle(SWAP,1)
	s_waitcnt lgkmcnt(0)
	v_add_f32_e32 v4, v14, v4
	ds_swizzle_b32 v5, v4 offset:swizzle(SWAP,2)
	s_waitcnt lgkmcnt(0)
	v_add_f32_e32 v4, v4, v5
	ds_swizzle_b32 v5, v4 offset:swizzle(SWAP,4)
	s_waitcnt lgkmcnt(0)
	v_add_f32_e32 v4, v4, v5
	ds_swizzle_b32 v5, v4 offset:swizzle(SWAP,8)
	s_waitcnt lgkmcnt(0)
	v_add_f32_e32 v4, v4, v5
	ds_swizzle_b32 v5, v4 offset:swizzle(SWAP,16)
	s_waitcnt lgkmcnt(0)
	v_add_f32_e32 v4, v4, v5
	v_fmamk_f32 v4, v4, 0x3c000000, v254
	s_nop 0
	s_nop 0
	s_nop 0
	s_nop 1
	s_nop 1
	s_nop 0
	v_rsq_f32_e32 v14, v4
	s_nop 0
	v_mul_f32_e32 v5, v12, v14
	v_mul_f32_e32 v12, v13, v14
	v_mul_f32_e32 v5, v7, v5
	v_mul_f32_e32 v12, v9, v12
	v_add_u32_e32 v4, 0x19000, v2
	v_cvt_pk_bf16_f32 v12, v5, v12
	v_mov_b32_e32 v5, v3
	v_lshl_add_u64 v[4:5], v[4:5], 1, s[6:7]
	global_store_short v[4:5], v12, off
	v_add_u32_e32 v4, 0x19020, v2
	v_mov_b32_e32 v5, v3
	v_lshl_add_u64 v[4:5], v[4:5], 1, s[6:7]
	global_store_short_d16_hi v[4:5], v12, off
	v_mul_f32_e32 v4, v15, v14
	v_mul_f32_e32 v5, v11, v14
	v_mul_f32_e32 v4, v6, v4
	v_mul_f32_e32 v5, v8, v5
	v_cvt_pk_bf16_f32 v11, v4, v5
	v_add_u32_e32 v4, 0x19040, v2
	v_mov_b32_e32 v5, v3
	v_lshl_add_u64 v[4:5], v[4:5], 1, s[6:7]
	global_store_short v[4:5], v11, off
	v_add_u32_e32 v4, 0x19060, v2
	v_mov_b32_e32 v5, v3
	v_lshl_add_u64 v[4:5], v[4:5], 1, s[6:7]
	global_store_short_d16_hi v[4:5], v11, off
	ds_read_b32 v11, v10 offset:104
	ds_read2st64_b32 v[4:5], v1 offset0:14 offset1:30
	s_waitcnt lgkmcnt(0)
	v_fma_f32 v12, v82, v11, -v4
	v_fma_f32 v13, v98, v11, -v5
	ds_read2st64_b32 v[4:5], v1 offset0:46 offset1:62
	v_mul_f32_e32 v14, v13, v13
	v_fmac_f32_e32 v14, v12, v12
	s_waitcnt lgkmcnt(0)
	v_fma_f32 v15, v114, v11, -v4
	v_fmac_f32_e32 v14, v15, v15
	v_fma_f32 v11, v130, v11, -v5
	v_fmac_f32_e32 v14, v11, v11
	ds_swizzle_b32 v4, v14 offset:swizzle(SWAP,1)
	s_waitcnt lgkmcnt(0)
	v_add_f32_e32 v4, v14, v4
	ds_swizzle_b32 v5, v4 offset:swizzle(SWAP,2)
	s_waitcnt lgkmcnt(0)
	v_add_f32_e32 v4, v4, v5
	ds_swizzle_b32 v5, v4 offset:swizzle(SWAP,4)
	s_waitcnt lgkmcnt(0)
	v_add_f32_e32 v4, v4, v5
	ds_swizzle_b32 v5, v4 offset:swizzle(SWAP,8)
	s_waitcnt lgkmcnt(0)
	v_add_f32_e32 v4, v4, v5
	ds_swizzle_b32 v5, v4 offset:swizzle(SWAP,16)
	s_waitcnt lgkmcnt(0)
	v_add_f32_e32 v4, v4, v5
	v_fmamk_f32 v4, v4, 0x3c000000, v254
	s_nop 0
	s_nop 0
	s_nop 0
	s_nop 1
	s_nop 1
	s_nop 0
	v_rsq_f32_e32 v14, v4
	s_nop 0
	v_mul_f32_e32 v5, v12, v14
	v_mul_f32_e32 v12, v13, v14
	v_mul_f32_e32 v5, v7, v5
	v_mul_f32_e32 v12, v9, v12
	v_add_u32_e32 v4, 0x1a000, v2
	v_cvt_pk_bf16_f32 v12, v5, v12
	v_mov_b32_e32 v5, v3
	v_lshl_add_u64 v[4:5], v[4:5], 1, s[6:7]
	global_store_short v[4:5], v12, off
	v_add_u32_e32 v4, 0x1a020, v2
	v_mov_b32_e32 v5, v3
	v_lshl_add_u64 v[4:5], v[4:5], 1, s[6:7]
	global_store_short_d16_hi v[4:5], v12, off
	v_mul_f32_e32 v4, v15, v14
	v_mul_f32_e32 v5, v11, v14
	v_mul_f32_e32 v4, v6, v4
	v_mul_f32_e32 v5, v8, v5
	v_cvt_pk_bf16_f32 v11, v4, v5
	v_add_u32_e32 v4, 0x1a040, v2
	v_mov_b32_e32 v5, v3
	v_lshl_add_u64 v[4:5], v[4:5], 1, s[6:7]
	global_store_short v[4:5], v11, off
	v_add_u32_e32 v4, 0x1a060, v2
	v_mov_b32_e32 v5, v3
	v_lshl_add_u64 v[4:5], v[4:5], 1, s[6:7]
	global_store_short_d16_hi v[4:5], v11, off
	ds_read_b32 v10, v10 offset:108
	ds_read2st64_b32 v[4:5], v1 offset0:15 offset1:31
	s_waitcnt lgkmcnt(0)
	v_fma_f32 v11, v83, v10, -v4
	v_fma_f32 v12, v99, v10, -v5
	ds_read2st64_b32 v[4:5], v1 offset0:47 offset1:63
	v_mul_f32_e32 v13, v12, v12
	v_fmac_f32_e32 v13, v11, v11
	s_waitcnt lgkmcnt(0)
	v_fma_f32 v1, v115, v10, -v4
	v_fmac_f32_e32 v13, v1, v1
	v_fma_f32 v10, v131, v10, -v5
	v_fmac_f32_e32 v13, v10, v10
	ds_swizzle_b32 v4, v13 offset:swizzle(SWAP,1)
	s_waitcnt lgkmcnt(0)
	v_add_f32_e32 v4, v13, v4
	ds_swizzle_b32 v5, v4 offset:swizzle(SWAP,2)
	s_waitcnt lgkmcnt(0)
	v_add_f32_e32 v4, v4, v5
	ds_swizzle_b32 v5, v4 offset:swizzle(SWAP,4)
	s_waitcnt lgkmcnt(0)
	v_add_f32_e32 v4, v4, v5
	ds_swizzle_b32 v5, v4 offset:swizzle(SWAP,8)
	s_waitcnt lgkmcnt(0)
	v_add_f32_e32 v4, v4, v5
	ds_swizzle_b32 v5, v4 offset:swizzle(SWAP,16)
	s_waitcnt lgkmcnt(0)
	v_add_f32_e32 v4, v4, v5
	v_fmamk_f32 v4, v4, 0x3c000000, v254
	s_nop 0
	s_nop 0
	s_nop 0
	s_nop 1
	s_nop 1
	s_nop 0
	v_rsq_f32_e32 v13, v4
	s_nop 0
	v_mul_f32_e32 v5, v11, v13
	v_mul_f32_e32 v5, v7, v5
	v_mul_f32_e32 v7, v12, v13
	v_mul_f32_e32 v7, v9, v7
	v_add_u32_e32 v4, 0x1b000, v2
	v_cvt_pk_bf16_f32 v7, v5, v7
	v_mov_b32_e32 v5, v3
	v_lshl_add_u64 v[4:5], v[4:5], 1, s[6:7]
	global_store_short v[4:5], v7, off
	v_add_u32_e32 v4, 0x1b020, v2
	v_mov_b32_e32 v5, v3
	v_lshl_add_u64 v[4:5], v[4:5], 1, s[6:7]
	global_store_short_d16_hi v[4:5], v7, off
	v_mul_f32_e32 v1, v1, v13
	v_mul_f32_e32 v4, v10, v13
	v_mul_f32_e32 v1, v6, v1
	v_mul_f32_e32 v4, v8, v4
	v_cvt_pk_bf16_f32 v1, v1, v4
	v_add_u32_e32 v4, 0x1b040, v2
	v_mov_b32_e32 v5, v3
	v_lshl_add_u64 v[4:5], v[4:5], 1, s[6:7]
	v_add_u32_e32 v2, 0x1b060, v2
	global_store_short v[4:5], v1, off
	v_lshl_add_u64 v[4:5], v[2:3], 1, s[6:7]
	global_store_short_d16_hi v[4:5], v1, off

.LBB0_1374:
	s_or_b64 exec, exec, s[4:5]
	s_waitcnt lgkmcnt(0)
	v_lshlrev_b32_e32 v4, 2, v158
	global_load_dword v248, v4, s[0:1]
	global_load_dword v249, v4, s[0:1] offset:128
	global_load_dword v250, v4, s[0:1] offset:256
	global_load_dword v251, v4, s[0:1] offset:384
	v_add_u32_e32 v9, s29, v148
	s_lshl_b64 s[4:5], s[24:25], 13
	s_add_u32 s6, s86, s4
	s_addc_u32 s7, s87, s5
	s_waitcnt vmcnt(0)
	v_mul_f32_e32 v6, v164, v248
	v_mul_f32_e32 v8, v164, v249
	v_mul_f32_e32 v2, v164, v250
	v_mul_f32_e32 v7, v164, v251
	v_lshl_or_b32 v4, v159, 14, v158
	ds_read_b32 v5, v9
	ds_read2st64_b32 v[10:11], v1 offset1:16
	s_waitcnt lgkmcnt(0)
	v_fma_f32 v12, v68, v5, -v10
	v_fma_f32 v13, v84, v5, -v11
	ds_read2st64_b32 v[10:11], v1 offset0:32 offset1:48
	v_mul_f32_e32 v14, v13, v13
	v_fmac_f32_e32 v14, v12, v12
	s_waitcnt lgkmcnt(0)
	v_fma_f32 v15, v100, v5, -v10
	v_fmac_f32_e32 v14, v15, v15
	v_fma_f32 v16, v116, v5, -v11
	v_fmac_f32_e32 v14, v16, v16
	ds_swizzle_b32 v5, v14 offset:swizzle(SWAP,1)
	s_waitcnt lgkmcnt(0)
	v_add_f32_e32 v5, v14, v5
	ds_swizzle_b32 v10, v5 offset:swizzle(SWAP,2)
	s_waitcnt lgkmcnt(0)
	v_add_f32_e32 v5, v5, v10
	ds_swizzle_b32 v10, v5 offset:swizzle(SWAP,4)
	s_waitcnt lgkmcnt(0)
	v_add_f32_e32 v5, v5, v10
	ds_swizzle_b32 v10, v5 offset:swizzle(SWAP,8)
	s_waitcnt lgkmcnt(0)
	v_add_f32_e32 v5, v5, v10
	ds_swizzle_b32 v10, v5 offset:swizzle(SWAP,16)
	s_waitcnt lgkmcnt(0)
	v_add_f32_e32 v5, v5, v10
	v_fmamk_f32 v5, v5, 0x3c000000, v254
	s_nop 0
	s_nop 0
	s_nop 0
	s_nop 1
	s_nop 1
	s_nop 0
	v_rsq_f32_e32 v14, v5
	s_nop 0
	v_mul_f32_e32 v5, v12, v14
	v_mul_f32_e32 v5, v6, v5
	v_mul_f32_e32 v10, v13, v14
	v_mul_f32_e32 v10, v8, v10
	v_cvt_pk_bf16_f32 v12, v5, v10
	v_mov_b32_e32 v5, v3
	v_lshl_add_u64 v[10:11], v[4:5], 1, s[6:7]
	global_store_short v[10:11], v12, off offset:768
	v_add_u32_e32 v10, 32, v4
	v_mov_b32_e32 v11, v3
	v_lshl_add_u64 v[10:11], v[10:11], 1, s[6:7]
	global_store_short_d16_hi v[10:11], v12, off offset:768
	v_mul_f32_e32 v5, v15, v14
	v_mul_f32_e32 v10, v16, v14
	v_mul_f32_e32 v5, v2, v5
	v_mul_f32_e32 v10, v7, v10
	v_cvt_pk_bf16_f32 v5, v5, v10
	v_add_u32_e32 v10, 64, v4
	v_mov_b32_e32 v11, v3
	v_lshl_add_u64 v[10:11], v[10:11], 1, s[6:7]
	global_store_short v[10:11], v5, off offset:768
	v_add_u32_e32 v10, 0x60, v4
	v_mov_b32_e32 v11, v3
	v_lshl_add_u64 v[10:11], v[10:11], 1, s[6:7]
	global_store_short_d16_hi v[10:11], v5, off offset:768
	ds_read_b32 v5, v9 offset:4
	ds_read2st64_b32 v[10:11], v1 offset0:1 offset1:17
	s_waitcnt lgkmcnt(0)
	v_fma_f32 v12, v69, v5, -v10
	v_fma_f32 v13, v85, v5, -v11
	ds_read2st64_b32 v[10:11], v1 offset0:33 offset1:49
	v_mul_f32_e32 v14, v13, v13
	v_fmac_f32_e32 v14, v12, v12
	s_waitcnt lgkmcnt(0)
	v_fma_f32 v15, v101, v5, -v10
	v_fmac_f32_e32 v14, v15, v15
	v_fma_f32 v5, v117, v5, -v11
	v_fmac_f32_e32 v14, v5, v5
	ds_swizzle_b32 v10, v14 offset:swizzle(SWAP,1)
	s_waitcnt lgkmcnt(0)
	v_add_f32_e32 v10, v14, v10
	ds_swizzle_b32 v11, v10 offset:swizzle(SWAP,2)
	s_waitcnt lgkmcnt(0)
	v_add_f32_e32 v10, v10, v11
	ds_swizzle_b32 v11, v10 offset:swizzle(SWAP,4)
	s_waitcnt lgkmcnt(0)
	v_add_f32_e32 v10, v10, v11
	ds_swizzle_b32 v11, v10 offset:swizzle(SWAP,8)
	s_waitcnt lgkmcnt(0)
	v_add_f32_e32 v10, v10, v11
	ds_swizzle_b32 v11, v10 offset:swizzle(SWAP,16)
	s_waitcnt lgkmcnt(0)
	v_add_f32_e32 v10, v10, v11
	v_fmamk_f32 v10, v10, 0x3c000000, v254
	s_nop 0
	s_nop 0
	s_nop 0
	s_nop 1
	s_nop 1
	s_nop 0
	v_rsq_f32_e32 v14, v10
	s_nop 0
	v_mul_f32_e32 v11, v12, v14
	v_mul_f32_e32 v12, v13, v14
	v_mul_f32_e32 v11, v6, v11
	v_mul_f32_e32 v12, v8, v12
	v_add_u32_e32 v10, 0x1000, v4
	v_cvt_pk_bf16_f32 v12, v11, v12
	v_mov_b32_e32 v11, v3
	v_lshl_add_u64 v[10:11], v[10:11], 1, s[6:7]
	global_store_short v[10:11], v12, off offset:768
	v_add_u32_e32 v10, 0x1020, v4
	v_mov_b32_e32 v11, v3
	v_lshl_add_u64 v[10:11], v[10:11], 1, s[6:7]
	global_store_short_d16_hi v[10:11], v12, off offset:768
	v_mul_f32_e32 v10, v15, v14
	v_mul_f32_e32 v5, v5, v14
	v_mul_f32_e32 v10, v2, v10
	v_mul_f32_e32 v5, v7, v5
	v_cvt_pk_bf16_f32 v5, v10, v5
	v_add_u32_e32 v10, 0x1040, v4
	v_mov_b32_e32 v11, v3
	v_lshl_add_u64 v[10:11], v[10:11], 1, s[6:7]
	global_store_short v[10:11], v5, off offset:768
	v_add_u32_e32 v10, 0x1060, v4
	v_mov_b32_e32 v11, v3
	v_lshl_add_u64 v[10:11], v[10:11], 1, s[6:7]
	global_store_short_d16_hi v[10:11], v5, off offset:768
	ds_read_b32 v5, v9 offset:8
	ds_read2st64_b32 v[10:11], v1 offset0:2 offset1:18
	s_waitcnt lgkmcnt(0)
	v_fma_f32 v12, v70, v5, -v10
	v_fma_f32 v13, v86, v5, -v11
	ds_read2st64_b32 v[10:11], v1 offset0:34 offset1:50
	v_mul_f32_e32 v14, v13, v13
	v_fmac_f32_e32 v14, v12, v12
	s_waitcnt lgkmcnt(0)
	v_fma_f32 v15, v102, v5, -v10
	v_fmac_f32_e32 v14, v15, v15
	v_fma_f32 v5, v118, v5, -v11
	v_fmac_f32_e32 v14, v5, v5
	ds_swizzle_b32 v10, v14 offset:swizzle(SWAP,1)
	s_waitcnt lgkmcnt(0)
	v_add_f32_e32 v10, v14, v10
	ds_swizzle_b32 v11, v10 offset:swizzle(SWAP,2)
	s_waitcnt lgkmcnt(0)
	v_add_f32_e32 v10, v10, v11
	ds_swizzle_b32 v11, v10 offset:swizzle(SWAP,4)
	s_waitcnt lgkmcnt(0)
	v_add_f32_e32 v10, v10, v11
	ds_swizzle_b32 v11, v10 offset:swizzle(SWAP,8)
	s_waitcnt lgkmcnt(0)
	v_add_f32_e32 v10, v10, v11
	ds_swizzle_b32 v11, v10 offset:swizzle(SWAP,16)
	s_waitcnt lgkmcnt(0)
	v_add_f32_e32 v10, v10, v11
	v_fmamk_f32 v10, v10, 0x3c000000, v254
	s_nop 0
	s_nop 0
	s_nop 0
	s_nop 1
	s_nop 1
	s_nop 0
	v_rsq_f32_e32 v14, v10
	s_nop 0
	v_mul_f32_e32 v11, v12, v14
	v_mul_f32_e32 v12, v13, v14
	v_mul_f32_e32 v11, v6, v11
	v_mul_f32_e32 v12, v8, v12
	v_add_u32_e32 v10, 0x2000, v4
	v_cvt_pk_bf16_f32 v12, v11, v12
	v_mov_b32_e32 v11, v3
	v_lshl_add_u64 v[10:11], v[10:11], 1, s[6:7]
	global_store_short v[10:11], v12, off offset:768
	v_add_u32_e32 v10, 0x2020, v4
	v_mov_b32_e32 v11, v3
	v_lshl_add_u64 v[10:11], v[10:11], 1, s[6:7]
	global_store_short_d16_hi v[10:11], v12, off offset:768
	v_mul_f32_e32 v10, v15, v14
	v_mul_f32_e32 v5, v5, v14
	v_mul_f32_e32 v10, v2, v10
	v_mul_f32_e32 v5, v7, v5
	v_cvt_pk_bf16_f32 v5, v10, v5
	v_add_u32_e32 v10, 0x2040, v4
	v_mov_b32_e32 v11, v3
	v_lshl_add_u64 v[10:11], v[10:11], 1, s[6:7]
	global_store_short v[10:11], v5, off offset:768
	v_add_u32_e32 v10, 0x2060, v4
	v_mov_b32_e32 v11, v3
	v_lshl_add_u64 v[10:11], v[10:11], 1, s[6:7]
	global_store_short_d16_hi v[10:11], v5, off offset:768
	ds_read_b32 v5, v9 offset:12
	ds_read2st64_b32 v[10:11], v1 offset0:3 offset1:19
	s_waitcnt lgkmcnt(0)
	v_fma_f32 v12, v71, v5, -v10
	v_fma_f32 v13, v87, v5, -v11
	ds_read2st64_b32 v[10:11], v1 offset0:35 offset1:51
	v_mul_f32_e32 v14, v13, v13
	v_fmac_f32_e32 v14, v12, v12
	s_waitcnt lgkmcnt(0)
	v_fma_f32 v15, v103, v5, -v10
	v_fmac_f32_e32 v14, v15, v15
	v_fma_f32 v5, v119, v5, -v11
	v_fmac_f32_e32 v14, v5, v5
	ds_swizzle_b32 v10, v14 offset:swizzle(SWAP,1)
	s_waitcnt lgkmcnt(0)
	v_add_f32_e32 v10, v14, v10
	ds_swizzle_b32 v11, v10 offset:swizzle(SWAP,2)
	s_waitcnt lgkmcnt(0)
	v_add_f32_e32 v10, v10, v11
	ds_swizzle_b32 v11, v10 offset:swizzle(SWAP,4)
	s_waitcnt lgkmcnt(0)
	v_add_f32_e32 v10, v10, v11
	ds_swizzle_b32 v11, v10 offset:swizzle(SWAP,8)
	s_waitcnt lgkmcnt(0)
	v_add_f32_e32 v10, v10, v11
	ds_swizzle_b32 v11, v10 offset:swizzle(SWAP,16)
	s_waitcnt lgkmcnt(0)
	v_add_f32_e32 v10, v10, v11
	v_fmamk_f32 v10, v10, 0x3c000000, v254
	s_nop 0
	s_nop 0
	s_nop 0
	s_nop 1
	s_nop 1
	s_nop 0
	v_rsq_f32_e32 v14, v10
	s_nop 0
	v_mul_f32_e32 v11, v12, v14
	v_mul_f32_e32 v12, v13, v14
	v_mul_f32_e32 v11, v6, v11
	v_mul_f32_e32 v12, v8, v12
	v_add_u32_e32 v10, 0x3000, v4
	v_cvt_pk_bf16_f32 v12, v11, v12
	v_mov_b32_e32 v11, v3
	v_lshl_add_u64 v[10:11], v[10:11], 1, s[6:7]
	global_store_short v[10:11], v12, off offset:768
	v_add_u32_e32 v10, 0x3020, v4
	v_mov_b32_e32 v11, v3
	v_lshl_add_u64 v[10:11], v[10:11], 1, s[6:7]
	global_store_short_d16_hi v[10:11], v12, off offset:768
	v_mul_f32_e32 v10, v15, v14
	v_mul_f32_e32 v5, v5, v14
	v_mul_f32_e32 v10, v2, v10
	v_mul_f32_e32 v5, v7, v5
	v_cvt_pk_bf16_f32 v5, v10, v5
	v_add_u32_e32 v10, 0x3040, v4
	v_mov_b32_e32 v11, v3
	v_lshl_add_u64 v[10:11], v[10:11], 1, s[6:7]
	global_store_short v[10:11], v5, off offset:768
	v_add_u32_e32 v10, 0x3060, v4
	v_mov_b32_e32 v11, v3
	v_lshl_add_u64 v[10:11], v[10:11], 1, s[6:7]
	global_store_short_d16_hi v[10:11], v5, off offset:768
	ds_read_b32 v5, v9 offset:32
	ds_read2st64_b32 v[10:11], v1 offset0:4 offset1:20
	s_waitcnt lgkmcnt(0)
	v_fma_f32 v12, v72, v5, -v10
	v_fma_f32 v13, v88, v5, -v11
	ds_read2st64_b32 v[10:11], v1 offset0:36 offset1:52
	v_mul_f32_e32 v14, v13, v13
	v_fmac_f32_e32 v14, v12, v12
	s_waitcnt lgkmcnt(0)
	v_fma_f32 v15, v104, v5, -v10
	v_fmac_f32_e32 v14, v15, v15
	v_fma_f32 v5, v120, v5, -v11
	v_fmac_f32_e32 v14, v5, v5
	ds_swizzle_b32 v10, v14 offset:swizzle(SWAP,1)
	s_waitcnt lgkmcnt(0)
	v_add_f32_e32 v10, v14, v10
	ds_swizzle_b32 v11, v10 offset:swizzle(SWAP,2)
	s_waitcnt lgkmcnt(0)
	v_add_f32_e32 v10, v10, v11
	ds_swizzle_b32 v11, v10 offset:swizzle(SWAP,4)
	s_waitcnt lgkmcnt(0)
	v_add_f32_e32 v10, v10, v11
	ds_swizzle_b32 v11, v10 offset:swizzle(SWAP,8)
	s_waitcnt lgkmcnt(0)
	v_add_f32_e32 v10, v10, v11
	ds_swizzle_b32 v11, v10 offset:swizzle(SWAP,16)
	s_waitcnt lgkmcnt(0)
	v_add_f32_e32 v10, v10, v11
	v_fmamk_f32 v10, v10, 0x3c000000, v254
	s_nop 0
	s_nop 0
	s_nop 0
	s_nop 1
	s_nop 1
	s_nop 0
	v_rsq_f32_e32 v14, v10
	s_nop 0
	v_mul_f32_e32 v11, v12, v14
	v_mul_f32_e32 v12, v13, v14
	v_mul_f32_e32 v11, v6, v11
	v_mul_f32_e32 v12, v8, v12
	v_add_u32_e32 v10, 0x8000, v4
	v_cvt_pk_bf16_f32 v12, v11, v12
	v_mov_b32_e32 v11, v3
	v_lshl_add_u64 v[10:11], v[10:11], 1, s[6:7]
	global_store_short v[10:11], v12, off offset:768
	v_add_u32_e32 v10, 0x8020, v4
	v_mov_b32_e32 v11, v3
	v_lshl_add_u64 v[10:11], v[10:11], 1, s[6:7]
	global_store_short_d16_hi v[10:11], v12, off offset:768
	v_mul_f32_e32 v10, v15, v14
	v_mul_f32_e32 v5, v5, v14
	v_mul_f32_e32 v10, v2, v10
	v_mul_f32_e32 v5, v7, v5
	v_cvt_pk_bf16_f32 v5, v10, v5
	v_add_u32_e32 v10, 0x8040, v4
	v_mov_b32_e32 v11, v3
	v_lshl_add_u64 v[10:11], v[10:11], 1, s[6:7]
	global_store_short v[10:11], v5, off offset:768
	v_add_u32_e32 v10, 0x8060, v4
	v_mov_b32_e32 v11, v3
	v_lshl_add_u64 v[10:11], v[10:11], 1, s[6:7]
	global_store_short_d16_hi v[10:11], v5, off offset:768
	ds_read_b32 v5, v9 offset:36
	ds_read2st64_b32 v[10:11], v1 offset0:5 offset1:21
	s_waitcnt lgkmcnt(0)
	v_fma_f32 v12, v73, v5, -v10
	v_fma_f32 v13, v89, v5, -v11
	ds_read2st64_b32 v[10:11], v1 offset0:37 offset1:53
	v_mul_f32_e32 v14, v13, v13
	v_fmac_f32_e32 v14, v12, v12
	s_waitcnt lgkmcnt(0)
	v_fma_f32 v15, v105, v5, -v10
	v_fmac_f32_e32 v14, v15, v15
	v_fma_f32 v5, v121, v5, -v11
	v_fmac_f32_e32 v14, v5, v5
	ds_swizzle_b32 v10, v14 offset:swizzle(SWAP,1)
	s_waitcnt lgkmcnt(0)
	v_add_f32_e32 v10, v14, v10
	ds_swizzle_b32 v11, v10 offset:swizzle(SWAP,2)
	s_waitcnt lgkmcnt(0)
	v_add_f32_e32 v10, v10, v11
	ds_swizzle_b32 v11, v10 offset:swizzle(SWAP,4)
	s_waitcnt lgkmcnt(0)
	v_add_f32_e32 v10, v10, v11
	ds_swizzle_b32 v11, v10 offset:swizzle(SWAP,8)
	s_waitcnt lgkmcnt(0)
	v_add_f32_e32 v10, v10, v11
	ds_swizzle_b32 v11, v10 offset:swizzle(SWAP,16)
	s_waitcnt lgkmcnt(0)
	v_add_f32_e32 v10, v10, v11
	v_fmamk_f32 v10, v10, 0x3c000000, v254
	s_nop 0
	s_nop 0
	s_nop 0
	s_nop 1
	s_nop 1
	s_nop 0
	v_rsq_f32_e32 v14, v10
	s_nop 0
	v_mul_f32_e32 v11, v12, v14
	v_mul_f32_e32 v12, v13, v14
	v_mul_f32_e32 v11, v6, v11
	v_mul_f32_e32 v12, v8, v12
	v_add_u32_e32 v10, 0x9000, v4
	v_cvt_pk_bf16_f32 v12, v11, v12
	v_mov_b32_e32 v11, v3
	v_lshl_add_u64 v[10:11], v[10:11], 1, s[6:7]
	global_store_short v[10:11], v12, off offset:768
	v_add_u32_e32 v10, 0x9020, v4
	v_mov_b32_e32 v11, v3
	v_lshl_add_u64 v[10:11], v[10:11], 1, s[6:7]
	global_store_short_d16_hi v[10:11], v12, off offset:768
	v_mul_f32_e32 v10, v15, v14
	v_mul_f32_e32 v5, v5, v14
	v_mul_f32_e32 v10, v2, v10
	v_mul_f32_e32 v5, v7, v5
	v_cvt_pk_bf16_f32 v5, v10, v5
	v_add_u32_e32 v10, 0x9040, v4
	v_mov_b32_e32 v11, v3
	v_lshl_add_u64 v[10:11], v[10:11], 1, s[6:7]
	global_store_short v[10:11], v5, off offset:768
	v_add_u32_e32 v10, 0x9060, v4
	v_mov_b32_e32 v11, v3
	v_lshl_add_u64 v[10:11], v[10:11], 1, s[6:7]
	global_store_short_d16_hi v[10:11], v5, off offset:768
	ds_read_b32 v5, v9 offset:40
	ds_read2st64_b32 v[10:11], v1 offset0:6 offset1:22
	s_waitcnt lgkmcnt(0)
	v_fma_f32 v12, v74, v5, -v10
	v_fma_f32 v13, v90, v5, -v11
	ds_read2st64_b32 v[10:11], v1 offset0:38 offset1:54
	v_mul_f32_e32 v14, v13, v13
	v_fmac_f32_e32 v14, v12, v12
	s_waitcnt lgkmcnt(0)
	v_fma_f32 v15, v106, v5, -v10
	v_fmac_f32_e32 v14, v15, v15
	v_fma_f32 v5, v122, v5, -v11
	v_fmac_f32_e32 v14, v5, v5
	ds_swizzle_b32 v10, v14 offset:swizzle(SWAP,1)
	s_waitcnt lgkmcnt(0)
	v_add_f32_e32 v10, v14, v10
	ds_swizzle_b32 v11, v10 offset:swizzle(SWAP,2)
	s_waitcnt lgkmcnt(0)
	v_add_f32_e32 v10, v10, v11
	ds_swizzle_b32 v11, v10 offset:swizzle(SWAP,4)
	s_waitcnt lgkmcnt(0)
	v_add_f32_e32 v10, v10, v11
	ds_swizzle_b32 v11, v10 offset:swizzle(SWAP,8)
	s_waitcnt lgkmcnt(0)
	v_add_f32_e32 v10, v10, v11
	ds_swizzle_b32 v11, v10 offset:swizzle(SWAP,16)
	s_waitcnt lgkmcnt(0)
	v_add_f32_e32 v10, v10, v11
	v_fmamk_f32 v10, v10, 0x3c000000, v254
	s_nop 0
	s_nop 0
	s_nop 0
	s_nop 1
	s_nop 1
	s_nop 0
	v_rsq_f32_e32 v14, v10
	s_nop 0
	v_mul_f32_e32 v11, v12, v14
	v_mul_f32_e32 v12, v13, v14
	v_mul_f32_e32 v11, v6, v11
	v_mul_f32_e32 v12, v8, v12
	v_add_u32_e32 v10, 0xa000, v4
	v_cvt_pk_bf16_f32 v12, v11, v12
	v_mov_b32_e32 v11, v3
	v_lshl_add_u64 v[10:11], v[10:11], 1, s[6:7]
	global_store_short v[10:11], v12, off offset:768
	v_add_u32_e32 v10, 0xa020, v4
	v_mov_b32_e32 v11, v3
	v_lshl_add_u64 v[10:11], v[10:11], 1, s[6:7]
	global_store_short_d16_hi v[10:11], v12, off offset:768
	v_mul_f32_e32 v10, v15, v14
	v_mul_f32_e32 v5, v5, v14
	v_mul_f32_e32 v10, v2, v10
	v_mul_f32_e32 v5, v7, v5
	v_cvt_pk_bf16_f32 v5, v10, v5
	v_add_u32_e32 v10, 0xa040, v4
	v_mov_b32_e32 v11, v3
	v_lshl_add_u64 v[10:11], v[10:11], 1, s[6:7]
	global_store_short v[10:11], v5, off offset:768
	v_add_u32_e32 v10, 0xa060, v4
	v_mov_b32_e32 v11, v3
	v_lshl_add_u64 v[10:11], v[10:11], 1, s[6:7]
	global_store_short_d16_hi v[10:11], v5, off offset:768
	ds_read_b32 v5, v9 offset:44
	ds_read2st64_b32 v[10:11], v1 offset0:7 offset1:23
	s_waitcnt lgkmcnt(0)
	v_fma_f32 v12, v75, v5, -v10
	v_fma_f32 v13, v91, v5, -v11
	ds_read2st64_b32 v[10:11], v1 offset0:39 offset1:55
	v_mul_f32_e32 v14, v13, v13
	v_fmac_f32_e32 v14, v12, v12
	s_waitcnt lgkmcnt(0)
	v_fma_f32 v15, v107, v5, -v10
	v_fmac_f32_e32 v14, v15, v15
	v_fma_f32 v5, v123, v5, -v11
	v_fmac_f32_e32 v14, v5, v5
	ds_swizzle_b32 v10, v14 offset:swizzle(SWAP,1)
	s_waitcnt lgkmcnt(0)
	v_add_f32_e32 v10, v14, v10
	ds_swizzle_b32 v11, v10 offset:swizzle(SWAP,2)
	s_waitcnt lgkmcnt(0)
	v_add_f32_e32 v10, v10, v11
	ds_swizzle_b32 v11, v10 offset:swizzle(SWAP,4)
	s_waitcnt lgkmcnt(0)
	v_add_f32_e32 v10, v10, v11
	ds_swizzle_b32 v11, v10 offset:swizzle(SWAP,8)
	s_waitcnt lgkmcnt(0)
	v_add_f32_e32 v10, v10, v11
	ds_swizzle_b32 v11, v10 offset:swizzle(SWAP,16)
	s_waitcnt lgkmcnt(0)
	v_add_f32_e32 v10, v10, v11
	v_fmamk_f32 v10, v10, 0x3c000000, v254
	s_nop 0
	s_nop 0
	s_nop 0
	s_nop 1
	s_nop 1
	s_nop 0
	v_rsq_f32_e32 v14, v10
	s_nop 0
	v_mul_f32_e32 v11, v12, v14
	v_mul_f32_e32 v12, v13, v14
	v_mul_f32_e32 v11, v6, v11
	v_mul_f32_e32 v12, v8, v12
	v_add_u32_e32 v10, 0xb000, v4
	v_cvt_pk_bf16_f32 v12, v11, v12
	v_mov_b32_e32 v11, v3
	v_lshl_add_u64 v[10:11], v[10:11], 1, s[6:7]
	global_store_short v[10:11], v12, off offset:768
	v_add_u32_e32 v10, 0xb020, v4
	v_mov_b32_e32 v11, v3
	v_lshl_add_u64 v[10:11], v[10:11], 1, s[6:7]
	global_store_short_d16_hi v[10:11], v12, off offset:768
	v_mul_f32_e32 v10, v15, v14
	v_mul_f32_e32 v5, v5, v14
	v_mul_f32_e32 v10, v2, v10
	v_mul_f32_e32 v5, v7, v5
	v_cvt_pk_bf16_f32 v5, v10, v5
	v_add_u32_e32 v10, 0xb040, v4
	v_mov_b32_e32 v11, v3
	v_lshl_add_u64 v[10:11], v[10:11], 1, s[6:7]
	global_store_short v[10:11], v5, off offset:768
	v_add_u32_e32 v10, 0xb060, v4
	v_mov_b32_e32 v11, v3
	v_lshl_add_u64 v[10:11], v[10:11], 1, s[6:7]
	global_store_short_d16_hi v[10:11], v5, off offset:768
	ds_read_b32 v5, v9 offset:64
	ds_read2st64_b32 v[10:11], v1 offset0:8 offset1:24
	s_waitcnt lgkmcnt(0)
	v_fma_f32 v12, v76, v5, -v10
	v_fma_f32 v13, v92, v5, -v11
	ds_read2st64_b32 v[10:11], v1 offset0:40 offset1:56
	v_mul_f32_e32 v14, v13, v13
	v_fmac_f32_e32 v14, v12, v12
	s_waitcnt lgkmcnt(0)
	v_fma_f32 v15, v108, v5, -v10
	v_fmac_f32_e32 v14, v15, v15
	v_fma_f32 v5, v124, v5, -v11
	v_fmac_f32_e32 v14, v5, v5
	ds_swizzle_b32 v10, v14 offset:swizzle(SWAP,1)
	s_waitcnt lgkmcnt(0)
	v_add_f32_e32 v10, v14, v10
	ds_swizzle_b32 v11, v10 offset:swizzle(SWAP,2)
	s_waitcnt lgkmcnt(0)
	v_add_f32_e32 v10, v10, v11
	ds_swizzle_b32 v11, v10 offset:swizzle(SWAP,4)
	s_waitcnt lgkmcnt(0)
	v_add_f32_e32 v10, v10, v11
	ds_swizzle_b32 v11, v10 offset:swizzle(SWAP,8)
	s_waitcnt lgkmcnt(0)
	v_add_f32_e32 v10, v10, v11
	ds_swizzle_b32 v11, v10 offset:swizzle(SWAP,16)
	s_waitcnt lgkmcnt(0)
	v_add_f32_e32 v10, v10, v11
	v_fmamk_f32 v10, v10, 0x3c000000, v254
	s_nop 0
	s_nop 0
	s_nop 0
	s_nop 1
	s_nop 1
	s_nop 0
	v_rsq_f32_e32 v14, v10
	s_nop 0
	v_mul_f32_e32 v11, v12, v14
	v_mul_f32_e32 v12, v13, v14
	v_mul_f32_e32 v11, v6, v11
	v_mul_f32_e32 v12, v8, v12
	v_add_u32_e32 v10, 0x10000, v4
	v_cvt_pk_bf16_f32 v12, v11, v12
	v_mov_b32_e32 v11, v3
	v_lshl_add_u64 v[10:11], v[10:11], 1, s[6:7]
	global_store_short v[10:11], v12, off offset:768
	v_add_u32_e32 v10, 0x10020, v4
	v_mov_b32_e32 v11, v3
	v_lshl_add_u64 v[10:11], v[10:11], 1, s[6:7]
	global_store_short_d16_hi v[10:11], v12, off offset:768
	v_mul_f32_e32 v10, v15, v14
	v_mul_f32_e32 v5, v5, v14
	v_mul_f32_e32 v10, v2, v10
	v_mul_f32_e32 v5, v7, v5
	v_cvt_pk_bf16_f32 v5, v10, v5
	v_add_u32_e32 v10, 0x10040, v4
	v_mov_b32_e32 v11, v3
	v_lshl_add_u64 v[10:11], v[10:11], 1, s[6:7]
	global_store_short v[10:11], v5, off offset:768
	v_add_u32_e32 v10, 0x10060, v4
	v_mov_b32_e32 v11, v3
	v_lshl_add_u64 v[10:11], v[10:11], 1, s[6:7]
	global_store_short_d16_hi v[10:11], v5, off offset:768
	ds_read_b32 v5, v9 offset:68
	ds_read2st64_b32 v[10:11], v1 offset0:9 offset1:25
	s_waitcnt lgkmcnt(0)
	v_fma_f32 v12, v77, v5, -v10
	v_fma_f32 v13, v93, v5, -v11
	ds_read2st64_b32 v[10:11], v1 offset0:41 offset1:57
	v_mul_f32_e32 v14, v13, v13
	v_fmac_f32_e32 v14, v12, v12
	s_waitcnt lgkmcnt(0)
	v_fma_f32 v15, v109, v5, -v10
	v_fmac_f32_e32 v14, v15, v15
	v_fma_f32 v5, v125, v5, -v11
	v_fmac_f32_e32 v14, v5, v5
	ds_swizzle_b32 v10, v14 offset:swizzle(SWAP,1)
	s_waitcnt lgkmcnt(0)
	v_add_f32_e32 v10, v14, v10
	ds_swizzle_b32 v11, v10 offset:swizzle(SWAP,2)
	s_waitcnt lgkmcnt(0)
	v_add_f32_e32 v10, v10, v11
	ds_swizzle_b32 v11, v10 offset:swizzle(SWAP,4)
	s_waitcnt lgkmcnt(0)
	v_add_f32_e32 v10, v10, v11
	ds_swizzle_b32 v11, v10 offset:swizzle(SWAP,8)
	s_waitcnt lgkmcnt(0)
	v_add_f32_e32 v10, v10, v11
	ds_swizzle_b32 v11, v10 offset:swizzle(SWAP,16)
	s_waitcnt lgkmcnt(0)
	v_add_f32_e32 v10, v10, v11
	v_fmamk_f32 v10, v10, 0x3c000000, v254
	s_nop 0
	s_nop 0
	s_nop 0
	s_nop 1
	s_nop 1
	s_nop 0
	v_rsq_f32_e32 v14, v10
	s_nop 0
	v_mul_f32_e32 v11, v12, v14
	v_mul_f32_e32 v12, v13, v14
	v_mul_f32_e32 v11, v6, v11
	v_mul_f32_e32 v12, v8, v12
	v_add_u32_e32 v10, 0x11000, v4
	v_cvt_pk_bf16_f32 v12, v11, v12
	v_mov_b32_e32 v11, v3
	v_lshl_add_u64 v[10:11], v[10:11], 1, s[6:7]
	global_store_short v[10:11], v12, off offset:768
	v_add_u32_e32 v10, 0x11020, v4
	v_mov_b32_e32 v11, v3
	v_lshl_add_u64 v[10:11], v[10:11], 1, s[6:7]
	global_store_short_d16_hi v[10:11], v12, off offset:768
	v_mul_f32_e32 v10, v15, v14
	v_mul_f32_e32 v5, v5, v14
	v_mul_f32_e32 v10, v2, v10
	v_mul_f32_e32 v5, v7, v5
	v_cvt_pk_bf16_f32 v5, v10, v5
	v_add_u32_e32 v10, 0x11040, v4
	v_mov_b32_e32 v11, v3
	v_lshl_add_u64 v[10:11], v[10:11], 1, s[6:7]
	global_store_short v[10:11], v5, off offset:768
	v_add_u32_e32 v10, 0x11060, v4
	v_mov_b32_e32 v11, v3
	v_lshl_add_u64 v[10:11], v[10:11], 1, s[6:7]
	global_store_short_d16_hi v[10:11], v5, off offset:768
	ds_read_b32 v5, v9 offset:72
	ds_read2st64_b32 v[10:11], v1 offset0:10 offset1:26
	s_waitcnt lgkmcnt(0)
	v_fma_f32 v12, v78, v5, -v10
	v_fma_f32 v13, v94, v5, -v11
	ds_read2st64_b32 v[10:11], v1 offset0:42 offset1:58
	v_mul_f32_e32 v14, v13, v13
	v_fmac_f32_e32 v14, v12, v12
	s_waitcnt lgkmcnt(0)
	v_fma_f32 v15, v110, v5, -v10
	v_fmac_f32_e32 v14, v15, v15
	v_fma_f32 v5, v126, v5, -v11
	v_fmac_f32_e32 v14, v5, v5
	ds_swizzle_b32 v10, v14 offset:swizzle(SWAP,1)
	s_waitcnt lgkmcnt(0)
	v_add_f32_e32 v10, v14, v10
	ds_swizzle_b32 v11, v10 offset:swizzle(SWAP,2)
	s_waitcnt lgkmcnt(0)
	v_add_f32_e32 v10, v10, v11
	ds_swizzle_b32 v11, v10 offset:swizzle(SWAP,4)
	s_waitcnt lgkmcnt(0)
	v_add_f32_e32 v10, v10, v11
	ds_swizzle_b32 v11, v10 offset:swizzle(SWAP,8)
	s_waitcnt lgkmcnt(0)
	v_add_f32_e32 v10, v10, v11
	ds_swizzle_b32 v11, v10 offset:swizzle(SWAP,16)
	s_waitcnt lgkmcnt(0)
	v_add_f32_e32 v10, v10, v11
	v_fmamk_f32 v10, v10, 0x3c000000, v254
	s_nop 0
	s_nop 0
	s_nop 0
	s_nop 1
	s_nop 1
	s_nop 0
	v_rsq_f32_e32 v14, v10
	s_nop 0
	v_mul_f32_e32 v11, v12, v14
	v_mul_f32_e32 v12, v13, v14
	v_mul_f32_e32 v11, v6, v11
	v_mul_f32_e32 v12, v8, v12
	v_add_u32_e32 v10, 0x12000, v4
	v_cvt_pk_bf16_f32 v12, v11, v12
	v_mov_b32_e32 v11, v3
	v_lshl_add_u64 v[10:11], v[10:11], 1, s[6:7]
	global_store_short v[10:11], v12, off offset:768
	v_add_u32_e32 v10, 0x12020, v4
	v_mov_b32_e32 v11, v3
	v_lshl_add_u64 v[10:11], v[10:11], 1, s[6:7]
	global_store_short_d16_hi v[10:11], v12, off offset:768
	v_mul_f32_e32 v10, v15, v14
	v_mul_f32_e32 v5, v5, v14
	v_mul_f32_e32 v10, v2, v10
	v_mul_f32_e32 v5, v7, v5
	v_cvt_pk_bf16_f32 v5, v10, v5
	v_add_u32_e32 v10, 0x12040, v4
	v_mov_b32_e32 v11, v3
	v_lshl_add_u64 v[10:11], v[10:11], 1, s[6:7]
	global_store_short v[10:11], v5, off offset:768
	v_add_u32_e32 v10, 0x12060, v4
	v_mov_b32_e32 v11, v3
	v_lshl_add_u64 v[10:11], v[10:11], 1, s[6:7]
	global_store_short_d16_hi v[10:11], v5, off offset:768
	ds_read_b32 v5, v9 offset:76
	ds_read2st64_b32 v[10:11], v1 offset0:11 offset1:27
	s_waitcnt lgkmcnt(0)
	v_fma_f32 v12, v79, v5, -v10
	v_fma_f32 v13, v95, v5, -v11
	ds_read2st64_b32 v[10:11], v1 offset0:43 offset1:59
	v_mul_f32_e32 v14, v13, v13
	v_fmac_f32_e32 v14, v12, v12
	s_waitcnt lgkmcnt(0)
	v_fma_f32 v15, v111, v5, -v10
	v_fmac_f32_e32 v14, v15, v15
	v_fma_f32 v5, v127, v5, -v11
	v_fmac_f32_e32 v14, v5, v5
	ds_swizzle_b32 v10, v14 offset:swizzle(SWAP,1)
	s_waitcnt lgkmcnt(0)
	v_add_f32_e32 v10, v14, v10
	ds_swizzle_b32 v11, v10 offset:swizzle(SWAP,2)
	s_waitcnt lgkmcnt(0)
	v_add_f32_e32 v10, v10, v11
	ds_swizzle_b32 v11, v10 offset:swizzle(SWAP,4)
	s_waitcnt lgkmcnt(0)
	v_add_f32_e32 v10, v10, v11
	ds_swizzle_b32 v11, v10 offset:swizzle(SWAP,8)
	s_waitcnt lgkmcnt(0)
	v_add_f32_e32 v10, v10, v11
	ds_swizzle_b32 v11, v10 offset:swizzle(SWAP,16)
	s_waitcnt lgkmcnt(0)
	v_add_f32_e32 v10, v10, v11
	v_fmamk_f32 v10, v10, 0x3c000000, v254
	s_nop 0
	s_nop 0
	s_nop 0
	s_nop 1
	s_nop 1
	s_nop 0
	v_rsq_f32_e32 v14, v10
	s_nop 0
	v_mul_f32_e32 v11, v12, v14
	v_mul_f32_e32 v12, v13, v14
	v_mul_f32_e32 v11, v6, v11
	v_mul_f32_e32 v12, v8, v12
	v_add_u32_e32 v10, 0x13000, v4
	v_cvt_pk_bf16_f32 v12, v11, v12
	v_mov_b32_e32 v11, v3
	v_lshl_add_u64 v[10:11], v[10:11], 1, s[6:7]
	global_store_short v[10:11], v12, off offset:768
	v_add_u32_e32 v10, 0x13020, v4
	v_mov_b32_e32 v11, v3
	v_lshl_add_u64 v[10:11], v[10:11], 1, s[6:7]
	global_store_short_d16_hi v[10:11], v12, off offset:768
	v_mul_f32_e32 v10, v15, v14
	v_mul_f32_e32 v5, v5, v14
	v_mul_f32_e32 v10, v2, v10
	v_mul_f32_e32 v5, v7, v5
	v_cvt_pk_bf16_f32 v5, v10, v5
	v_add_u32_e32 v10, 0x13040, v4
	v_mov_b32_e32 v11, v3
	v_lshl_add_u64 v[10:11], v[10:11], 1, s[6:7]
	global_store_short v[10:11], v5, off offset:768
	v_add_u32_e32 v10, 0x13060, v4
	v_mov_b32_e32 v11, v3
	v_lshl_add_u64 v[10:11], v[10:11], 1, s[6:7]
	global_store_short_d16_hi v[10:11], v5, off offset:768
	ds_read_b32 v5, v9 offset:96
	ds_read2st64_b32 v[10:11], v1 offset0:12 offset1:28
	s_waitcnt lgkmcnt(0)
	v_fma_f32 v12, v80, v5, -v10
	v_fma_f32 v13, v96, v5, -v11
	ds_read2st64_b32 v[10:11], v1 offset0:44 offset1:60
	v_mul_f32_e32 v14, v13, v13
	v_fmac_f32_e32 v14, v12, v12
	s_waitcnt lgkmcnt(0)
	v_fma_f32 v15, v112, v5, -v10
	v_fmac_f32_e32 v14, v15, v15
	v_fma_f32 v5, v128, v5, -v11
	v_fmac_f32_e32 v14, v5, v5
	ds_swizzle_b32 v10, v14 offset:swizzle(SWAP,1)
	s_waitcnt lgkmcnt(0)
	v_add_f32_e32 v10, v14, v10
	ds_swizzle_b32 v11, v10 offset:swizzle(SWAP,2)
	s_waitcnt lgkmcnt(0)
	v_add_f32_e32 v10, v10, v11
	ds_swizzle_b32 v11, v10 offset:swizzle(SWAP,4)
	s_waitcnt lgkmcnt(0)
	v_add_f32_e32 v10, v10, v11
	ds_swizzle_b32 v11, v10 offset:swizzle(SWAP,8)
	s_waitcnt lgkmcnt(0)
	v_add_f32_e32 v10, v10, v11
	ds_swizzle_b32 v11, v10 offset:swizzle(SWAP,16)
	s_waitcnt lgkmcnt(0)
	v_add_f32_e32 v10, v10, v11
	v_fmamk_f32 v10, v10, 0x3c000000, v254
	s_nop 0
	s_nop 0
	s_nop 0
	s_nop 1
	s_nop 1
	s_nop 0
	v_rsq_f32_e32 v14, v10
	s_nop 0
	v_mul_f32_e32 v11, v12, v14
	v_mul_f32_e32 v12, v13, v14
	v_mul_f32_e32 v11, v6, v11
	v_mul_f32_e32 v12, v8, v12
	v_add_u32_e32 v10, 0x18000, v4
	v_cvt_pk_bf16_f32 v12, v11, v12
	v_mov_b32_e32 v11, v3
	v_lshl_add_u64 v[10:11], v[10:11], 1, s[6:7]
	global_store_short v[10:11], v12, off offset:768
	v_add_u32_e32 v10, 0x18020, v4
	v_mov_b32_e32 v11, v3
	v_lshl_add_u64 v[10:11], v[10:11], 1, s[6:7]
	global_store_short_d16_hi v[10:11], v12, off offset:768
	v_mul_f32_e32 v10, v15, v14
	v_mul_f32_e32 v5, v5, v14
	v_mul_f32_e32 v10, v2, v10
	v_mul_f32_e32 v5, v7, v5
	v_cvt_pk_bf16_f32 v5, v10, v5
	v_add_u32_e32 v10, 0x18040, v4
	v_mov_b32_e32 v11, v3
	v_lshl_add_u64 v[10:11], v[10:11], 1, s[6:7]
	global_store_short v[10:11], v5, off offset:768
	v_add_u32_e32 v10, 0x18060, v4
	v_mov_b32_e32 v11, v3
	v_lshl_add_u64 v[10:11], v[10:11], 1, s[6:7]
	global_store_short_d16_hi v[10:11], v5, off offset:768
	ds_read_b32 v5, v9 offset:100
	ds_read2st64_b32 v[10:11], v1 offset0:13 offset1:29
	s_waitcnt lgkmcnt(0)
	v_fma_f32 v12, v81, v5, -v10
	v_fma_f32 v13, v97, v5, -v11
	ds_read2st64_b32 v[10:11], v1 offset0:45 offset1:61
	v_mul_f32_e32 v14, v13, v13
	v_fmac_f32_e32 v14, v12, v12
	s_waitcnt lgkmcnt(0)
	v_fma_f32 v15, v113, v5, -v10
	v_fmac_f32_e32 v14, v15, v15
	v_fma_f32 v5, v129, v5, -v11
	v_fmac_f32_e32 v14, v5, v5
	ds_swizzle_b32 v10, v14 offset:swizzle(SWAP,1)
	s_waitcnt lgkmcnt(0)
	v_add_f32_e32 v10, v14, v10
	ds_swizzle_b32 v11, v10 offset:swizzle(SWAP,2)
	s_waitcnt lgkmcnt(0)
	v_add_f32_e32 v10, v10, v11
	ds_swizzle_b32 v11, v10 offset:swizzle(SWAP,4)
	s_waitcnt lgkmcnt(0)
	v_add_f32_e32 v10, v10, v11
	ds_swizzle_b32 v11, v10 offset:swizzle(SWAP,8)
	s_waitcnt lgkmcnt(0)
	v_add_f32_e32 v10, v10, v11
	ds_swizzle_b32 v11, v10 offset:swizzle(SWAP,16)
	s_waitcnt lgkmcnt(0)
	v_add_f32_e32 v10, v10, v11
	v_fmamk_f32 v10, v10, 0x3c000000, v254
	s_nop 0
	s_nop 0
	s_nop 0
	s_nop 1
	s_nop 1
	s_nop 0
	v_rsq_f32_e32 v14, v10
	s_nop 0
	v_mul_f32_e32 v11, v12, v14
	v_mul_f32_e32 v12, v13, v14
	v_mul_f32_e32 v11, v6, v11
	v_mul_f32_e32 v12, v8, v12
	v_add_u32_e32 v10, 0x19000, v4
	v_cvt_pk_bf16_f32 v12, v11, v12
	v_mov_b32_e32 v11, v3
	v_lshl_add_u64 v[10:11], v[10:11], 1, s[6:7]
	global_store_short v[10:11], v12, off offset:768
	v_add_u32_e32 v10, 0x19020, v4
	v_mov_b32_e32 v11, v3
	v_lshl_add_u64 v[10:11], v[10:11], 1, s[6:7]
	global_store_short_d16_hi v[10:11], v12, off offset:768
	v_mul_f32_e32 v10, v15, v14
	v_mul_f32_e32 v5, v5, v14
	v_mul_f32_e32 v10, v2, v10
	v_mul_f32_e32 v5, v7, v5
	v_cvt_pk_bf16_f32 v5, v10, v5
	v_add_u32_e32 v10, 0x19040, v4
	v_mov_b32_e32 v11, v3
	v_lshl_add_u64 v[10:11], v[10:11], 1, s[6:7]
	global_store_short v[10:11], v5, off offset:768
	v_add_u32_e32 v10, 0x19060, v4
	v_mov_b32_e32 v11, v3
	v_lshl_add_u64 v[10:11], v[10:11], 1, s[6:7]
	global_store_short_d16_hi v[10:11], v5, off offset:768
	ds_read_b32 v5, v9 offset:104
	ds_read2st64_b32 v[10:11], v1 offset0:14 offset1:30
	s_waitcnt lgkmcnt(0)
	v_fma_f32 v12, v82, v5, -v10
	v_fma_f32 v13, v98, v5, -v11
	ds_read2st64_b32 v[10:11], v1 offset0:46 offset1:62
	v_mul_f32_e32 v14, v13, v13
	v_fmac_f32_e32 v14, v12, v12
	s_waitcnt lgkmcnt(0)
	v_fma_f32 v15, v114, v5, -v10
	v_fmac_f32_e32 v14, v15, v15
	v_fma_f32 v5, v130, v5, -v11
	v_fmac_f32_e32 v14, v5, v5
	ds_swizzle_b32 v10, v14 offset:swizzle(SWAP,1)
	s_waitcnt lgkmcnt(0)
	v_add_f32_e32 v10, v14, v10
	ds_swizzle_b32 v11, v10 offset:swizzle(SWAP,2)
	s_waitcnt lgkmcnt(0)
	v_add_f32_e32 v10, v10, v11
	ds_swizzle_b32 v11, v10 offset:swizzle(SWAP,4)
	s_waitcnt lgkmcnt(0)
	v_add_f32_e32 v10, v10, v11
	ds_swizzle_b32 v11, v10 offset:swizzle(SWAP,8)
	s_waitcnt lgkmcnt(0)
	v_add_f32_e32 v10, v10, v11
	ds_swizzle_b32 v11, v10 offset:swizzle(SWAP,16)
	s_waitcnt lgkmcnt(0)
	v_add_f32_e32 v10, v10, v11
	v_fmamk_f32 v10, v10, 0x3c000000, v254
	v_cmp_gt_f32_e32 vcc, s90, v10
	v_mul_f32_e32 v11, 0x4f800000, v10
	s_nop 0
	v_cndmask_b32_e32 v10, v10, v11, vcc
	v_sqrt_f32_e32 v11, v10
	s_nop 0
	v_add_u32_e32 v14, -1, v11
	v_fma_f32 v16, -v14, v11, v10
	v_cmp_ge_f32_e64 s[4:5], 0, v16
	v_add_u32_e32 v16, 1, v11
	s_nop 0
	v_cndmask_b32_e64 v14, v11, v14, s[4:5]
	v_fma_f32 v11, -v16, v11, v10
	v_cmp_lt_f32_e64 s[4:5], 0, v11
	s_nop 1
	v_cndmask_b32_e64 v11, v14, v16, s[4:5]
	v_mul_f32_e32 v14, 0x37800000, v11
	v_cndmask_b32_e32 v11, v11, v14, vcc
	v_cmp_class_f32_e32 vcc, v10, v209
	s_nop 1
	v_cndmask_b32_e32 v10, v11, v10, vcc
	v_div_scale_f32 v11, s[4:5], v10, v10, 1.0
	v_rcp_f32_e32 v14, v11
	s_nop 0
	v_fma_f32 v16, -v11, v14, 1.0
	v_fmac_f32_e32 v14, v16, v14
	v_div_scale_f32 v16, vcc, 1.0, v10, 1.0
	v_mul_f32_e32 v17, v16, v14
	v_fma_f32 v18, -v11, v17, v16
	v_fmac_f32_e32 v17, v18, v14
	v_fma_f32 v11, -v11, v17, v16
	v_div_fmas_f32 v11, v11, v14, v17
	v_div_fixup_f32 v14, v11, v10, 1.0
	v_mul_f32_e32 v11, v12, v14
	v_mul_f32_e32 v12, v13, v14
	v_mul_f32_e32 v11, v6, v11
	v_mul_f32_e32 v12, v8, v12
	v_add_u32_e32 v10, 0x1a000, v4
	v_cvt_pk_bf16_f32 v12, v11, v12
	v_mov_b32_e32 v11, v3
	v_lshl_add_u64 v[10:11], v[10:11], 1, s[6:7]
	global_store_short v[10:11], v12, off offset:768
	v_add_u32_e32 v10, 0x1a020, v4
	v_mov_b32_e32 v11, v3
	v_lshl_add_u64 v[10:11], v[10:11], 1, s[6:7]
	global_store_short_d16_hi v[10:11], v12, off offset:768
	v_mul_f32_e32 v10, v15, v14
	v_mul_f32_e32 v5, v5, v14
	v_mul_f32_e32 v10, v2, v10
	v_mul_f32_e32 v5, v7, v5
	v_cvt_pk_bf16_f32 v5, v10, v5
	v_add_u32_e32 v10, 0x1a040, v4
	v_mov_b32_e32 v11, v3
	v_lshl_add_u64 v[10:11], v[10:11], 1, s[6:7]
	global_store_short v[10:11], v5, off offset:768
	v_add_u32_e32 v10, 0x1a060, v4
	v_mov_b32_e32 v11, v3
	v_lshl_add_u64 v[10:11], v[10:11], 1, s[6:7]
	global_store_short_d16_hi v[10:11], v5, off offset:768
	ds_read_b32 v5, v9 offset:108
	ds_read2st64_b32 v[10:11], v1 offset0:15 offset1:31
	s_waitcnt lgkmcnt(0)
	v_fma_f32 v9, v83, v5, -v10
	v_fma_f32 v12, v99, v5, -v11
	ds_read2st64_b32 v[10:11], v1 offset0:47 offset1:63
	v_mul_f32_e32 v13, v12, v12
	v_fmac_f32_e32 v13, v9, v9
	s_waitcnt lgkmcnt(0)
	v_fma_f32 v1, v115, v5, -v10
	v_fmac_f32_e32 v13, v1, v1
	v_fma_f32 v5, v131, v5, -v11
	v_fmac_f32_e32 v13, v5, v5
	ds_swizzle_b32 v10, v13 offset:swizzle(SWAP,1)
	s_waitcnt lgkmcnt(0)
	v_add_f32_e32 v10, v13, v10
	ds_swizzle_b32 v11, v10 offset:swizzle(SWAP,2)
	s_waitcnt lgkmcnt(0)
	v_add_f32_e32 v10, v10, v11
	ds_swizzle_b32 v11, v10 offset:swizzle(SWAP,4)
	s_waitcnt lgkmcnt(0)
	v_add_f32_e32 v10, v10, v11
	ds_swizzle_b32 v11, v10 offset:swizzle(SWAP,8)
	s_waitcnt lgkmcnt(0)
	v_add_f32_e32 v10, v10, v11
	ds_swizzle_b32 v11, v10 offset:swizzle(SWAP,16)
	s_waitcnt lgkmcnt(0)
	v_add_f32_e32 v10, v10, v11
	v_fmamk_f32 v10, v10, 0x3c000000, v254
	v_cmp_gt_f32_e32 vcc, s90, v10
	v_mul_f32_e32 v11, 0x4f800000, v10
	s_nop 0
	v_cndmask_b32_e32 v10, v10, v11, vcc
	v_sqrt_f32_e32 v11, v10
	s_nop 0
	v_add_u32_e32 v13, -1, v11
	v_fma_f32 v14, -v13, v11, v10
	v_cmp_ge_f32_e64 s[4:5], 0, v14
	v_add_u32_e32 v14, 1, v11
	s_nop 0
	v_cndmask_b32_e64 v13, v11, v13, s[4:5]
	v_fma_f32 v11, -v14, v11, v10
	v_cmp_lt_f32_e64 s[4:5], 0, v11
	s_nop 1
	v_cndmask_b32_e64 v11, v13, v14, s[4:5]
	v_mul_f32_e32 v13, 0x37800000, v11
	v_cndmask_b32_e32 v11, v11, v13, vcc
	v_cmp_class_f32_e32 vcc, v10, v209
	s_nop 1
	v_cndmask_b32_e32 v10, v11, v10, vcc
	v_div_scale_f32 v11, s[4:5], v10, v10, 1.0
	v_rcp_f32_e32 v13, v11
	s_nop 0
	v_fma_f32 v14, -v11, v13, 1.0
	v_fmac_f32_e32 v13, v14, v13
	v_div_scale_f32 v14, vcc, 1.0, v10, 1.0
	v_mul_f32_e32 v15, v14, v13
	v_fma_f32 v16, -v11, v15, v14
	v_fmac_f32_e32 v15, v16, v13
	v_fma_f32 v11, -v11, v15, v14
	v_div_fmas_f32 v11, v11, v13, v15
	v_div_fixup_f32 v13, v11, v10, 1.0
	v_mul_f32_e32 v9, v9, v13
	v_mul_f32_e32 v6, v6, v9
	v_mul_f32_e32 v9, v12, v13
	v_add_u32_e32 v10, 0x1b000, v4
	v_mul_f32_e32 v8, v8, v9
	v_mov_b32_e32 v11, v3
	v_cvt_pk_bf16_f32 v6, v6, v8
	v_lshl_add_u64 v[8:9], v[10:11], 1, s[6:7]
	global_store_short v[8:9], v6, off offset:768
	v_add_u32_e32 v8, 0x1b020, v4
	v_mov_b32_e32 v9, v3
	v_mul_f32_e32 v1, v1, v13
	v_lshl_add_u64 v[8:9], v[8:9], 1, s[6:7]
	v_mul_f32_e32 v1, v2, v1
	v_mul_f32_e32 v2, v5, v13
	global_store_short_d16_hi v[8:9], v6, off offset:768
	v_mul_f32_e32 v2, v7, v2
	v_add_u32_e32 v6, 0x1b040, v4
	v_mov_b32_e32 v7, v3
	v_add_u32_e32 v4, 0x1b060, v4
	v_mov_b32_e32 v5, v3
	v_lshl_add_u64 v[6:7], v[6:7], 1, s[6:7]
	v_lshl_add_u64 v[4:5], v[4:5], 1, s[6:7]
	v_cvt_pk_bf16_f32 v1, v1, v2
	global_store_short v[6:7], v1, off offset:768
	global_store_short_d16_hi v[4:5], v1, off offset:768

.LBB0_1426:
	s_or_b64 exec, exec, s[4:5]
	s_waitcnt lgkmcnt(0)
	v_lshlrev_b32_e32 v68, 2, v1
	global_load_dword v248, v68, s[0:1]
	global_load_dword v249, v68, s[0:1] offset:128
	global_load_dword v250, v68, s[0:1] offset:256
	global_load_dword v251, v68, s[0:1] offset:384
	s_or_b32 s24, s24, s35
	s_lshl_b64 s[4:5], s[24:25], 13
	s_add_u32 s6, s86, s4
	s_addc_u32 s7, s87, s5
	s_lshl_b64 s[4:5], s[46:47], 1
	s_add_u32 s6, s6, s4
	s_addc_u32 s7, s7, s5
	s_waitcnt vmcnt(0)
	v_mul_f32_e32 v72, v164, v248
	v_mul_f32_e32 v74, v164, v249
	v_mul_f32_e32 v71, v164, v250
	v_mul_f32_e32 v73, v164, v251
	v_lshl_or_b32 v68, v2, 14, v1
	v_lshl_add_u32 v1, v2, 4, s34
	ds_read_b32 v2, v1
	ds_read2st64_b32 v[76:77], v70 offset1:16
	s_waitcnt lgkmcnt(0)
	v_fma_f32 v52, v52, v2, -v76
	v_fma_f32 v36, v36, v2, -v77
	ds_read2st64_b32 v[76:77], v70 offset0:32 offset1:48
	v_mul_f32_e32 v69, v36, v36
	v_fmac_f32_e32 v69, v52, v52
	s_waitcnt lgkmcnt(0)
	v_fma_f32 v20, v20, v2, -v76
	v_fmac_f32_e32 v69, v20, v20
	v_fma_f32 v2, v4, v2, -v77
	v_fmac_f32_e32 v69, v2, v2
	ds_swizzle_b32 v4, v69 offset:swizzle(SWAP,1)
	s_waitcnt lgkmcnt(0)
	v_add_f32_e32 v4, v69, v4
	ds_swizzle_b32 v69, v4 offset:swizzle(SWAP,2)
	s_waitcnt lgkmcnt(0)
	v_add_f32_e32 v4, v4, v69
	ds_swizzle_b32 v69, v4 offset:swizzle(SWAP,4)
	s_waitcnt lgkmcnt(0)
	v_add_f32_e32 v4, v4, v69
	ds_swizzle_b32 v69, v4 offset:swizzle(SWAP,8)
	s_waitcnt lgkmcnt(0)
	v_add_f32_e32 v4, v4, v69
	ds_swizzle_b32 v69, v4 offset:swizzle(SWAP,16)
	s_waitcnt lgkmcnt(0)
	v_add_f32_e32 v4, v4, v69
	v_fmamk_f32 v4, v4, 0x3c000000, v254
	v_cmp_gt_f32_e32 vcc, s90, v4
	v_mul_f32_e32 v69, 0x4f800000, v4
	s_nop 0
	v_cndmask_b32_e32 v4, v4, v69, vcc
	v_sqrt_f32_e32 v69, v4
	s_nop 0
	v_add_u32_e32 v75, -1, v69
	v_fma_f32 v76, -v75, v69, v4
	v_cmp_ge_f32_e64 s[4:5], 0, v76
	v_add_u32_e32 v76, 1, v69
	s_nop 0
	v_cndmask_b32_e64 v75, v69, v75, s[4:5]
	v_fma_f32 v69, -v76, v69, v4
	v_cmp_lt_f32_e64 s[4:5], 0, v69
	s_nop 1
	v_cndmask_b32_e64 v69, v75, v76, s[4:5]
	v_mul_f32_e32 v75, 0x37800000, v69
	v_cndmask_b32_e32 v69, v69, v75, vcc
	v_cmp_class_f32_e32 vcc, v4, v209
	s_nop 1
	v_cndmask_b32_e32 v4, v69, v4, vcc
	v_div_scale_f32 v69, s[4:5], v4, v4, 1.0
	v_rcp_f32_e32 v75, v69
	s_nop 0
	v_fma_f32 v76, -v69, v75, 1.0
	v_fmac_f32_e32 v75, v76, v75
	v_div_scale_f32 v76, vcc, 1.0, v4, 1.0
	v_mul_f32_e32 v77, v76, v75
	v_fma_f32 v78, -v69, v77, v76
	v_fmac_f32_e32 v77, v78, v75
	v_fma_f32 v69, -v69, v77, v76
	v_div_fmas_f32 v69, v69, v75, v77
	v_div_fixup_f32 v4, v69, v4, 1.0
	v_mul_f32_e32 v36, v36, v4
	v_mov_b32_e32 v69, v3
	v_mul_f32_e32 v52, v52, v4
	v_mul_f32_e32 v36, v74, v36
	v_lshl_add_u64 v[76:77], v[68:69], 1, s[6:7]
	v_mul_f32_e32 v52, v72, v52
	v_cvt_pk_bf16_f32 v36, v52, v36
	global_store_short v[76:77], v36, off
	v_add_u32_e32 v76, 32, v68
	v_mov_b32_e32 v77, v3
	v_lshl_add_u64 v[76:77], v[76:77], 1, s[6:7]
	global_store_short_d16_hi v[76:77], v36, off
	v_mul_f32_e32 v2, v2, v4
	v_add_u32_e32 v76, 64, v68
	v_mov_b32_e32 v77, v3
	v_mul_f32_e32 v20, v20, v4
	v_mul_f32_e32 v2, v73, v2
	v_lshl_add_u64 v[76:77], v[76:77], 1, s[6:7]
	v_mul_f32_e32 v20, v71, v20
	v_cvt_pk_bf16_f32 v2, v20, v2
	global_store_short v[76:77], v2, off
	v_add_u32_e32 v76, 0x60, v68
	v_mov_b32_e32 v77, v3
	v_lshl_add_u64 v[76:77], v[76:77], 1, s[6:7]
	global_store_short_d16_hi v[76:77], v2, off
	ds_read_b32 v2, v1 offset:4
	ds_read2st64_b32 v[76:77], v70 offset0:1 offset1:17
	s_waitcnt lgkmcnt(0)
	v_fma_f32 v52, v37, v2, -v77
	ds_read2st64_b32 v[36:37], v70 offset0:33 offset1:49
	v_fma_f32 v20, v53, v2, -v76
	v_mul_f32_e32 v4, v52, v52
	v_fmac_f32_e32 v4, v20, v20
	s_waitcnt lgkmcnt(0)
	v_fma_f32 v21, v21, v2, -v36
	v_fmac_f32_e32 v4, v21, v21
	v_fma_f32 v2, v5, v2, -v37
	v_fmac_f32_e32 v4, v2, v2
	ds_swizzle_b32 v5, v4 offset:swizzle(SWAP,1)
	s_waitcnt lgkmcnt(0)
	v_add_f32_e32 v4, v4, v5
	ds_swizzle_b32 v5, v4 offset:swizzle(SWAP,2)
	s_waitcnt lgkmcnt(0)
	v_add_f32_e32 v4, v4, v5
	ds_swizzle_b32 v5, v4 offset:swizzle(SWAP,4)
	s_waitcnt lgkmcnt(0)
	v_add_f32_e32 v4, v4, v5
	ds_swizzle_b32 v5, v4 offset:swizzle(SWAP,8)
	s_waitcnt lgkmcnt(0)
	v_add_f32_e32 v4, v4, v5
	ds_swizzle_b32 v5, v4 offset:swizzle(SWAP,16)
	s_waitcnt lgkmcnt(0)
	v_add_f32_e32 v4, v4, v5
	v_fmamk_f32 v4, v4, 0x3c000000, v254
	v_cmp_gt_f32_e32 vcc, s90, v4
	v_mul_f32_e32 v5, 0x4f800000, v4
	s_nop 0
	v_cndmask_b32_e32 v4, v4, v5, vcc
	v_sqrt_f32_e32 v5, v4
	s_nop 0
	v_add_u32_e32 v36, -1, v5
	v_fma_f32 v37, -v36, v5, v4
	v_cmp_ge_f32_e64 s[4:5], 0, v37
	v_add_u32_e32 v37, 1, v5
	s_nop 0
	v_cndmask_b32_e64 v36, v5, v36, s[4:5]
	v_fma_f32 v5, -v37, v5, v4
	v_cmp_lt_f32_e64 s[4:5], 0, v5
	s_nop 1
	v_cndmask_b32_e64 v5, v36, v37, s[4:5]
	v_mul_f32_e32 v36, 0x37800000, v5
	v_cndmask_b32_e32 v5, v5, v36, vcc
	v_cmp_class_f32_e32 vcc, v4, v209
	s_nop 1
	v_cndmask_b32_e32 v4, v5, v4, vcc
	v_div_scale_f32 v5, s[4:5], v4, v4, 1.0
	v_rcp_f32_e32 v36, v5
	s_nop 0
	v_fma_f32 v37, -v5, v36, 1.0
	v_fmac_f32_e32 v36, v37, v36
	v_div_scale_f32 v37, vcc, 1.0, v4, 1.0
	v_mul_f32_e32 v53, v37, v36
	v_fma_f32 v69, -v5, v53, v37
	v_fmac_f32_e32 v53, v69, v36
	v_fma_f32 v5, -v5, v53, v37
	v_div_fmas_f32 v5, v5, v36, v53
	v_div_fixup_f32 v36, v5, v4, 1.0
	v_mul_f32_e32 v5, v20, v36
	v_mul_f32_e32 v20, v52, v36
	v_mul_f32_e32 v5, v72, v5
	v_mul_f32_e32 v20, v74, v20
	v_add_u32_e32 v4, 0x1000, v68
	v_cvt_pk_bf16_f32 v20, v5, v20
	v_mov_b32_e32 v5, v3
	v_lshl_add_u64 v[4:5], v[4:5], 1, s[6:7]
	global_store_short v[4:5], v20, off
	v_add_u32_e32 v4, 0x1020, v68
	v_mov_b32_e32 v5, v3
	v_lshl_add_u64 v[4:5], v[4:5], 1, s[6:7]
	global_store_short_d16_hi v[4:5], v20, off
	v_mul_f32_e32 v4, v21, v36
	v_mul_f32_e32 v2, v2, v36
	v_mul_f32_e32 v4, v71, v4
	v_mul_f32_e32 v2, v73, v2
	v_cvt_pk_bf16_f32 v2, v4, v2
	v_add_u32_e32 v4, 0x1040, v68
	v_mov_b32_e32 v5, v3
	v_lshl_add_u64 v[4:5], v[4:5], 1, s[6:7]
	global_store_short v[4:5], v2, off
	v_add_u32_e32 v4, 0x1060, v68
	v_mov_b32_e32 v5, v3
	v_lshl_add_u64 v[4:5], v[4:5], 1, s[6:7]
	global_store_short_d16_hi v[4:5], v2, off
	ds_read_b32 v2, v1 offset:8
	ds_read2st64_b32 v[4:5], v70 offset0:2 offset1:18
	s_waitcnt lgkmcnt(0)
	v_fma_f32 v20, v54, v2, -v4
	v_fma_f32 v21, v38, v2, -v5
	ds_read2st64_b32 v[4:5], v70 offset0:34 offset1:50
	v_mul_f32_e32 v36, v21, v21
	v_fmac_f32_e32 v36, v20, v20
	s_waitcnt lgkmcnt(0)
	v_fma_f32 v22, v22, v2, -v4
	v_fmac_f32_e32 v36, v22, v22
	v_fma_f32 v2, v6, v2, -v5
	v_fmac_f32_e32 v36, v2, v2
	ds_swizzle_b32 v4, v36 offset:swizzle(SWAP,1)
	s_waitcnt lgkmcnt(0)
	v_add_f32_e32 v4, v36, v4
	ds_swizzle_b32 v5, v4 offset:swizzle(SWAP,2)
	s_waitcnt lgkmcnt(0)
	v_add_f32_e32 v4, v4, v5
	ds_swizzle_b32 v5, v4 offset:swizzle(SWAP,4)
	s_waitcnt lgkmcnt(0)
	v_add_f32_e32 v4, v4, v5
	ds_swizzle_b32 v5, v4 offset:swizzle(SWAP,8)
	s_waitcnt lgkmcnt(0)
	v_add_f32_e32 v4, v4, v5
	ds_swizzle_b32 v5, v4 offset:swizzle(SWAP,16)
	s_waitcnt lgkmcnt(0)
	v_add_f32_e32 v4, v4, v5
	v_fmamk_f32 v4, v4, 0x3c000000, v254
	s_nop 0
	s_nop 0
	s_nop 0
	s_nop 1
	s_nop 1
	s_nop 0
	v_rsq_f32_e32 v6, v4
	s_nop 0
	v_mul_f32_e32 v5, v20, v6
	v_mul_f32_e32 v20, v21, v6
	v_mul_f32_e32 v5, v72, v5
	v_mul_f32_e32 v20, v74, v20
	v_add_u32_e32 v4, 0x2000, v68
	v_cvt_pk_bf16_f32 v20, v5, v20
	v_mov_b32_e32 v5, v3
	v_lshl_add_u64 v[4:5], v[4:5], 1, s[6:7]
	global_store_short v[4:5], v20, off
	v_add_u32_e32 v4, 0x2020, v68
	v_mov_b32_e32 v5, v3
	v_lshl_add_u64 v[4:5], v[4:5], 1, s[6:7]
	global_store_short_d16_hi v[4:5], v20, off
	v_mul_f32_e32 v4, v22, v6
	v_mul_f32_e32 v2, v2, v6
	v_mul_f32_e32 v4, v71, v4
	v_mul_f32_e32 v2, v73, v2
	v_cvt_pk_bf16_f32 v2, v4, v2
	v_add_u32_e32 v4, 0x2040, v68
	v_mov_b32_e32 v5, v3
	v_lshl_add_u64 v[4:5], v[4:5], 1, s[6:7]
	global_store_short v[4:5], v2, off
	v_add_u32_e32 v4, 0x2060, v68
	v_mov_b32_e32 v5, v3
	v_lshl_add_u64 v[4:5], v[4:5], 1, s[6:7]
	global_store_short_d16_hi v[4:5], v2, off
	ds_read_b32 v2, v1 offset:12
	ds_read2st64_b32 v[4:5], v70 offset0:3 offset1:19
	s_waitcnt lgkmcnt(0)
	v_fma_f32 v6, v55, v2, -v4
	v_fma_f32 v20, v39, v2, -v5
	ds_read2st64_b32 v[4:5], v70 offset0:35 offset1:51
	v_mul_f32_e32 v21, v20, v20
	v_fmac_f32_e32 v21, v6, v6
	s_waitcnt lgkmcnt(0)
	v_fma_f32 v22, v23, v2, -v4
	v_fmac_f32_e32 v21, v22, v22
	v_fma_f32 v2, v7, v2, -v5
	v_fmac_f32_e32 v21, v2, v2
	ds_swizzle_b32 v4, v21 offset:swizzle(SWAP,1)
	s_waitcnt lgkmcnt(0)
	v_add_f32_e32 v4, v21, v4
	ds_swizzle_b32 v5, v4 offset:swizzle(SWAP,2)
	s_waitcnt lgkmcnt(0)
	v_add_f32_e32 v4, v4, v5
	ds_swizzle_b32 v5, v4 offset:swizzle(SWAP,4)
	s_waitcnt lgkmcnt(0)
	v_add_f32_e32 v4, v4, v5
	ds_swizzle_b32 v5, v4 offset:swizzle(SWAP,8)
	s_waitcnt lgkmcnt(0)
	v_add_f32_e32 v4, v4, v5
	ds_swizzle_b32 v5, v4 offset:swizzle(SWAP,16)
	s_waitcnt lgkmcnt(0)
	v_add_f32_e32 v4, v4, v5
	v_fmamk_f32 v4, v4, 0x3c000000, v254
	s_nop 0
	s_nop 0
	s_nop 0
	s_nop 1
	s_nop 1
	s_nop 0
	v_rsq_f32_e32 v7, v4
	s_nop 0
	v_mul_f32_e32 v5, v6, v7
	v_mul_f32_e32 v6, v20, v7
	v_mul_f32_e32 v5, v72, v5
	v_mul_f32_e32 v6, v74, v6
	v_add_u32_e32 v4, 0x3000, v68
	v_cvt_pk_bf16_f32 v6, v5, v6
	v_mov_b32_e32 v5, v3
	v_lshl_add_u64 v[4:5], v[4:5], 1, s[6:7]
	global_store_short v[4:5], v6, off
	v_add_u32_e32 v4, 0x3020, v68
	v_mov_b32_e32 v5, v3
	v_lshl_add_u64 v[4:5], v[4:5], 1, s[6:7]
	global_store_short_d16_hi v[4:5], v6, off
	v_mul_f32_e32 v4, v22, v7
	v_mul_f32_e32 v2, v2, v7
	v_mul_f32_e32 v4, v71, v4
	v_mul_f32_e32 v2, v73, v2
	v_cvt_pk_bf16_f32 v2, v4, v2
	v_add_u32_e32 v4, 0x3040, v68
	v_mov_b32_e32 v5, v3
	v_lshl_add_u64 v[4:5], v[4:5], 1, s[6:7]
	global_store_short v[4:5], v2, off
	v_add_u32_e32 v4, 0x3060, v68
	v_mov_b32_e32 v5, v3
	v_lshl_add_u64 v[4:5], v[4:5], 1, s[6:7]
	global_store_short_d16_hi v[4:5], v2, off
	ds_read_b32 v2, v1 offset:32
	ds_read2st64_b32 v[4:5], v70 offset0:4 offset1:20
	s_waitcnt lgkmcnt(0)
	v_fma_f32 v6, v56, v2, -v4
	v_fma_f32 v7, v40, v2, -v5
	ds_read2st64_b32 v[4:5], v70 offset0:36 offset1:52
	v_mul_f32_e32 v20, v7, v7
	v_fmac_f32_e32 v20, v6, v6
	s_waitcnt lgkmcnt(0)
	v_fma_f32 v21, v24, v2, -v4
	v_fmac_f32_e32 v20, v21, v21
	v_fma_f32 v2, v8, v2, -v5
	v_fmac_f32_e32 v20, v2, v2
	ds_swizzle_b32 v4, v20 offset:swizzle(SWAP,1)
	s_waitcnt lgkmcnt(0)
	v_add_f32_e32 v4, v20, v4
	ds_swizzle_b32 v5, v4 offset:swizzle(SWAP,2)
	s_waitcnt lgkmcnt(0)
	v_add_f32_e32 v4, v4, v5
	ds_swizzle_b32 v5, v4 offset:swizzle(SWAP,4)
	s_waitcnt lgkmcnt(0)
	v_add_f32_e32 v4, v4, v5
	ds_swizzle_b32 v5, v4 offset:swizzle(SWAP,8)
	s_waitcnt lgkmcnt(0)
	v_add_f32_e32 v4, v4, v5
	ds_swizzle_b32 v5, v4 offset:swizzle(SWAP,16)
	s_waitcnt lgkmcnt(0)
	v_add_f32_e32 v4, v4, v5
	v_fmamk_f32 v4, v4, 0x3c000000, v254
	s_nop 0
	s_nop 0
	s_nop 0
	s_nop 1
	s_nop 1
	s_nop 0
	v_rsq_f32_e32 v8, v4
	s_nop 0
	v_mul_f32_e32 v5, v6, v8
	v_mul_f32_e32 v6, v7, v8
	v_mul_f32_e32 v5, v72, v5
	v_mul_f32_e32 v6, v74, v6
	v_add_u32_e32 v4, 0x8000, v68
	v_cvt_pk_bf16_f32 v6, v5, v6
	v_mov_b32_e32 v5, v3
	v_lshl_add_u64 v[4:5], v[4:5], 1, s[6:7]
	global_store_short v[4:5], v6, off
	v_add_u32_e32 v4, 0x8020, v68
	v_mov_b32_e32 v5, v3
	v_lshl_add_u64 v[4:5], v[4:5], 1, s[6:7]
	global_store_short_d16_hi v[4:5], v6, off
	v_mul_f32_e32 v4, v21, v8
	v_mul_f32_e32 v2, v2, v8
	v_mul_f32_e32 v4, v71, v4
	v_mul_f32_e32 v2, v73, v2
	v_cvt_pk_bf16_f32 v2, v4, v2
	v_add_u32_e32 v4, 0x8040, v68
	v_mov_b32_e32 v5, v3
	v_lshl_add_u64 v[4:5], v[4:5], 1, s[6:7]
	global_store_short v[4:5], v2, off
	v_add_u32_e32 v4, 0x8060, v68
	v_mov_b32_e32 v5, v3
	v_lshl_add_u64 v[4:5], v[4:5], 1, s[6:7]
	global_store_short_d16_hi v[4:5], v2, off
	ds_read_b32 v2, v1 offset:36
	ds_read2st64_b32 v[4:5], v70 offset0:5 offset1:21
	s_waitcnt lgkmcnt(0)
	v_fma_f32 v6, v57, v2, -v4
	v_fma_f32 v7, v41, v2, -v5
	ds_read2st64_b32 v[4:5], v70 offset0:37 offset1:53
	v_mul_f32_e32 v8, v7, v7
	v_fmac_f32_e32 v8, v6, v6
	s_waitcnt lgkmcnt(0)
	v_fma_f32 v20, v25, v2, -v4
	v_fmac_f32_e32 v8, v20, v20
	v_fma_f32 v2, v9, v2, -v5
	v_fmac_f32_e32 v8, v2, v2
	ds_swizzle_b32 v4, v8 offset:swizzle(SWAP,1)
	s_waitcnt lgkmcnt(0)
	v_add_f32_e32 v4, v8, v4
	ds_swizzle_b32 v5, v4 offset:swizzle(SWAP,2)
	s_waitcnt lgkmcnt(0)
	v_add_f32_e32 v4, v4, v5
	ds_swizzle_b32 v5, v4 offset:swizzle(SWAP,4)
	s_waitcnt lgkmcnt(0)
	v_add_f32_e32 v4, v4, v5
	ds_swizzle_b32 v5, v4 offset:swizzle(SWAP,8)
	s_waitcnt lgkmcnt(0)
	v_add_f32_e32 v4, v4, v5
	ds_swizzle_b32 v5, v4 offset:swizzle(SWAP,16)
	s_waitcnt lgkmcnt(0)
	v_add_f32_e32 v4, v4, v5
	v_fmamk_f32 v4, v4, 0x3c000000, v254
	s_nop 0
	s_nop 0
	s_nop 0
	s_nop 1
	s_nop 1
	s_nop 0
	v_rsq_f32_e32 v8, v4
	s_nop 0
	v_mul_f32_e32 v5, v6, v8
	v_mul_f32_e32 v6, v7, v8
	v_mul_f32_e32 v5, v72, v5
	v_mul_f32_e32 v6, v74, v6
	v_add_u32_e32 v4, 0x9000, v68
	v_cvt_pk_bf16_f32 v6, v5, v6
	v_mov_b32_e32 v5, v3
	v_lshl_add_u64 v[4:5], v[4:5], 1, s[6:7]
	global_store_short v[4:5], v6, off
	v_add_u32_e32 v4, 0x9020, v68
	v_mov_b32_e32 v5, v3
	v_lshl_add_u64 v[4:5], v[4:5], 1, s[6:7]
	global_store_short_d16_hi v[4:5], v6, off
	v_mul_f32_e32 v4, v20, v8
	v_mul_f32_e32 v2, v2, v8
	v_mul_f32_e32 v4, v71, v4
	v_mul_f32_e32 v2, v73, v2
	v_cvt_pk_bf16_f32 v2, v4, v2
	v_add_u32_e32 v4, 0x9040, v68
	v_mov_b32_e32 v5, v3
	v_lshl_add_u64 v[4:5], v[4:5], 1, s[6:7]
	global_store_short v[4:5], v2, off
	v_add_u32_e32 v4, 0x9060, v68
	v_mov_b32_e32 v5, v3
	v_lshl_add_u64 v[4:5], v[4:5], 1, s[6:7]
	global_store_short_d16_hi v[4:5], v2, off
	ds_read_b32 v2, v1 offset:40
	ds_read2st64_b32 v[4:5], v70 offset0:6 offset1:22
	s_waitcnt lgkmcnt(0)
	v_fma_f32 v6, v58, v2, -v4
	v_fma_f32 v7, v42, v2, -v5
	ds_read2st64_b32 v[4:5], v70 offset0:38 offset1:54
	v_mul_f32_e32 v8, v7, v7
	v_fmac_f32_e32 v8, v6, v6
	s_waitcnt lgkmcnt(0)
	v_fma_f32 v9, v26, v2, -v4
	v_fmac_f32_e32 v8, v9, v9
	v_fma_f32 v2, v10, v2, -v5
	v_fmac_f32_e32 v8, v2, v2
	ds_swizzle_b32 v4, v8 offset:swizzle(SWAP,1)
	s_waitcnt lgkmcnt(0)
	v_add_f32_e32 v4, v8, v4
	ds_swizzle_b32 v5, v4 offset:swizzle(SWAP,2)
	s_waitcnt lgkmcnt(0)
	v_add_f32_e32 v4, v4, v5
	ds_swizzle_b32 v5, v4 offset:swizzle(SWAP,4)
	s_waitcnt lgkmcnt(0)
	v_add_f32_e32 v4, v4, v5
	ds_swizzle_b32 v5, v4 offset:swizzle(SWAP,8)
	s_waitcnt lgkmcnt(0)
	v_add_f32_e32 v4, v4, v5
	ds_swizzle_b32 v5, v4 offset:swizzle(SWAP,16)
	s_waitcnt lgkmcnt(0)
	v_add_f32_e32 v4, v4, v5
	v_fmamk_f32 v4, v4, 0x3c000000, v254
	s_nop 0
	s_nop 0
	s_nop 0
	s_nop 1
	s_nop 1
	s_nop 0
	v_rsq_f32_e32 v8, v4
	s_nop 0
	v_mul_f32_e32 v5, v6, v8
	v_mul_f32_e32 v6, v7, v8
	v_mul_f32_e32 v5, v72, v5
	v_mul_f32_e32 v6, v74, v6
	v_add_u32_e32 v4, 0xa000, v68
	v_cvt_pk_bf16_f32 v6, v5, v6
	v_mov_b32_e32 v5, v3
	v_lshl_add_u64 v[4:5], v[4:5], 1, s[6:7]
	global_store_short v[4:5], v6, off
	v_add_u32_e32 v4, 0xa020, v68
	v_mov_b32_e32 v5, v3
	v_lshl_add_u64 v[4:5], v[4:5], 1, s[6:7]
	global_store_short_d16_hi v[4:5], v6, off
	v_mul_f32_e32 v4, v9, v8
	v_mul_f32_e32 v2, v2, v8
	v_mul_f32_e32 v4, v71, v4
	v_mul_f32_e32 v2, v73, v2
	v_cvt_pk_bf16_f32 v2, v4, v2
	v_add_u32_e32 v4, 0xa040, v68
	v_mov_b32_e32 v5, v3
	v_lshl_add_u64 v[4:5], v[4:5], 1, s[6:7]
	global_store_short v[4:5], v2, off
	v_add_u32_e32 v4, 0xa060, v68
	v_mov_b32_e32 v5, v3
	v_lshl_add_u64 v[4:5], v[4:5], 1, s[6:7]
	global_store_short_d16_hi v[4:5], v2, off
	ds_read_b32 v2, v1 offset:44
	ds_read2st64_b32 v[4:5], v70 offset0:7 offset1:23
	s_waitcnt lgkmcnt(0)
	v_fma_f32 v6, v59, v2, -v4
	v_fma_f32 v7, v43, v2, -v5
	ds_read2st64_b32 v[4:5], v70 offset0:39 offset1:55
	v_mul_f32_e32 v8, v7, v7
	v_fmac_f32_e32 v8, v6, v6
	s_waitcnt lgkmcnt(0)
	v_fma_f32 v9, v27, v2, -v4
	v_fmac_f32_e32 v8, v9, v9
	v_fma_f32 v2, v11, v2, -v5
	v_fmac_f32_e32 v8, v2, v2
	ds_swizzle_b32 v4, v8 offset:swizzle(SWAP,1)
	s_waitcnt lgkmcnt(0)
	v_add_f32_e32 v4, v8, v4
	ds_swizzle_b32 v5, v4 offset:swizzle(SWAP,2)
	s_waitcnt lgkmcnt(0)
	v_add_f32_e32 v4, v4, v5
	ds_swizzle_b32 v5, v4 offset:swizzle(SWAP,4)
	s_waitcnt lgkmcnt(0)
	v_add_f32_e32 v4, v4, v5
	ds_swizzle_b32 v5, v4 offset:swizzle(SWAP,8)
	s_waitcnt lgkmcnt(0)
	v_add_f32_e32 v4, v4, v5
	ds_swizzle_b32 v5, v4 offset:swizzle(SWAP,16)
	s_waitcnt lgkmcnt(0)
	v_add_f32_e32 v4, v4, v5
	v_fmamk_f32 v4, v4, 0x3c000000, v254
	s_nop 0
	s_nop 0
	s_nop 0
	s_nop 1
	s_nop 1
	s_nop 0
	v_rsq_f32_e32 v8, v4
	s_nop 0
	v_mul_f32_e32 v5, v6, v8
	v_mul_f32_e32 v6, v7, v8
	v_mul_f32_e32 v5, v72, v5
	v_mul_f32_e32 v6, v74, v6
	v_add_u32_e32 v4, 0xb000, v68
	v_cvt_pk_bf16_f32 v6, v5, v6
	v_mov_b32_e32 v5, v3
	v_lshl_add_u64 v[4:5], v[4:5], 1, s[6:7]
	global_store_short v[4:5], v6, off
	v_add_u32_e32 v4, 0xb020, v68
	v_mov_b32_e32 v5, v3
	v_lshl_add_u64 v[4:5], v[4:5], 1, s[6:7]
	global_store_short_d16_hi v[4:5], v6, off
	v_mul_f32_e32 v4, v9, v8
	v_mul_f32_e32 v2, v2, v8
	v_mul_f32_e32 v4, v71, v4
	v_mul_f32_e32 v2, v73, v2
	v_cvt_pk_bf16_f32 v2, v4, v2
	v_add_u32_e32 v4, 0xb040, v68
	v_mov_b32_e32 v5, v3
	v_lshl_add_u64 v[4:5], v[4:5], 1, s[6:7]
	global_store_short v[4:5], v2, off
	v_add_u32_e32 v4, 0xb060, v68
	v_mov_b32_e32 v5, v3
	v_lshl_add_u64 v[4:5], v[4:5], 1, s[6:7]
	global_store_short_d16_hi v[4:5], v2, off
	ds_read_b32 v2, v1 offset:64
	ds_read2st64_b32 v[4:5], v70 offset0:8 offset1:24
	s_waitcnt lgkmcnt(0)
	v_fma_f32 v6, v60, v2, -v4
	v_fma_f32 v7, v44, v2, -v5
	ds_read2st64_b32 v[4:5], v70 offset0:40 offset1:56
	v_mul_f32_e32 v8, v7, v7
	v_fmac_f32_e32 v8, v6, v6
	s_waitcnt lgkmcnt(0)
	v_fma_f32 v9, v28, v2, -v4
	v_fmac_f32_e32 v8, v9, v9
	v_fma_f32 v2, v12, v2, -v5
	v_fmac_f32_e32 v8, v2, v2
	ds_swizzle_b32 v4, v8 offset:swizzle(SWAP,1)
	s_waitcnt lgkmcnt(0)
	v_add_f32_e32 v4, v8, v4
	ds_swizzle_b32 v5, v4 offset:swizzle(SWAP,2)
	s_waitcnt lgkmcnt(0)
	v_add_f32_e32 v4, v4, v5
	ds_swizzle_b32 v5, v4 offset:swizzle(SWAP,4)
	s_waitcnt lgkmcnt(0)
	v_add_f32_e32 v4, v4, v5
	ds_swizzle_b32 v5, v4 offset:swizzle(SWAP,8)
	s_waitcnt lgkmcnt(0)
	v_add_f32_e32 v4, v4, v5
	ds_swizzle_b32 v5, v4 offset:swizzle(SWAP,16)
	s_waitcnt lgkmcnt(0)
	v_add_f32_e32 v4, v4, v5
	v_fmamk_f32 v4, v4, 0x3c000000, v254
	s_nop 0
	s_nop 0
	s_nop 0
	s_nop 1
	s_nop 1
	s_nop 0
	v_rsq_f32_e32 v8, v4
	s_nop 0
	v_mul_f32_e32 v5, v6, v8
	v_mul_f32_e32 v6, v7, v8
	v_mul_f32_e32 v5, v72, v5
	v_mul_f32_e32 v6, v74, v6
	v_add_u32_e32 v4, 0x10000, v68
	v_cvt_pk_bf16_f32 v6, v5, v6
	v_mov_b32_e32 v5, v3
	v_lshl_add_u64 v[4:5], v[4:5], 1, s[6:7]
	global_store_short v[4:5], v6, off
	v_add_u32_e32 v4, 0x10020, v68
	v_mov_b32_e32 v5, v3
	v_lshl_add_u64 v[4:5], v[4:5], 1, s[6:7]
	global_store_short_d16_hi v[4:5], v6, off
	v_mul_f32_e32 v4, v9, v8
	v_mul_f32_e32 v2, v2, v8
	v_mul_f32_e32 v4, v71, v4
	v_mul_f32_e32 v2, v73, v2
	v_cvt_pk_bf16_f32 v2, v4, v2
	v_add_u32_e32 v4, 0x10040, v68
	v_mov_b32_e32 v5, v3
	v_lshl_add_u64 v[4:5], v[4:5], 1, s[6:7]
	global_store_short v[4:5], v2, off
	v_add_u32_e32 v4, 0x10060, v68
	v_mov_b32_e32 v5, v3
	v_lshl_add_u64 v[4:5], v[4:5], 1, s[6:7]
	global_store_short_d16_hi v[4:5], v2, off
	ds_read_b32 v2, v1 offset:68
	ds_read2st64_b32 v[4:5], v70 offset0:9 offset1:25
	s_waitcnt lgkmcnt(0)
	v_fma_f32 v6, v61, v2, -v4
	v_fma_f32 v7, v45, v2, -v5
	ds_read2st64_b32 v[4:5], v70 offset0:41 offset1:57
	v_mul_f32_e32 v8, v7, v7
	v_fmac_f32_e32 v8, v6, v6
	s_waitcnt lgkmcnt(0)
	v_fma_f32 v9, v29, v2, -v4
	v_fmac_f32_e32 v8, v9, v9
	v_fma_f32 v2, v13, v2, -v5
	v_fmac_f32_e32 v8, v2, v2
	ds_swizzle_b32 v4, v8 offset:swizzle(SWAP,1)
	s_waitcnt lgkmcnt(0)
	v_add_f32_e32 v4, v8, v4
	ds_swizzle_b32 v5, v4 offset:swizzle(SWAP,2)
	s_waitcnt lgkmcnt(0)
	v_add_f32_e32 v4, v4, v5
	ds_swizzle_b32 v5, v4 offset:swizzle(SWAP,4)
	s_waitcnt lgkmcnt(0)
	v_add_f32_e32 v4, v4, v5
	ds_swizzle_b32 v5, v4 offset:swizzle(SWAP,8)
	s_waitcnt lgkmcnt(0)
	v_add_f32_e32 v4, v4, v5
	ds_swizzle_b32 v5, v4 offset:swizzle(SWAP,16)
	s_waitcnt lgkmcnt(0)
	v_add_f32_e32 v4, v4, v5
	v_fmamk_f32 v4, v4, 0x3c000000, v254
	s_nop 0
	s_nop 0
	s_nop 0
	s_nop 1
	s_nop 1
	s_nop 0
	v_rsq_f32_e32 v8, v4
	s_nop 0
	v_mul_f32_e32 v5, v6, v8
	v_mul_f32_e32 v6, v7, v8
	v_mul_f32_e32 v5, v72, v5
	v_mul_f32_e32 v6, v74, v6
	v_add_u32_e32 v4, 0x11000, v68
	v_cvt_pk_bf16_f32 v6, v5, v6
	v_mov_b32_e32 v5, v3
	v_lshl_add_u64 v[4:5], v[4:5], 1, s[6:7]
	global_store_short v[4:5], v6, off
	v_add_u32_e32 v4, 0x11020, v68
	v_mov_b32_e32 v5, v3
	v_lshl_add_u64 v[4:5], v[4:5], 1, s[6:7]
	global_store_short_d16_hi v[4:5], v6, off
	v_mul_f32_e32 v4, v9, v8
	v_mul_f32_e32 v2, v2, v8
	v_mul_f32_e32 v4, v71, v4
	v_mul_f32_e32 v2, v73, v2
	v_cvt_pk_bf16_f32 v2, v4, v2
	v_add_u32_e32 v4, 0x11040, v68
	v_mov_b32_e32 v5, v3
	v_lshl_add_u64 v[4:5], v[4:5], 1, s[6:7]
	global_store_short v[4:5], v2, off
	v_add_u32_e32 v4, 0x11060, v68
	v_mov_b32_e32 v5, v3
	v_lshl_add_u64 v[4:5], v[4:5], 1, s[6:7]
	global_store_short_d16_hi v[4:5], v2, off
	ds_read_b32 v2, v1 offset:72
	ds_read2st64_b32 v[4:5], v70 offset0:10 offset1:26
	s_waitcnt lgkmcnt(0)
	v_fma_f32 v6, v62, v2, -v4
	v_fma_f32 v7, v46, v2, -v5
	ds_read2st64_b32 v[4:5], v70 offset0:42 offset1:58
	v_mul_f32_e32 v8, v7, v7
	v_fmac_f32_e32 v8, v6, v6
	s_waitcnt lgkmcnt(0)
	v_fma_f32 v9, v30, v2, -v4
	v_fmac_f32_e32 v8, v9, v9
	v_fma_f32 v2, v14, v2, -v5
	v_fmac_f32_e32 v8, v2, v2
	ds_swizzle_b32 v4, v8 offset:swizzle(SWAP,1)
	s_waitcnt lgkmcnt(0)
	v_add_f32_e32 v4, v8, v4
	ds_swizzle_b32 v5, v4 offset:swizzle(SWAP,2)
	s_waitcnt lgkmcnt(0)
	v_add_f32_e32 v4, v4, v5
	ds_swizzle_b32 v5, v4 offset:swizzle(SWAP,4)
	s_waitcnt lgkmcnt(0)
	v_add_f32_e32 v4, v4, v5
	ds_swizzle_b32 v5, v4 offset:swizzle(SWAP,8)
	s_waitcnt lgkmcnt(0)
	v_add_f32_e32 v4, v4, v5
	ds_swizzle_b32 v5, v4 offset:swizzle(SWAP,16)
	s_waitcnt lgkmcnt(0)
	v_add_f32_e32 v4, v4, v5
	v_fmamk_f32 v4, v4, 0x3c000000, v254
	s_nop 0
	s_nop 0
	s_nop 0
	s_nop 1
	s_nop 1
	s_nop 0
	v_rsq_f32_e32 v8, v4
	s_nop 0
	v_mul_f32_e32 v5, v6, v8
	v_mul_f32_e32 v6, v7, v8
	v_mul_f32_e32 v5, v72, v5
	v_mul_f32_e32 v6, v74, v6
	v_add_u32_e32 v4, 0x12000, v68
	v_cvt_pk_bf16_f32 v6, v5, v6
	v_mov_b32_e32 v5, v3
	v_lshl_add_u64 v[4:5], v[4:5], 1, s[6:7]
	global_store_short v[4:5], v6, off
	v_add_u32_e32 v4, 0x12020, v68
	v_mov_b32_e32 v5, v3
	v_lshl_add_u64 v[4:5], v[4:5], 1, s[6:7]
	global_store_short_d16_hi v[4:5], v6, off
	v_mul_f32_e32 v4, v9, v8
	v_mul_f32_e32 v2, v2, v8
	v_mul_f32_e32 v4, v71, v4
	v_mul_f32_e32 v2, v73, v2
	v_cvt_pk_bf16_f32 v2, v4, v2
	v_add_u32_e32 v4, 0x12040, v68
	v_mov_b32_e32 v5, v3
	v_lshl_add_u64 v[4:5], v[4:5], 1, s[6:7]
	global_store_short v[4:5], v2, off
	v_add_u32_e32 v4, 0x12060, v68
	v_mov_b32_e32 v5, v3
	v_lshl_add_u64 v[4:5], v[4:5], 1, s[6:7]
	global_store_short_d16_hi v[4:5], v2, off
	ds_read_b32 v2, v1 offset:76
	ds_read2st64_b32 v[4:5], v70 offset0:11 offset1:27
	s_waitcnt lgkmcnt(0)
	v_fma_f32 v6, v63, v2, -v4
	v_fma_f32 v7, v47, v2, -v5
	ds_read2st64_b32 v[4:5], v70 offset0:43 offset1:59
	v_mul_f32_e32 v8, v7, v7
	v_fmac_f32_e32 v8, v6, v6
	s_waitcnt lgkmcnt(0)
	v_fma_f32 v9, v31, v2, -v4
	v_fmac_f32_e32 v8, v9, v9
	v_fma_f32 v2, v15, v2, -v5
	v_fmac_f32_e32 v8, v2, v2
	ds_swizzle_b32 v4, v8 offset:swizzle(SWAP,1)
	s_waitcnt lgkmcnt(0)
	v_add_f32_e32 v4, v8, v4
	ds_swizzle_b32 v5, v4 offset:swizzle(SWAP,2)
	s_waitcnt lgkmcnt(0)
	v_add_f32_e32 v4, v4, v5
	ds_swizzle_b32 v5, v4 offset:swizzle(SWAP,4)
	s_waitcnt lgkmcnt(0)
	v_add_f32_e32 v4, v4, v5
	ds_swizzle_b32 v5, v4 offset:swizzle(SWAP,8)
	s_waitcnt lgkmcnt(0)
	v_add_f32_e32 v4, v4, v5
	ds_swizzle_b32 v5, v4 offset:swizzle(SWAP,16)
	s_waitcnt lgkmcnt(0)
	v_add_f32_e32 v4, v4, v5
	v_fmamk_f32 v4, v4, 0x3c000000, v254
	s_nop 0
	s_nop 0
	s_nop 0
	s_nop 1
	s_nop 1
	s_nop 0
	v_rsq_f32_e32 v8, v4
	s_nop 0
	v_mul_f32_e32 v5, v6, v8
	v_mul_f32_e32 v6, v7, v8
	v_mul_f32_e32 v5, v72, v5
	v_mul_f32_e32 v6, v74, v6
	v_add_u32_e32 v4, 0x13000, v68
	v_cvt_pk_bf16_f32 v6, v5, v6
	v_mov_b32_e32 v5, v3
	v_lshl_add_u64 v[4:5], v[4:5], 1, s[6:7]
	global_store_short v[4:5], v6, off
	v_add_u32_e32 v4, 0x13020, v68
	v_mov_b32_e32 v5, v3
	v_lshl_add_u64 v[4:5], v[4:5], 1, s[6:7]
	global_store_short_d16_hi v[4:5], v6, off
	v_mul_f32_e32 v4, v9, v8
	v_mul_f32_e32 v2, v2, v8
	v_mul_f32_e32 v4, v71, v4
	v_mul_f32_e32 v2, v73, v2
	v_cvt_pk_bf16_f32 v2, v4, v2
	v_add_u32_e32 v4, 0x13040, v68
	v_mov_b32_e32 v5, v3
	v_lshl_add_u64 v[4:5], v[4:5], 1, s[6:7]
	global_store_short v[4:5], v2, off
	v_add_u32_e32 v4, 0x13060, v68
	v_mov_b32_e32 v5, v3
	v_lshl_add_u64 v[4:5], v[4:5], 1, s[6:7]
	global_store_short_d16_hi v[4:5], v2, off
	ds_read_b32 v2, v1 offset:96
	ds_read2st64_b32 v[4:5], v70 offset0:12 offset1:28
	s_waitcnt lgkmcnt(0)
	v_fma_f32 v6, v64, v2, -v4
	v_fma_f32 v7, v48, v2, -v5
	ds_read2st64_b32 v[4:5], v70 offset0:44 offset1:60
	v_mul_f32_e32 v8, v7, v7
	v_fmac_f32_e32 v8, v6, v6
	s_waitcnt lgkmcnt(0)
	v_fma_f32 v9, v32, v2, -v4
	v_fmac_f32_e32 v8, v9, v9
	v_fma_f32 v2, v16, v2, -v5
	v_fmac_f32_e32 v8, v2, v2
	ds_swizzle_b32 v4, v8 offset:swizzle(SWAP,1)
	s_waitcnt lgkmcnt(0)
	v_add_f32_e32 v4, v8, v4
	ds_swizzle_b32 v5, v4 offset:swizzle(SWAP,2)
	s_waitcnt lgkmcnt(0)
	v_add_f32_e32 v4, v4, v5
	ds_swizzle_b32 v5, v4 offset:swizzle(SWAP,4)
	s_waitcnt lgkmcnt(0)
	v_add_f32_e32 v4, v4, v5
	ds_swizzle_b32 v5, v4 offset:swizzle(SWAP,8)
	s_waitcnt lgkmcnt(0)
	v_add_f32_e32 v4, v4, v5
	ds_swizzle_b32 v5, v4 offset:swizzle(SWAP,16)
	s_waitcnt lgkmcnt(0)
	v_add_f32_e32 v4, v4, v5
	v_fmamk_f32 v4, v4, 0x3c000000, v254
	s_nop 0
	s_nop 0
	s_nop 0
	s_nop 1
	s_nop 1
	s_nop 0
	v_rsq_f32_e32 v8, v4
	s_nop 0
	v_mul_f32_e32 v5, v6, v8
	v_mul_f32_e32 v6, v7, v8
	v_mul_f32_e32 v5, v72, v5
	v_mul_f32_e32 v6, v74, v6
	v_add_u32_e32 v4, 0x18000, v68
	v_cvt_pk_bf16_f32 v6, v5, v6
	v_mov_b32_e32 v5, v3
	v_lshl_add_u64 v[4:5], v[4:5], 1, s[6:7]
	global_store_short v[4:5], v6, off
	v_add_u32_e32 v4, 0x18020, v68
	v_mov_b32_e32 v5, v3
	v_lshl_add_u64 v[4:5], v[4:5], 1, s[6:7]
	global_store_short_d16_hi v[4:5], v6, off
	v_mul_f32_e32 v4, v9, v8
	v_mul_f32_e32 v2, v2, v8
	v_mul_f32_e32 v4, v71, v4
	v_mul_f32_e32 v2, v73, v2
	v_cvt_pk_bf16_f32 v2, v4, v2
	v_add_u32_e32 v4, 0x18040, v68
	v_mov_b32_e32 v5, v3
	v_lshl_add_u64 v[4:5], v[4:5], 1, s[6:7]
	global_store_short v[4:5], v2, off
	v_add_u32_e32 v4, 0x18060, v68
	v_mov_b32_e32 v5, v3
	v_lshl_add_u64 v[4:5], v[4:5], 1, s[6:7]
	global_store_short_d16_hi v[4:5], v2, off
	ds_read_b32 v2, v1 offset:100
	ds_read2st64_b32 v[4:5], v70 offset0:13 offset1:29
	s_waitcnt lgkmcnt(0)
	v_fma_f32 v6, v65, v2, -v4
	v_fma_f32 v7, v49, v2, -v5
	ds_read2st64_b32 v[4:5], v70 offset0:45 offset1:61
	v_mul_f32_e32 v8, v7, v7
	v_fmac_f32_e32 v8, v6, v6
	s_waitcnt lgkmcnt(0)
	v_fma_f32 v9, v33, v2, -v4
	v_fmac_f32_e32 v8, v9, v9
	v_fma_f32 v2, v17, v2, -v5
	v_fmac_f32_e32 v8, v2, v2
	ds_swizzle_b32 v4, v8 offset:swizzle(SWAP,1)
	s_waitcnt lgkmcnt(0)
	v_add_f32_e32 v4, v8, v4
	ds_swizzle_b32 v5, v4 offset:swizzle(SWAP,2)
	s_waitcnt lgkmcnt(0)
	v_add_f32_e32 v4, v4, v5
	ds_swizzle_b32 v5, v4 offset:swizzle(SWAP,4)
	s_waitcnt lgkmcnt(0)
	v_add_f32_e32 v4, v4, v5
	ds_swizzle_b32 v5, v4 offset:swizzle(SWAP,8)
	s_waitcnt lgkmcnt(0)
	v_add_f32_e32 v4, v4, v5
	ds_swizzle_b32 v5, v4 offset:swizzle(SWAP,16)
	s_waitcnt lgkmcnt(0)
	v_add_f32_e32 v4, v4, v5
	v_fmamk_f32 v4, v4, 0x3c000000, v254
	s_nop 0
	s_nop 0
	s_nop 0
	s_nop 1
	s_nop 1
	s_nop 0
	v_rsq_f32_e32 v8, v4
	s_nop 0
	v_mul_f32_e32 v5, v6, v8
	v_mul_f32_e32 v6, v7, v8
	v_mul_f32_e32 v5, v72, v5
	v_mul_f32_e32 v6, v74, v6
	v_add_u32_e32 v4, 0x19000, v68
	v_cvt_pk_bf16_f32 v6, v5, v6
	v_mov_b32_e32 v5, v3
	v_lshl_add_u64 v[4:5], v[4:5], 1, s[6:7]
	global_store_short v[4:5], v6, off
	v_add_u32_e32 v4, 0x19020, v68
	v_mov_b32_e32 v5, v3
	v_lshl_add_u64 v[4:5], v[4:5], 1, s[6:7]
	global_store_short_d16_hi v[4:5], v6, off
	v_mul_f32_e32 v4, v9, v8
	v_mul_f32_e32 v2, v2, v8
	v_mul_f32_e32 v4, v71, v4
	v_mul_f32_e32 v2, v73, v2
	v_cvt_pk_bf16_f32 v2, v4, v2
	v_add_u32_e32 v4, 0x19040, v68
	v_mov_b32_e32 v5, v3
	v_lshl_add_u64 v[4:5], v[4:5], 1, s[6:7]
	global_store_short v[4:5], v2, off
	v_add_u32_e32 v4, 0x19060, v68
	v_mov_b32_e32 v5, v3
	v_lshl_add_u64 v[4:5], v[4:5], 1, s[6:7]
	global_store_short_d16_hi v[4:5], v2, off
	ds_read_b32 v2, v1 offset:104
	ds_read2st64_b32 v[4:5], v70 offset0:14 offset1:30
	s_waitcnt lgkmcnt(0)
	v_fma_f32 v6, v66, v2, -v4
	v_fma_f32 v7, v50, v2, -v5
	ds_read2st64_b32 v[4:5], v70 offset0:46 offset1:62
	v_mul_f32_e32 v8, v7, v7
	v_fmac_f32_e32 v8, v6, v6
	s_waitcnt lgkmcnt(0)
	v_fma_f32 v9, v34, v2, -v4
	v_fmac_f32_e32 v8, v9, v9
	v_fma_f32 v2, v18, v2, -v5
	v_fmac_f32_e32 v8, v2, v2
	ds_swizzle_b32 v4, v8 offset:swizzle(SWAP,1)
	s_waitcnt lgkmcnt(0)
	v_add_f32_e32 v4, v8, v4
	ds_swizzle_b32 v5, v4 offset:swizzle(SWAP,2)
	s_waitcnt lgkmcnt(0)
	v_add_f32_e32 v4, v4, v5
	ds_swizzle_b32 v5, v4 offset:swizzle(SWAP,4)
	s_waitcnt lgkmcnt(0)
	v_add_f32_e32 v4, v4, v5
	ds_swizzle_b32 v5, v4 offset:swizzle(SWAP,8)
	s_waitcnt lgkmcnt(0)
	v_add_f32_e32 v4, v4, v5
	ds_swizzle_b32 v5, v4 offset:swizzle(SWAP,16)
	s_waitcnt lgkmcnt(0)
	v_add_f32_e32 v4, v4, v5
	v_fmamk_f32 v4, v4, 0x3c000000, v254
	v_cmp_gt_f32_e32 vcc, s90, v4
	v_mul_f32_e32 v5, 0x4f800000, v4
	s_nop 0
	v_cndmask_b32_e32 v4, v4, v5, vcc
	v_sqrt_f32_e32 v5, v4
	s_nop 0
	v_add_u32_e32 v8, -1, v5
	v_fma_f32 v10, -v8, v5, v4
	v_cmp_ge_f32_e64 s[4:5], 0, v10
	v_add_u32_e32 v10, 1, v5
	s_nop 0
	v_cndmask_b32_e64 v8, v5, v8, s[4:5]
	v_fma_f32 v5, -v10, v5, v4
	v_cmp_lt_f32_e64 s[4:5], 0, v5
	s_nop 1
	v_cndmask_b32_e64 v5, v8, v10, s[4:5]
	v_mul_f32_e32 v8, 0x37800000, v5
	v_cndmask_b32_e32 v5, v5, v8, vcc
	v_cmp_class_f32_e32 vcc, v4, v209
	s_nop 1
	v_cndmask_b32_e32 v4, v5, v4, vcc
	v_div_scale_f32 v5, s[4:5], v4, v4, 1.0
	v_rcp_f32_e32 v8, v5
	s_nop 0
	v_fma_f32 v10, -v5, v8, 1.0
	v_fmac_f32_e32 v8, v10, v8
	v_div_scale_f32 v10, vcc, 1.0, v4, 1.0
	v_mul_f32_e32 v11, v10, v8
	v_fma_f32 v12, -v5, v11, v10
	v_fmac_f32_e32 v11, v12, v8
	v_fma_f32 v5, -v5, v11, v10
	v_div_fmas_f32 v5, v5, v8, v11
	v_div_fixup_f32 v8, v5, v4, 1.0
	v_mul_f32_e32 v5, v6, v8
	v_mul_f32_e32 v6, v7, v8
	v_mul_f32_e32 v5, v72, v5
	v_mul_f32_e32 v6, v74, v6
	v_add_u32_e32 v4, 0x1a000, v68
	v_cvt_pk_bf16_f32 v6, v5, v6
	v_mov_b32_e32 v5, v3
	v_lshl_add_u64 v[4:5], v[4:5], 1, s[6:7]
	global_store_short v[4:5], v6, off
	v_add_u32_e32 v4, 0x1a020, v68
	v_mov_b32_e32 v5, v3
	v_lshl_add_u64 v[4:5], v[4:5], 1, s[6:7]
	global_store_short_d16_hi v[4:5], v6, off
	v_mul_f32_e32 v4, v9, v8
	v_mul_f32_e32 v2, v2, v8
	v_mul_f32_e32 v4, v71, v4
	v_mul_f32_e32 v2, v73, v2
	v_cvt_pk_bf16_f32 v2, v4, v2
	v_add_u32_e32 v4, 0x1a040, v68
	v_mov_b32_e32 v5, v3
	v_lshl_add_u64 v[4:5], v[4:5], 1, s[6:7]
	global_store_short v[4:5], v2, off
	v_add_u32_e32 v4, 0x1a060, v68
	v_mov_b32_e32 v5, v3
	v_lshl_add_u64 v[4:5], v[4:5], 1, s[6:7]
	global_store_short_d16_hi v[4:5], v2, off
	ds_read_b32 v1, v1 offset:108
	ds_read2st64_b32 v[4:5], v70 offset0:15 offset1:31
	s_waitcnt lgkmcnt(0)
	v_fma_f32 v2, v67, v1, -v4
	v_fma_f32 v6, v51, v1, -v5
	ds_read2st64_b32 v[4:5], v70 offset0:47 offset1:63
	v_mul_f32_e32 v7, v6, v6
	v_fmac_f32_e32 v7, v2, v2
	s_waitcnt lgkmcnt(0)
	v_fma_f32 v8, v35, v1, -v4
	v_fmac_f32_e32 v7, v8, v8
	v_fma_f32 v1, v19, v1, -v5
	v_fmac_f32_e32 v7, v1, v1
	ds_swizzle_b32 v4, v7 offset:swizzle(SWAP,1)
	s_waitcnt lgkmcnt(0)
	v_add_f32_e32 v4, v7, v4
	ds_swizzle_b32 v5, v4 offset:swizzle(SWAP,2)
	s_waitcnt lgkmcnt(0)
	v_add_f32_e32 v4, v4, v5
	ds_swizzle_b32 v5, v4 offset:swizzle(SWAP,4)
	s_waitcnt lgkmcnt(0)
	v_add_f32_e32 v4, v4, v5
	ds_swizzle_b32 v5, v4 offset:swizzle(SWAP,8)
	s_waitcnt lgkmcnt(0)
	v_add_f32_e32 v4, v4, v5
	ds_swizzle_b32 v5, v4 offset:swizzle(SWAP,16)
	s_waitcnt lgkmcnt(0)
	v_add_f32_e32 v4, v4, v5
	v_fmamk_f32 v4, v4, 0x3c000000, v254
	v_cmp_gt_f32_e32 vcc, s90, v4
	v_mul_f32_e32 v5, 0x4f800000, v4
	s_nop 0
	v_cndmask_b32_e32 v4, v4, v5, vcc
	v_sqrt_f32_e32 v5, v4
	s_nop 0
	v_add_u32_e32 v7, -1, v5
	v_fma_f32 v9, -v7, v5, v4
	v_cmp_ge_f32_e64 s[4:5], 0, v9
	v_add_u32_e32 v9, 1, v5
	s_nop 0
	v_cndmask_b32_e64 v7, v5, v7, s[4:5]
	v_fma_f32 v5, -v9, v5, v4
	v_cmp_lt_f32_e64 s[4:5], 0, v5
	s_nop 1
	v_cndmask_b32_e64 v5, v7, v9, s[4:5]
	v_mul_f32_e32 v7, 0x37800000, v5
	v_cndmask_b32_e32 v5, v5, v7, vcc
	v_cmp_class_f32_e32 vcc, v4, v209
	s_nop 1
	v_cndmask_b32_e32 v4, v5, v4, vcc
	v_div_scale_f32 v5, s[4:5], v4, v4, 1.0
	v_rcp_f32_e32 v7, v5
	s_nop 0
	v_fma_f32 v9, -v5, v7, 1.0
	v_fmac_f32_e32 v7, v9, v7
	v_div_scale_f32 v9, vcc, 1.0, v4, 1.0
	v_mul_f32_e32 v10, v9, v7
	v_fma_f32 v11, -v5, v10, v9
	v_fmac_f32_e32 v10, v11, v7
	v_fma_f32 v5, -v5, v10, v9
	v_div_fmas_f32 v5, v5, v7, v10
	v_div_fixup_f32 v7, v5, v4, 1.0
	v_mul_f32_e32 v2, v2, v7
	v_mul_f32_e32 v5, v6, v7
	v_mul_f32_e32 v2, v72, v2
	v_mul_f32_e32 v5, v74, v5
	v_add_u32_e32 v4, 0x1b000, v68
	v_cvt_pk_bf16_f32 v2, v2, v5
	v_mov_b32_e32 v5, v3
	v_lshl_add_u64 v[4:5], v[4:5], 1, s[6:7]
	global_store_short v[4:5], v2, off
	v_add_u32_e32 v4, 0x1b020, v68
	v_mov_b32_e32 v5, v3
	v_lshl_add_u64 v[4:5], v[4:5], 1, s[6:7]
	global_store_short_d16_hi v[4:5], v2, off
	v_mul_f32_e32 v1, v1, v7
	v_add_u32_e32 v4, 0x1b040, v68
	v_mov_b32_e32 v5, v3
	v_mul_f32_e32 v2, v8, v7
	v_mul_f32_e32 v1, v73, v1
	v_lshl_add_u64 v[4:5], v[4:5], 1, s[6:7]
	v_mul_f32_e32 v2, v71, v2
	v_cvt_pk_bf16_f32 v1, v2, v1
	global_store_short v[4:5], v1, off
	v_add_u32_e32 v4, 0x1b060, v68
	v_mov_b32_e32 v5, v3
	v_lshl_add_u64 v[4:5], v[4:5], 1, s[6:7]
	global_store_short_d16_hi v[4:5], v1, off

.LBB0_1588:
	s_or_b64 exec, exec, s[4:5]
	v_readlane_b32 s4, v255, 7
	s_waitcnt lgkmcnt(0)
	s_barrier
	v_mov_b32_e32 v1, s4
	ds_read_b32 v1, v1
	s_mov_b64 s[4:5], -1
	s_waitcnt lgkmcnt(0)
	v_readfirstlane_b32 s40, v1
	s_cmp_lg_u64 s[72:73], 0
	s_cbranch_scc1 .Ltick_noremap
	s_cmp_gt_u32 s40, 88
	s_cbranch_scc1 .Ltick_noremap
	s_add_i32 s6, s40, 64
	s_add_i32 s7, s40, -25
	s_cmp_lt_u32 s40, 25
	s_cselect_b32 s40, s6, s7
.Ltick_noremap:
	s_cmp_lt_i32 s40, 32
	s_cbranch_scc0 .LBB0_1659
	v_mov_b32_e32 v1, v0
	s_sub_i32 s4, 31, s40
	v_readfirstlane_b32 s41, v1
	s_ashr_i32 s60, s41, 6
	s_lshl_b32 s5, s4, 7
	s_lshl_b32 s43, s4, 1
	s_lshl_b32 s4, s60, 12
	s_lshl_b32 s26, s60, 1
	s_add_i32 s4, s4, 0
	s_ashr_i32 s48, s41, 8
	s_and_b32 s49, s60, 3
	s_and_b32 s6, s41, 0x3fffffc0
	s_lshl_b32 s7, s60, 2
	s_and_b32 s68, s26, 4
	s_and_b32 s69, s41, 64
	s_add_i32 s52, s43, 2
	s_add_i32 s28, s4, 0x18000
	s_add_u32 s4, s74, s5
	s_addc_u32 s27, s75, 0
	s_lshl_b32 s5, s49, 5
	v_and_b32_e32 v158, 31, v1
	s_or_b32 s26, s4, s5
	v_or_b32_e32 v4, s26, v158
	v_mov_b32_e32 v5, s27
	v_lshlrev_b64 v[4:5], 13, v[4:5]
	s_lshl_b32 s4, s48, 6
	v_bfe_u32 v159, v1, 5, 1
	v_lshl_add_u64 v[4:5], s[44:45], 0, v[4:5]
	s_ashr_i32 s5, s4, 31
	v_lshl_add_u64 v[4:5], s[4:5], 1, v[4:5]
	v_lshlrev_b32_e32 v148, 4, v159
	v_mov_b32_e32 v149, v3
	v_lshl_add_u64 v[16:17], v[4:5], 0, v[148:149]
	global_load_dwordx4 v[4:7], v[16:17], off offset:768
	global_load_dwordx4 v[8:11], v[16:17], off offset:800
	global_load_dwordx4 v[12:15], v[16:17], off offset:832
	s_nop 0
	global_load_dwordx4 v[16:19], v[16:17], off offset:864
	v_bfe_u32 v169, v1, 4, 2
	v_lshrrev_b32_e32 v22, 1, v1
	v_and_b32_e32 v149, 63, v1
	v_and_b32_e32 v2, 15, v1
	v_and_b32_e32 v171, 8, v22
	v_or_b32_e32 v22, s7, v169
	v_lshlrev_b32_e32 v30, 3, v149
	v_bitop3_b32 v2, v22, v2, 15 bitop3:0x6c
	v_and_b32_e32 v170, 32, v1
	v_bfe_u32 v20, v1, 2, 4
	v_lshlrev_b32_e32 v31, 4, v149
	v_and_b32_e32 v172, 24, v30
	v_lshlrev_b32_e32 v173, 4, v2
	v_bitop3_b32 v174, s7, v252, v20 bitop3:0xc8
	v_or3_b32 v20, v170, s69, v172
	v_add_u32_e32 v161, s28, v31
	v_lshl_or_b32 v2, v22, 13, v173
	s_lshl_b32 s4, s60, 10
	v_or3_b32 v23, v171, v174, s68
	v_lshlrev_b32_e32 v20, 1, v20
	v_lshl_add_u64 v[24:25], s[82:83], 0, v[2:3]
	s_add_i32 s53, s4, 0
	s_mov_b64 s[4:5], 0x300
	v_mov_b32_e32 v21, v3
	v_lshl_or_b32 v20, v23, 13, v20
	s_mov_b64 s[28:29], 0x40300
	v_lshl_add_u64 v[28:29], v[24:25], 0, s[4:5]
	s_mov_b32 m0, s53
	v_lshl_add_u64 v[22:23], s[58:59], 0, v[20:21]
	v_lshl_add_u64 v[24:25], v[24:25], 0, s[28:29]
	v_lshl_add_u64 v[26:27], v[22:23], 0, s[4:5]
	v_lshl_add_u64 v[22:23], v[22:23], 0, s[28:29]
	s_lshl_b32 s4, s6, 2
	s_add_i32 s46, s4, 0
	s_add_i32 s46, s46, 0x20400
	v_lshl_add_u64 v[156:157], s[50:51], 0, v[2:3]
	v_lshlrev_b32_e32 v167, 8, v158
	v_lshl_add_u64 v[152:153], s[2:3], 0, v[20:21]
	v_lshl_add_u64 v[154:155], v[156:157], 0, s[54:55]
	v_lshl_add_u64 v[150:151], v[152:153], 0, s[54:55]
	s_waitcnt vmcnt(3)
	ds_write_b128 v161, v[4:7]
	s_waitcnt vmcnt(2)
	ds_write_b128 v161, v[8:11] offset:1024
	s_waitcnt vmcnt(1)
	ds_write_b128 v161, v[12:15] offset:2048
	s_waitcnt vmcnt(0)
	ds_write_b128 v161, v[16:19] offset:3072
	s_waitcnt vmcnt(0)
	global_load_lds_dwordx4 v[28:29], off
	s_add_i32 m0, s53, 0x2000
	v_lshlrev_b32_e32 v4, 1, v1
	global_load_lds_dwordx4 v[24:25], off
	s_add_i32 m0, s53, 0x4000
	v_and_b32_e32 v4, 32, v4
	global_load_lds_dwordx4 v[26:27], off
	s_add_i32 m0, s53, 0x6000
	s_cmp_lt_u32 s49, 2
	global_load_lds_dwordx4 v[22:23], off
	s_cselect_b64 s[4:5], -1, 0
	s_lshl_b32 s6, s48, 7
	s_add_i32 s42, s6, 0
	s_xor_b32 s6, s48, s60
	s_bitcmp1_b32 s6, 0
	s_cselect_b64 s[28:29], -1, 0
	v_lshlrev_b32_e32 v1, 4, v1
	v_and_or_b32 v4, v31, s91, v4
	v_and_b32_e32 v5, 0x100, v30
	v_and_b32_e32 v2, 0x70, v1
	s_movk_i32 s6, 0x70
	s_and_b64 vcc, exec, s[28:29]
	s_movk_i32 s28, 0x60
	v_or3_b32 v4, v4, v5, v172
	v_add_u32_e32 v168, s42, v167
	v_bitop3_b32 v166, v148, v1, s6 bitop3:0x78
	v_bitop3_b32 v165, v148, v2, 32 bitop3:0x36
	v_bitop3_b32 v163, v148, v2, 64 bitop3:0x36
	v_bitop3_b32 v162, v148, v2, s28 bitop3:0x36
	v_and_b32_e32 v240, 0x80, v1
	v_and_b32_e32 v241, s42, v240
	v_lshlrev_b32_e32 v241, 1, v241
	v_sub_u32_e32 v240, v240, v241
	v_add_u32_e32 v166, v166, v240
	v_add_u32_e32 v165, v165, v240
	v_add_u32_e32 v163, v163, v240
	v_add_u32_e32 v162, v162, v240
	v_add_u32_e32 v160, s88, v4
	s_mov_b64 s[6:7], -1
	v_add_u32_e32 v178, v168, v166
	v_add_u32_e32 v177, v168, v165
	v_add_u32_e32 v176, v168, v163
	v_add_u32_e32 v175, v168, v162
	s_cbranch_vccz .LBB0_1621
	s_waitcnt vmcnt(0)
	s_waitcnt lgkmcnt(0)
	s_barrier
	s_add_i32 m0, s53, 0x8000
	s_mov_b32 s70, 0
	global_load_lds_dwordx4 v[156:157], off
	s_add_i32 m0, s53, 0xa000
	s_nop 0
	global_load_lds_dwordx4 v[154:155], off
	s_add_i32 m0, s53, 0xc000
	s_nop 0
	global_load_lds_dwordx4 v[152:153], off
	s_add_i32 m0, s53, 0xe000
	s_cmp_eq_u32 s40, 31
	global_load_lds_dwordx4 v[150:151], off
	ds_read_b128 v[4:7], v161
	ds_read_b128 v[8:11], v178 offset:8192
	ds_read_b128 v[12:15], v178
	s_waitcnt lgkmcnt(0)
	v_mfma_f32_32x32x16_bf16 v[20:35], v[12:15], v[4:7], 0
	ds_read_b128 v[36:39], v161 offset:1024
	ds_read_b128 v[40:43], v177 offset:8192
	ds_read_b128 v[44:47], v177
	v_mfma_f32_32x32x16_bf16 v[4:19], v[8:11], v[4:7], 0
	s_waitcnt lgkmcnt(0)
	v_mfma_f32_32x32x16_bf16 v[20:35], v[44:47], v[36:39], v[20:35]
	v_mfma_f32_32x32x16_bf16 v[4:19], v[40:43], v[36:39], v[4:19]
	ds_read_b128 v[36:39], v161 offset:2048
	ds_read_b128 v[40:43], v176 offset:8192
	ds_read_b128 v[44:47], v176
	s_waitcnt lgkmcnt(0)
	v_mfma_f32_32x32x16_bf16 v[20:35], v[44:47], v[36:39], v[20:35]
	v_mfma_f32_32x32x16_bf16 v[4:19], v[40:43], v[36:39], v[4:19]
	ds_read_b128 v[36:39], v161 offset:3072
	ds_read_b128 v[40:43], v175 offset:8192
	ds_read_b128 v[44:47], v175
	s_waitcnt lgkmcnt(0)
	v_mfma_f32_32x32x16_bf16 v[20:35], v[44:47], v[36:39], v[20:35]
	v_mfma_f32_32x32x16_bf16 v[4:19], v[40:43], v[36:39], v[4:19]
	s_nop 10
	v_max_f32_e32 v1, v21, v21
	v_max_f32_e32 v2, v20, v20
	v_max_f32_e32 v1, v2, v1
	v_max3_f32 v1, v1, v22, v23
	v_max3_f32 v1, v1, v24, v25
	v_max3_f32 v1, v1, v26, v27
	v_max3_f32 v1, v1, v28, v29
	v_max3_f32 v1, v1, v30, v31
	v_max3_f32 v1, v1, v32, v33
	v_max3_f32 v1, v1, v34, v35
	v_max3_f32 v1, v1, v4, v5
	v_max3_f32 v1, v1, v6, v7
	v_max3_f32 v1, v1, v8, v9
	v_max3_f32 v1, v1, v10, v11
	v_max3_f32 v1, v1, v12, v13
	v_max3_f32 v1, v1, v14, v15
	v_max3_f32 v1, v1, v16, v17
	v_max3_f32 v1, v1, v18, v19
	v_mov_b32_e32 v2, v1
	s_nop 1
	v_permlane32_swap_b32_e32 v1, v2
	v_max_f32_e32 v2, v2, v2
	v_max_f32_e32 v1, v1, v1
	v_max_f32_e32 v180, v1, v2
	v_sub_f32_e32 v1, v20, v180
	v_sub_f32_e32 v2, v21, v180
	v_sub_f32_e32 v20, v22, v180
	v_sub_f32_e32 v21, v23, v180
	v_sub_f32_e32 v22, v24, v180
	v_sub_f32_e32 v23, v25, v180
	v_sub_f32_e32 v24, v26, v180
	v_sub_f32_e32 v25, v27, v180
	v_sub_f32_e32 v26, v28, v180
	v_sub_f32_e32 v27, v29, v180
	v_sub_f32_e32 v28, v30, v180
	v_sub_f32_e32 v29, v31, v180
	v_sub_f32_e32 v30, v32, v180
	v_sub_f32_e32 v31, v33, v180
	v_sub_f32_e32 v32, v34, v180
	v_sub_f32_e32 v33, v35, v180
	v_exp_f32_e32 v196, v1
	v_exp_f32_e32 v197, v2
	v_exp_f32_e32 v194, v20
	v_exp_f32_e32 v195, v21
	v_exp_f32_e32 v192, v22
	v_exp_f32_e32 v193, v23
	v_exp_f32_e32 v190, v24
	v_exp_f32_e32 v191, v25
	v_exp_f32_e32 v188, v26
	v_exp_f32_e32 v189, v27
	v_exp_f32_e32 v186, v28
	v_exp_f32_e32 v187, v29
	v_exp_f32_e32 v184, v30
	v_exp_f32_e32 v185, v31
	v_exp_f32_e32 v182, v32
	v_exp_f32_e32 v183, v33
	v_xor_b32_e32 v84, 0x80000000, v180
	v_mov_b32_e32 v85, v84
	v_mov_b32_e32 v86, v84
	v_mov_b32_e32 v87, v84
	v_mov_b32_e32 v88, v84
	v_mov_b32_e32 v89, v84
	v_mov_b32_e32 v90, v84
	v_mov_b32_e32 v91, v84
	v_mov_b32_e32 v92, v84
	v_mov_b32_e32 v93, v84
	v_mov_b32_e32 v94, v84
	v_mov_b32_e32 v95, v84
	v_mov_b32_e32 v96, v84
	v_mov_b32_e32 v97, v84
	v_mov_b32_e32 v98, v84
	v_mov_b32_e32 v99, v84
	v_sub_f32_e32 v83, v19, v180
	v_sub_f32_e32 v82, v18, v180
	v_sub_f32_e32 v81, v17, v180
	v_sub_f32_e32 v80, v16, v180
	v_sub_f32_e32 v79, v15, v180
	v_sub_f32_e32 v78, v14, v180
	v_sub_f32_e32 v77, v13, v180
	v_sub_f32_e32 v76, v12, v180
	v_sub_f32_e32 v75, v11, v180
	v_sub_f32_e32 v74, v10, v180
	v_sub_f32_e32 v73, v9, v180
	v_sub_f32_e32 v72, v8, v180
	v_sub_f32_e32 v71, v7, v180
	v_sub_f32_e32 v70, v6, v180
	v_sub_f32_e32 v69, v5, v180
	v_sub_f32_e32 v68, v4, v180
	s_cbranch_scc1 .LBB0_1609
	v_add_u32_e32 v4, s69, v170
	v_add3_u32 v2, v174, v171, s68
	v_add_lshl_u32 v4, v4, v172, 1
	v_lshl_or_b32 v2, v2, 13, v4
	s_lshl_b32 s28, s60, 15
	v_lshlrev_b32_e32 v4, 13, v169
	v_mov_b32_e32 v179, 0
	v_cmp_gt_u32_e64 s[6:7], 32, v149
	s_mov_b32 s71, 2
	v_lshl_add_u32 v1, v158, 2, s46
	v_or3_b32 v132, s28, v4, v173
	v_mov_b32_e32 v133, v3
	v_mov_b32_e32 v138, 1.0
	s_mov_b32 s30, 0
	s_mov_b64 s[28:29], s[24:25]
	v_mov_b32_e32 v20, 0
	v_mov_b32_e32 v21, v179
	v_mov_b32_e32 v22, v179
	v_mov_b32_e32 v23, v179
	v_mov_b32_e32 v24, v179
	v_mov_b32_e32 v25, v179
	v_mov_b32_e32 v26, v179
	v_mov_b32_e32 v27, v179
	v_mov_b32_e32 v28, v179
	v_mov_b32_e32 v29, v179
	v_mov_b32_e32 v30, v179
	v_mov_b32_e32 v31, v179
	v_mov_b32_e32 v32, v179
	v_mov_b32_e32 v33, v179
	v_mov_b32_e32 v34, v179
	v_mov_b32_e32 v35, v179
	v_mov_b32_e32 v36, 0
	v_mov_b32_e32 v37, v179
	v_mov_b32_e32 v38, v179
	v_mov_b32_e32 v39, v179
	v_mov_b32_e32 v40, v179
	v_mov_b32_e32 v41, v179
	v_mov_b32_e32 v42, v179
	v_mov_b32_e32 v43, v179
	v_mov_b32_e32 v44, v179
	v_mov_b32_e32 v45, v179
	v_mov_b32_e32 v46, v179
	v_mov_b32_e32 v47, v179
	v_mov_b32_e32 v48, v179
	v_mov_b32_e32 v49, v179
	v_mov_b32_e32 v50, v179
	v_mov_b32_e32 v51, v179
	v_mov_b32_e32 v52, 0
	v_mov_b32_e32 v53, v179
	v_mov_b32_e32 v54, v179
	v_mov_b32_e32 v55, v179
	v_mov_b32_e32 v56, v179
	v_mov_b32_e32 v57, v179
	v_mov_b32_e32 v58, v179
	v_mov_b32_e32 v59, v179
	v_mov_b32_e32 v60, v179
	v_mov_b32_e32 v61, v179
	v_mov_b32_e32 v62, v179
	v_mov_b32_e32 v63, v179
	v_mov_b32_e32 v64, v179
	v_mov_b32_e32 v65, v179
	v_mov_b32_e32 v66, v179
	v_mov_b32_e32 v67, v179
	v_mov_b32_e32 v4, 0
	v_mov_b32_e32 v5, v179
	v_mov_b32_e32 v6, v179
	v_mov_b32_e32 v7, v179
	v_mov_b32_e32 v8, v179
	v_mov_b32_e32 v9, v179
	v_mov_b32_e32 v10, v179
	v_mov_b32_e32 v11, v179
	v_mov_b32_e32 v12, v179
	v_mov_b32_e32 v13, v179
	v_mov_b32_e32 v14, v179
	v_mov_b32_e32 v15, v179
	v_mov_b32_e32 v16, v179
	v_mov_b32_e32 v17, v179
	v_mov_b32_e32 v18, v179
	v_mov_b32_e32 v19, v179

.LBB0_1657:
	s_or_b64 exec, exec, s[4:5]
	s_waitcnt lgkmcnt(0)
	v_lshlrev_b32_e32 v2, 2, v158
	global_load_dword v248, v2, s[0:1]
	global_load_dword v249, v2, s[0:1] offset:128
	global_load_dword v250, v2, s[0:1] offset:256
	global_load_dword v251, v2, s[0:1] offset:384
	v_add_u32_e32 v8, s46, v148
	s_lshl_b64 s[4:5], s[26:27], 13
	s_add_u32 s6, s86, s4
	s_addc_u32 s7, s87, s5
	s_waitcnt vmcnt(0)
	v_mul_f32_e32 v5, v164, v248
	v_mul_f32_e32 v7, v164, v249
	v_mul_f32_e32 v4, v164, v250
	v_mul_f32_e32 v6, v164, v251
	v_lshl_or_b32 v2, v159, 14, v158
	ds_read_b32 v9, v8
	ds_read2st64_b32 v[10:11], v1 offset1:16
	s_waitcnt lgkmcnt(0)
	v_fma_f32 v12, v68, v9, -v10
	v_fma_f32 v13, v100, v9, -v11
	ds_read2st64_b32 v[10:11], v1 offset0:32 offset1:48
	v_mul_f32_e32 v14, v13, v13
	v_fmac_f32_e32 v14, v12, v12
	s_waitcnt lgkmcnt(0)
	v_fma_f32 v15, v116, v9, -v10
	v_fmac_f32_e32 v14, v15, v15
	v_fma_f32 v9, v132, v9, -v11
	v_fmac_f32_e32 v14, v9, v9
	ds_swizzle_b32 v10, v14 offset:swizzle(SWAP,1)
	s_waitcnt lgkmcnt(0)
	v_add_f32_e32 v10, v14, v10
	ds_swizzle_b32 v11, v10 offset:swizzle(SWAP,2)
	s_waitcnt lgkmcnt(0)
	v_add_f32_e32 v10, v10, v11
	ds_swizzle_b32 v11, v10 offset:swizzle(SWAP,4)
	s_waitcnt lgkmcnt(0)
	v_add_f32_e32 v10, v10, v11
	ds_swizzle_b32 v11, v10 offset:swizzle(SWAP,8)
	s_waitcnt lgkmcnt(0)
	v_add_f32_e32 v10, v10, v11
	ds_swizzle_b32 v11, v10 offset:swizzle(SWAP,16)
	s_waitcnt lgkmcnt(0)
	v_add_f32_e32 v10, v10, v11
	v_fmamk_f32 v10, v10, 0x3c000000, v254
	s_nop 0
	s_nop 0
	s_nop 0
	s_nop 1
	s_nop 1
	s_nop 0
	v_rsq_f32_e32 v14, v10
	s_nop 0
	v_mul_f32_e32 v10, v12, v14
	v_mul_f32_e32 v11, v13, v14
	v_mul_f32_e32 v10, v5, v10
	v_mul_f32_e32 v11, v7, v11
	v_cvt_pk_bf16_f32 v12, v10, v11
	v_lshl_add_u64 v[10:11], v[2:3], 1, s[6:7]
	global_store_short v[10:11], v12, off offset:768
	v_add_u32_e32 v10, 32, v2
	v_mov_b32_e32 v11, v3
	v_lshl_add_u64 v[10:11], v[10:11], 1, s[6:7]
	global_store_short_d16_hi v[10:11], v12, off offset:768
	v_mul_f32_e32 v10, v15, v14
	v_mul_f32_e32 v9, v9, v14
	v_mul_f32_e32 v10, v4, v10
	v_mul_f32_e32 v9, v6, v9
	v_cvt_pk_bf16_f32 v9, v10, v9
	v_add_u32_e32 v10, 64, v2
	v_mov_b32_e32 v11, v3
	v_lshl_add_u64 v[10:11], v[10:11], 1, s[6:7]
	global_store_short v[10:11], v9, off offset:768
	v_add_u32_e32 v10, 0x60, v2
	v_mov_b32_e32 v11, v3
	v_lshl_add_u64 v[10:11], v[10:11], 1, s[6:7]
	global_store_short_d16_hi v[10:11], v9, off offset:768
	ds_read_b32 v9, v8 offset:4
	ds_read2st64_b32 v[10:11], v1 offset0:1 offset1:17
	s_waitcnt lgkmcnt(0)
	v_fma_f32 v12, v69, v9, -v10
	v_fma_f32 v13, v101, v9, -v11
	ds_read2st64_b32 v[10:11], v1 offset0:33 offset1:49
	v_mul_f32_e32 v14, v13, v13
	v_fmac_f32_e32 v14, v12, v12
	s_waitcnt lgkmcnt(0)
	v_fma_f32 v15, v117, v9, -v10
	v_fmac_f32_e32 v14, v15, v15
	v_fma_f32 v9, v133, v9, -v11
	v_fmac_f32_e32 v14, v9, v9
	ds_swizzle_b32 v10, v14 offset:swizzle(SWAP,1)
	s_waitcnt lgkmcnt(0)
	v_add_f32_e32 v10, v14, v10
	ds_swizzle_b32 v11, v10 offset:swizzle(SWAP,2)
	s_waitcnt lgkmcnt(0)
	v_add_f32_e32 v10, v10, v11
	ds_swizzle_b32 v11, v10 offset:swizzle(SWAP,4)
	s_waitcnt lgkmcnt(0)
	v_add_f32_e32 v10, v10, v11
	ds_swizzle_b32 v11, v10 offset:swizzle(SWAP,8)
	s_waitcnt lgkmcnt(0)
	v_add_f32_e32 v10, v10, v11
	ds_swizzle_b32 v11, v10 offset:swizzle(SWAP,16)
	s_waitcnt lgkmcnt(0)
	v_add_f32_e32 v10, v10, v11
	v_fmamk_f32 v10, v10, 0x3c000000, v254
	s_nop 0
	s_nop 0
	s_nop 0
	s_nop 1
	s_nop 1
	s_nop 0
	v_rsq_f32_e32 v14, v10
	s_nop 0
	v_mul_f32_e32 v11, v12, v14
	v_mul_f32_e32 v12, v13, v14
	v_mul_f32_e32 v11, v5, v11
	v_mul_f32_e32 v12, v7, v12
	v_add_u32_e32 v10, 0x1000, v2
	v_cvt_pk_bf16_f32 v12, v11, v12
	v_mov_b32_e32 v11, v3
	v_lshl_add_u64 v[10:11], v[10:11], 1, s[6:7]
	global_store_short v[10:11], v12, off offset:768
	v_add_u32_e32 v10, 0x1020, v2
	v_mov_b32_e32 v11, v3
	v_lshl_add_u64 v[10:11], v[10:11], 1, s[6:7]
	global_store_short_d16_hi v[10:11], v12, off offset:768
	v_mul_f32_e32 v10, v15, v14
	v_mul_f32_e32 v9, v9, v14
	v_mul_f32_e32 v10, v4, v10
	v_mul_f32_e32 v9, v6, v9
	v_cvt_pk_bf16_f32 v9, v10, v9
	v_add_u32_e32 v10, 0x1040, v2
	v_mov_b32_e32 v11, v3
	v_lshl_add_u64 v[10:11], v[10:11], 1, s[6:7]
	global_store_short v[10:11], v9, off offset:768
	v_add_u32_e32 v10, 0x1060, v2
	v_mov_b32_e32 v11, v3
	v_lshl_add_u64 v[10:11], v[10:11], 1, s[6:7]
	global_store_short_d16_hi v[10:11], v9, off offset:768
	ds_read_b32 v9, v8 offset:8
	ds_read2st64_b32 v[10:11], v1 offset0:2 offset1:18
	s_waitcnt lgkmcnt(0)
	v_fma_f32 v12, v70, v9, -v10
	v_fma_f32 v13, v102, v9, -v11
	ds_read2st64_b32 v[10:11], v1 offset0:34 offset1:50
	v_mul_f32_e32 v14, v13, v13
	v_fmac_f32_e32 v14, v12, v12
	s_waitcnt lgkmcnt(0)
	v_fma_f32 v15, v118, v9, -v10
	v_fmac_f32_e32 v14, v15, v15
	v_fma_f32 v9, v134, v9, -v11
	v_fmac_f32_e32 v14, v9, v9
	ds_swizzle_b32 v10, v14 offset:swizzle(SWAP,1)
	s_waitcnt lgkmcnt(0)
	v_add_f32_e32 v10, v14, v10
	ds_swizzle_b32 v11, v10 offset:swizzle(SWAP,2)
	s_waitcnt lgkmcnt(0)
	v_add_f32_e32 v10, v10, v11
	ds_swizzle_b32 v11, v10 offset:swizzle(SWAP,4)
	s_waitcnt lgkmcnt(0)
	v_add_f32_e32 v10, v10, v11
	ds_swizzle_b32 v11, v10 offset:swizzle(SWAP,8)
	s_waitcnt lgkmcnt(0)
	v_add_f32_e32 v10, v10, v11
	ds_swizzle_b32 v11, v10 offset:swizzle(SWAP,16)
	s_waitcnt lgkmcnt(0)
	v_add_f32_e32 v10, v10, v11
	v_fmamk_f32 v10, v10, 0x3c000000, v254
	s_nop 0
	s_nop 0
	s_nop 0
	s_nop 1
	s_nop 1
	s_nop 0
	v_rsq_f32_e32 v14, v10
	s_nop 0
	v_mul_f32_e32 v11, v12, v14
	v_mul_f32_e32 v12, v13, v14
	v_mul_f32_e32 v11, v5, v11
	v_mul_f32_e32 v12, v7, v12
	v_add_u32_e32 v10, 0x2000, v2
	v_cvt_pk_bf16_f32 v12, v11, v12
	v_mov_b32_e32 v11, v3
	v_lshl_add_u64 v[10:11], v[10:11], 1, s[6:7]
	global_store_short v[10:11], v12, off offset:768
	v_add_u32_e32 v10, 0x2020, v2
	v_mov_b32_e32 v11, v3
	v_lshl_add_u64 v[10:11], v[10:11], 1, s[6:7]
	global_store_short_d16_hi v[10:11], v12, off offset:768
	v_mul_f32_e32 v10, v15, v14
	v_mul_f32_e32 v9, v9, v14
	v_mul_f32_e32 v10, v4, v10
	v_mul_f32_e32 v9, v6, v9
	v_cvt_pk_bf16_f32 v9, v10, v9
	v_add_u32_e32 v10, 0x2040, v2
	v_mov_b32_e32 v11, v3
	v_lshl_add_u64 v[10:11], v[10:11], 1, s[6:7]
	global_store_short v[10:11], v9, off offset:768
	v_add_u32_e32 v10, 0x2060, v2
	v_mov_b32_e32 v11, v3
	v_lshl_add_u64 v[10:11], v[10:11], 1, s[6:7]
	global_store_short_d16_hi v[10:11], v9, off offset:768
	ds_read_b32 v9, v8 offset:12
	ds_read2st64_b32 v[10:11], v1 offset0:3 offset1:19
	s_waitcnt lgkmcnt(0)
	v_fma_f32 v12, v71, v9, -v10
	v_fma_f32 v13, v103, v9, -v11
	ds_read2st64_b32 v[10:11], v1 offset0:35 offset1:51
	v_mul_f32_e32 v14, v13, v13
	v_fmac_f32_e32 v14, v12, v12
	s_waitcnt lgkmcnt(0)
	v_fma_f32 v15, v119, v9, -v10
	v_fmac_f32_e32 v14, v15, v15
	v_fma_f32 v9, v135, v9, -v11
	v_fmac_f32_e32 v14, v9, v9
	ds_swizzle_b32 v10, v14 offset:swizzle(SWAP,1)
	s_waitcnt lgkmcnt(0)
	v_add_f32_e32 v10, v14, v10
	ds_swizzle_b32 v11, v10 offset:swizzle(SWAP,2)
	s_waitcnt lgkmcnt(0)
	v_add_f32_e32 v10, v10, v11
	ds_swizzle_b32 v11, v10 offset:swizzle(SWAP,4)
	s_waitcnt lgkmcnt(0)
	v_add_f32_e32 v10, v10, v11
	ds_swizzle_b32 v11, v10 offset:swizzle(SWAP,8)
	s_waitcnt lgkmcnt(0)
	v_add_f32_e32 v10, v10, v11
	ds_swizzle_b32 v11, v10 offset:swizzle(SWAP,16)
	s_waitcnt lgkmcnt(0)
	v_add_f32_e32 v10, v10, v11
	v_fmamk_f32 v10, v10, 0x3c000000, v254
	s_nop 0
	s_nop 0
	s_nop 0
	s_nop 1
	s_nop 1
	s_nop 0
	v_rsq_f32_e32 v14, v10
	s_nop 0
	v_mul_f32_e32 v11, v12, v14
	v_mul_f32_e32 v12, v13, v14
	v_mul_f32_e32 v11, v5, v11
	v_mul_f32_e32 v12, v7, v12
	v_add_u32_e32 v10, 0x3000, v2
	v_cvt_pk_bf16_f32 v12, v11, v12
	v_mov_b32_e32 v11, v3
	v_lshl_add_u64 v[10:11], v[10:11], 1, s[6:7]
	global_store_short v[10:11], v12, off offset:768
	v_add_u32_e32 v10, 0x3020, v2
	v_mov_b32_e32 v11, v3
	v_lshl_add_u64 v[10:11], v[10:11], 1, s[6:7]
	global_store_short_d16_hi v[10:11], v12, off offset:768
	v_mul_f32_e32 v10, v15, v14
	v_mul_f32_e32 v9, v9, v14
	v_mul_f32_e32 v10, v4, v10
	v_mul_f32_e32 v9, v6, v9
	v_cvt_pk_bf16_f32 v9, v10, v9
	v_add_u32_e32 v10, 0x3040, v2
	v_mov_b32_e32 v11, v3
	v_lshl_add_u64 v[10:11], v[10:11], 1, s[6:7]
	global_store_short v[10:11], v9, off offset:768
	v_add_u32_e32 v10, 0x3060, v2
	v_mov_b32_e32 v11, v3
	v_lshl_add_u64 v[10:11], v[10:11], 1, s[6:7]
	global_store_short_d16_hi v[10:11], v9, off offset:768
	ds_read_b32 v9, v8 offset:32
	ds_read2st64_b32 v[10:11], v1 offset0:4 offset1:20
	s_waitcnt lgkmcnt(0)
	v_fma_f32 v12, v72, v9, -v10
	v_fma_f32 v13, v104, v9, -v11
	ds_read2st64_b32 v[10:11], v1 offset0:36 offset1:52
	v_mul_f32_e32 v14, v13, v13
	v_fmac_f32_e32 v14, v12, v12
	s_waitcnt lgkmcnt(0)
	v_fma_f32 v15, v120, v9, -v10
	v_fmac_f32_e32 v14, v15, v15
	v_fma_f32 v9, v136, v9, -v11
	v_fmac_f32_e32 v14, v9, v9
	ds_swizzle_b32 v10, v14 offset:swizzle(SWAP,1)
	s_waitcnt lgkmcnt(0)
	v_add_f32_e32 v10, v14, v10
	ds_swizzle_b32 v11, v10 offset:swizzle(SWAP,2)
	s_waitcnt lgkmcnt(0)
	v_add_f32_e32 v10, v10, v11
	ds_swizzle_b32 v11, v10 offset:swizzle(SWAP,4)
	s_waitcnt lgkmcnt(0)
	v_add_f32_e32 v10, v10, v11
	ds_swizzle_b32 v11, v10 offset:swizzle(SWAP,8)
	s_waitcnt lgkmcnt(0)
	v_add_f32_e32 v10, v10, v11
	ds_swizzle_b32 v11, v10 offset:swizzle(SWAP,16)
	s_waitcnt lgkmcnt(0)
	v_add_f32_e32 v10, v10, v11
	v_fmamk_f32 v10, v10, 0x3c000000, v254
	s_nop 0
	s_nop 0
	s_nop 0
	s_nop 1
	s_nop 1
	s_nop 0
	v_rsq_f32_e32 v14, v10
	s_nop 0
	v_mul_f32_e32 v11, v12, v14
	v_mul_f32_e32 v12, v13, v14
	v_mul_f32_e32 v11, v5, v11
	v_mul_f32_e32 v12, v7, v12
	v_add_u32_e32 v10, 0x8000, v2
	v_cvt_pk_bf16_f32 v12, v11, v12
	v_mov_b32_e32 v11, v3
	v_lshl_add_u64 v[10:11], v[10:11], 1, s[6:7]
	global_store_short v[10:11], v12, off offset:768
	v_add_u32_e32 v10, 0x8020, v2
	v_mov_b32_e32 v11, v3
	v_lshl_add_u64 v[10:11], v[10:11], 1, s[6:7]
	global_store_short_d16_hi v[10:11], v12, off offset:768
	v_mul_f32_e32 v10, v15, v14
	v_mul_f32_e32 v9, v9, v14
	v_mul_f32_e32 v10, v4, v10
	v_mul_f32_e32 v9, v6, v9
	v_cvt_pk_bf16_f32 v9, v10, v9
	v_add_u32_e32 v10, 0x8040, v2
	v_mov_b32_e32 v11, v3
	v_lshl_add_u64 v[10:11], v[10:11], 1, s[6:7]
	global_store_short v[10:11], v9, off offset:768
	v_add_u32_e32 v10, 0x8060, v2
	v_mov_b32_e32 v11, v3
	v_lshl_add_u64 v[10:11], v[10:11], 1, s[6:7]
	global_store_short_d16_hi v[10:11], v9, off offset:768
	ds_read_b32 v9, v8 offset:36
	ds_read2st64_b32 v[10:11], v1 offset0:5 offset1:21
	s_waitcnt lgkmcnt(0)
	v_fma_f32 v12, v73, v9, -v10
	v_fma_f32 v13, v105, v9, -v11
	ds_read2st64_b32 v[10:11], v1 offset0:37 offset1:53
	v_mul_f32_e32 v14, v13, v13
	v_fmac_f32_e32 v14, v12, v12
	s_waitcnt lgkmcnt(0)
	v_fma_f32 v15, v121, v9, -v10
	v_fmac_f32_e32 v14, v15, v15
	v_fma_f32 v9, v137, v9, -v11
	v_fmac_f32_e32 v14, v9, v9
	ds_swizzle_b32 v10, v14 offset:swizzle(SWAP,1)
	s_waitcnt lgkmcnt(0)
	v_add_f32_e32 v10, v14, v10
	ds_swizzle_b32 v11, v10 offset:swizzle(SWAP,2)
	s_waitcnt lgkmcnt(0)
	v_add_f32_e32 v10, v10, v11
	ds_swizzle_b32 v11, v10 offset:swizzle(SWAP,4)
	s_waitcnt lgkmcnt(0)
	v_add_f32_e32 v10, v10, v11
	ds_swizzle_b32 v11, v10 offset:swizzle(SWAP,8)
	s_waitcnt lgkmcnt(0)
	v_add_f32_e32 v10, v10, v11
	ds_swizzle_b32 v11, v10 offset:swizzle(SWAP,16)
	s_waitcnt lgkmcnt(0)
	v_add_f32_e32 v10, v10, v11
	v_fmamk_f32 v10, v10, 0x3c000000, v254
	s_nop 0
	s_nop 0
	s_nop 0
	s_nop 1
	s_nop 1
	s_nop 0
	v_rsq_f32_e32 v14, v10
	s_nop 0
	v_mul_f32_e32 v11, v12, v14
	v_mul_f32_e32 v12, v13, v14
	v_mul_f32_e32 v11, v5, v11
	v_mul_f32_e32 v12, v7, v12
	v_add_u32_e32 v10, 0x9000, v2
	v_cvt_pk_bf16_f32 v12, v11, v12
	v_mov_b32_e32 v11, v3
	v_lshl_add_u64 v[10:11], v[10:11], 1, s[6:7]
	global_store_short v[10:11], v12, off offset:768
	v_add_u32_e32 v10, 0x9020, v2
	v_mov_b32_e32 v11, v3
	v_lshl_add_u64 v[10:11], v[10:11], 1, s[6:7]
	global_store_short_d16_hi v[10:11], v12, off offset:768
	v_mul_f32_e32 v10, v15, v14
	v_mul_f32_e32 v9, v9, v14
	v_mul_f32_e32 v10, v4, v10
	v_mul_f32_e32 v9, v6, v9
	v_cvt_pk_bf16_f32 v9, v10, v9
	v_add_u32_e32 v10, 0x9040, v2
	v_mov_b32_e32 v11, v3
	v_lshl_add_u64 v[10:11], v[10:11], 1, s[6:7]
	global_store_short v[10:11], v9, off offset:768
	v_add_u32_e32 v10, 0x9060, v2
	v_mov_b32_e32 v11, v3
	v_lshl_add_u64 v[10:11], v[10:11], 1, s[6:7]
	global_store_short_d16_hi v[10:11], v9, off offset:768
	ds_read_b32 v9, v8 offset:40
	ds_read2st64_b32 v[10:11], v1 offset0:6 offset1:22
	s_waitcnt lgkmcnt(0)
	v_fma_f32 v12, v74, v9, -v10
	v_fma_f32 v13, v106, v9, -v11
	ds_read2st64_b32 v[10:11], v1 offset0:38 offset1:54
	v_mul_f32_e32 v14, v13, v13
	v_fmac_f32_e32 v14, v12, v12
	s_waitcnt lgkmcnt(0)
	v_fma_f32 v15, v122, v9, -v10
	v_fmac_f32_e32 v14, v15, v15
	v_fma_f32 v9, v138, v9, -v11
	v_fmac_f32_e32 v14, v9, v9
	ds_swizzle_b32 v10, v14 offset:swizzle(SWAP,1)
	s_waitcnt lgkmcnt(0)
	v_add_f32_e32 v10, v14, v10
	ds_swizzle_b32 v11, v10 offset:swizzle(SWAP,2)
	s_waitcnt lgkmcnt(0)
	v_add_f32_e32 v10, v10, v11
	ds_swizzle_b32 v11, v10 offset:swizzle(SWAP,4)
	s_waitcnt lgkmcnt(0)
	v_add_f32_e32 v10, v10, v11
	ds_swizzle_b32 v11, v10 offset:swizzle(SWAP,8)
	s_waitcnt lgkmcnt(0)
	v_add_f32_e32 v10, v10, v11
	ds_swizzle_b32 v11, v10 offset:swizzle(SWAP,16)
	s_waitcnt lgkmcnt(0)
	v_add_f32_e32 v10, v10, v11
	v_fmamk_f32 v10, v10, 0x3c000000, v254
	s_nop 0
	s_nop 0
	s_nop 0
	s_nop 1
	s_nop 1
	s_nop 0
	v_rsq_f32_e32 v14, v10
	s_nop 0
	v_mul_f32_e32 v11, v12, v14
	v_mul_f32_e32 v12, v13, v14
	v_mul_f32_e32 v11, v5, v11
	v_mul_f32_e32 v12, v7, v12
	v_add_u32_e32 v10, 0xa000, v2
	v_cvt_pk_bf16_f32 v12, v11, v12
	v_mov_b32_e32 v11, v3
	v_lshl_add_u64 v[10:11], v[10:11], 1, s[6:7]
	global_store_short v[10:11], v12, off offset:768
	v_add_u32_e32 v10, 0xa020, v2
	v_mov_b32_e32 v11, v3
	v_lshl_add_u64 v[10:11], v[10:11], 1, s[6:7]
	global_store_short_d16_hi v[10:11], v12, off offset:768
	v_mul_f32_e32 v10, v15, v14
	v_mul_f32_e32 v9, v9, v14
	v_mul_f32_e32 v10, v4, v10
	v_mul_f32_e32 v9, v6, v9
	v_cvt_pk_bf16_f32 v9, v10, v9
	v_add_u32_e32 v10, 0xa040, v2
	v_mov_b32_e32 v11, v3
	v_lshl_add_u64 v[10:11], v[10:11], 1, s[6:7]
	global_store_short v[10:11], v9, off offset:768
	v_add_u32_e32 v10, 0xa060, v2
	v_mov_b32_e32 v11, v3
	v_lshl_add_u64 v[10:11], v[10:11], 1, s[6:7]
	global_store_short_d16_hi v[10:11], v9, off offset:768
	ds_read_b32 v9, v8 offset:44
	ds_read2st64_b32 v[10:11], v1 offset0:7 offset1:23
	s_waitcnt lgkmcnt(0)
	v_fma_f32 v12, v75, v9, -v10
	v_fma_f32 v13, v107, v9, -v11
	ds_read2st64_b32 v[10:11], v1 offset0:39 offset1:55
	v_mul_f32_e32 v14, v13, v13
	v_fmac_f32_e32 v14, v12, v12
	s_waitcnt lgkmcnt(0)
	v_fma_f32 v15, v123, v9, -v10
	v_fmac_f32_e32 v14, v15, v15
	v_fma_f32 v9, v139, v9, -v11
	v_fmac_f32_e32 v14, v9, v9
	ds_swizzle_b32 v10, v14 offset:swizzle(SWAP,1)
	s_waitcnt lgkmcnt(0)
	v_add_f32_e32 v10, v14, v10
	ds_swizzle_b32 v11, v10 offset:swizzle(SWAP,2)
	s_waitcnt lgkmcnt(0)
	v_add_f32_e32 v10, v10, v11
	ds_swizzle_b32 v11, v10 offset:swizzle(SWAP,4)
	s_waitcnt lgkmcnt(0)
	v_add_f32_e32 v10, v10, v11
	ds_swizzle_b32 v11, v10 offset:swizzle(SWAP,8)
	s_waitcnt lgkmcnt(0)
	v_add_f32_e32 v10, v10, v11
	ds_swizzle_b32 v11, v10 offset:swizzle(SWAP,16)
	s_waitcnt lgkmcnt(0)
	v_add_f32_e32 v10, v10, v11
	v_fmamk_f32 v10, v10, 0x3c000000, v254
	s_nop 0
	s_nop 0
	s_nop 0
	s_nop 1
	s_nop 1
	s_nop 0
	v_rsq_f32_e32 v14, v10
	s_nop 0
	v_mul_f32_e32 v11, v12, v14
	v_mul_f32_e32 v12, v13, v14
	v_mul_f32_e32 v11, v5, v11
	v_mul_f32_e32 v12, v7, v12
	v_add_u32_e32 v10, 0xb000, v2
	v_cvt_pk_bf16_f32 v12, v11, v12
	v_mov_b32_e32 v11, v3
	v_lshl_add_u64 v[10:11], v[10:11], 1, s[6:7]
	global_store_short v[10:11], v12, off offset:768
	v_add_u32_e32 v10, 0xb020, v2
	v_mov_b32_e32 v11, v3
	v_lshl_add_u64 v[10:11], v[10:11], 1, s[6:7]
	global_store_short_d16_hi v[10:11], v12, off offset:768
	v_mul_f32_e32 v10, v15, v14
	v_mul_f32_e32 v9, v9, v14
	v_mul_f32_e32 v10, v4, v10
	v_mul_f32_e32 v9, v6, v9
	v_cvt_pk_bf16_f32 v9, v10, v9
	v_add_u32_e32 v10, 0xb040, v2
	v_mov_b32_e32 v11, v3
	v_lshl_add_u64 v[10:11], v[10:11], 1, s[6:7]
	global_store_short v[10:11], v9, off offset:768
	v_add_u32_e32 v10, 0xb060, v2
	v_mov_b32_e32 v11, v3
	v_lshl_add_u64 v[10:11], v[10:11], 1, s[6:7]
	global_store_short_d16_hi v[10:11], v9, off offset:768
	ds_read_b32 v9, v8 offset:64
	ds_read2st64_b32 v[10:11], v1 offset0:8 offset1:24
	s_waitcnt lgkmcnt(0)
	v_fma_f32 v12, v76, v9, -v10
	v_fma_f32 v13, v108, v9, -v11
	ds_read2st64_b32 v[10:11], v1 offset0:40 offset1:56
	v_mul_f32_e32 v14, v13, v13
	v_fmac_f32_e32 v14, v12, v12
	s_waitcnt lgkmcnt(0)
	v_fma_f32 v15, v124, v9, -v10
	v_fmac_f32_e32 v14, v15, v15
	v_fma_f32 v9, v140, v9, -v11
	v_fmac_f32_e32 v14, v9, v9
	ds_swizzle_b32 v10, v14 offset:swizzle(SWAP,1)
	s_waitcnt lgkmcnt(0)
	v_add_f32_e32 v10, v14, v10
	ds_swizzle_b32 v11, v10 offset:swizzle(SWAP,2)
	s_waitcnt lgkmcnt(0)
	v_add_f32_e32 v10, v10, v11
	ds_swizzle_b32 v11, v10 offset:swizzle(SWAP,4)
	s_waitcnt lgkmcnt(0)
	v_add_f32_e32 v10, v10, v11
	ds_swizzle_b32 v11, v10 offset:swizzle(SWAP,8)
	s_waitcnt lgkmcnt(0)
	v_add_f32_e32 v10, v10, v11
	ds_swizzle_b32 v11, v10 offset:swizzle(SWAP,16)
	s_waitcnt lgkmcnt(0)
	v_add_f32_e32 v10, v10, v11
	v_fmamk_f32 v10, v10, 0x3c000000, v254
	s_nop 0
	s_nop 0
	s_nop 0
	s_nop 1
	s_nop 1
	s_nop 0
	v_rsq_f32_e32 v14, v10
	s_nop 0
	v_mul_f32_e32 v11, v12, v14
	v_mul_f32_e32 v12, v13, v14
	v_mul_f32_e32 v11, v5, v11
	v_mul_f32_e32 v12, v7, v12
	v_add_u32_e32 v10, 0x10000, v2
	v_cvt_pk_bf16_f32 v12, v11, v12
	v_mov_b32_e32 v11, v3
	v_lshl_add_u64 v[10:11], v[10:11], 1, s[6:7]
	global_store_short v[10:11], v12, off offset:768
	v_add_u32_e32 v10, 0x10020, v2
	v_mov_b32_e32 v11, v3
	v_lshl_add_u64 v[10:11], v[10:11], 1, s[6:7]
	global_store_short_d16_hi v[10:11], v12, off offset:768
	v_mul_f32_e32 v10, v15, v14
	v_mul_f32_e32 v9, v9, v14
	v_mul_f32_e32 v10, v4, v10
	v_mul_f32_e32 v9, v6, v9
	v_cvt_pk_bf16_f32 v9, v10, v9
	v_add_u32_e32 v10, 0x10040, v2
	v_mov_b32_e32 v11, v3
	v_lshl_add_u64 v[10:11], v[10:11], 1, s[6:7]
	global_store_short v[10:11], v9, off offset:768
	v_add_u32_e32 v10, 0x10060, v2
	v_mov_b32_e32 v11, v3
	v_lshl_add_u64 v[10:11], v[10:11], 1, s[6:7]
	global_store_short_d16_hi v[10:11], v9, off offset:768
	ds_read_b32 v9, v8 offset:68
	ds_read2st64_b32 v[10:11], v1 offset0:9 offset1:25
	s_waitcnt lgkmcnt(0)
	v_fma_f32 v12, v77, v9, -v10
	v_fma_f32 v13, v109, v9, -v11
	ds_read2st64_b32 v[10:11], v1 offset0:41 offset1:57
	v_mul_f32_e32 v14, v13, v13
	v_fmac_f32_e32 v14, v12, v12
	s_waitcnt lgkmcnt(0)
	v_fma_f32 v15, v125, v9, -v10
	v_fmac_f32_e32 v14, v15, v15
	v_fma_f32 v9, v141, v9, -v11
	v_fmac_f32_e32 v14, v9, v9
	ds_swizzle_b32 v10, v14 offset:swizzle(SWAP,1)
	s_waitcnt lgkmcnt(0)
	v_add_f32_e32 v10, v14, v10
	ds_swizzle_b32 v11, v10 offset:swizzle(SWAP,2)
	s_waitcnt lgkmcnt(0)
	v_add_f32_e32 v10, v10, v11
	ds_swizzle_b32 v11, v10 offset:swizzle(SWAP,4)
	s_waitcnt lgkmcnt(0)
	v_add_f32_e32 v10, v10, v11
	ds_swizzle_b32 v11, v10 offset:swizzle(SWAP,8)
	s_waitcnt lgkmcnt(0)
	v_add_f32_e32 v10, v10, v11
	ds_swizzle_b32 v11, v10 offset:swizzle(SWAP,16)
	s_waitcnt lgkmcnt(0)
	v_add_f32_e32 v10, v10, v11
	v_fmamk_f32 v10, v10, 0x3c000000, v254
	s_nop 0
	s_nop 0
	s_nop 0
	s_nop 1
	s_nop 1
	s_nop 0
	v_rsq_f32_e32 v14, v10
	s_nop 0
	v_mul_f32_e32 v11, v12, v14
	v_mul_f32_e32 v12, v13, v14
	v_mul_f32_e32 v11, v5, v11
	v_mul_f32_e32 v12, v7, v12
	v_add_u32_e32 v10, 0x11000, v2
	v_cvt_pk_bf16_f32 v12, v11, v12
	v_mov_b32_e32 v11, v3
	v_lshl_add_u64 v[10:11], v[10:11], 1, s[6:7]
	global_store_short v[10:11], v12, off offset:768
	v_add_u32_e32 v10, 0x11020, v2
	v_mov_b32_e32 v11, v3
	v_lshl_add_u64 v[10:11], v[10:11], 1, s[6:7]
	global_store_short_d16_hi v[10:11], v12, off offset:768
	v_mul_f32_e32 v10, v15, v14
	v_mul_f32_e32 v9, v9, v14
	v_mul_f32_e32 v10, v4, v10
	v_mul_f32_e32 v9, v6, v9
	v_cvt_pk_bf16_f32 v9, v10, v9
	v_add_u32_e32 v10, 0x11040, v2
	v_mov_b32_e32 v11, v3
	v_lshl_add_u64 v[10:11], v[10:11], 1, s[6:7]
	global_store_short v[10:11], v9, off offset:768
	v_add_u32_e32 v10, 0x11060, v2
	v_mov_b32_e32 v11, v3
	v_lshl_add_u64 v[10:11], v[10:11], 1, s[6:7]
	global_store_short_d16_hi v[10:11], v9, off offset:768
	ds_read_b32 v9, v8 offset:72
	ds_read2st64_b32 v[10:11], v1 offset0:10 offset1:26
	s_waitcnt lgkmcnt(0)
	v_fma_f32 v12, v78, v9, -v10
	v_fma_f32 v13, v110, v9, -v11
	ds_read2st64_b32 v[10:11], v1 offset0:42 offset1:58
	v_mul_f32_e32 v14, v13, v13
	v_fmac_f32_e32 v14, v12, v12
	s_waitcnt lgkmcnt(0)
	v_fma_f32 v15, v126, v9, -v10
	v_fmac_f32_e32 v14, v15, v15
	v_fma_f32 v9, v142, v9, -v11
	v_fmac_f32_e32 v14, v9, v9
	ds_swizzle_b32 v10, v14 offset:swizzle(SWAP,1)
	s_waitcnt lgkmcnt(0)
	v_add_f32_e32 v10, v14, v10
	ds_swizzle_b32 v11, v10 offset:swizzle(SWAP,2)
	s_waitcnt lgkmcnt(0)
	v_add_f32_e32 v10, v10, v11
	ds_swizzle_b32 v11, v10 offset:swizzle(SWAP,4)
	s_waitcnt lgkmcnt(0)
	v_add_f32_e32 v10, v10, v11
	ds_swizzle_b32 v11, v10 offset:swizzle(SWAP,8)
	s_waitcnt lgkmcnt(0)
	v_add_f32_e32 v10, v10, v11
	ds_swizzle_b32 v11, v10 offset:swizzle(SWAP,16)
	s_waitcnt lgkmcnt(0)
	v_add_f32_e32 v10, v10, v11
	v_fmamk_f32 v10, v10, 0x3c000000, v254
	s_nop 0
	s_nop 0
	s_nop 0
	s_nop 1
	s_nop 1
	s_nop 0
	v_rsq_f32_e32 v14, v10
	s_nop 0
	v_mul_f32_e32 v11, v12, v14
	v_mul_f32_e32 v12, v13, v14
	v_mul_f32_e32 v11, v5, v11
	v_mul_f32_e32 v12, v7, v12
	v_add_u32_e32 v10, 0x12000, v2
	v_cvt_pk_bf16_f32 v12, v11, v12
	v_mov_b32_e32 v11, v3
	v_lshl_add_u64 v[10:11], v[10:11], 1, s[6:7]
	global_store_short v[10:11], v12, off offset:768
	v_add_u32_e32 v10, 0x12020, v2
	v_mov_b32_e32 v11, v3
	v_lshl_add_u64 v[10:11], v[10:11], 1, s[6:7]
	global_store_short_d16_hi v[10:11], v12, off offset:768
	v_mul_f32_e32 v10, v15, v14
	v_mul_f32_e32 v9, v9, v14
	v_mul_f32_e32 v10, v4, v10
	v_mul_f32_e32 v9, v6, v9
	v_cvt_pk_bf16_f32 v9, v10, v9
	v_add_u32_e32 v10, 0x12040, v2
	v_mov_b32_e32 v11, v3
	v_lshl_add_u64 v[10:11], v[10:11], 1, s[6:7]
	global_store_short v[10:11], v9, off offset:768
	v_add_u32_e32 v10, 0x12060, v2
	v_mov_b32_e32 v11, v3
	v_lshl_add_u64 v[10:11], v[10:11], 1, s[6:7]
	global_store_short_d16_hi v[10:11], v9, off offset:768
	ds_read_b32 v9, v8 offset:76
	ds_read2st64_b32 v[10:11], v1 offset0:11 offset1:27
	s_waitcnt lgkmcnt(0)
	v_fma_f32 v12, v79, v9, -v10
	v_fma_f32 v13, v111, v9, -v11
	ds_read2st64_b32 v[10:11], v1 offset0:43 offset1:59
	v_mul_f32_e32 v14, v13, v13
	v_fmac_f32_e32 v14, v12, v12
	s_waitcnt lgkmcnt(0)
	v_fma_f32 v15, v127, v9, -v10
	v_fmac_f32_e32 v14, v15, v15
	v_fma_f32 v9, v143, v9, -v11
	v_fmac_f32_e32 v14, v9, v9
	ds_swizzle_b32 v10, v14 offset:swizzle(SWAP,1)
	s_waitcnt lgkmcnt(0)
	v_add_f32_e32 v10, v14, v10
	ds_swizzle_b32 v11, v10 offset:swizzle(SWAP,2)
	s_waitcnt lgkmcnt(0)
	v_add_f32_e32 v10, v10, v11
	ds_swizzle_b32 v11, v10 offset:swizzle(SWAP,4)
	s_waitcnt lgkmcnt(0)
	v_add_f32_e32 v10, v10, v11
	ds_swizzle_b32 v11, v10 offset:swizzle(SWAP,8)
	s_waitcnt lgkmcnt(0)
	v_add_f32_e32 v10, v10, v11
	ds_swizzle_b32 v11, v10 offset:swizzle(SWAP,16)
	s_waitcnt lgkmcnt(0)
	v_add_f32_e32 v10, v10, v11
	v_fmamk_f32 v10, v10, 0x3c000000, v254
	s_nop 0
	s_nop 0
	s_nop 0
	s_nop 1
	s_nop 1
	s_nop 0
	v_rsq_f32_e32 v14, v10
	s_nop 0
	v_mul_f32_e32 v11, v12, v14
	v_mul_f32_e32 v12, v13, v14
	v_mul_f32_e32 v11, v5, v11
	v_mul_f32_e32 v12, v7, v12
	v_add_u32_e32 v10, 0x13000, v2
	v_cvt_pk_bf16_f32 v12, v11, v12
	v_mov_b32_e32 v11, v3
	v_lshl_add_u64 v[10:11], v[10:11], 1, s[6:7]
	global_store_short v[10:11], v12, off offset:768
	v_add_u32_e32 v10, 0x13020, v2
	v_mov_b32_e32 v11, v3
	v_lshl_add_u64 v[10:11], v[10:11], 1, s[6:7]
	global_store_short_d16_hi v[10:11], v12, off offset:768
	v_mul_f32_e32 v10, v15, v14
	v_mul_f32_e32 v9, v9, v14
	v_mul_f32_e32 v10, v4, v10
	v_mul_f32_e32 v9, v6, v9
	v_cvt_pk_bf16_f32 v9, v10, v9
	v_add_u32_e32 v10, 0x13040, v2
	v_mov_b32_e32 v11, v3
	v_lshl_add_u64 v[10:11], v[10:11], 1, s[6:7]
	global_store_short v[10:11], v9, off offset:768
	v_add_u32_e32 v10, 0x13060, v2
	v_mov_b32_e32 v11, v3
	v_lshl_add_u64 v[10:11], v[10:11], 1, s[6:7]
	global_store_short_d16_hi v[10:11], v9, off offset:768
	ds_read_b32 v9, v8 offset:96
	ds_read2st64_b32 v[10:11], v1 offset0:12 offset1:28
	s_waitcnt lgkmcnt(0)
	v_fma_f32 v12, v80, v9, -v10
	v_fma_f32 v13, v112, v9, -v11
	ds_read2st64_b32 v[10:11], v1 offset0:44 offset1:60
	v_mul_f32_e32 v14, v13, v13
	v_fmac_f32_e32 v14, v12, v12
	s_waitcnt lgkmcnt(0)
	v_fma_f32 v15, v128, v9, -v10
	v_fmac_f32_e32 v14, v15, v15
	v_fma_f32 v9, v144, v9, -v11
	v_fmac_f32_e32 v14, v9, v9
	ds_swizzle_b32 v10, v14 offset:swizzle(SWAP,1)
	s_waitcnt lgkmcnt(0)
	v_add_f32_e32 v10, v14, v10
	ds_swizzle_b32 v11, v10 offset:swizzle(SWAP,2)
	s_waitcnt lgkmcnt(0)
	v_add_f32_e32 v10, v10, v11
	ds_swizzle_b32 v11, v10 offset:swizzle(SWAP,4)
	s_waitcnt lgkmcnt(0)
	v_add_f32_e32 v10, v10, v11
	ds_swizzle_b32 v11, v10 offset:swizzle(SWAP,8)
	s_waitcnt lgkmcnt(0)
	v_add_f32_e32 v10, v10, v11
	ds_swizzle_b32 v11, v10 offset:swizzle(SWAP,16)
	s_waitcnt lgkmcnt(0)
	v_add_f32_e32 v10, v10, v11
	v_fmamk_f32 v10, v10, 0x3c000000, v254
	s_nop 0
	s_nop 0
	s_nop 0
	s_nop 1
	s_nop 1
	s_nop 0
	v_rsq_f32_e32 v14, v10
	s_nop 0
	v_mul_f32_e32 v11, v12, v14
	v_mul_f32_e32 v12, v13, v14
	v_mul_f32_e32 v11, v5, v11
	v_mul_f32_e32 v12, v7, v12
	v_add_u32_e32 v10, 0x18000, v2
	v_cvt_pk_bf16_f32 v12, v11, v12
	v_mov_b32_e32 v11, v3
	v_lshl_add_u64 v[10:11], v[10:11], 1, s[6:7]
	global_store_short v[10:11], v12, off offset:768
	v_add_u32_e32 v10, 0x18020, v2
	v_mov_b32_e32 v11, v3
	v_lshl_add_u64 v[10:11], v[10:11], 1, s[6:7]
	global_store_short_d16_hi v[10:11], v12, off offset:768
	v_mul_f32_e32 v10, v15, v14
	v_mul_f32_e32 v9, v9, v14
	v_mul_f32_e32 v10, v4, v10
	v_mul_f32_e32 v9, v6, v9
	v_cvt_pk_bf16_f32 v9, v10, v9
	v_add_u32_e32 v10, 0x18040, v2
	v_mov_b32_e32 v11, v3
	v_lshl_add_u64 v[10:11], v[10:11], 1, s[6:7]
	global_store_short v[10:11], v9, off offset:768
	v_add_u32_e32 v10, 0x18060, v2
	v_mov_b32_e32 v11, v3
	v_lshl_add_u64 v[10:11], v[10:11], 1, s[6:7]
	global_store_short_d16_hi v[10:11], v9, off offset:768
	ds_read_b32 v9, v8 offset:100
	ds_read2st64_b32 v[10:11], v1 offset0:13 offset1:29
	s_waitcnt lgkmcnt(0)
	v_fma_f32 v12, v81, v9, -v10
	v_fma_f32 v13, v113, v9, -v11
	ds_read2st64_b32 v[10:11], v1 offset0:45 offset1:61
	v_mul_f32_e32 v14, v13, v13
	v_fmac_f32_e32 v14, v12, v12
	s_waitcnt lgkmcnt(0)
	v_fma_f32 v15, v129, v9, -v10
	v_fmac_f32_e32 v14, v15, v15
	v_fma_f32 v9, v145, v9, -v11
	v_fmac_f32_e32 v14, v9, v9
	ds_swizzle_b32 v10, v14 offset:swizzle(SWAP,1)
	s_waitcnt lgkmcnt(0)
	v_add_f32_e32 v10, v14, v10
	ds_swizzle_b32 v11, v10 offset:swizzle(SWAP,2)
	s_waitcnt lgkmcnt(0)
	v_add_f32_e32 v10, v10, v11
	ds_swizzle_b32 v11, v10 offset:swizzle(SWAP,4)
	s_waitcnt lgkmcnt(0)
	v_add_f32_e32 v10, v10, v11
	ds_swizzle_b32 v11, v10 offset:swizzle(SWAP,8)
	s_waitcnt lgkmcnt(0)
	v_add_f32_e32 v10, v10, v11
	ds_swizzle_b32 v11, v10 offset:swizzle(SWAP,16)
	s_waitcnt lgkmcnt(0)
	v_add_f32_e32 v10, v10, v11
	v_fmamk_f32 v10, v10, 0x3c000000, v254
	s_nop 0
	s_nop 0
	s_nop 0
	s_nop 1
	s_nop 1
	s_nop 0
	v_rsq_f32_e32 v14, v10
	s_nop 0
	v_mul_f32_e32 v11, v12, v14
	v_mul_f32_e32 v12, v13, v14
	v_mul_f32_e32 v11, v5, v11
	v_mul_f32_e32 v12, v7, v12
	v_add_u32_e32 v10, 0x19000, v2
	v_cvt_pk_bf16_f32 v12, v11, v12
	v_mov_b32_e32 v11, v3
	v_lshl_add_u64 v[10:11], v[10:11], 1, s[6:7]
	global_store_short v[10:11], v12, off offset:768
	v_add_u32_e32 v10, 0x19020, v2
	v_mov_b32_e32 v11, v3
	v_lshl_add_u64 v[10:11], v[10:11], 1, s[6:7]
	global_store_short_d16_hi v[10:11], v12, off offset:768
	v_mul_f32_e32 v10, v15, v14
	v_mul_f32_e32 v9, v9, v14
	v_mul_f32_e32 v10, v4, v10
	v_mul_f32_e32 v9, v6, v9
	v_cvt_pk_bf16_f32 v9, v10, v9
	v_add_u32_e32 v10, 0x19040, v2
	v_mov_b32_e32 v11, v3
	v_lshl_add_u64 v[10:11], v[10:11], 1, s[6:7]
	global_store_short v[10:11], v9, off offset:768
	v_add_u32_e32 v10, 0x19060, v2
	v_mov_b32_e32 v11, v3
	v_lshl_add_u64 v[10:11], v[10:11], 1, s[6:7]
	global_store_short_d16_hi v[10:11], v9, off offset:768
	ds_read_b32 v9, v8 offset:104
	ds_read2st64_b32 v[10:11], v1 offset0:14 offset1:30
	s_waitcnt lgkmcnt(0)
	v_fma_f32 v12, v82, v9, -v10
	v_fma_f32 v13, v114, v9, -v11
	ds_read2st64_b32 v[10:11], v1 offset0:46 offset1:62
	v_mul_f32_e32 v14, v13, v13
	v_fmac_f32_e32 v14, v12, v12
	s_waitcnt lgkmcnt(0)
	v_fma_f32 v15, v130, v9, -v10
	v_fmac_f32_e32 v14, v15, v15
	v_fma_f32 v9, v146, v9, -v11
	v_fmac_f32_e32 v14, v9, v9
	ds_swizzle_b32 v10, v14 offset:swizzle(SWAP,1)
	s_waitcnt lgkmcnt(0)
	v_add_f32_e32 v10, v14, v10
	ds_swizzle_b32 v11, v10 offset:swizzle(SWAP,2)
	s_waitcnt lgkmcnt(0)
	v_add_f32_e32 v10, v10, v11
	ds_swizzle_b32 v11, v10 offset:swizzle(SWAP,4)
	s_waitcnt lgkmcnt(0)
	v_add_f32_e32 v10, v10, v11
	ds_swizzle_b32 v11, v10 offset:swizzle(SWAP,8)
	s_waitcnt lgkmcnt(0)
	v_add_f32_e32 v10, v10, v11
	ds_swizzle_b32 v11, v10 offset:swizzle(SWAP,16)
	s_waitcnt lgkmcnt(0)
	v_add_f32_e32 v10, v10, v11
	v_fmamk_f32 v10, v10, 0x3c000000, v254
	v_cmp_gt_f32_e32 vcc, s90, v10
	v_mul_f32_e32 v11, 0x4f800000, v10
	s_nop 0
	v_cndmask_b32_e32 v10, v10, v11, vcc
	v_sqrt_f32_e32 v11, v10
	s_nop 0
	v_add_u32_e32 v14, -1, v11
	v_fma_f32 v16, -v14, v11, v10
	v_cmp_ge_f32_e64 s[4:5], 0, v16
	v_add_u32_e32 v16, 1, v11
	s_nop 0
	v_cndmask_b32_e64 v14, v11, v14, s[4:5]
	v_fma_f32 v11, -v16, v11, v10
	v_cmp_lt_f32_e64 s[4:5], 0, v11
	s_nop 1
	v_cndmask_b32_e64 v11, v14, v16, s[4:5]
	v_mul_f32_e32 v14, 0x37800000, v11
	v_cndmask_b32_e32 v11, v11, v14, vcc
	v_cmp_class_f32_e32 vcc, v10, v209
	s_nop 1
	v_cndmask_b32_e32 v10, v11, v10, vcc
	v_div_scale_f32 v11, s[4:5], v10, v10, 1.0
	v_rcp_f32_e32 v14, v11
	s_nop 0
	v_fma_f32 v16, -v11, v14, 1.0
	v_fmac_f32_e32 v14, v16, v14
	v_div_scale_f32 v16, vcc, 1.0, v10, 1.0
	v_mul_f32_e32 v17, v16, v14
	v_fma_f32 v18, -v11, v17, v16
	v_fmac_f32_e32 v17, v18, v14
	v_fma_f32 v11, -v11, v17, v16
	v_div_fmas_f32 v11, v11, v14, v17
	v_div_fixup_f32 v14, v11, v10, 1.0
	v_mul_f32_e32 v11, v12, v14
	v_mul_f32_e32 v12, v13, v14
	v_mul_f32_e32 v11, v5, v11
	v_mul_f32_e32 v12, v7, v12
	v_add_u32_e32 v10, 0x1a000, v2
	v_cvt_pk_bf16_f32 v12, v11, v12
	v_mov_b32_e32 v11, v3
	v_lshl_add_u64 v[10:11], v[10:11], 1, s[6:7]
	global_store_short v[10:11], v12, off offset:768
	v_add_u32_e32 v10, 0x1a020, v2
	v_mov_b32_e32 v11, v3
	v_lshl_add_u64 v[10:11], v[10:11], 1, s[6:7]
	global_store_short_d16_hi v[10:11], v12, off offset:768
	v_mul_f32_e32 v10, v15, v14
	v_mul_f32_e32 v9, v9, v14
	v_mul_f32_e32 v10, v4, v10
	v_mul_f32_e32 v9, v6, v9
	v_cvt_pk_bf16_f32 v9, v10, v9
	v_add_u32_e32 v10, 0x1a040, v2
	v_mov_b32_e32 v11, v3
	v_lshl_add_u64 v[10:11], v[10:11], 1, s[6:7]
	global_store_short v[10:11], v9, off offset:768
	v_add_u32_e32 v10, 0x1a060, v2
	v_mov_b32_e32 v11, v3
	v_lshl_add_u64 v[10:11], v[10:11], 1, s[6:7]
	global_store_short_d16_hi v[10:11], v9, off offset:768
	ds_read_b32 v10, v8 offset:108
	ds_read2st64_b32 v[8:9], v1 offset0:15 offset1:31
	s_waitcnt lgkmcnt(0)
	v_fma_f32 v11, v83, v10, -v8
	v_fma_f32 v12, v115, v10, -v9
	ds_read2st64_b32 v[8:9], v1 offset0:47 offset1:63
	v_mul_f32_e32 v13, v12, v12
	v_fmac_f32_e32 v13, v11, v11
	s_waitcnt lgkmcnt(0)
	v_fma_f32 v1, v131, v10, -v8
	v_fmac_f32_e32 v13, v1, v1
	v_fma_f32 v10, v147, v10, -v9
	v_fmac_f32_e32 v13, v10, v10
	ds_swizzle_b32 v8, v13 offset:swizzle(SWAP,1)
	s_waitcnt lgkmcnt(0)
	v_add_f32_e32 v8, v13, v8
	ds_swizzle_b32 v9, v8 offset:swizzle(SWAP,2)
	s_waitcnt lgkmcnt(0)
	v_add_f32_e32 v8, v8, v9
	ds_swizzle_b32 v9, v8 offset:swizzle(SWAP,4)
	s_waitcnt lgkmcnt(0)
	v_add_f32_e32 v8, v8, v9
	ds_swizzle_b32 v9, v8 offset:swizzle(SWAP,8)
	s_waitcnt lgkmcnt(0)
	v_add_f32_e32 v8, v8, v9
	ds_swizzle_b32 v9, v8 offset:swizzle(SWAP,16)
	s_waitcnt lgkmcnt(0)
	v_add_f32_e32 v8, v8, v9
	v_fmamk_f32 v8, v8, 0x3c000000, v254
	v_cmp_gt_f32_e32 vcc, s90, v8
	v_mul_f32_e32 v9, 0x4f800000, v8
	s_nop 0
	v_cndmask_b32_e32 v8, v8, v9, vcc
	v_sqrt_f32_e32 v9, v8
	s_nop 0
	v_add_u32_e32 v13, -1, v9
	v_fma_f32 v14, -v13, v9, v8
	v_cmp_ge_f32_e64 s[4:5], 0, v14
	v_add_u32_e32 v14, 1, v9
	s_nop 0
	v_cndmask_b32_e64 v13, v9, v13, s[4:5]
	v_fma_f32 v9, -v14, v9, v8
	v_cmp_lt_f32_e64 s[4:5], 0, v9
	s_nop 1
	v_cndmask_b32_e64 v9, v13, v14, s[4:5]
	v_mul_f32_e32 v13, 0x37800000, v9
	v_cndmask_b32_e32 v9, v9, v13, vcc
	v_cmp_class_f32_e32 vcc, v8, v209
	s_nop 1
	v_cndmask_b32_e32 v8, v9, v8, vcc
	v_div_scale_f32 v9, s[4:5], v8, v8, 1.0
	v_rcp_f32_e32 v13, v9
	s_nop 0
	v_fma_f32 v14, -v9, v13, 1.0
	v_fmac_f32_e32 v13, v14, v13
	v_div_scale_f32 v14, vcc, 1.0, v8, 1.0
	v_mul_f32_e32 v15, v14, v13
	v_fma_f32 v16, -v9, v15, v14
	v_fmac_f32_e32 v15, v16, v13
	v_fma_f32 v9, -v9, v15, v14
	v_div_fmas_f32 v9, v9, v13, v15
	v_div_fixup_f32 v13, v9, v8, 1.0
	v_mul_f32_e32 v9, v11, v13
	v_mul_f32_e32 v5, v5, v9
	v_mul_f32_e32 v9, v12, v13
	v_add_u32_e32 v8, 0x1b000, v2
	v_mul_f32_e32 v7, v7, v9
	v_mov_b32_e32 v9, v3
	v_lshl_add_u64 v[8:9], v[8:9], 1, s[6:7]
	v_mul_f32_e32 v1, v1, v13
	v_cvt_pk_bf16_f32 v5, v5, v7
	global_store_short v[8:9], v5, off offset:768
	v_add_u32_e32 v8, 0x1b020, v2
	v_mov_b32_e32 v9, v3
	v_mul_f32_e32 v1, v4, v1
	v_mul_f32_e32 v4, v10, v13
	v_lshl_add_u64 v[8:9], v[8:9], 1, s[6:7]
	v_mul_f32_e32 v4, v6, v4
	global_store_short_d16_hi v[8:9], v5, off offset:768
	v_cvt_pk_bf16_f32 v1, v1, v4
	v_add_u32_e32 v4, 0x1b040, v2
	v_mov_b32_e32 v5, v3
	v_lshl_add_u64 v[4:5], v[4:5], 1, s[6:7]
	global_store_short v[4:5], v1, off offset:768
	v_add_u32_e32 v4, 0x1b060, v2
	v_mov_b32_e32 v5, v3
	v_lshl_add_u64 v[4:5], v[4:5], 1, s[6:7]
	global_store_short_d16_hi v[4:5], v1, off offset:768

.LBB0_2188:
	s_mov_b32 s44, s43
	s_add_i32 s43, s43, 1
	s_mov_b64 s[26:27], s[14:15]
	s_and_b32 s14, s43, 0x7fffffc
	s_cmp_eq_u32 s14, 0
	s_cselect_b64 s[28:29], -1, 0
	s_lshl_b32 s14, s43, 3
	s_and_b32 s14, s14, 24
	s_mov_b64 s[4:5], s[18:19]
	s_or_b32 s18, s14, s12
	s_and_b64 s[14:15], s[28:29], exec
	s_mov_b32 s48, s24
	s_cselect_b32 s24, s18, s24
	s_mov_b32 s45, s22
	s_cselect_b32 s22, s36, s22
	s_ashr_i32 s25, s24, 31
	s_lshl_b64 s[14:15], s[24:25], 19
	s_add_u32 s18, s31, s14
	s_addc_u32 s19, s34, s15
	s_and_b64 s[14:15], s[28:29], exec
	s_cselect_b32 s25, s19, s5
	s_cselect_b32 s49, s18, s4
	s_ashr_i32 s23, s22, 31
	s_lshl_b64 s[14:15], s[22:23], 19
	s_add_u32 s14, s8, s14
	s_addc_u32 s15, s9, s15
	s_and_b64 s[28:29], s[28:29], exec
	s_cselect_b32 s23, s15, s27
	s_cselect_b32 s50, s14, s26
	s_add_u32 s4, s4, 0x40080
	s_addc_u32 s5, s5, 0
	s_add_u32 s51, s26, 0x100
	v_mov_b32_e32 v4, 0
	s_addc_u32 s52, s27, 0
	s_mov_b32 s53, -2
	v_mov_b32_e32 v5, v4
	v_mov_b32_e32 v6, v4
	v_mov_b32_e32 v7, v4
	v_mov_b32_e32 v8, v4
	v_mov_b32_e32 v9, v4
	v_mov_b32_e32 v10, v4
	v_mov_b32_e32 v11, v4
	v_mov_b32_e32 v20, v4
	v_mov_b32_e32 v21, v4
	v_mov_b32_e32 v22, v4
	v_mov_b32_e32 v23, v4
	v_mov_b32_e32 v24, v4
	v_mov_b32_e32 v25, v4
	v_mov_b32_e32 v26, v4
	v_mov_b32_e32 v27, v4
	v_mov_b32_e32 v36, v4
	v_mov_b32_e32 v37, v4
	v_mov_b32_e32 v38, v4
	v_mov_b32_e32 v39, v4
	v_mov_b32_e32 v40, v4
	v_mov_b32_e32 v41, v4
	v_mov_b32_e32 v42, v4
	v_mov_b32_e32 v43, v4
	v_mov_b32_e32 v52, v4
	v_mov_b32_e32 v53, v4
	v_mov_b32_e32 v54, v4
	v_mov_b32_e32 v55, v4
	v_mov_b32_e32 v56, v4
	v_mov_b32_e32 v57, v4
	v_mov_b32_e32 v58, v4
	v_mov_b32_e32 v59, v4
	v_mov_b32_e32 v12, v4
	v_mov_b32_e32 v13, v4
	v_mov_b32_e32 v14, v4
	v_mov_b32_e32 v15, v4
	v_mov_b32_e32 v16, v4
	v_mov_b32_e32 v17, v4
	v_mov_b32_e32 v18, v4
	v_mov_b32_e32 v19, v4
	v_mov_b32_e32 v28, v4
	v_mov_b32_e32 v29, v4
	v_mov_b32_e32 v30, v4
	v_mov_b32_e32 v31, v4
	v_mov_b32_e32 v32, v4
	v_mov_b32_e32 v33, v4
	v_mov_b32_e32 v34, v4
	v_mov_b32_e32 v35, v4
	v_mov_b32_e32 v44, v4
	v_mov_b32_e32 v45, v4
	v_mov_b32_e32 v46, v4
	v_mov_b32_e32 v47, v4
	v_mov_b32_e32 v48, v4
	v_mov_b32_e32 v49, v4
	v_mov_b32_e32 v50, v4
	v_mov_b32_e32 v51, v4
	v_mov_b32_e32 v60, v4
	v_mov_b32_e32 v61, v4
	v_mov_b32_e32 v62, v4
	v_mov_b32_e32 v63, v4
	v_mov_b32_e32 v64, v4
	v_mov_b32_e32 v65, v4
	v_mov_b32_e32 v66, v4
	v_mov_b32_e32 v67, v4
	v_mov_b32_e32 v68, v4
	v_mov_b32_e32 v69, v4
	v_mov_b32_e32 v70, v4
	v_mov_b32_e32 v71, v4
	v_mov_b32_e32 v72, v4
	v_mov_b32_e32 v73, v4
	v_mov_b32_e32 v74, v4
	v_mov_b32_e32 v75, v4
	v_mov_b32_e32 v84, v4
	v_mov_b32_e32 v85, v4
	v_mov_b32_e32 v86, v4
	v_mov_b32_e32 v87, v4
	v_mov_b32_e32 v88, v4
	v_mov_b32_e32 v89, v4
	v_mov_b32_e32 v90, v4
	v_mov_b32_e32 v91, v4
	v_mov_b32_e32 v100, v4
	v_mov_b32_e32 v101, v4
	v_mov_b32_e32 v102, v4
	v_mov_b32_e32 v103, v4
	v_mov_b32_e32 v104, v4
	v_mov_b32_e32 v105, v4
	v_mov_b32_e32 v106, v4
	v_mov_b32_e32 v107, v4
	v_mov_b32_e32 v116, v4
	v_mov_b32_e32 v117, v4
	v_mov_b32_e32 v118, v4
	v_mov_b32_e32 v119, v4
	v_mov_b32_e32 v120, v4
	v_mov_b32_e32 v121, v4
	v_mov_b32_e32 v122, v4
	v_mov_b32_e32 v123, v4
	v_mov_b32_e32 v76, v4
	v_mov_b32_e32 v77, v4
	v_mov_b32_e32 v78, v4
	v_mov_b32_e32 v79, v4
	v_mov_b32_e32 v80, v4
	v_mov_b32_e32 v81, v4
	v_mov_b32_e32 v82, v4
	v_mov_b32_e32 v83, v4
	v_mov_b32_e32 v92, v4
	v_mov_b32_e32 v93, v4
	v_mov_b32_e32 v94, v4
	v_mov_b32_e32 v95, v4
	v_mov_b32_e32 v96, v4
	v_mov_b32_e32 v97, v4
	v_mov_b32_e32 v98, v4
	v_mov_b32_e32 v99, v4
	v_mov_b32_e32 v108, v4
	v_mov_b32_e32 v109, v4
	v_mov_b32_e32 v110, v4
	v_mov_b32_e32 v111, v4
	v_mov_b32_e32 v112, v4
	v_mov_b32_e32 v113, v4
	v_mov_b32_e32 v114, v4
	v_mov_b32_e32 v115, v4
	v_mov_b32_e32 v124, v4
	v_mov_b32_e32 v125, v4
	v_mov_b32_e32 v126, v4
	v_mov_b32_e32 v127, v4
	v_mov_b32_e32 v128, v4
	v_mov_b32_e32 v129, v4
	v_mov_b32_e32 v130, v4
	v_mov_b32_e32 v131, v4
	s_lshl_b32 s99, s48, 8
	v_mov_b32_e32 v153, v1
	s_add_i32 s99, s99, s40
	v_add_u32_e32 v228, s99, v153
	v_ashrrev_i32_e32 v229, 31, v228
	v_lshl_add_u64 v[230:231], v[228:229], 2, s[2:3]
	global_load_dword v217, v[230:231], off
	global_load_dword v232, v[230:231], off offset:64
	global_load_dword v233, v[230:231], off offset:128
	global_load_dword v234, v[230:231], off offset:192
	global_load_dword v235, v[230:231], off offset:512
	global_load_dword v236, v[230:231], off offset:576
	global_load_dword v237, v[230:231], off offset:640
	global_load_dword v238, v[230:231], off offset:704

.LBB0_2192:
	s_lshl_b32 s4, s48, 8
	v_mov_b32_e32 v2, v1
	v_mov_b32_e32 v145, v150
	s_add_i32 s4, s4, s40
	s_lshl_b32 s26, s45, 8
	v_add_u32_e32 v144, s4, v2
	v_lshlrev_b32_e32 v148, 3, v145
	v_ashrrev_i32_e32 v145, 31, v144
	v_lshl_add_u64 v[146:147], v[144:145], 2, s[2:3]
	v_mov_b32_e32 v2, v217
	v_mov_b32_e32 v158, v232
	v_mov_b32_e32 v159, v233
	v_mov_b32_e32 v160, v234
	v_mov_b32_e32 v161, v235
	v_mov_b32_e32 v162, v236
	v_mov_b32_e32 v163, v237
	v_mov_b32_e32 v164, v238
	s_ashr_i32 s27, s26, 31
	s_lshl_b64 s[26:27], s[26:27], 1
	v_ashrrev_i32_e32 v149, 31, v148
	s_cmp_eq_u32 s44, 3
	s_waitcnt vmcnt(8)
	v_fmamk_f32 v2, v2, 0x3a800000, v208
	s_nop 0
	s_nop 0
	s_nop 0
	s_nop 1
	s_nop 1
	s_nop 0
	v_rsq_f32_e32 v2, v2
	s_nop 0
	v_mul_f32_e32 v2, 0x3db8aa3b, v2
	v_pk_mul_f32 v[128:129], v[128:129], v[2:3] op_sel_hi:[1,0]
	v_pk_mul_f32 v[154:155], v[126:127], v[2:3] op_sel_hi:[1,0]
	v_pk_mul_f32 v[126:127], v[124:125], v[2:3] op_sel_hi:[1,0]
	v_cvt_pk_bf16_f32 v124, v128, v129
	v_lshlrev_b64 v[128:129], 13, v[144:145]
	v_lshl_add_u64 v[128:129], s[0:1], 0, v[128:129]
	v_pk_mul_f32 v[130:131], v[130:131], v[2:3] op_sel_hi:[1,0]
	v_lshl_add_u64 v[128:129], v[128:129], 0, s[26:27]
	v_cvt_pk_bf16_f32 v125, v130, v131
	v_lshl_add_u64 v[130:131], v[128:129], 0, s[46:47]
	v_lshlrev_b64 v[128:129], 1, v[148:149]
	v_lshl_add_u64 v[130:131], v[130:131], 0, v[128:129]
	v_cvt_pk_bf16_f32 v126, v126, v127
	v_cvt_pk_bf16_f32 v127, v154, v155
	global_store_dwordx4 v[130:131], v[124:127], off nt
	v_pk_mul_f32 v[122:123], v[122:123], v[2:3] op_sel_hi:[1,0]
	v_pk_mul_f32 v[120:121], v[120:121], v[2:3] op_sel_hi:[1,0]
	v_pk_mul_f32 v[124:125], v[118:119], v[2:3] op_sel_hi:[1,0]
	v_pk_mul_f32 v[118:119], v[116:117], v[2:3] op_sel_hi:[1,0]
	v_cvt_pk_bf16_f32 v116, v120, v121
	v_cvt_pk_bf16_f32 v117, v122, v123
	s_nop 0
	v_cvt_pk_bf16_f32 v118, v118, v119
	v_cvt_pk_bf16_f32 v119, v124, v125
	global_store_dwordx4 v[130:131], v[116:119], off offset:256 nt
	s_nop 1
	v_mov_b32_e32 v2, v158
	v_fmamk_f32 v2, v2, 0x3a800000, v208
	v_add_u32_e32 v116, 16, v144
	v_ashrrev_i32_e32 v117, 31, v116
	s_nop 0
	s_nop 1
	s_nop 1
	s_nop 0
	v_rsq_f32_e32 v2, v2
	s_nop 0
	v_mul_f32_e32 v2, 0x3db8aa3b, v2
	v_pk_mul_f32 v[112:113], v[112:113], v[2:3] op_sel_hi:[1,0]
	v_pk_mul_f32 v[118:119], v[110:111], v[2:3] op_sel_hi:[1,0]
	v_pk_mul_f32 v[110:111], v[108:109], v[2:3] op_sel_hi:[1,0]
	v_cvt_pk_bf16_f32 v108, v112, v113
	v_lshlrev_b64 v[112:113], 13, v[116:117]
	v_lshl_add_u64 v[112:113], s[0:1], 0, v[112:113]
	v_lshl_add_u64 v[112:113], v[112:113], 0, s[26:27]
	v_lshl_add_u64 v[112:113], v[112:113], 0, s[46:47]
	v_pk_mul_f32 v[114:115], v[114:115], v[2:3] op_sel_hi:[1,0]
	v_lshl_add_u64 v[112:113], v[112:113], 0, v[128:129]
	v_cvt_pk_bf16_f32 v109, v114, v115
	v_cvt_pk_bf16_f32 v110, v110, v111
	v_cvt_pk_bf16_f32 v111, v118, v119
	global_store_dwordx4 v[112:113], v[108:111], off nt
	v_pk_mul_f32 v[106:107], v[106:107], v[2:3] op_sel_hi:[1,0]
	v_pk_mul_f32 v[104:105], v[104:105], v[2:3] op_sel_hi:[1,0]
	v_pk_mul_f32 v[108:109], v[102:103], v[2:3] op_sel_hi:[1,0]
	v_pk_mul_f32 v[102:103], v[100:101], v[2:3] op_sel_hi:[1,0]
	v_cvt_pk_bf16_f32 v100, v104, v105
	v_cvt_pk_bf16_f32 v101, v106, v107
	s_nop 0
	v_cvt_pk_bf16_f32 v102, v102, v103
	v_cvt_pk_bf16_f32 v103, v108, v109
	global_store_dwordx4 v[112:113], v[100:103], off offset:256 nt
	s_nop 1
	v_mov_b32_e32 v2, v159
	v_fmamk_f32 v2, v2, 0x3a800000, v208
	v_add_u32_e32 v100, 32, v144
	v_ashrrev_i32_e32 v101, 31, v100
	s_nop 0
	s_nop 1
	s_nop 1
	s_nop 0
	v_rsq_f32_e32 v2, v2
	s_nop 0
	v_mul_f32_e32 v2, 0x3db8aa3b, v2
	v_pk_mul_f32 v[96:97], v[96:97], v[2:3] op_sel_hi:[1,0]
	v_pk_mul_f32 v[102:103], v[94:95], v[2:3] op_sel_hi:[1,0]
	v_pk_mul_f32 v[94:95], v[92:93], v[2:3] op_sel_hi:[1,0]
	v_cvt_pk_bf16_f32 v92, v96, v97
	v_lshlrev_b64 v[96:97], 13, v[100:101]
	v_lshl_add_u64 v[96:97], s[0:1], 0, v[96:97]
	v_lshl_add_u64 v[96:97], v[96:97], 0, s[26:27]
	v_lshl_add_u64 v[96:97], v[96:97], 0, s[46:47]
	v_pk_mul_f32 v[98:99], v[98:99], v[2:3] op_sel_hi:[1,0]
	v_lshl_add_u64 v[96:97], v[96:97], 0, v[128:129]
	v_cvt_pk_bf16_f32 v93, v98, v99
	v_cvt_pk_bf16_f32 v94, v94, v95
	v_cvt_pk_bf16_f32 v95, v102, v103
	global_store_dwordx4 v[96:97], v[92:95], off nt
	v_pk_mul_f32 v[90:91], v[90:91], v[2:3] op_sel_hi:[1,0]
	v_pk_mul_f32 v[88:89], v[88:89], v[2:3] op_sel_hi:[1,0]
	v_pk_mul_f32 v[92:93], v[86:87], v[2:3] op_sel_hi:[1,0]
	v_pk_mul_f32 v[86:87], v[84:85], v[2:3] op_sel_hi:[1,0]
	v_cvt_pk_bf16_f32 v84, v88, v89
	v_cvt_pk_bf16_f32 v85, v90, v91
	s_nop 0
	v_cvt_pk_bf16_f32 v86, v86, v87
	v_cvt_pk_bf16_f32 v87, v92, v93
	global_store_dwordx4 v[96:97], v[84:87], off offset:256 nt
	s_nop 1
	v_mov_b32_e32 v2, v160
	v_fmamk_f32 v2, v2, 0x3a800000, v208
	v_add_u32_e32 v84, 48, v144
	v_ashrrev_i32_e32 v85, 31, v84
	s_nop 0
	s_nop 1
	s_nop 1
	s_nop 0
	v_rsq_f32_e32 v2, v2
	s_nop 0
	v_mul_f32_e32 v2, 0x3db8aa3b, v2
	v_pk_mul_f32 v[80:81], v[80:81], v[2:3] op_sel_hi:[1,0]
	v_pk_mul_f32 v[86:87], v[78:79], v[2:3] op_sel_hi:[1,0]
	v_pk_mul_f32 v[78:79], v[76:77], v[2:3] op_sel_hi:[1,0]
	v_cvt_pk_bf16_f32 v76, v80, v81
	v_lshlrev_b64 v[80:81], 13, v[84:85]
	v_lshl_add_u64 v[80:81], s[0:1], 0, v[80:81]
	v_lshl_add_u64 v[80:81], v[80:81], 0, s[26:27]
	v_lshl_add_u64 v[80:81], v[80:81], 0, s[46:47]
	v_pk_mul_f32 v[82:83], v[82:83], v[2:3] op_sel_hi:[1,0]
	v_lshl_add_u64 v[80:81], v[80:81], 0, v[128:129]
	v_cvt_pk_bf16_f32 v77, v82, v83
	v_cvt_pk_bf16_f32 v78, v78, v79
	v_cvt_pk_bf16_f32 v79, v86, v87
	global_store_dwordx4 v[80:81], v[76:79], off nt
	v_pk_mul_f32 v[74:75], v[74:75], v[2:3] op_sel_hi:[1,0]
	v_pk_mul_f32 v[72:73], v[72:73], v[2:3] op_sel_hi:[1,0]
	v_pk_mul_f32 v[76:77], v[70:71], v[2:3] op_sel_hi:[1,0]
	v_pk_mul_f32 v[70:71], v[68:69], v[2:3] op_sel_hi:[1,0]
	v_cvt_pk_bf16_f32 v68, v72, v73
	v_cvt_pk_bf16_f32 v69, v74, v75
	s_nop 0
	v_cvt_pk_bf16_f32 v70, v70, v71
	v_cvt_pk_bf16_f32 v71, v76, v77
	global_store_dwordx4 v[80:81], v[68:71], off offset:256 nt
	s_nop 1
	v_mov_b32_e32 v2, v161
	v_fmamk_f32 v2, v2, 0x3a800000, v208
	v_add_u32_e32 v68, 0x80, v144
	v_ashrrev_i32_e32 v69, 31, v68
	s_nop 0
	s_nop 1
	s_nop 1
	s_nop 0
	v_rsq_f32_e32 v2, v2
	s_nop 0
	v_mul_f32_e32 v2, 0x3db8aa3b, v2
	v_pk_mul_f32 v[64:65], v[64:65], v[2:3] op_sel_hi:[1,0]
	v_pk_mul_f32 v[70:71], v[62:63], v[2:3] op_sel_hi:[1,0]
	v_pk_mul_f32 v[62:63], v[60:61], v[2:3] op_sel_hi:[1,0]
	v_cvt_pk_bf16_f32 v60, v64, v65
	v_lshlrev_b64 v[64:65], 13, v[68:69]
	v_lshl_add_u64 v[64:65], s[0:1], 0, v[64:65]
	v_lshl_add_u64 v[64:65], v[64:65], 0, s[26:27]
	v_lshl_add_u64 v[64:65], v[64:65], 0, s[46:47]
	v_pk_mul_f32 v[66:67], v[66:67], v[2:3] op_sel_hi:[1,0]
	v_lshl_add_u64 v[64:65], v[64:65], 0, v[128:129]
	v_cvt_pk_bf16_f32 v61, v66, v67
	v_cvt_pk_bf16_f32 v62, v62, v63
	v_cvt_pk_bf16_f32 v63, v70, v71
	global_store_dwordx4 v[64:65], v[60:63], off nt
	v_pk_mul_f32 v[58:59], v[58:59], v[2:3] op_sel_hi:[1,0]
	v_pk_mul_f32 v[56:57], v[56:57], v[2:3] op_sel_hi:[1,0]
	v_pk_mul_f32 v[60:61], v[54:55], v[2:3] op_sel_hi:[1,0]
	v_pk_mul_f32 v[54:55], v[52:53], v[2:3] op_sel_hi:[1,0]
	v_cvt_pk_bf16_f32 v52, v56, v57
	v_cvt_pk_bf16_f32 v53, v58, v59
	s_nop 0
	v_cvt_pk_bf16_f32 v54, v54, v55
	v_cvt_pk_bf16_f32 v55, v60, v61
	global_store_dwordx4 v[64:65], v[52:55], off offset:256 nt
	s_nop 1
	v_mov_b32_e32 v2, v162
	v_fmamk_f32 v2, v2, 0x3a800000, v208
	v_add_u32_e32 v52, 0x90, v144
	v_ashrrev_i32_e32 v53, 31, v52
	s_nop 0
	s_nop 1
	s_nop 1
	s_nop 0
	v_rsq_f32_e32 v2, v2
	s_nop 0
	v_mul_f32_e32 v2, 0x3db8aa3b, v2
	v_pk_mul_f32 v[48:49], v[48:49], v[2:3] op_sel_hi:[1,0]
	v_pk_mul_f32 v[54:55], v[46:47], v[2:3] op_sel_hi:[1,0]
	v_pk_mul_f32 v[46:47], v[44:45], v[2:3] op_sel_hi:[1,0]
	v_cvt_pk_bf16_f32 v44, v48, v49
	v_lshlrev_b64 v[48:49], 13, v[52:53]
	v_lshl_add_u64 v[48:49], s[0:1], 0, v[48:49]
	v_lshl_add_u64 v[48:49], v[48:49], 0, s[26:27]
	v_lshl_add_u64 v[48:49], v[48:49], 0, s[46:47]
	v_pk_mul_f32 v[50:51], v[50:51], v[2:3] op_sel_hi:[1,0]
	v_lshl_add_u64 v[48:49], v[48:49], 0, v[128:129]
	v_cvt_pk_bf16_f32 v45, v50, v51
	v_cvt_pk_bf16_f32 v46, v46, v47
	v_cvt_pk_bf16_f32 v47, v54, v55
	global_store_dwordx4 v[48:49], v[44:47], off nt
	v_pk_mul_f32 v[42:43], v[42:43], v[2:3] op_sel_hi:[1,0]
	v_pk_mul_f32 v[40:41], v[40:41], v[2:3] op_sel_hi:[1,0]
	v_pk_mul_f32 v[44:45], v[38:39], v[2:3] op_sel_hi:[1,0]
	v_pk_mul_f32 v[38:39], v[36:37], v[2:3] op_sel_hi:[1,0]
	v_cvt_pk_bf16_f32 v36, v40, v41
	v_cvt_pk_bf16_f32 v37, v42, v43
	s_nop 0
	v_cvt_pk_bf16_f32 v38, v38, v39
	v_cvt_pk_bf16_f32 v39, v44, v45
	global_store_dwordx4 v[48:49], v[36:39], off offset:256 nt
	s_nop 1
	v_mov_b32_e32 v2, v163
	v_fmamk_f32 v2, v2, 0x3a800000, v208
	v_add_u32_e32 v36, 0xa0, v144
	v_ashrrev_i32_e32 v37, 31, v36
	s_nop 0
	s_nop 1
	s_nop 1
	s_nop 0
	v_rsq_f32_e32 v2, v2
	s_nop 0
	v_mul_f32_e32 v2, 0x3db8aa3b, v2
	v_pk_mul_f32 v[32:33], v[32:33], v[2:3] op_sel_hi:[1,0]
	v_pk_mul_f32 v[38:39], v[30:31], v[2:3] op_sel_hi:[1,0]
	v_pk_mul_f32 v[30:31], v[28:29], v[2:3] op_sel_hi:[1,0]
	v_cvt_pk_bf16_f32 v28, v32, v33
	v_lshlrev_b64 v[32:33], 13, v[36:37]
	v_lshl_add_u64 v[32:33], s[0:1], 0, v[32:33]
	v_lshl_add_u64 v[32:33], v[32:33], 0, s[26:27]
	v_lshl_add_u64 v[32:33], v[32:33], 0, s[46:47]
	v_pk_mul_f32 v[34:35], v[34:35], v[2:3] op_sel_hi:[1,0]
	v_lshl_add_u64 v[32:33], v[32:33], 0, v[128:129]
	v_cvt_pk_bf16_f32 v29, v34, v35
	v_cvt_pk_bf16_f32 v30, v30, v31
	v_cvt_pk_bf16_f32 v31, v38, v39
	global_store_dwordx4 v[32:33], v[28:31], off nt
	v_pk_mul_f32 v[26:27], v[26:27], v[2:3] op_sel_hi:[1,0]
	v_pk_mul_f32 v[24:25], v[24:25], v[2:3] op_sel_hi:[1,0]
	v_pk_mul_f32 v[28:29], v[22:23], v[2:3] op_sel_hi:[1,0]
	v_pk_mul_f32 v[22:23], v[20:21], v[2:3] op_sel_hi:[1,0]
	v_cvt_pk_bf16_f32 v20, v24, v25
	v_cvt_pk_bf16_f32 v21, v26, v27
	s_nop 0
	v_cvt_pk_bf16_f32 v22, v22, v23
	v_cvt_pk_bf16_f32 v23, v28, v29
	global_store_dwordx4 v[32:33], v[20:23], off offset:256 nt
	s_nop 1
	v_mov_b32_e32 v2, v164
	v_fmamk_f32 v2, v2, 0x3a800000, v208
	v_add_u32_e32 v20, 0xb0, v144
	v_ashrrev_i32_e32 v21, 31, v20
	s_nop 0
	s_nop 1
	s_nop 1
	s_mov_b64 s[4:5], -1
	v_rsq_f32_e32 v2, v2
	s_nop 0
	v_mul_f32_e32 v2, 0x3db8aa3b, v2
	v_pk_mul_f32 v[16:17], v[16:17], v[2:3] op_sel_hi:[1,0]
	v_pk_mul_f32 v[22:23], v[14:15], v[2:3] op_sel_hi:[1,0]
	v_pk_mul_f32 v[14:15], v[12:13], v[2:3] op_sel_hi:[1,0]
	v_cvt_pk_bf16_f32 v12, v16, v17
	v_lshlrev_b64 v[16:17], 13, v[20:21]
	v_lshl_add_u64 v[16:17], s[0:1], 0, v[16:17]
	v_lshl_add_u64 v[16:17], v[16:17], 0, s[26:27]
	v_lshl_add_u64 v[16:17], v[16:17], 0, s[46:47]
	v_pk_mul_f32 v[18:19], v[18:19], v[2:3] op_sel_hi:[1,0]
	v_lshl_add_u64 v[16:17], v[16:17], 0, v[128:129]
	v_cvt_pk_bf16_f32 v13, v18, v19
	v_cvt_pk_bf16_f32 v14, v14, v15
	v_cvt_pk_bf16_f32 v15, v22, v23
	global_store_dwordx4 v[16:17], v[12:15], off nt
	v_pk_mul_f32 v[10:11], v[10:11], v[2:3] op_sel_hi:[1,0]
	v_pk_mul_f32 v[8:9], v[8:9], v[2:3] op_sel_hi:[1,0]
	v_pk_mul_f32 v[12:13], v[6:7], v[2:3] op_sel_hi:[1,0]
	v_pk_mul_f32 v[6:7], v[4:5], v[2:3] op_sel_hi:[1,0]
	v_cvt_pk_bf16_f32 v4, v8, v9
	v_cvt_pk_bf16_f32 v5, v10, v11
	s_nop 0
	v_cvt_pk_bf16_f32 v6, v6, v7
	v_cvt_pk_bf16_f32 v7, v12, v13
	global_store_dwordx4 v[16:17], v[4:7], off offset:256 nt
	s_cbranch_scc1 .LBB0_2187
	s_andn2_b64 vcc, exec, s[16:17]
	s_cbranch_vccnz .LBB0_2186
	s_barrier
	s_branch .LBB0_2186

.LBB0_2531:
	s_add_i32 s15, s15, 0x10000
	v_or_b32_e32 v2, s15, v2
	v_add_u32_e32 v4, s16, v2
	v_ashrrev_i32_e32 v5, 31, v4
	v_lshl_add_u64 v[6:7], v[4:5], 2, s[2:3]
	global_load_dword v2, v[6:7], off
	v_lshlrev_b32_e32 v6, 3, v1
	v_lshlrev_b64 v[4:5], 13, v[4:5]
	s_lshl_b32 s46, s14, 1
	v_lshl_add_u64 v[4:5], s[0:1], 0, v[4:5]
	v_mov_b32_e32 v7, v3
	v_lshl_add_u64 v[4:5], v[4:5], 0, s[46:47]
	v_lshl_add_u64 v[4:5], v[4:5], 0, v[6:7]
	s_waitcnt vmcnt(0)
	v_fmamk_f32 v1, v2, 0x3a800000, v208
	v_mul_f32_e32 v2, 0x4f800000, v1
	s_nop 1
	s_nop 0
	s_nop 1
	s_nop 1
	s_nop 1
	v_rsq_f32_e32 v2, v1
	s_nop 0
	v_pk_mul_f32 v[6:7], v[110:111], v[2:3] op_sel_hi:[1,0]
	v_pk_mul_f32 v[8:9], v[108:109], v[2:3] op_sel_hi:[1,0]
	v_max_f32_e32 v7, 0, v7
	v_pk_mul_f32 v[10:11], v[114:115], v[2:3] op_sel_hi:[1,0]
	v_pk_mul_f32 v[12:13], v[112:113], v[2:3] op_sel_hi:[1,0]
	v_pk_mul_f32 v[16:17], v[104:105], v[2:3] op_sel_hi:[1,0]
	v_pk_mul_f32 v[20:21], v[100:101], v[2:3] op_sel_hi:[1,0]
	v_pk_mul_f32 v[24:25], v[96:97], v[2:3] op_sel_hi:[1,0]
	v_pk_mul_f32 v[28:29], v[92:93], v[2:3] op_sel_hi:[1,0]
	v_max_f32_e32 v1, 0, v8
	v_max_f32_e32 v8, 0, v9
	v_max_f32_e32 v6, 0, v6
	v_mul_f32_e32 v7, v7, v7
	v_pk_mul_f32 v[14:15], v[106:107], v[2:3] op_sel_hi:[1,0]
	v_max_f32_e32 v9, 0, v12
	v_max_f32_e32 v12, 0, v13
	v_max_f32_e32 v10, 0, v10
	v_max_f32_e32 v11, 0, v11
	v_max_f32_e32 v13, 0, v16
	v_max_f32_e32 v16, 0, v17
	v_max_f32_e32 v17, 0, v20
	v_max_f32_e32 v20, 0, v21
	v_max_f32_e32 v21, 0, v24
	v_max_f32_e32 v24, 0, v25
	v_max_f32_e32 v25, 0, v28
	v_max_f32_e32 v28, 0, v29
	v_mul_f32_e32 v1, v1, v1
	v_mul_f32_e32 v8, v8, v8
	v_mul_f32_e32 v29, v6, v6
	v_cvt_pk_bf16_f32 v6, v1, v8
	v_cvt_pk_bf16_f32 v7, v29, v7
	v_pk_mul_f32 v[18:19], v[102:103], v[2:3] op_sel_hi:[1,0]
	v_max_f32_e32 v14, 0, v14
	v_max_f32_e32 v15, 0, v15
	v_mul_f32_e32 v9, v9, v9
	v_mul_f32_e32 v12, v12, v12
	v_mul_f32_e32 v10, v10, v10
	v_mul_f32_e32 v11, v11, v11
	global_store_dwordx2 v[4:5], v[6:7], off
	v_cvt_pk_bf16_f32 v6, v9, v12
	v_cvt_pk_bf16_f32 v7, v10, v11
	v_pk_mul_f32 v[22:23], v[98:99], v[2:3] op_sel_hi:[1,0]
	v_max_f32_e32 v18, 0, v18
	v_max_f32_e32 v19, 0, v19
	v_mul_f32_e32 v13, v13, v13
	v_mul_f32_e32 v16, v16, v16
	v_mul_f32_e32 v14, v14, v14
	v_mul_f32_e32 v15, v15, v15
	global_store_dwordx2 v[4:5], v[6:7], off offset:32
	v_cvt_pk_bf16_f32 v6, v13, v16
	v_cvt_pk_bf16_f32 v7, v14, v15
	v_pk_mul_f32 v[26:27], v[94:95], v[2:3] op_sel_hi:[1,0]
	v_max_f32_e32 v22, 0, v22
	v_max_f32_e32 v23, 0, v23
	v_mul_f32_e32 v17, v17, v17
	v_mul_f32_e32 v20, v20, v20
	v_mul_f32_e32 v18, v18, v18
	v_mul_f32_e32 v19, v19, v19
	global_store_dwordx2 v[4:5], v[6:7], off offset:64
	v_cvt_pk_bf16_f32 v6, v17, v20
	v_cvt_pk_bf16_f32 v7, v18, v19
	v_max_f32_e32 v26, 0, v26
	v_max_f32_e32 v27, 0, v27
	v_mul_f32_e32 v21, v21, v21
	v_mul_f32_e32 v24, v24, v24
	v_mul_f32_e32 v22, v22, v22
	v_mul_f32_e32 v23, v23, v23
	global_store_dwordx2 v[4:5], v[6:7], off offset:96
	v_cvt_pk_bf16_f32 v6, v21, v24
	v_cvt_pk_bf16_f32 v7, v22, v23
	v_mul_f32_e32 v25, v25, v25
	v_mul_f32_e32 v28, v28, v28
	v_mul_f32_e32 v26, v26, v26
	v_mul_f32_e32 v27, v27, v27
	global_store_dwordx2 v[4:5], v[6:7], off offset:128
	v_cvt_pk_bf16_f32 v6, v25, v28
	v_cvt_pk_bf16_f32 v7, v26, v27
	global_store_dwordx2 v[4:5], v[6:7], off offset:160
	v_pk_mul_f32 v[6:7], v[90:91], v[2:3] op_sel_hi:[1,0]
	v_pk_mul_f32 v[8:9], v[88:89], v[2:3] op_sel_hi:[1,0]
	v_max_f32_e32 v6, 0, v6
	v_max_f32_e32 v1, 0, v8
	v_max_f32_e32 v8, 0, v9
	v_mul_f32_e32 v9, v6, v6
	v_max_f32_e32 v6, 0, v7
	v_mul_f32_e32 v7, v6, v6
	v_mul_f32_e32 v1, v1, v1
	v_mul_f32_e32 v8, v8, v8
	v_cvt_pk_bf16_f32 v6, v1, v8
	v_cvt_pk_bf16_f32 v7, v9, v7
	global_store_dwordx2 v[4:5], v[6:7], off offset:192
	v_pk_mul_f32 v[6:7], v[86:87], v[2:3] op_sel_hi:[1,0]
	v_pk_mul_f32 v[8:9], v[84:85], v[2:3] op_sel_hi:[1,0]
	v_max_f32_e32 v6, 0, v6
	v_max_f32_e32 v1, 0, v8
	v_max_f32_e32 v8, 0, v9
	v_mul_f32_e32 v9, v6, v6
	v_max_f32_e32 v6, 0, v7
	v_mul_f32_e32 v7, v6, v6
	v_mul_f32_e32 v1, v1, v1
	v_mul_f32_e32 v8, v8, v8
	v_cvt_pk_bf16_f32 v6, v1, v8
	v_cvt_pk_bf16_f32 v7, v9, v7
	global_store_dwordx2 v[4:5], v[6:7], off offset:224
	v_pk_mul_f32 v[6:7], v[82:83], v[2:3] op_sel_hi:[1,0]
	v_pk_mul_f32 v[8:9], v[80:81], v[2:3] op_sel_hi:[1,0]
	v_max_f32_e32 v6, 0, v6
	v_max_f32_e32 v1, 0, v8
	v_max_f32_e32 v8, 0, v9
	v_mul_f32_e32 v9, v6, v6
	v_max_f32_e32 v6, 0, v7
	v_mul_f32_e32 v7, v6, v6
	v_mul_f32_e32 v1, v1, v1
	v_mul_f32_e32 v8, v8, v8
	v_cvt_pk_bf16_f32 v6, v1, v8
	v_cvt_pk_bf16_f32 v7, v9, v7
	global_store_dwordx2 v[4:5], v[6:7], off offset:256
	v_pk_mul_f32 v[6:7], v[78:79], v[2:3] op_sel_hi:[1,0]
	v_pk_mul_f32 v[8:9], v[76:77], v[2:3] op_sel_hi:[1,0]
	v_max_f32_e32 v6, 0, v6
	v_max_f32_e32 v1, 0, v8
	v_max_f32_e32 v8, 0, v9
	v_mul_f32_e32 v9, v6, v6
	v_max_f32_e32 v6, 0, v7
	v_mul_f32_e32 v7, v6, v6
	v_mul_f32_e32 v1, v1, v1
	v_mul_f32_e32 v8, v8, v8
	v_cvt_pk_bf16_f32 v6, v1, v8
	v_cvt_pk_bf16_f32 v7, v9, v7
	global_store_dwordx2 v[4:5], v[6:7], off offset:288
	v_pk_mul_f32 v[6:7], v[74:75], v[2:3] op_sel_hi:[1,0]
	v_pk_mul_f32 v[8:9], v[72:73], v[2:3] op_sel_hi:[1,0]
	v_max_f32_e32 v6, 0, v6
	v_max_f32_e32 v1, 0, v8
	v_max_f32_e32 v8, 0, v9
	v_mul_f32_e32 v9, v6, v6
	v_max_f32_e32 v6, 0, v7
	v_mul_f32_e32 v7, v6, v6
	v_mul_f32_e32 v1, v1, v1
	v_mul_f32_e32 v8, v8, v8
	v_cvt_pk_bf16_f32 v6, v1, v8
	v_cvt_pk_bf16_f32 v7, v9, v7
	global_store_dwordx2 v[4:5], v[6:7], off offset:320
	v_pk_mul_f32 v[6:7], v[70:71], v[2:3] op_sel_hi:[1,0]
	v_pk_mul_f32 v[8:9], v[68:69], v[2:3] op_sel_hi:[1,0]
	v_max_f32_e32 v6, 0, v6
	v_max_f32_e32 v1, 0, v8
	v_max_f32_e32 v8, 0, v9
	v_mul_f32_e32 v9, v6, v6
	v_max_f32_e32 v6, 0, v7
	v_mul_f32_e32 v7, v6, v6
	v_mul_f32_e32 v1, v1, v1
	v_mul_f32_e32 v8, v8, v8
	v_cvt_pk_bf16_f32 v6, v1, v8
	v_cvt_pk_bf16_f32 v7, v9, v7
	global_store_dwordx2 v[4:5], v[6:7], off offset:352
	v_pk_mul_f32 v[6:7], v[66:67], v[2:3] op_sel_hi:[1,0]
	v_pk_mul_f32 v[8:9], v[64:65], v[2:3] op_sel_hi:[1,0]
	v_max_f32_e32 v6, 0, v6
	v_max_f32_e32 v1, 0, v8
	v_max_f32_e32 v8, 0, v9
	v_mul_f32_e32 v9, v6, v6
	v_max_f32_e32 v6, 0, v7
	v_mul_f32_e32 v7, v6, v6
	v_mul_f32_e32 v1, v1, v1
	v_mul_f32_e32 v8, v8, v8
	v_cvt_pk_bf16_f32 v6, v1, v8
	v_cvt_pk_bf16_f32 v7, v9, v7
	global_store_dwordx2 v[4:5], v[6:7], off offset:384
	v_pk_mul_f32 v[6:7], v[62:63], v[2:3] op_sel_hi:[1,0]
	v_pk_mul_f32 v[8:9], v[60:61], v[2:3] op_sel_hi:[1,0]
	v_max_f32_e32 v6, 0, v6
	v_max_f32_e32 v1, 0, v8
	v_max_f32_e32 v8, 0, v9
	v_mul_f32_e32 v9, v6, v6
	v_max_f32_e32 v6, 0, v7
	v_mul_f32_e32 v7, v6, v6
	v_mul_f32_e32 v1, v1, v1
	v_mul_f32_e32 v8, v8, v8
	v_cvt_pk_bf16_f32 v6, v1, v8
	v_cvt_pk_bf16_f32 v7, v9, v7
	global_store_dwordx2 v[4:5], v[6:7], off offset:416
	v_pk_mul_f32 v[6:7], v[58:59], v[2:3] op_sel_hi:[1,0]
	v_pk_mul_f32 v[8:9], v[56:57], v[2:3] op_sel_hi:[1,0]
	v_max_f32_e32 v6, 0, v6
	v_max_f32_e32 v1, 0, v8
	v_max_f32_e32 v8, 0, v9
	v_mul_f32_e32 v9, v6, v6
	v_max_f32_e32 v6, 0, v7
	v_mul_f32_e32 v7, v6, v6
	v_mul_f32_e32 v1, v1, v1
	v_mul_f32_e32 v8, v8, v8
	v_cvt_pk_bf16_f32 v6, v1, v8
	v_cvt_pk_bf16_f32 v7, v9, v7
	global_store_dwordx2 v[4:5], v[6:7], off offset:448
	v_pk_mul_f32 v[6:7], v[54:55], v[2:3] op_sel_hi:[1,0]
	v_pk_mul_f32 v[8:9], v[52:53], v[2:3] op_sel_hi:[1,0]
	v_max_f32_e32 v6, 0, v6
	v_max_f32_e32 v1, 0, v8
	v_mul_f32_e32 v8, v6, v6
	v_max_f32_e32 v6, 0, v7
	v_max_f32_e32 v2, 0, v9
	v_mul_f32_e32 v7, v6, v6
	v_mul_f32_e32 v1, v1, v1
	v_mul_f32_e32 v2, v2, v2
	v_cvt_pk_bf16_f32 v6, v1, v2
	v_cvt_pk_bf16_f32 v7, v8, v7
	global_store_dwordx2 v[4:5], v[6:7], off offset:480

.LBB0_2539:
	s_ashr_i32 s19, s18, 31
	s_lshl_b64 s[22:23], s[18:19], 19
	s_add_u32 s22, s31, s22
	s_addc_u32 s23, s34, s23
	s_and_b64 s[24:25], s[28:29], exec
	s_cselect_b32 s19, s23, s5
	s_cselect_b32 s49, s22, s4
	s_ashr_i32 s21, s20, 31
	s_lshl_b64 s[24:25], s[20:21], 19
	s_add_u32 s24, s8, s24
	s_addc_u32 s25, s9, s25
	s_and_b64 s[28:29], s[28:29], exec
	s_cselect_b32 s21, s25, s27
	s_cselect_b32 s50, s24, s26
	s_add_u32 s4, s4, 0x40080
	s_addc_u32 s5, s5, 0
	s_add_u32 s51, s26, 0x100
	v_mov_b32_e32 v4, 0
	s_addc_u32 s52, s27, 0
	s_mov_b32 s53, -2
	v_mov_b32_e32 v5, v4
	v_mov_b32_e32 v6, v4
	v_mov_b32_e32 v7, v4
	v_mov_b32_e32 v8, v4
	v_mov_b32_e32 v9, v4
	v_mov_b32_e32 v10, v4
	v_mov_b32_e32 v11, v4
	v_mov_b32_e32 v20, v4
	v_mov_b32_e32 v21, v4
	v_mov_b32_e32 v22, v4
	v_mov_b32_e32 v23, v4
	v_mov_b32_e32 v24, v4
	v_mov_b32_e32 v25, v4
	v_mov_b32_e32 v26, v4
	v_mov_b32_e32 v27, v4
	v_mov_b32_e32 v36, v4
	v_mov_b32_e32 v37, v4
	v_mov_b32_e32 v38, v4
	v_mov_b32_e32 v39, v4
	v_mov_b32_e32 v40, v4
	v_mov_b32_e32 v41, v4
	v_mov_b32_e32 v42, v4
	v_mov_b32_e32 v43, v4
	v_mov_b32_e32 v52, v4
	v_mov_b32_e32 v53, v4
	v_mov_b32_e32 v54, v4
	v_mov_b32_e32 v55, v4
	v_mov_b32_e32 v56, v4
	v_mov_b32_e32 v57, v4
	v_mov_b32_e32 v58, v4
	v_mov_b32_e32 v59, v4
	v_mov_b32_e32 v12, v4
	v_mov_b32_e32 v13, v4
	v_mov_b32_e32 v14, v4
	v_mov_b32_e32 v15, v4
	v_mov_b32_e32 v16, v4
	v_mov_b32_e32 v17, v4
	v_mov_b32_e32 v18, v4
	v_mov_b32_e32 v19, v4
	v_mov_b32_e32 v28, v4
	v_mov_b32_e32 v29, v4
	v_mov_b32_e32 v30, v4
	v_mov_b32_e32 v31, v4
	v_mov_b32_e32 v32, v4
	v_mov_b32_e32 v33, v4
	v_mov_b32_e32 v34, v4
	v_mov_b32_e32 v35, v4
	v_mov_b32_e32 v44, v4
	v_mov_b32_e32 v45, v4
	v_mov_b32_e32 v46, v4
	v_mov_b32_e32 v47, v4
	v_mov_b32_e32 v48, v4
	v_mov_b32_e32 v49, v4
	v_mov_b32_e32 v50, v4
	v_mov_b32_e32 v51, v4
	v_mov_b32_e32 v60, v4
	v_mov_b32_e32 v61, v4
	v_mov_b32_e32 v62, v4
	v_mov_b32_e32 v63, v4
	v_mov_b32_e32 v64, v4
	v_mov_b32_e32 v65, v4
	v_mov_b32_e32 v66, v4
	v_mov_b32_e32 v67, v4
	v_mov_b32_e32 v68, v4
	v_mov_b32_e32 v69, v4
	v_mov_b32_e32 v70, v4
	v_mov_b32_e32 v71, v4
	v_mov_b32_e32 v72, v4
	v_mov_b32_e32 v73, v4
	v_mov_b32_e32 v74, v4
	v_mov_b32_e32 v75, v4
	v_mov_b32_e32 v84, v4
	v_mov_b32_e32 v85, v4
	v_mov_b32_e32 v86, v4
	v_mov_b32_e32 v87, v4
	v_mov_b32_e32 v88, v4
	v_mov_b32_e32 v89, v4
	v_mov_b32_e32 v90, v4
	v_mov_b32_e32 v91, v4
	v_mov_b32_e32 v100, v4
	v_mov_b32_e32 v101, v4
	v_mov_b32_e32 v102, v4
	v_mov_b32_e32 v103, v4
	v_mov_b32_e32 v104, v4
	v_mov_b32_e32 v105, v4
	v_mov_b32_e32 v106, v4
	v_mov_b32_e32 v107, v4
	v_mov_b32_e32 v116, v4
	v_mov_b32_e32 v117, v4
	v_mov_b32_e32 v118, v4
	v_mov_b32_e32 v119, v4
	v_mov_b32_e32 v120, v4
	v_mov_b32_e32 v121, v4
	v_mov_b32_e32 v122, v4
	v_mov_b32_e32 v123, v4
	v_mov_b32_e32 v76, v4
	v_mov_b32_e32 v77, v4
	v_mov_b32_e32 v78, v4
	v_mov_b32_e32 v79, v4
	v_mov_b32_e32 v80, v4
	v_mov_b32_e32 v81, v4
	v_mov_b32_e32 v82, v4
	v_mov_b32_e32 v83, v4
	v_mov_b32_e32 v92, v4
	v_mov_b32_e32 v93, v4
	v_mov_b32_e32 v94, v4
	v_mov_b32_e32 v95, v4
	v_mov_b32_e32 v96, v4
	v_mov_b32_e32 v97, v4
	v_mov_b32_e32 v98, v4
	v_mov_b32_e32 v99, v4
	v_mov_b32_e32 v108, v4
	v_mov_b32_e32 v109, v4
	v_mov_b32_e32 v110, v4
	v_mov_b32_e32 v111, v4
	v_mov_b32_e32 v112, v4
	v_mov_b32_e32 v113, v4
	v_mov_b32_e32 v114, v4
	v_mov_b32_e32 v115, v4
	v_mov_b32_e32 v124, v4
	v_mov_b32_e32 v125, v4
	v_mov_b32_e32 v126, v4
	v_mov_b32_e32 v127, v4
	v_mov_b32_e32 v128, v4
	v_mov_b32_e32 v129, v4
	v_mov_b32_e32 v130, v4
	v_mov_b32_e32 v131, v4
	s_lshl_b32 s99, s48, 8
	v_mov_b32_e32 v217, v1
	s_add_i32 s99, s99, s40
	v_add_u32_e32 v228, s99, v217
	v_ashrrev_i32_e32 v229, 31, v228
	v_lshl_add_u64 v[230:231], v[228:229], 2, s[2:3]
	global_load_dword v232, v[230:231], off
	global_load_dword v233, v[230:231], off offset:64
	global_load_dword v234, v[230:231], off offset:128
	global_load_dword v235, v[230:231], off offset:192
	global_load_dword v236, v[230:231], off offset:512
	global_load_dword v237, v[230:231], off offset:576
	global_load_dword v238, v[230:231], off offset:640
	global_load_dword v239, v[230:231], off offset:704

.LBB0_2543:
	s_lshl_b32 s4, s48, 8
	v_mov_b32_e32 v2, v1
	v_mov_b32_e32 v145, v150
	s_add_i32 s4, s4, s40
	s_lshl_b32 s26, s45, 8
	v_add_u32_e32 v144, s4, v2
	v_lshlrev_b32_e32 v148, 3, v145
	v_ashrrev_i32_e32 v145, 31, v144
	v_lshl_add_u64 v[146:147], v[144:145], 2, s[2:3]
	v_mov_b32_e32 v2, v232
	v_mov_b32_e32 v158, v233
	v_mov_b32_e32 v159, v234
	v_mov_b32_e32 v160, v235
	v_mov_b32_e32 v161, v236
	v_mov_b32_e32 v162, v237
	v_mov_b32_e32 v163, v238
	v_mov_b32_e32 v164, v239
	s_ashr_i32 s27, s26, 31
	s_lshl_b64 s[26:27], s[26:27], 1
	v_ashrrev_i32_e32 v149, 31, v148
	s_cmp_eq_u32 s44, 15
	s_waitcnt vmcnt(8)
	v_fmamk_f32 v2, v2, 0x3a800000, v208
	s_nop 0
	s_nop 0
	s_nop 0
	s_nop 1
	s_nop 1
	s_nop 0
	v_rsq_f32_e32 v2, v2
	s_nop 0
	v_pk_mul_f32 v[126:127], v[126:127], v[2:3] op_sel_hi:[1,0]
	v_pk_mul_f32 v[124:125], v[124:125], v[2:3] op_sel_hi:[1,0]
	v_pk_mul_f32 v[130:131], v[130:131], v[2:3] op_sel_hi:[1,0]
	v_pk_mul_f32 v[128:129], v[128:129], v[2:3] op_sel_hi:[1,0]
	v_max_f32_e32 v124, 0, v124
	v_max_f32_e32 v125, 0, v125
	v_max_f32_e32 v126, 0, v126
	v_max_f32_e32 v128, 0, v128
	v_mul_f32_e32 v153, v124, v124
	v_max_f32_e32 v124, 0, v129
	v_mul_f32_e32 v129, v125, v125
	v_max_f32_e32 v125, 0, v130
	v_mul_f32_e32 v130, v126, v126
	v_max_f32_e32 v126, 0, v131
	v_mul_f32_e32 v128, v128, v128
	v_mul_f32_e32 v124, v124, v124
	v_mul_f32_e32 v125, v125, v125
	v_mul_f32_e32 v126, v126, v126
	v_cvt_pk_bf16_f32 v124, v128, v124
	v_cvt_pk_bf16_f32 v125, v125, v126
	v_cvt_pk_bf16_f32 v126, v153, v129
	v_lshlrev_b64 v[128:129], 13, v[144:145]
	v_max_f32_e32 v127, 0, v127
	v_lshl_add_u64 v[128:129], s[0:1], 0, v[128:129]
	v_pk_mul_f32 v[118:119], v[118:119], v[2:3] op_sel_hi:[1,0]
	v_pk_mul_f32 v[116:117], v[116:117], v[2:3] op_sel_hi:[1,0]
	v_mul_f32_e32 v127, v127, v127
	v_lshl_add_u64 v[128:129], v[128:129], 0, s[26:27]
	v_pk_mul_f32 v[122:123], v[122:123], v[2:3] op_sel_hi:[1,0]
	v_pk_mul_f32 v[120:121], v[120:121], v[2:3] op_sel_hi:[1,0]
	v_max_f32_e32 v116, 0, v116
	v_max_f32_e32 v117, 0, v117
	v_max_f32_e32 v118, 0, v118
	v_cvt_pk_bf16_f32 v127, v130, v127
	v_lshl_add_u64 v[130:131], v[128:129], 0, s[46:47]
	v_lshlrev_b64 v[128:129], 1, v[148:149]
	v_max_f32_e32 v2, 0, v120
	v_mul_f32_e32 v120, v116, v116
	v_max_f32_e32 v116, 0, v121
	v_mul_f32_e32 v121, v117, v117
	v_max_f32_e32 v117, 0, v122
	v_mul_f32_e32 v122, v118, v118
	v_max_f32_e32 v118, 0, v123
	v_max_f32_e32 v119, 0, v119
	v_lshl_add_u64 v[130:131], v[130:131], 0, v[128:129]
	v_mul_f32_e32 v116, v116, v116
	v_mul_f32_e32 v117, v117, v117
	v_mul_f32_e32 v118, v118, v118
	v_mul_f32_e32 v119, v119, v119
	global_store_dwordx4 v[130:131], v[124:127], off nt
	v_mul_f32_e32 v2, v2, v2
	v_cvt_pk_bf16_f32 v116, v2, v116
	v_cvt_pk_bf16_f32 v117, v117, v118
	v_cvt_pk_bf16_f32 v118, v120, v121
	v_cvt_pk_bf16_f32 v119, v122, v119
	global_store_dwordx4 v[130:131], v[116:119], off offset:256 nt
	s_nop 1
	v_mov_b32_e32 v2, v158
	v_fmamk_f32 v2, v2, 0x3a800000, v208
	v_add_u32_e32 v116, 16, v144
	v_ashrrev_i32_e32 v117, 31, v116
	s_nop 0
	s_nop 1
	s_nop 1
	s_nop 0
	v_rsq_f32_e32 v2, v2
	s_nop 0
	v_pk_mul_f32 v[110:111], v[110:111], v[2:3] op_sel_hi:[1,0]
	v_pk_mul_f32 v[108:109], v[108:109], v[2:3] op_sel_hi:[1,0]
	v_pk_mul_f32 v[114:115], v[114:115], v[2:3] op_sel_hi:[1,0]
	v_pk_mul_f32 v[112:113], v[112:113], v[2:3] op_sel_hi:[1,0]
	v_max_f32_e32 v108, 0, v108
	v_max_f32_e32 v109, 0, v109
	v_max_f32_e32 v110, 0, v110
	v_max_f32_e32 v112, 0, v112
	v_mul_f32_e32 v118, v108, v108
	v_max_f32_e32 v108, 0, v113
	v_mul_f32_e32 v113, v109, v109
	v_max_f32_e32 v109, 0, v114
	v_mul_f32_e32 v114, v110, v110
	v_max_f32_e32 v110, 0, v115
	v_mul_f32_e32 v112, v112, v112
	v_mul_f32_e32 v108, v108, v108
	v_mul_f32_e32 v109, v109, v109
	v_mul_f32_e32 v110, v110, v110
	v_cvt_pk_bf16_f32 v108, v112, v108
	v_cvt_pk_bf16_f32 v109, v109, v110
	v_cvt_pk_bf16_f32 v110, v118, v113
	v_lshlrev_b64 v[112:113], 13, v[116:117]
	v_lshl_add_u64 v[112:113], s[0:1], 0, v[112:113]
	v_pk_mul_f32 v[102:103], v[102:103], v[2:3] op_sel_hi:[1,0]
	v_pk_mul_f32 v[100:101], v[100:101], v[2:3] op_sel_hi:[1,0]
	v_lshl_add_u64 v[112:113], v[112:113], 0, s[26:27]
	v_pk_mul_f32 v[106:107], v[106:107], v[2:3] op_sel_hi:[1,0]
	v_pk_mul_f32 v[104:105], v[104:105], v[2:3] op_sel_hi:[1,0]
	v_max_f32_e32 v100, 0, v100
	v_max_f32_e32 v101, 0, v101
	v_max_f32_e32 v102, 0, v102
	v_max_f32_e32 v111, 0, v111
	v_lshl_add_u64 v[112:113], v[112:113], 0, s[46:47]
	v_max_f32_e32 v2, 0, v104
	v_mul_f32_e32 v104, v100, v100
	v_max_f32_e32 v100, 0, v105
	v_mul_f32_e32 v105, v101, v101
	v_max_f32_e32 v101, 0, v106
	v_mul_f32_e32 v106, v102, v102
	v_max_f32_e32 v102, 0, v107
	v_max_f32_e32 v103, 0, v103
	v_mul_f32_e32 v111, v111, v111
	v_lshl_add_u64 v[112:113], v[112:113], 0, v[128:129]
	v_mul_f32_e32 v100, v100, v100
	v_mul_f32_e32 v101, v101, v101
	v_mul_f32_e32 v102, v102, v102
	v_mul_f32_e32 v103, v103, v103
	v_cvt_pk_bf16_f32 v111, v114, v111
	global_store_dwordx4 v[112:113], v[108:111], off nt
	v_mul_f32_e32 v2, v2, v2
	v_cvt_pk_bf16_f32 v100, v2, v100
	v_cvt_pk_bf16_f32 v101, v101, v102
	v_cvt_pk_bf16_f32 v102, v104, v105
	v_cvt_pk_bf16_f32 v103, v106, v103
	global_store_dwordx4 v[112:113], v[100:103], off offset:256 nt
	s_nop 1
	v_mov_b32_e32 v2, v159
	v_fmamk_f32 v2, v2, 0x3a800000, v208
	v_add_u32_e32 v100, 32, v144
	v_ashrrev_i32_e32 v101, 31, v100
	s_nop 0
	s_nop 1
	s_nop 1
	s_nop 0
	v_rsq_f32_e32 v2, v2
	s_nop 0
	v_pk_mul_f32 v[94:95], v[94:95], v[2:3] op_sel_hi:[1,0]
	v_pk_mul_f32 v[92:93], v[92:93], v[2:3] op_sel_hi:[1,0]
	v_pk_mul_f32 v[98:99], v[98:99], v[2:3] op_sel_hi:[1,0]
	v_pk_mul_f32 v[96:97], v[96:97], v[2:3] op_sel_hi:[1,0]
	v_max_f32_e32 v92, 0, v92
	v_max_f32_e32 v93, 0, v93
	v_max_f32_e32 v94, 0, v94
	v_max_f32_e32 v96, 0, v96
	v_mul_f32_e32 v102, v92, v92
	v_max_f32_e32 v92, 0, v97
	v_mul_f32_e32 v97, v93, v93
	v_max_f32_e32 v93, 0, v98
	v_mul_f32_e32 v98, v94, v94
	v_max_f32_e32 v94, 0, v99
	v_mul_f32_e32 v96, v96, v96
	v_mul_f32_e32 v92, v92, v92
	v_mul_f32_e32 v93, v93, v93
	v_mul_f32_e32 v94, v94, v94
	v_cvt_pk_bf16_f32 v92, v96, v92
	v_cvt_pk_bf16_f32 v93, v93, v94
	v_cvt_pk_bf16_f32 v94, v102, v97
	v_lshlrev_b64 v[96:97], 13, v[100:101]
	v_lshl_add_u64 v[96:97], s[0:1], 0, v[96:97]
	v_pk_mul_f32 v[86:87], v[86:87], v[2:3] op_sel_hi:[1,0]
	v_pk_mul_f32 v[84:85], v[84:85], v[2:3] op_sel_hi:[1,0]
	v_lshl_add_u64 v[96:97], v[96:97], 0, s[26:27]
	v_pk_mul_f32 v[90:91], v[90:91], v[2:3] op_sel_hi:[1,0]
	v_pk_mul_f32 v[88:89], v[88:89], v[2:3] op_sel_hi:[1,0]
	v_max_f32_e32 v84, 0, v84
	v_max_f32_e32 v85, 0, v85
	v_max_f32_e32 v86, 0, v86
	v_max_f32_e32 v95, 0, v95
	v_lshl_add_u64 v[96:97], v[96:97], 0, s[46:47]
	v_max_f32_e32 v2, 0, v88
	v_mul_f32_e32 v88, v84, v84
	v_max_f32_e32 v84, 0, v89
	v_mul_f32_e32 v89, v85, v85
	v_max_f32_e32 v85, 0, v90
	v_mul_f32_e32 v90, v86, v86
	v_max_f32_e32 v86, 0, v91
	v_max_f32_e32 v87, 0, v87
	v_mul_f32_e32 v95, v95, v95
	v_lshl_add_u64 v[96:97], v[96:97], 0, v[128:129]
	v_mul_f32_e32 v84, v84, v84
	v_mul_f32_e32 v85, v85, v85
	v_mul_f32_e32 v86, v86, v86
	v_mul_f32_e32 v87, v87, v87
	v_cvt_pk_bf16_f32 v95, v98, v95
	global_store_dwordx4 v[96:97], v[92:95], off nt
	v_mul_f32_e32 v2, v2, v2
	v_cvt_pk_bf16_f32 v84, v2, v84
	v_cvt_pk_bf16_f32 v85, v85, v86
	v_cvt_pk_bf16_f32 v86, v88, v89
	v_cvt_pk_bf16_f32 v87, v90, v87
	global_store_dwordx4 v[96:97], v[84:87], off offset:256 nt
	s_nop 1
	v_mov_b32_e32 v2, v160
	v_fmamk_f32 v2, v2, 0x3a800000, v208
	v_add_u32_e32 v84, 48, v144
	v_ashrrev_i32_e32 v85, 31, v84
	s_nop 0
	s_nop 1
	s_nop 1
	s_nop 0
	v_rsq_f32_e32 v2, v2
	s_nop 0
	v_pk_mul_f32 v[78:79], v[78:79], v[2:3] op_sel_hi:[1,0]
	v_pk_mul_f32 v[76:77], v[76:77], v[2:3] op_sel_hi:[1,0]
	v_pk_mul_f32 v[82:83], v[82:83], v[2:3] op_sel_hi:[1,0]
	v_pk_mul_f32 v[80:81], v[80:81], v[2:3] op_sel_hi:[1,0]
	v_max_f32_e32 v76, 0, v76
	v_max_f32_e32 v77, 0, v77
	v_max_f32_e32 v78, 0, v78
	v_max_f32_e32 v80, 0, v80
	v_mul_f32_e32 v86, v76, v76
	v_max_f32_e32 v76, 0, v81
	v_mul_f32_e32 v81, v77, v77
	v_max_f32_e32 v77, 0, v82
	v_mul_f32_e32 v82, v78, v78
	v_max_f32_e32 v78, 0, v83
	v_mul_f32_e32 v80, v80, v80
	v_mul_f32_e32 v76, v76, v76
	v_mul_f32_e32 v77, v77, v77
	v_mul_f32_e32 v78, v78, v78
	v_cvt_pk_bf16_f32 v76, v80, v76
	v_cvt_pk_bf16_f32 v77, v77, v78
	v_cvt_pk_bf16_f32 v78, v86, v81
	v_lshlrev_b64 v[80:81], 13, v[84:85]
	v_lshl_add_u64 v[80:81], s[0:1], 0, v[80:81]
	v_pk_mul_f32 v[70:71], v[70:71], v[2:3] op_sel_hi:[1,0]
	v_pk_mul_f32 v[68:69], v[68:69], v[2:3] op_sel_hi:[1,0]
	v_lshl_add_u64 v[80:81], v[80:81], 0, s[26:27]
	v_pk_mul_f32 v[74:75], v[74:75], v[2:3] op_sel_hi:[1,0]
	v_pk_mul_f32 v[72:73], v[72:73], v[2:3] op_sel_hi:[1,0]
	v_max_f32_e32 v68, 0, v68
	v_max_f32_e32 v69, 0, v69
	v_max_f32_e32 v70, 0, v70
	v_max_f32_e32 v79, 0, v79
	v_lshl_add_u64 v[80:81], v[80:81], 0, s[46:47]
	v_max_f32_e32 v2, 0, v72
	v_mul_f32_e32 v72, v68, v68
	v_max_f32_e32 v68, 0, v73
	v_mul_f32_e32 v73, v69, v69
	v_max_f32_e32 v69, 0, v74
	v_mul_f32_e32 v74, v70, v70
	v_max_f32_e32 v70, 0, v75
	v_max_f32_e32 v71, 0, v71
	v_mul_f32_e32 v79, v79, v79
	v_lshl_add_u64 v[80:81], v[80:81], 0, v[128:129]
	v_mul_f32_e32 v68, v68, v68
	v_mul_f32_e32 v69, v69, v69
	v_mul_f32_e32 v70, v70, v70
	v_mul_f32_e32 v71, v71, v71
	v_cvt_pk_bf16_f32 v79, v82, v79
	global_store_dwordx4 v[80:81], v[76:79], off nt
	v_mul_f32_e32 v2, v2, v2
	v_cvt_pk_bf16_f32 v68, v2, v68
	v_cvt_pk_bf16_f32 v69, v69, v70
	v_cvt_pk_bf16_f32 v70, v72, v73
	v_cvt_pk_bf16_f32 v71, v74, v71
	global_store_dwordx4 v[80:81], v[68:71], off offset:256 nt
	s_nop 1
	v_mov_b32_e32 v2, v161
	v_fmamk_f32 v2, v2, 0x3a800000, v208
	v_add_u32_e32 v68, 0x80, v144
	v_ashrrev_i32_e32 v69, 31, v68
	s_nop 0
	s_nop 1
	s_nop 1
	s_nop 0
	v_rsq_f32_e32 v2, v2
	s_nop 0
	v_pk_mul_f32 v[62:63], v[62:63], v[2:3] op_sel_hi:[1,0]
	v_pk_mul_f32 v[60:61], v[60:61], v[2:3] op_sel_hi:[1,0]
	v_pk_mul_f32 v[66:67], v[66:67], v[2:3] op_sel_hi:[1,0]
	v_pk_mul_f32 v[64:65], v[64:65], v[2:3] op_sel_hi:[1,0]
	v_max_f32_e32 v60, 0, v60
	v_max_f32_e32 v61, 0, v61
	v_max_f32_e32 v62, 0, v62
	v_max_f32_e32 v64, 0, v64
	v_mul_f32_e32 v70, v60, v60
	v_max_f32_e32 v60, 0, v65
	v_mul_f32_e32 v65, v61, v61
	v_max_f32_e32 v61, 0, v66
	v_mul_f32_e32 v66, v62, v62
	v_max_f32_e32 v62, 0, v67
	v_mul_f32_e32 v64, v64, v64
	v_mul_f32_e32 v60, v60, v60
	v_mul_f32_e32 v61, v61, v61
	v_mul_f32_e32 v62, v62, v62
	v_cvt_pk_bf16_f32 v60, v64, v60
	v_cvt_pk_bf16_f32 v61, v61, v62
	v_cvt_pk_bf16_f32 v62, v70, v65
	v_lshlrev_b64 v[64:65], 13, v[68:69]
	v_lshl_add_u64 v[64:65], s[0:1], 0, v[64:65]
	v_pk_mul_f32 v[54:55], v[54:55], v[2:3] op_sel_hi:[1,0]
	v_pk_mul_f32 v[52:53], v[52:53], v[2:3] op_sel_hi:[1,0]
	v_lshl_add_u64 v[64:65], v[64:65], 0, s[26:27]
	v_pk_mul_f32 v[58:59], v[58:59], v[2:3] op_sel_hi:[1,0]
	v_pk_mul_f32 v[56:57], v[56:57], v[2:3] op_sel_hi:[1,0]
	v_max_f32_e32 v52, 0, v52
	v_max_f32_e32 v53, 0, v53
	v_max_f32_e32 v54, 0, v54
	v_max_f32_e32 v63, 0, v63
	v_lshl_add_u64 v[64:65], v[64:65], 0, s[46:47]
	v_max_f32_e32 v2, 0, v56
	v_mul_f32_e32 v56, v52, v52
	v_max_f32_e32 v52, 0, v57
	v_mul_f32_e32 v57, v53, v53
	v_max_f32_e32 v53, 0, v58
	v_mul_f32_e32 v58, v54, v54
	v_max_f32_e32 v54, 0, v59
	v_max_f32_e32 v55, 0, v55
	v_mul_f32_e32 v63, v63, v63
	v_lshl_add_u64 v[64:65], v[64:65], 0, v[128:129]
	v_mul_f32_e32 v52, v52, v52
	v_mul_f32_e32 v53, v53, v53
	v_mul_f32_e32 v54, v54, v54
	v_mul_f32_e32 v55, v55, v55
	v_cvt_pk_bf16_f32 v63, v66, v63
	global_store_dwordx4 v[64:65], v[60:63], off nt
	v_mul_f32_e32 v2, v2, v2
	v_cvt_pk_bf16_f32 v52, v2, v52
	v_cvt_pk_bf16_f32 v53, v53, v54
	v_cvt_pk_bf16_f32 v54, v56, v57
	v_cvt_pk_bf16_f32 v55, v58, v55
	global_store_dwordx4 v[64:65], v[52:55], off offset:256 nt
	s_nop 1
	v_mov_b32_e32 v2, v162
	v_fmamk_f32 v2, v2, 0x3a800000, v208
	v_cmp_gt_f32_e32 vcc, s90, v2
	v_mul_f32_e32 v54, 0x4f800000, v2
	v_add_u32_e32 v52, 0x90, v144
	v_cndmask_b32_e32 v2, v2, v54, vcc
	v_sqrt_f32_e32 v54, v2
	v_ashrrev_i32_e32 v53, 31, v52
	v_add_u32_e32 v55, -1, v54
	v_fma_f32 v56, -v55, v54, v2
	v_cmp_ge_f32_e64 s[4:5], 0, v56
	v_add_u32_e32 v56, 1, v54
	s_nop 0
	v_cndmask_b32_e64 v55, v54, v55, s[4:5]
	v_fma_f32 v54, -v56, v54, v2
	v_cmp_lt_f32_e64 s[4:5], 0, v54
	s_nop 1
	v_cndmask_b32_e64 v54, v55, v56, s[4:5]
	v_mul_f32_e32 v55, 0x37800000, v54
	v_cndmask_b32_e32 v54, v54, v55, vcc
	v_cmp_class_f32_e32 vcc, v2, v209
	s_nop 1
	v_cndmask_b32_e32 v2, v54, v2, vcc
	v_div_scale_f32 v54, s[4:5], v2, v2, 1.0
	v_rcp_f32_e32 v55, v54
	s_nop 0
	v_fma_f32 v56, -v54, v55, 1.0
	v_fmac_f32_e32 v55, v56, v55
	v_div_scale_f32 v56, vcc, 1.0, v2, 1.0
	v_mul_f32_e32 v57, v56, v55
	v_fma_f32 v58, -v54, v57, v56
	v_fmac_f32_e32 v57, v58, v55
	v_fma_f32 v54, -v54, v57, v56
	v_div_fmas_f32 v54, v54, v55, v57
	v_div_fixup_f32 v2, v54, v2, 1.0
	v_pk_mul_f32 v[46:47], v[46:47], v[2:3] op_sel_hi:[1,0]
	v_pk_mul_f32 v[44:45], v[44:45], v[2:3] op_sel_hi:[1,0]
	v_pk_mul_f32 v[50:51], v[50:51], v[2:3] op_sel_hi:[1,0]
	v_pk_mul_f32 v[48:49], v[48:49], v[2:3] op_sel_hi:[1,0]
	v_max_f32_e32 v44, 0, v44
	v_max_f32_e32 v45, 0, v45
	v_max_f32_e32 v46, 0, v46
	v_max_f32_e32 v48, 0, v48
	v_mul_f32_e32 v54, v44, v44
	v_max_f32_e32 v44, 0, v49
	v_mul_f32_e32 v49, v45, v45
	v_max_f32_e32 v45, 0, v50
	v_mul_f32_e32 v50, v46, v46
	v_max_f32_e32 v46, 0, v51
	v_mul_f32_e32 v48, v48, v48
	v_mul_f32_e32 v44, v44, v44
	v_mul_f32_e32 v45, v45, v45
	v_mul_f32_e32 v46, v46, v46
	v_cvt_pk_bf16_f32 v44, v48, v44
	v_cvt_pk_bf16_f32 v45, v45, v46
	v_cvt_pk_bf16_f32 v46, v54, v49
	v_lshlrev_b64 v[48:49], 13, v[52:53]
	v_lshl_add_u64 v[48:49], s[0:1], 0, v[48:49]
	v_pk_mul_f32 v[38:39], v[38:39], v[2:3] op_sel_hi:[1,0]
	v_pk_mul_f32 v[36:37], v[36:37], v[2:3] op_sel_hi:[1,0]
	v_lshl_add_u64 v[48:49], v[48:49], 0, s[26:27]
	v_pk_mul_f32 v[42:43], v[42:43], v[2:3] op_sel_hi:[1,0]
	v_pk_mul_f32 v[40:41], v[40:41], v[2:3] op_sel_hi:[1,0]
	v_max_f32_e32 v36, 0, v36
	v_max_f32_e32 v37, 0, v37
	v_max_f32_e32 v38, 0, v38
	v_max_f32_e32 v47, 0, v47
	v_lshl_add_u64 v[48:49], v[48:49], 0, s[46:47]
	v_max_f32_e32 v2, 0, v40
	v_mul_f32_e32 v40, v36, v36
	v_max_f32_e32 v36, 0, v41
	v_mul_f32_e32 v41, v37, v37
	v_max_f32_e32 v37, 0, v42
	v_mul_f32_e32 v42, v38, v38
	v_max_f32_e32 v38, 0, v43
	v_max_f32_e32 v39, 0, v39
	v_mul_f32_e32 v47, v47, v47
	v_lshl_add_u64 v[48:49], v[48:49], 0, v[128:129]
	v_mul_f32_e32 v36, v36, v36
	v_mul_f32_e32 v37, v37, v37
	v_mul_f32_e32 v38, v38, v38
	v_mul_f32_e32 v39, v39, v39
	v_cvt_pk_bf16_f32 v47, v50, v47
	global_store_dwordx4 v[48:49], v[44:47], off nt
	v_mul_f32_e32 v2, v2, v2
	v_cvt_pk_bf16_f32 v36, v2, v36
	v_cvt_pk_bf16_f32 v37, v37, v38
	v_cvt_pk_bf16_f32 v38, v40, v41
	v_cvt_pk_bf16_f32 v39, v42, v39
	global_store_dwordx4 v[48:49], v[36:39], off offset:256 nt
	s_nop 1
	v_mov_b32_e32 v2, v163
	v_fmamk_f32 v2, v2, 0x3a800000, v208
	v_add_u32_e32 v36, 0xa0, v144
	v_ashrrev_i32_e32 v37, 31, v36
	s_nop 0
	s_nop 1
	s_nop 1
	s_nop 0
	v_rsq_f32_e32 v2, v2
	s_nop 0
	v_pk_mul_f32 v[30:31], v[30:31], v[2:3] op_sel_hi:[1,0]
	v_pk_mul_f32 v[28:29], v[28:29], v[2:3] op_sel_hi:[1,0]
	v_pk_mul_f32 v[34:35], v[34:35], v[2:3] op_sel_hi:[1,0]
	v_pk_mul_f32 v[32:33], v[32:33], v[2:3] op_sel_hi:[1,0]
	v_max_f32_e32 v28, 0, v28
	v_max_f32_e32 v29, 0, v29
	v_max_f32_e32 v30, 0, v30
	v_max_f32_e32 v32, 0, v32
	v_mul_f32_e32 v38, v28, v28
	v_max_f32_e32 v28, 0, v33
	v_mul_f32_e32 v33, v29, v29
	v_max_f32_e32 v29, 0, v34
	v_mul_f32_e32 v34, v30, v30
	v_max_f32_e32 v30, 0, v35
	v_mul_f32_e32 v32, v32, v32
	v_mul_f32_e32 v28, v28, v28
	v_mul_f32_e32 v29, v29, v29
	v_mul_f32_e32 v30, v30, v30
	v_cvt_pk_bf16_f32 v28, v32, v28
	v_cvt_pk_bf16_f32 v29, v29, v30
	v_cvt_pk_bf16_f32 v30, v38, v33
	v_lshlrev_b64 v[32:33], 13, v[36:37]
	v_lshl_add_u64 v[32:33], s[0:1], 0, v[32:33]
	v_pk_mul_f32 v[22:23], v[22:23], v[2:3] op_sel_hi:[1,0]
	v_pk_mul_f32 v[20:21], v[20:21], v[2:3] op_sel_hi:[1,0]
	v_lshl_add_u64 v[32:33], v[32:33], 0, s[26:27]
	v_pk_mul_f32 v[26:27], v[26:27], v[2:3] op_sel_hi:[1,0]
	v_pk_mul_f32 v[24:25], v[24:25], v[2:3] op_sel_hi:[1,0]
	v_max_f32_e32 v20, 0, v20
	v_max_f32_e32 v21, 0, v21
	v_max_f32_e32 v22, 0, v22
	v_max_f32_e32 v31, 0, v31
	v_lshl_add_u64 v[32:33], v[32:33], 0, s[46:47]
	v_max_f32_e32 v2, 0, v24
	v_mul_f32_e32 v24, v20, v20
	v_max_f32_e32 v20, 0, v25
	v_mul_f32_e32 v25, v21, v21
	v_max_f32_e32 v21, 0, v26
	v_mul_f32_e32 v26, v22, v22
	v_max_f32_e32 v22, 0, v27
	v_max_f32_e32 v23, 0, v23
	v_mul_f32_e32 v31, v31, v31
	v_lshl_add_u64 v[32:33], v[32:33], 0, v[128:129]
	v_mul_f32_e32 v20, v20, v20
	v_mul_f32_e32 v21, v21, v21
	v_mul_f32_e32 v22, v22, v22
	v_mul_f32_e32 v23, v23, v23
	v_cvt_pk_bf16_f32 v31, v34, v31
	global_store_dwordx4 v[32:33], v[28:31], off nt
	v_mul_f32_e32 v2, v2, v2
	v_cvt_pk_bf16_f32 v20, v2, v20
	v_cvt_pk_bf16_f32 v21, v21, v22
	v_cvt_pk_bf16_f32 v22, v24, v25
	v_cvt_pk_bf16_f32 v23, v26, v23
	global_store_dwordx4 v[32:33], v[20:23], off offset:256 nt
	s_nop 1
	v_mov_b32_e32 v2, v164
	v_fmamk_f32 v2, v2, 0x3a800000, v208
	v_add_u32_e32 v20, 0xb0, v144
	v_ashrrev_i32_e32 v21, 31, v20
	s_nop 0
	s_nop 1
	s_nop 1
	s_mov_b64 s[4:5], -1
	v_rsq_f32_e32 v2, v2
	s_nop 0
	v_pk_mul_f32 v[14:15], v[14:15], v[2:3] op_sel_hi:[1,0]
	v_pk_mul_f32 v[12:13], v[12:13], v[2:3] op_sel_hi:[1,0]
	v_pk_mul_f32 v[18:19], v[18:19], v[2:3] op_sel_hi:[1,0]
	v_pk_mul_f32 v[16:17], v[16:17], v[2:3] op_sel_hi:[1,0]
	v_max_f32_e32 v12, 0, v12
	v_max_f32_e32 v13, 0, v13
	v_max_f32_e32 v14, 0, v14
	v_max_f32_e32 v16, 0, v16
	v_mul_f32_e32 v22, v12, v12
	v_max_f32_e32 v12, 0, v17
	v_mul_f32_e32 v17, v13, v13
	v_max_f32_e32 v13, 0, v18
	v_mul_f32_e32 v18, v14, v14
	v_max_f32_e32 v14, 0, v19
	v_mul_f32_e32 v16, v16, v16
	v_mul_f32_e32 v12, v12, v12
	v_mul_f32_e32 v13, v13, v13
	v_mul_f32_e32 v14, v14, v14
	v_cvt_pk_bf16_f32 v12, v16, v12
	v_cvt_pk_bf16_f32 v13, v13, v14
	v_cvt_pk_bf16_f32 v14, v22, v17
	v_lshlrev_b64 v[16:17], 13, v[20:21]
	v_lshl_add_u64 v[16:17], s[0:1], 0, v[16:17]
	v_pk_mul_f32 v[6:7], v[6:7], v[2:3] op_sel_hi:[1,0]
	v_pk_mul_f32 v[4:5], v[4:5], v[2:3] op_sel_hi:[1,0]
	v_lshl_add_u64 v[16:17], v[16:17], 0, s[26:27]
	v_pk_mul_f32 v[10:11], v[10:11], v[2:3] op_sel_hi:[1,0]
	v_pk_mul_f32 v[8:9], v[8:9], v[2:3] op_sel_hi:[1,0]
	v_max_f32_e32 v4, 0, v4
	v_max_f32_e32 v5, 0, v5
	v_max_f32_e32 v6, 0, v6
	v_max_f32_e32 v15, 0, v15
	v_lshl_add_u64 v[16:17], v[16:17], 0, s[46:47]
	v_max_f32_e32 v2, 0, v8
	v_mul_f32_e32 v8, v4, v4
	v_max_f32_e32 v4, 0, v9
	v_mul_f32_e32 v9, v5, v5
	v_max_f32_e32 v5, 0, v10
	v_mul_f32_e32 v10, v6, v6
	v_max_f32_e32 v6, 0, v11
	v_max_f32_e32 v7, 0, v7
	v_mul_f32_e32 v15, v15, v15
	v_lshl_add_u64 v[16:17], v[16:17], 0, v[128:129]
	v_mul_f32_e32 v4, v4, v4
	v_mul_f32_e32 v5, v5, v5
	v_mul_f32_e32 v6, v6, v6
	v_mul_f32_e32 v7, v7, v7
	v_cvt_pk_bf16_f32 v15, v18, v15
	global_store_dwordx4 v[16:17], v[12:15], off nt
	v_mul_f32_e32 v2, v2, v2
	v_cvt_pk_bf16_f32 v4, v2, v4
	v_cvt_pk_bf16_f32 v5, v5, v6
	v_cvt_pk_bf16_f32 v6, v8, v9
	v_cvt_pk_bf16_f32 v7, v10, v7
	global_store_dwordx4 v[16:17], v[4:7], off offset:256 nt
	s_cbranch_scc1 .LBB0_2536
	s_andn2_b64 vcc, exec, s[14:15]
	s_cbranch_vccnz .LBB0_2535
	s_barrier
	s_branch .LBB0_2535

.LBB0_2555:
	s_add_i32 s11, s11, 0x10000
	v_or_b32_e32 v2, s11, v2
	v_add_u32_e32 v4, s8, v2
	v_ashrrev_i32_e32 v5, 31, v4
	v_lshl_add_u64 v[6:7], v[4:5], 2, s[2:3]
	global_load_dword v2, v[6:7], off
	v_lshlrev_b32_e32 v6, 3, v1
	v_lshlrev_b64 v[4:5], 13, v[4:5]
	v_lshl_add_u64 v[4:5], s[0:1], 0, v[4:5]
	s_lshl_b32 s46, s10, 1
	v_mov_b32_e32 v7, v3
	v_lshl_add_u64 v[4:5], v[4:5], 0, s[46:47]
	v_lshl_add_u64 v[4:5], v[4:5], 0, v[6:7]
	s_waitcnt vmcnt(0)
	v_fmamk_f32 v1, v2, 0x3a800000, v208
	v_mul_f32_e32 v2, 0x4f800000, v1
	s_nop 1
	s_nop 0
	s_nop 1
	s_nop 1
	s_nop 1
	v_rsq_f32_e32 v2, v1
	s_nop 0
	v_pk_mul_f32 v[6:7], v[110:111], v[2:3] op_sel_hi:[1,0]
	v_pk_mul_f32 v[8:9], v[108:109], v[2:3] op_sel_hi:[1,0]
	v_max_f32_e32 v7, 0, v7
	v_pk_mul_f32 v[10:11], v[114:115], v[2:3] op_sel_hi:[1,0]
	v_pk_mul_f32 v[12:13], v[112:113], v[2:3] op_sel_hi:[1,0]
	v_pk_mul_f32 v[16:17], v[104:105], v[2:3] op_sel_hi:[1,0]
	v_pk_mul_f32 v[20:21], v[100:101], v[2:3] op_sel_hi:[1,0]
	v_pk_mul_f32 v[24:25], v[96:97], v[2:3] op_sel_hi:[1,0]
	v_pk_mul_f32 v[28:29], v[92:93], v[2:3] op_sel_hi:[1,0]
	v_max_f32_e32 v1, 0, v8
	v_max_f32_e32 v8, 0, v9
	v_max_f32_e32 v6, 0, v6
	v_mul_f32_e32 v7, v7, v7
	v_pk_mul_f32 v[14:15], v[106:107], v[2:3] op_sel_hi:[1,0]
	v_max_f32_e32 v9, 0, v12
	v_max_f32_e32 v12, 0, v13
	v_max_f32_e32 v10, 0, v10
	v_max_f32_e32 v11, 0, v11
	v_max_f32_e32 v13, 0, v16
	v_max_f32_e32 v16, 0, v17
	v_max_f32_e32 v17, 0, v20
	v_max_f32_e32 v20, 0, v21
	v_max_f32_e32 v21, 0, v24
	v_max_f32_e32 v24, 0, v25
	v_max_f32_e32 v25, 0, v28
	v_max_f32_e32 v28, 0, v29
	v_mul_f32_e32 v1, v1, v1
	v_mul_f32_e32 v8, v8, v8
	v_mul_f32_e32 v29, v6, v6
	v_cvt_pk_bf16_f32 v6, v1, v8
	v_cvt_pk_bf16_f32 v7, v29, v7
	v_pk_mul_f32 v[18:19], v[102:103], v[2:3] op_sel_hi:[1,0]
	v_max_f32_e32 v14, 0, v14
	v_max_f32_e32 v15, 0, v15
	v_mul_f32_e32 v9, v9, v9
	v_mul_f32_e32 v12, v12, v12
	v_mul_f32_e32 v10, v10, v10
	v_mul_f32_e32 v11, v11, v11
	global_store_dwordx2 v[4:5], v[6:7], off
	v_cvt_pk_bf16_f32 v6, v9, v12
	v_cvt_pk_bf16_f32 v7, v10, v11
	v_pk_mul_f32 v[22:23], v[98:99], v[2:3] op_sel_hi:[1,0]
	v_max_f32_e32 v18, 0, v18
	v_max_f32_e32 v19, 0, v19
	v_mul_f32_e32 v13, v13, v13
	v_mul_f32_e32 v16, v16, v16
	v_mul_f32_e32 v14, v14, v14
	v_mul_f32_e32 v15, v15, v15
	global_store_dwordx2 v[4:5], v[6:7], off offset:32
	v_cvt_pk_bf16_f32 v6, v13, v16
	v_cvt_pk_bf16_f32 v7, v14, v15
	v_pk_mul_f32 v[26:27], v[94:95], v[2:3] op_sel_hi:[1,0]
	v_max_f32_e32 v22, 0, v22
	v_max_f32_e32 v23, 0, v23
	v_mul_f32_e32 v17, v17, v17
	v_mul_f32_e32 v20, v20, v20
	v_mul_f32_e32 v18, v18, v18
	v_mul_f32_e32 v19, v19, v19
	global_store_dwordx2 v[4:5], v[6:7], off offset:64
	v_cvt_pk_bf16_f32 v6, v17, v20
	v_cvt_pk_bf16_f32 v7, v18, v19
	v_max_f32_e32 v26, 0, v26
	v_max_f32_e32 v27, 0, v27
	v_mul_f32_e32 v21, v21, v21
	v_mul_f32_e32 v24, v24, v24
	v_mul_f32_e32 v22, v22, v22
	v_mul_f32_e32 v23, v23, v23
	global_store_dwordx2 v[4:5], v[6:7], off offset:96
	v_cvt_pk_bf16_f32 v6, v21, v24
	v_cvt_pk_bf16_f32 v7, v22, v23
	v_mul_f32_e32 v25, v25, v25
	v_mul_f32_e32 v28, v28, v28
	v_mul_f32_e32 v26, v26, v26
	v_mul_f32_e32 v27, v27, v27
	global_store_dwordx2 v[4:5], v[6:7], off offset:128
	v_cvt_pk_bf16_f32 v6, v25, v28
	v_cvt_pk_bf16_f32 v7, v26, v27
	global_store_dwordx2 v[4:5], v[6:7], off offset:160
	v_pk_mul_f32 v[6:7], v[90:91], v[2:3] op_sel_hi:[1,0]
	v_pk_mul_f32 v[8:9], v[88:89], v[2:3] op_sel_hi:[1,0]
	v_max_f32_e32 v6, 0, v6
	v_max_f32_e32 v1, 0, v8
	v_max_f32_e32 v8, 0, v9
	v_mul_f32_e32 v9, v6, v6
	v_max_f32_e32 v6, 0, v7
	v_mul_f32_e32 v7, v6, v6
	v_mul_f32_e32 v1, v1, v1
	v_mul_f32_e32 v8, v8, v8
	v_cvt_pk_bf16_f32 v6, v1, v8
	v_cvt_pk_bf16_f32 v7, v9, v7
	global_store_dwordx2 v[4:5], v[6:7], off offset:192
	v_pk_mul_f32 v[6:7], v[86:87], v[2:3] op_sel_hi:[1,0]
	v_pk_mul_f32 v[8:9], v[84:85], v[2:3] op_sel_hi:[1,0]
	v_max_f32_e32 v6, 0, v6
	v_max_f32_e32 v1, 0, v8
	v_max_f32_e32 v8, 0, v9
	v_mul_f32_e32 v9, v6, v6
	v_max_f32_e32 v6, 0, v7
	v_mul_f32_e32 v7, v6, v6
	v_mul_f32_e32 v1, v1, v1
	v_mul_f32_e32 v8, v8, v8
	v_cvt_pk_bf16_f32 v6, v1, v8
	v_cvt_pk_bf16_f32 v7, v9, v7
	global_store_dwordx2 v[4:5], v[6:7], off offset:224
	v_pk_mul_f32 v[6:7], v[82:83], v[2:3] op_sel_hi:[1,0]
	v_pk_mul_f32 v[8:9], v[80:81], v[2:3] op_sel_hi:[1,0]
	v_max_f32_e32 v6, 0, v6
	v_max_f32_e32 v1, 0, v8
	v_max_f32_e32 v8, 0, v9
	v_mul_f32_e32 v9, v6, v6
	v_max_f32_e32 v6, 0, v7
	v_mul_f32_e32 v7, v6, v6
	v_mul_f32_e32 v1, v1, v1
	v_mul_f32_e32 v8, v8, v8
	v_cvt_pk_bf16_f32 v6, v1, v8
	v_cvt_pk_bf16_f32 v7, v9, v7
	global_store_dwordx2 v[4:5], v[6:7], off offset:256
	v_pk_mul_f32 v[6:7], v[78:79], v[2:3] op_sel_hi:[1,0]
	v_pk_mul_f32 v[8:9], v[76:77], v[2:3] op_sel_hi:[1,0]
	v_max_f32_e32 v6, 0, v6
	v_max_f32_e32 v1, 0, v8
	v_max_f32_e32 v8, 0, v9
	v_mul_f32_e32 v9, v6, v6
	v_max_f32_e32 v6, 0, v7
	v_mul_f32_e32 v7, v6, v6
	v_mul_f32_e32 v1, v1, v1
	v_mul_f32_e32 v8, v8, v8
	v_cvt_pk_bf16_f32 v6, v1, v8
	v_cvt_pk_bf16_f32 v7, v9, v7
	global_store_dwordx2 v[4:5], v[6:7], off offset:288
	v_pk_mul_f32 v[6:7], v[74:75], v[2:3] op_sel_hi:[1,0]
	v_pk_mul_f32 v[8:9], v[72:73], v[2:3] op_sel_hi:[1,0]
	v_max_f32_e32 v6, 0, v6
	v_max_f32_e32 v1, 0, v8
	v_max_f32_e32 v8, 0, v9
	v_mul_f32_e32 v9, v6, v6
	v_max_f32_e32 v6, 0, v7
	v_mul_f32_e32 v7, v6, v6
	v_mul_f32_e32 v1, v1, v1
	v_mul_f32_e32 v8, v8, v8
	v_cvt_pk_bf16_f32 v6, v1, v8
	v_cvt_pk_bf16_f32 v7, v9, v7
	global_store_dwordx2 v[4:5], v[6:7], off offset:320
	v_pk_mul_f32 v[6:7], v[70:71], v[2:3] op_sel_hi:[1,0]
	v_pk_mul_f32 v[8:9], v[68:69], v[2:3] op_sel_hi:[1,0]
	v_max_f32_e32 v6, 0, v6
	v_max_f32_e32 v1, 0, v8
	v_max_f32_e32 v8, 0, v9
	v_mul_f32_e32 v9, v6, v6
	v_max_f32_e32 v6, 0, v7
	v_mul_f32_e32 v7, v6, v6
	v_mul_f32_e32 v1, v1, v1
	v_mul_f32_e32 v8, v8, v8
	v_cvt_pk_bf16_f32 v6, v1, v8
	v_cvt_pk_bf16_f32 v7, v9, v7
	global_store_dwordx2 v[4:5], v[6:7], off offset:352
	v_pk_mul_f32 v[6:7], v[66:67], v[2:3] op_sel_hi:[1,0]
	v_pk_mul_f32 v[8:9], v[64:65], v[2:3] op_sel_hi:[1,0]
	v_max_f32_e32 v6, 0, v6
	v_max_f32_e32 v1, 0, v8
	v_max_f32_e32 v8, 0, v9
	v_mul_f32_e32 v9, v6, v6
	v_max_f32_e32 v6, 0, v7
	v_mul_f32_e32 v7, v6, v6
	v_mul_f32_e32 v1, v1, v1
	v_mul_f32_e32 v8, v8, v8
	v_cvt_pk_bf16_f32 v6, v1, v8
	v_cvt_pk_bf16_f32 v7, v9, v7
	global_store_dwordx2 v[4:5], v[6:7], off offset:384
	v_pk_mul_f32 v[6:7], v[62:63], v[2:3] op_sel_hi:[1,0]
	v_pk_mul_f32 v[8:9], v[60:61], v[2:3] op_sel_hi:[1,0]
	v_max_f32_e32 v6, 0, v6
	v_max_f32_e32 v1, 0, v8
	v_max_f32_e32 v8, 0, v9
	v_mul_f32_e32 v9, v6, v6
	v_max_f32_e32 v6, 0, v7
	v_mul_f32_e32 v7, v6, v6
	v_mul_f32_e32 v1, v1, v1
	v_mul_f32_e32 v8, v8, v8
	v_cvt_pk_bf16_f32 v6, v1, v8
	v_cvt_pk_bf16_f32 v7, v9, v7
	global_store_dwordx2 v[4:5], v[6:7], off offset:416
	v_pk_mul_f32 v[6:7], v[58:59], v[2:3] op_sel_hi:[1,0]
	v_pk_mul_f32 v[8:9], v[56:57], v[2:3] op_sel_hi:[1,0]
	v_max_f32_e32 v6, 0, v6
	v_max_f32_e32 v1, 0, v8
	v_max_f32_e32 v8, 0, v9
	v_mul_f32_e32 v9, v6, v6
	v_max_f32_e32 v6, 0, v7
	v_mul_f32_e32 v7, v6, v6
	v_mul_f32_e32 v1, v1, v1
	v_mul_f32_e32 v8, v8, v8
	v_cvt_pk_bf16_f32 v6, v1, v8
	v_cvt_pk_bf16_f32 v7, v9, v7
	global_store_dwordx2 v[4:5], v[6:7], off offset:448
	v_pk_mul_f32 v[6:7], v[54:55], v[2:3] op_sel_hi:[1,0]
	v_pk_mul_f32 v[8:9], v[52:53], v[2:3] op_sel_hi:[1,0]
	v_max_f32_e32 v6, 0, v6
	v_max_f32_e32 v1, 0, v8
	v_mul_f32_e32 v8, v6, v6
	v_max_f32_e32 v6, 0, v7
	v_max_f32_e32 v2, 0, v9
	v_mul_f32_e32 v7, v6, v6
	v_mul_f32_e32 v1, v1, v1
	v_mul_f32_e32 v2, v2, v2
	v_cvt_pk_bf16_f32 v6, v1, v2
	v_cvt_pk_bf16_f32 v7, v8, v7
	global_store_dwordx2 v[4:5], v[6:7], off offset:480
